# GEMM K-loops: s_setprio 1 issued before the pre-MFMA barrier so the first instruction after the barrier is an MFMA
# speedup vs baseline: 1.0055x; 1.0009x over previous
;     __host__ __device__ bool next(int i, Unit& u) const { const bool ok = StaticOrder::next(i, u); u.pm = 0; u.pn = 0; return ok; }
; #define PG8_STAGE(bufoff, gbase, voff) do { _Pragma("unroll") for (int _i = 0; _i < 2; ++_i) \
;         __builtin_amdgcn_global_load_lds((const unsigned*)((const char*)(gbase) + (voff)[_i]), (PG8_LAS unsigned*)(lds + (bufoff) + ldsw + _i * 8192), 16, 0, 0); } while (0)
; #define PG8_BAR __builtin_amdgcn_s_barrier()
; template <class Epi, class Sched, bool ALIGN_EPI = false, bool SP2 = false>
; __device__ __forceinline__ void gemm_phase(PG8_LAS unsigned char* lds, const Gemm g, const Sched& S, const Epi& E, const int wave_in) {
;     ...
;     for (;;) {
;         const bool has_next = S.next(ui + 1, nxt);
;         const char* nA = has_next ? (const char*)g.A + (size_t)nxt.pm * tstepA : cA; const char* nB = has_next ? (const char*)g.Bt + (size_t)nxt.pn * tstepB : cB;
;         for (int t = 0; t < nt; t += 2) {
;             const bool last = (t == nt - 2);
;             const char* a1 = cA + (size_t)(t + 1) * kstep;
;             const char* a2 = last ? nA : cA + (size_t)(t + 2) * kstep; const char* b2 = last ? nB : cB + (size_t)(t + 2) * kstep;
;             const char* a3 = a2 + kstep; const char* b3 = b2 + kstep;
;             if (last && has_next) S.a_ready(nxt);
;             if constexpr (SP2) {
;             PG8_LDB(B0, 0, 0); PG8_LDB(B1, 0, 1); PG8_SCHED; PG8_LDA(At, 0, 0); PG8_STAGE(PG8_SA(1, 1), a1 + hstepA, voffA);
;             PG8_WAIT_V(8); PG8_WAIT_L(0); PG8_BAR; PG8_MMA(0, 0, At, B0); PG8_MMA(0, 1, At, B1); PG8_BAR; PG8_SCHED;
;             PG8_LDA(At, 0, 1); PG8_STAGE(PG8_SB(0, 0), b2, voffB); PG8_STAGE(PG8_SB(0, 1), b2 + hstepB, voffB); PG8_STAGE(PG8_SA(0, 0), a2, voffA);
;             PG8_WAIT_V(8); PG8_WAIT_L(0); PG8_BAR; PG8_MMA(1, 0, At, B0); PG8_MMA(1, 1, At, B1); PG8_BAR; PG8_SCHED;
;             PG8_LDB(B0, 1, 0); PG8_LDB(B1, 1, 1); PG8_SCHED; PG8_LDA(At, 1, 0); PG8_STAGE(PG8_SA(0, 1), a2 + hstepA, voffA);
;             PG8_WAIT_V(8); PG8_WAIT_L(0); PG8_BAR; PG8_MMA(0, 0, At, B0); PG8_MMA(0, 1, At, B1); PG8_BAR; PG8_SCHED;
;             PG8_LDA(At, 1, 1); PG8_STAGE(PG8_SB(1, 0), b3, voffB); PG8_STAGE(PG8_SB(1, 1), b3 + hstepB, voffB); PG8_STAGE(PG8_SA(1, 0), a3, voffA);
;             PG8_WAIT_V(8); PG8_WAIT_L(0); PG8_BAR; PG8_MMA(1, 0, At, B0); PG8_MMA(1, 1, At, B1); PG8_BAR; PG8_SCHED;
.LBB0_157:
	s_ashr_i32 s15, s14, 31
	s_lshl_b64 s[16:17], s[14:15], 20
	s_add_u32 s16, s28, s16
	s_addc_u32 s17, s29, s17
	s_and_b64 s[18:19], s[2:3], exec
	s_cselect_b32 s5, s17, s23
	s_cselect_b32 s15, s16, s22
	s_ashr_i32 s13, s12, 31
	s_lshl_b64 s[18:19], s[12:13], 20
	s_add_u32 s18, s30, s18
	s_addc_u32 s19, s31, s19
	s_and_b64 s[26:27], s[2:3], exec
	s_cselect_b32 s13, s19, s25
	s_cselect_b32 s46, s18, s24
	s_add_u32 s22, s22, 0x80080
	s_addc_u32 s23, s23, 0
	s_add_u32 s47, s24, 0x100
	v_mov_b32_e32 v0, 0
	s_addc_u32 s48, s25, 0
	s_mov_b32 s49, -2
	ds_read_b128 v[144:147], v151
	ds_read_b128 v[154:157], v151 offset:1024
	ds_read_b128 v[158:161], v151 offset:2048
	ds_read_b128 v[162:165], v151 offset:3072
	ds_read_b128 v[166:169], v152
	ds_read_b128 v[170:173], v152 offset:1024
	ds_read_b128 v[174:177], v152 offset:2048
	ds_read_b128 v[178:181], v152 offset:3072
	s_add_u32 s24, s22, 0xfff80080
	s_addc_u32 s25, s23, -1
	s_cmp_eq_u32 s49, 28
	s_cselect_b32 s27, s5, s25
	s_cselect_b32 s26, s15, s24
	s_cselect_b32 s25, s13, s48
	s_cselect_b32 s24, s46, s47
	v_lshl_add_u64 v[214:215], s[22:23], 0, v[136:137]
	s_add_i32 m0, s21, 0xc000
	ds_read_b128 v[182:185], v153
	ds_read_b128 v[186:189], v153 offset:1024
	ds_read_b128 v[190:193], v153 offset:2048
	ds_read_b128 v[194:197], v153 offset:3072
	ds_read_b128 v[198:201], v153 offset:4096
	ds_read_b128 v[202:205], v153 offset:5120
	ds_read_b128 v[206:209], v153 offset:6144
	ds_read_b128 v[210:213], v153 offset:7168
	global_load_lds_dwordx4 v[214:215], off
	v_lshl_add_u64 v[214:215], s[22:23], 0, v[138:139]
	s_add_i32 m0, s21, 0xe000
	s_nop 0
	global_load_lds_dwordx4 v[214:215], off
	s_waitcnt vmcnt(8)
	s_waitcnt lgkmcnt(0)
	s_setprio 1
	s_barrier
	v_mfma_f32_16x16x32_bf16 v[124:127], v[144:147], v[182:185], 0
	v_mfma_f32_16x16x32_bf16 v[120:123], v[158:161], v[182:185], 0
	v_mfma_f32_16x16x32_bf16 v[108:111], v[144:147], v[190:193], 0
	v_mfma_f32_16x16x32_bf16 v[104:107], v[158:161], v[190:193], 0
	v_mfma_f32_16x16x32_bf16 v[92:95], v[144:147], v[198:201], 0
	v_mfma_f32_16x16x32_bf16 v[88:91], v[158:161], v[198:201], 0
	v_mfma_f32_16x16x32_bf16 v[76:79], v[144:147], v[206:209], 0
	v_mfma_f32_16x16x32_bf16 v[72:75], v[158:161], v[206:209], 0
	v_mfma_f32_16x16x32_bf16 v[124:127], v[154:157], v[186:189], v[124:127]
	v_mfma_f32_16x16x32_bf16 v[120:123], v[162:165], v[186:189], v[120:123]
	v_mfma_f32_16x16x32_bf16 v[108:111], v[154:157], v[194:197], v[108:111]
	v_mfma_f32_16x16x32_bf16 v[104:107], v[162:165], v[194:197], v[104:107]
	v_mfma_f32_16x16x32_bf16 v[92:95], v[154:157], v[202:205], v[92:95]
	v_mfma_f32_16x16x32_bf16 v[88:91], v[162:165], v[202:205], v[88:91]
	v_mfma_f32_16x16x32_bf16 v[76:79], v[154:157], v[210:213], v[76:79]
	v_mfma_f32_16x16x32_bf16 v[72:75], v[162:165], v[210:213], v[72:75]
	v_mfma_f32_16x16x32_bf16 v[116:119], v[166:169], v[182:185], 0
	v_mfma_f32_16x16x32_bf16 v[112:115], v[174:177], v[182:185], 0
	v_mfma_f32_16x16x32_bf16 v[100:103], v[166:169], v[190:193], 0
	v_mfma_f32_16x16x32_bf16 v[96:99], v[174:177], v[190:193], 0
	v_mfma_f32_16x16x32_bf16 v[84:87], v[166:169], v[198:201], 0
	v_mfma_f32_16x16x32_bf16 v[80:83], v[174:177], v[198:201], 0
	v_mfma_f32_16x16x32_bf16 v[68:71], v[166:169], v[206:209], 0
	v_mfma_f32_16x16x32_bf16 v[64:67], v[174:177], v[206:209], 0
	v_mfma_f32_16x16x32_bf16 v[116:119], v[170:173], v[186:189], v[116:119]
	v_mfma_f32_16x16x32_bf16 v[112:115], v[178:181], v[186:189], v[112:115]
	v_mfma_f32_16x16x32_bf16 v[100:103], v[170:173], v[194:197], v[100:103]
	v_mfma_f32_16x16x32_bf16 v[96:99], v[178:181], v[194:197], v[96:99]
	v_mfma_f32_16x16x32_bf16 v[84:87], v[170:173], v[202:205], v[84:87]
	v_mfma_f32_16x16x32_bf16 v[80:83], v[178:181], v[202:205], v[80:83]
	v_mfma_f32_16x16x32_bf16 v[68:71], v[170:173], v[210:213], v[68:71]
	v_mfma_f32_16x16x32_bf16 v[64:67], v[178:181], v[210:213], v[64:67]
	s_setprio 0
	s_barrier
	s_add_i32 s50, s43, s34
	v_lshl_add_u64 v[214:215], s[24:25], 0, v[130:131]
	s_mov_b32 m0, s50
	ds_read_b128 v[182:185], v153 offset:16384
	ds_read_b128 v[186:189], v153 offset:17408
	ds_read_b128 v[190:193], v153 offset:18432
	ds_read_b128 v[194:197], v153 offset:19456
	ds_read_b128 v[198:201], v153 offset:20480
	ds_read_b128 v[202:205], v153 offset:21504
	ds_read_b128 v[206:209], v153 offset:22528
	ds_read_b128 v[210:213], v153 offset:23552
	global_load_lds_dwordx4 v[214:215], off
	s_add_i32 m0, s50, 0x2000
	s_add_u32 s50, s24, 0x80000
	v_lshl_add_u64 v[216:217], s[24:25], 0, v[134:135]
	s_addc_u32 s51, s25, 0
	s_add_i32 s52, s44, s34
	global_load_lds_dwordx4 v[216:217], off
	v_lshl_add_u64 v[218:219], s[50:51], 0, v[130:131]
	s_mov_b32 m0, s52
	v_lshl_add_u64 v[220:221], s[26:27], 0, v[132:133]
	global_load_lds_dwordx4 v[218:219], off
	v_lshl_add_u64 v[218:219], s[50:51], 0, v[134:135]
	s_add_i32 m0, s52, 0x2000
	s_nop 0
	global_load_lds_dwordx4 v[218:219], off
	v_lshl_add_u64 v[218:219], s[26:27], 0, v[128:129]
	s_mov_b32 m0, s21
	s_nop 0
	global_load_lds_dwordx4 v[218:219], off
	s_mov_b32 m0, s35
	s_nop 0
	global_load_lds_dwordx4 v[220:221], off
	s_waitcnt vmcnt(8)
	s_waitcnt lgkmcnt(0)
	s_setprio 1
	s_barrier
; #define PG8_STAGE(bufoff, gbase, voff) do { _Pragma("unroll") for (int _i = 0; _i < 2; ++_i) \
;         __builtin_amdgcn_global_load_lds((const unsigned*)((const char*)(gbase) + (voff)[_i]), (PG8_LAS unsigned*)(lds + (bufoff) + ldsw + _i * 8192), 16, 0, 0); } while (0)
; #define PG8_LDA(dst, b, h) do { _Pragma("unroll") for (int m = 0; m < 4; ++m) _Pragma("unroll") for (int k = 0; k < 2; ++k) dst[m][k] = *(const PG8_LAS bf16x8*)(lds + PG8_SA(b, h) + aoff + m * 2048 + k * 1024); } while (0)
; #define PG8_LDB(dst, b, h) do { _Pragma("unroll") for (int n = 0; n < 2; ++n) _Pragma("unroll") for (int k = 0; k < 2; ++k) dst[n][k] = *(const PG8_LAS bf16x8*)(lds + PG8_SB(b, h) + boff + n * 2048 + k * 1024); } while (0)
; #define PG8_MMA(ai, bj, At, Bt) do { __builtin_amdgcn_s_setprio(1); _Pragma("unroll") for (int m = 0; m < 4; ++m) _Pragma("unroll") for (int n = 0; n < 2; ++n) _Pragma("unroll") for (int k = 0; k < 2; ++k) \
;         acc[ai][bj][m][n] = __builtin_amdgcn_mfma_f32_16x16x32_bf16(Bt[n][k], At[m][k], acc[ai][bj][m][n], 0, 0, 0); __builtin_amdgcn_s_setprio(0); } while (0)
; #define PG8_WAIT_V(n) asm volatile("s_waitcnt vmcnt(" #n ")" ::: "memory")
; #define PG8_WAIT_L(n) asm volatile("s_waitcnt lgkmcnt(" #n ")" ::: "memory")
; #define PG8_BAR __builtin_amdgcn_s_barrier()
; #define PG8_SCHED __builtin_amdgcn_sched_barrier(0)
; template <class Epi, class Sched, bool ALIGN_EPI = false, bool SP2 = false>
; __device__ __forceinline__ void gemm_phase(PG8_LAS unsigned char* lds, const Gemm g, const Sched& S, const Epi& E, const int wave_in) {
;     ...
;             PG8_WAIT_V(8); PG8_WAIT_L(0); PG8_BAR; PG8_MMA(0, 0, At, B0); PG8_MMA(0, 1, At, B1); PG8_BAR; PG8_SCHED;
;             PG8_LDA(At, 0, 1); PG8_STAGE(PG8_SB(0, 0), b2, voffB); PG8_STAGE(PG8_SB(0, 1), b2 + hstepB, voffB); PG8_STAGE(PG8_SA(0, 0), a2, voffA);
;             PG8_WAIT_V(8); PG8_WAIT_L(0); PG8_BAR; PG8_MMA(1, 0, At, B0); PG8_MMA(1, 1, At, B1); PG8_BAR; PG8_SCHED;
;             PG8_LDB(B0, 1, 0); PG8_LDB(B1, 1, 1); PG8_SCHED; PG8_LDA(At, 1, 0); PG8_STAGE(PG8_SA(0, 1), a2 + hstepA, voffA);
;             PG8_WAIT_V(8); PG8_WAIT_L(0); PG8_BAR; PG8_MMA(0, 0, At, B0); PG8_MMA(0, 1, At, B1); PG8_BAR; PG8_SCHED;
	v_mfma_f32_16x16x32_bf16 v[60:63], v[144:147], v[182:185], 0
	v_mfma_f32_16x16x32_bf16 v[56:59], v[158:161], v[182:185], 0
	v_mfma_f32_16x16x32_bf16 v[44:47], v[144:147], v[190:193], 0
	v_mfma_f32_16x16x32_bf16 v[40:43], v[158:161], v[190:193], 0
	v_mfma_f32_16x16x32_bf16 v[28:31], v[144:147], v[198:201], 0
	v_mfma_f32_16x16x32_bf16 v[24:27], v[158:161], v[198:201], 0
	v_mfma_f32_16x16x32_bf16 v[12:15], v[144:147], v[206:209], 0
	v_mfma_f32_16x16x32_bf16 v[8:11], v[158:161], v[206:209], 0
	v_mfma_f32_16x16x32_bf16 v[60:63], v[154:157], v[186:189], v[60:63]
	v_mfma_f32_16x16x32_bf16 v[56:59], v[162:165], v[186:189], v[56:59]
	v_mfma_f32_16x16x32_bf16 v[44:47], v[154:157], v[194:197], v[44:47]
	v_mfma_f32_16x16x32_bf16 v[40:43], v[162:165], v[194:197], v[40:43]
	v_mfma_f32_16x16x32_bf16 v[28:31], v[154:157], v[202:205], v[28:31]
	v_mfma_f32_16x16x32_bf16 v[24:27], v[162:165], v[202:205], v[24:27]
	v_mfma_f32_16x16x32_bf16 v[12:15], v[154:157], v[210:213], v[12:15]
	v_mfma_f32_16x16x32_bf16 v[8:11], v[162:165], v[210:213], v[8:11]
	v_mfma_f32_16x16x32_bf16 v[52:55], v[166:169], v[182:185], 0
	v_mfma_f32_16x16x32_bf16 v[48:51], v[174:177], v[182:185], 0
	v_mfma_f32_16x16x32_bf16 v[36:39], v[166:169], v[190:193], 0
	v_mfma_f32_16x16x32_bf16 v[32:35], v[174:177], v[190:193], 0
	v_mfma_f32_16x16x32_bf16 v[20:23], v[166:169], v[198:201], 0
	v_mfma_f32_16x16x32_bf16 v[16:19], v[174:177], v[198:201], 0
	v_mfma_f32_16x16x32_bf16 v[4:7], v[166:169], v[206:209], 0
	v_mfma_f32_16x16x32_bf16 v[0:3], v[174:177], v[206:209], 0
	v_mfma_f32_16x16x32_bf16 v[52:55], v[170:173], v[186:189], v[52:55]
	v_mfma_f32_16x16x32_bf16 v[48:51], v[178:181], v[186:189], v[48:51]
	v_mfma_f32_16x16x32_bf16 v[36:39], v[170:173], v[194:197], v[36:39]
	v_mfma_f32_16x16x32_bf16 v[32:35], v[178:181], v[194:197], v[32:35]
	v_mfma_f32_16x16x32_bf16 v[20:23], v[170:173], v[202:205], v[20:23]
	v_mfma_f32_16x16x32_bf16 v[16:19], v[178:181], v[202:205], v[16:19]
	v_mfma_f32_16x16x32_bf16 v[4:7], v[170:173], v[210:213], v[4:7]
	v_mfma_f32_16x16x32_bf16 v[0:3], v[178:181], v[210:213], v[0:3]
	s_setprio 0
	s_barrier
	s_add_i32 s50, 0, 0x18000
	s_add_i32 s51, 0, 0x1c000
	v_add_u32_e32 v162, s50, v149
	v_add_u32_e32 v178, s51, v149
	ds_read_b128 v[144:147], v162
	ds_read_b128 v[154:157], v162 offset:1024
	ds_read_b128 v[158:161], v162 offset:2048
	ds_read_b128 v[162:165], v162 offset:3072
	ds_read_b128 v[166:169], v178
	ds_read_b128 v[170:173], v178 offset:1024
	ds_read_b128 v[174:177], v178 offset:2048
	ds_read_b128 v[178:181], v178 offset:3072
	s_add_u32 s26, s26, 0x80000
	s_addc_u32 s27, s27, 0
	s_mov_b32 m0, s36
	v_lshl_add_u64 v[222:223], s[26:27], 0, v[128:129]
	ds_read_b128 v[182:185], v153 offset:32768
	ds_read_b128 v[186:189], v153 offset:33792
	ds_read_b128 v[190:193], v153 offset:34816
	ds_read_b128 v[194:197], v153 offset:35840
	ds_read_b128 v[198:201], v153 offset:36864
	ds_read_b128 v[202:205], v153 offset:37888
	ds_read_b128 v[206:209], v153 offset:38912
	ds_read_b128 v[210:213], v153 offset:39936
	global_load_lds_dwordx4 v[222:223], off
	v_lshl_add_u64 v[222:223], s[26:27], 0, v[132:133]
	s_mov_b32 m0, s37
	s_nop 0
	global_load_lds_dwordx4 v[222:223], off
	s_waitcnt vmcnt(8)
	s_waitcnt lgkmcnt(0)
	s_setprio 1
	s_barrier
	v_mfma_f32_16x16x32_bf16 v[124:127], v[144:147], v[182:185], v[124:127]
	v_mfma_f32_16x16x32_bf16 v[120:123], v[158:161], v[182:185], v[120:123]
	v_mfma_f32_16x16x32_bf16 v[108:111], v[144:147], v[190:193], v[108:111]
	v_mfma_f32_16x16x32_bf16 v[104:107], v[158:161], v[190:193], v[104:107]
	v_mfma_f32_16x16x32_bf16 v[92:95], v[144:147], v[198:201], v[92:95]
	v_mfma_f32_16x16x32_bf16 v[88:91], v[158:161], v[198:201], v[88:91]
	v_mfma_f32_16x16x32_bf16 v[76:79], v[144:147], v[206:209], v[76:79]
	v_mfma_f32_16x16x32_bf16 v[72:75], v[158:161], v[206:209], v[72:75]
	v_mfma_f32_16x16x32_bf16 v[124:127], v[154:157], v[186:189], v[124:127]
	v_mfma_f32_16x16x32_bf16 v[120:123], v[162:165], v[186:189], v[120:123]
	v_mfma_f32_16x16x32_bf16 v[108:111], v[154:157], v[194:197], v[108:111]
	v_mfma_f32_16x16x32_bf16 v[104:107], v[162:165], v[194:197], v[104:107]
	v_mfma_f32_16x16x32_bf16 v[92:95], v[154:157], v[202:205], v[92:95]
	v_mfma_f32_16x16x32_bf16 v[88:91], v[162:165], v[202:205], v[88:91]
	v_mfma_f32_16x16x32_bf16 v[76:79], v[154:157], v[210:213], v[76:79]
	v_mfma_f32_16x16x32_bf16 v[72:75], v[162:165], v[210:213], v[72:75]
	v_mfma_f32_16x16x32_bf16 v[116:119], v[166:169], v[182:185], v[116:119]
	v_mfma_f32_16x16x32_bf16 v[112:115], v[174:177], v[182:185], v[112:115]
	v_mfma_f32_16x16x32_bf16 v[100:103], v[166:169], v[190:193], v[100:103]
	v_mfma_f32_16x16x32_bf16 v[96:99], v[174:177], v[190:193], v[96:99]
	v_mfma_f32_16x16x32_bf16 v[84:87], v[166:169], v[198:201], v[84:87]
	v_mfma_f32_16x16x32_bf16 v[80:83], v[174:177], v[198:201], v[80:83]
	v_mfma_f32_16x16x32_bf16 v[68:71], v[166:169], v[206:209], v[68:71]
	v_mfma_f32_16x16x32_bf16 v[64:67], v[174:177], v[206:209], v[64:67]
	v_mfma_f32_16x16x32_bf16 v[116:119], v[170:173], v[186:189], v[116:119]
	v_mfma_f32_16x16x32_bf16 v[112:115], v[178:181], v[186:189], v[112:115]
	v_mfma_f32_16x16x32_bf16 v[100:103], v[170:173], v[194:197], v[100:103]
	v_mfma_f32_16x16x32_bf16 v[96:99], v[178:181], v[194:197], v[96:99]
	v_mfma_f32_16x16x32_bf16 v[84:87], v[170:173], v[202:205], v[84:87]
	v_mfma_f32_16x16x32_bf16 v[80:83], v[178:181], v[202:205], v[80:83]
	v_mfma_f32_16x16x32_bf16 v[68:71], v[170:173], v[210:213], v[68:71]
	v_mfma_f32_16x16x32_bf16 v[64:67], v[178:181], v[210:213], v[64:67]
	s_setprio 0
	s_barrier
; #define PG8_STAGE(bufoff, gbase, voff) do { _Pragma("unroll") for (int _i = 0; _i < 2; ++_i) \
;         __builtin_amdgcn_global_load_lds((const unsigned*)((const char*)(gbase) + (voff)[_i]), (PG8_LAS unsigned*)(lds + (bufoff) + ldsw + _i * 8192), 16, 0, 0); } while (0)
; #define PG8_LDA(dst, b, h) do { _Pragma("unroll") for (int m = 0; m < 4; ++m) _Pragma("unroll") for (int k = 0; k < 2; ++k) dst[m][k] = *(const PG8_LAS bf16x8*)(lds + PG8_SA(b, h) + aoff + m * 2048 + k * 1024); } while (0)
; #define PG8_LDB(dst, b, h) do { _Pragma("unroll") for (int n = 0; n < 2; ++n) _Pragma("unroll") for (int k = 0; k < 2; ++k) dst[n][k] = *(const PG8_LAS bf16x8*)(lds + PG8_SB(b, h) + boff + n * 2048 + k * 1024); } while (0)
; #define PG8_MMA(ai, bj, At, Bt) do { __builtin_amdgcn_s_setprio(1); _Pragma("unroll") for (int m = 0; m < 4; ++m) _Pragma("unroll") for (int n = 0; n < 2; ++n) _Pragma("unroll") for (int k = 0; k < 2; ++k) \
;         acc[ai][bj][m][n] = __builtin_amdgcn_mfma_f32_16x16x32_bf16(Bt[n][k], At[m][k], acc[ai][bj][m][n], 0, 0, 0); __builtin_amdgcn_s_setprio(0); } while (0)
; #define PG8_WAIT_V(n) asm volatile("s_waitcnt vmcnt(" #n ")" ::: "memory")
; #define PG8_WAIT_L(n) asm volatile("s_waitcnt lgkmcnt(" #n ")" ::: "memory")
; #define PG8_BAR __builtin_amdgcn_s_barrier()
; template <class Epi, class Sched, bool ALIGN_EPI = false, bool SP2 = false>
; __device__ __forceinline__ void gemm_phase(PG8_LAS unsigned char* lds, const Gemm g, const Sched& S, const Epi& E, const int wave_in) {
;     ...
;         for (int t = 0; t < nt; t += 2) {
;             const bool last = (t == nt - 2);
;             const char* a1 = cA + (size_t)(t + 1) * kstep;
;             const char* a2 = last ? nA : cA + (size_t)(t + 2) * kstep; const char* b2 = last ? nB : cB + (size_t)(t + 2) * kstep;
;             const char* a3 = a2 + kstep; const char* b3 = b2 + kstep;
;             if (last && has_next) S.a_ready(nxt);
;             if constexpr (SP2) {
;             PG8_LDB(B0, 0, 0); PG8_LDB(B1, 0, 1); PG8_SCHED; PG8_LDA(At, 0, 0); PG8_STAGE(PG8_SA(1, 1), a1 + hstepA, voffA);
;     ...
;             PG8_LDA(At, 1, 1); PG8_STAGE(PG8_SB(1, 0), b3, voffB); PG8_STAGE(PG8_SB(1, 1), b3 + hstepB, voffB); PG8_STAGE(PG8_SA(1, 0), a3, voffA);
;             PG8_WAIT_V(8); PG8_WAIT_L(0); PG8_BAR; PG8_MMA(1, 0, At, B0); PG8_MMA(1, 1, At, B1); PG8_BAR; PG8_SCHED;
	s_add_i32 s26, s50, s34
	v_lshl_add_u64 v[214:215], v[214:215], 0, s[8:9]
	s_mov_b32 m0, s26
	ds_read_b128 v[182:185], v153 offset:49152
	ds_read_b128 v[186:189], v153 offset:50176
	ds_read_b128 v[190:193], v153 offset:51200
	ds_read_b128 v[194:197], v153 offset:52224
	ds_read_b128 v[198:201], v153 offset:53248
	ds_read_b128 v[202:205], v153 offset:54272
	ds_read_b128 v[206:209], v153 offset:55296
	ds_read_b128 v[210:213], v153 offset:56320
	global_load_lds_dwordx4 v[214:215], off
	s_add_i32 m0, s26, 0x2000
	s_add_u32 s24, s24, 0x80080
	v_lshl_add_u64 v[214:215], v[216:217], 0, s[8:9]
	s_addc_u32 s25, s25, 0
	s_add_i32 s26, s51, s34
	global_load_lds_dwordx4 v[214:215], off
	v_lshl_add_u64 v[214:215], s[24:25], 0, v[130:131]
	s_mov_b32 m0, s26
	s_nop 0
	global_load_lds_dwordx4 v[214:215], off
	v_lshl_add_u64 v[214:215], s[24:25], 0, v[134:135]
	s_add_i32 m0, s26, 0x2000
	s_nop 0
	global_load_lds_dwordx4 v[214:215], off
	v_lshl_add_u64 v[214:215], v[218:219], 0, s[8:9]
	s_mov_b32 m0, s39
	s_nop 0
	global_load_lds_dwordx4 v[214:215], off
	v_lshl_add_u64 v[214:215], v[220:221], 0, s[8:9]
	s_mov_b32 m0, s40
	s_nop 0
	global_load_lds_dwordx4 v[214:215], off
	s_waitcnt vmcnt(8)
	s_waitcnt lgkmcnt(0)
	s_setprio 1
	s_barrier
	v_mfma_f32_16x16x32_bf16 v[60:63], v[144:147], v[182:185], v[60:63]
	v_mfma_f32_16x16x32_bf16 v[56:59], v[158:161], v[182:185], v[56:59]
	v_mfma_f32_16x16x32_bf16 v[44:47], v[144:147], v[190:193], v[44:47]
	v_mfma_f32_16x16x32_bf16 v[40:43], v[158:161], v[190:193], v[40:43]
	v_mfma_f32_16x16x32_bf16 v[28:31], v[144:147], v[198:201], v[28:31]
	v_mfma_f32_16x16x32_bf16 v[24:27], v[158:161], v[198:201], v[24:27]
	v_mfma_f32_16x16x32_bf16 v[12:15], v[144:147], v[206:209], v[12:15]
	v_mfma_f32_16x16x32_bf16 v[8:11], v[158:161], v[206:209], v[8:11]
	v_mfma_f32_16x16x32_bf16 v[60:63], v[154:157], v[186:189], v[60:63]
	v_mfma_f32_16x16x32_bf16 v[56:59], v[162:165], v[186:189], v[56:59]
	v_mfma_f32_16x16x32_bf16 v[44:47], v[154:157], v[194:197], v[44:47]
	v_mfma_f32_16x16x32_bf16 v[40:43], v[162:165], v[194:197], v[40:43]
	v_mfma_f32_16x16x32_bf16 v[28:31], v[154:157], v[202:205], v[28:31]
	v_mfma_f32_16x16x32_bf16 v[24:27], v[162:165], v[202:205], v[24:27]
	v_mfma_f32_16x16x32_bf16 v[12:15], v[154:157], v[210:213], v[12:15]
	v_mfma_f32_16x16x32_bf16 v[8:11], v[162:165], v[210:213], v[8:11]
	v_mfma_f32_16x16x32_bf16 v[52:55], v[166:169], v[182:185], v[52:55]
	v_mfma_f32_16x16x32_bf16 v[48:51], v[174:177], v[182:185], v[48:51]
	v_mfma_f32_16x16x32_bf16 v[36:39], v[166:169], v[190:193], v[36:39]
	v_mfma_f32_16x16x32_bf16 v[32:35], v[174:177], v[190:193], v[32:35]
	v_mfma_f32_16x16x32_bf16 v[20:23], v[166:169], v[198:201], v[20:23]
	v_mfma_f32_16x16x32_bf16 v[16:19], v[174:177], v[198:201], v[16:19]
	v_mfma_f32_16x16x32_bf16 v[4:7], v[166:169], v[206:209], v[4:7]
	v_mfma_f32_16x16x32_bf16 v[0:3], v[174:177], v[206:209], v[0:3]
	v_mfma_f32_16x16x32_bf16 v[52:55], v[170:173], v[186:189], v[52:55]
	v_mfma_f32_16x16x32_bf16 v[48:51], v[178:181], v[186:189], v[48:51]
	v_mfma_f32_16x16x32_bf16 v[36:39], v[170:173], v[194:197], v[36:39]
	v_mfma_f32_16x16x32_bf16 v[32:35], v[178:181], v[194:197], v[32:35]
	v_mfma_f32_16x16x32_bf16 v[20:23], v[170:173], v[202:205], v[20:23]
	v_mfma_f32_16x16x32_bf16 v[16:19], v[178:181], v[202:205], v[16:19]
	v_mfma_f32_16x16x32_bf16 v[4:7], v[170:173], v[210:213], v[4:7]
	v_mfma_f32_16x16x32_bf16 v[0:3], v[178:181], v[210:213], v[0:3]
	s_setprio 0
	s_barrier
	s_add_i32 s49, s49, 2
	s_add_u32 s22, s22, 0x100
	s_addc_u32 s23, s23, 0
	s_add_u32 s47, s47, 0x100
	s_addc_u32 s48, s48, 0
	s_cmp_gt_u32 s49, 29
	s_cbranch_scc0 .LBB0_158
	s_branch .Lkx_2
.LBB0_158:
	ds_read_b128 v[144:147], v151
	ds_read_b128 v[154:157], v151 offset:1024
	ds_read_b128 v[158:161], v151 offset:2048
	ds_read_b128 v[162:165], v151 offset:3072
	ds_read_b128 v[166:169], v152
	ds_read_b128 v[170:173], v152 offset:1024
	ds_read_b128 v[174:177], v152 offset:2048
	ds_read_b128 v[178:181], v152 offset:3072
	s_add_u32 s24, s22, 0xfff80080
	s_addc_u32 s25, s23, -1
	s_cmp_eq_u32 s49, 28
	s_cselect_b32 s27, s5, s25
	s_cselect_b32 s26, s15, s24
	s_cselect_b32 s25, s13, s48
	s_cselect_b32 s24, s46, s47
	v_lshl_add_u64 v[214:215], s[22:23], 0, v[136:137]
	s_add_i32 m0, s21, 0xc000
	ds_read_b128 v[182:185], v153
	ds_read_b128 v[186:189], v153 offset:1024
	ds_read_b128 v[190:193], v153 offset:2048
	ds_read_b128 v[194:197], v153 offset:3072
	ds_read_b128 v[198:201], v153 offset:4096
	ds_read_b128 v[202:205], v153 offset:5120
	ds_read_b128 v[206:209], v153 offset:6144
	ds_read_b128 v[210:213], v153 offset:7168
	global_load_lds_dwordx4 v[214:215], off
	v_lshl_add_u64 v[214:215], s[22:23], 0, v[138:139]
	s_add_i32 m0, s21, 0xe000
	s_nop 0
	global_load_lds_dwordx4 v[214:215], off
	s_waitcnt vmcnt(8)
	s_waitcnt lgkmcnt(0)
	s_setprio 1
	s_barrier
; #define PG8_STAGE(bufoff, gbase, voff) do { _Pragma("unroll") for (int _i = 0; _i < 2; ++_i) \
;         __builtin_amdgcn_global_load_lds((const unsigned*)((const char*)(gbase) + (voff)[_i]), (PG8_LAS unsigned*)(lds + (bufoff) + ldsw + _i * 8192), 16, 0, 0); } while (0)
; #define PG8_LDA(dst, b, h) do { _Pragma("unroll") for (int m = 0; m < 4; ++m) _Pragma("unroll") for (int k = 0; k < 2; ++k) dst[m][k] = *(const PG8_LAS bf16x8*)(lds + PG8_SA(b, h) + aoff + m * 2048 + k * 1024); } while (0)
; #define PG8_LDB(dst, b, h) do { _Pragma("unroll") for (int n = 0; n < 2; ++n) _Pragma("unroll") for (int k = 0; k < 2; ++k) dst[n][k] = *(const PG8_LAS bf16x8*)(lds + PG8_SB(b, h) + boff + n * 2048 + k * 1024); } while (0)
; #define PG8_MMA(ai, bj, At, Bt) do { __builtin_amdgcn_s_setprio(1); _Pragma("unroll") for (int m = 0; m < 4; ++m) _Pragma("unroll") for (int n = 0; n < 2; ++n) _Pragma("unroll") for (int k = 0; k < 2; ++k) \
;         acc[ai][bj][m][n] = __builtin_amdgcn_mfma_f32_16x16x32_bf16(Bt[n][k], At[m][k], acc[ai][bj][m][n], 0, 0, 0); __builtin_amdgcn_s_setprio(0); } while (0)
; #define PG8_BAR __builtin_amdgcn_s_barrier()
; template <class Epi, class Sched, bool ALIGN_EPI = false, bool SP2 = false>
; __device__ __forceinline__ void gemm_phase(PG8_LAS unsigned char* lds, const Gemm g, const Sched& S, const Epi& E, const int wave_in) {
;     ...
;             PG8_LDB(B0, 0, 0); PG8_LDB(B1, 0, 1); PG8_SCHED; PG8_LDA(At, 0, 0); PG8_STAGE(PG8_SA(1, 1), a1 + hstepA, voffA);
;             PG8_WAIT_V(8); PG8_WAIT_L(0); PG8_BAR; PG8_MMA(0, 0, At, B0); PG8_MMA(0, 1, At, B1); PG8_BAR; PG8_SCHED;
;             PG8_LDA(At, 0, 1); PG8_STAGE(PG8_SB(0, 0), b2, voffB); PG8_STAGE(PG8_SB(0, 1), b2 + hstepB, voffB); PG8_STAGE(PG8_SA(0, 0), a2, voffA);
;             PG8_WAIT_V(8); PG8_WAIT_L(0); PG8_BAR; PG8_MMA(1, 0, At, B0); PG8_MMA(1, 1, At, B1); PG8_BAR; PG8_SCHED;
;             PG8_LDB(B0, 1, 0); PG8_LDB(B1, 1, 1); PG8_SCHED; PG8_LDA(At, 1, 0); PG8_STAGE(PG8_SA(0, 1), a2 + hstepA, voffA);
;             PG8_WAIT_V(8); PG8_WAIT_L(0); PG8_BAR; PG8_MMA(0, 0, At, B0); PG8_MMA(0, 1, At, B1); PG8_BAR; PG8_SCHED;
;             PG8_LDA(At, 1, 1); PG8_STAGE(PG8_SB(1, 0), b3, voffB); PG8_STAGE(PG8_SB(1, 1), b3 + hstepB, voffB); PG8_STAGE(PG8_SA(1, 0), a3, voffA);
;             PG8_WAIT_V(8); PG8_WAIT_L(0); PG8_BAR; PG8_MMA(1, 0, At, B0); PG8_MMA(1, 1, At, B1); PG8_BAR; PG8_SCHED;
	v_mfma_f32_16x16x32_bf16 v[124:127], v[144:147], v[182:185], v[124:127]
	v_mfma_f32_16x16x32_bf16 v[120:123], v[158:161], v[182:185], v[120:123]
	v_mfma_f32_16x16x32_bf16 v[108:111], v[144:147], v[190:193], v[108:111]
	v_mfma_f32_16x16x32_bf16 v[104:107], v[158:161], v[190:193], v[104:107]
	v_mfma_f32_16x16x32_bf16 v[92:95], v[144:147], v[198:201], v[92:95]
	v_mfma_f32_16x16x32_bf16 v[88:91], v[158:161], v[198:201], v[88:91]
	v_mfma_f32_16x16x32_bf16 v[76:79], v[144:147], v[206:209], v[76:79]
	v_mfma_f32_16x16x32_bf16 v[72:75], v[158:161], v[206:209], v[72:75]
	v_mfma_f32_16x16x32_bf16 v[124:127], v[154:157], v[186:189], v[124:127]
	v_mfma_f32_16x16x32_bf16 v[120:123], v[162:165], v[186:189], v[120:123]
	v_mfma_f32_16x16x32_bf16 v[108:111], v[154:157], v[194:197], v[108:111]
	v_mfma_f32_16x16x32_bf16 v[104:107], v[162:165], v[194:197], v[104:107]
	v_mfma_f32_16x16x32_bf16 v[92:95], v[154:157], v[202:205], v[92:95]
	v_mfma_f32_16x16x32_bf16 v[88:91], v[162:165], v[202:205], v[88:91]
	v_mfma_f32_16x16x32_bf16 v[76:79], v[154:157], v[210:213], v[76:79]
	v_mfma_f32_16x16x32_bf16 v[72:75], v[162:165], v[210:213], v[72:75]
	v_mfma_f32_16x16x32_bf16 v[116:119], v[166:169], v[182:185], v[116:119]
	v_mfma_f32_16x16x32_bf16 v[112:115], v[174:177], v[182:185], v[112:115]
	v_mfma_f32_16x16x32_bf16 v[100:103], v[166:169], v[190:193], v[100:103]
	v_mfma_f32_16x16x32_bf16 v[96:99], v[174:177], v[190:193], v[96:99]
	v_mfma_f32_16x16x32_bf16 v[84:87], v[166:169], v[198:201], v[84:87]
	v_mfma_f32_16x16x32_bf16 v[80:83], v[174:177], v[198:201], v[80:83]
	v_mfma_f32_16x16x32_bf16 v[68:71], v[166:169], v[206:209], v[68:71]
	v_mfma_f32_16x16x32_bf16 v[64:67], v[174:177], v[206:209], v[64:67]
	v_mfma_f32_16x16x32_bf16 v[116:119], v[170:173], v[186:189], v[116:119]
	v_mfma_f32_16x16x32_bf16 v[112:115], v[178:181], v[186:189], v[112:115]
	v_mfma_f32_16x16x32_bf16 v[100:103], v[170:173], v[194:197], v[100:103]
	v_mfma_f32_16x16x32_bf16 v[96:99], v[178:181], v[194:197], v[96:99]
	v_mfma_f32_16x16x32_bf16 v[84:87], v[170:173], v[202:205], v[84:87]
	v_mfma_f32_16x16x32_bf16 v[80:83], v[178:181], v[202:205], v[80:83]
	v_mfma_f32_16x16x32_bf16 v[68:71], v[170:173], v[210:213], v[68:71]
	v_mfma_f32_16x16x32_bf16 v[64:67], v[178:181], v[210:213], v[64:67]
	s_setprio 0
	s_barrier
	s_add_i32 s50, s43, s34
	v_lshl_add_u64 v[214:215], s[24:25], 0, v[130:131]
	s_mov_b32 m0, s50
	ds_read_b128 v[182:185], v153 offset:16384
	ds_read_b128 v[186:189], v153 offset:17408
	ds_read_b128 v[190:193], v153 offset:18432
	ds_read_b128 v[194:197], v153 offset:19456
	ds_read_b128 v[198:201], v153 offset:20480
	ds_read_b128 v[202:205], v153 offset:21504
	ds_read_b128 v[206:209], v153 offset:22528
	ds_read_b128 v[210:213], v153 offset:23552
	global_load_lds_dwordx4 v[214:215], off
	s_add_i32 m0, s50, 0x2000
	s_add_u32 s50, s24, 0x80000
	v_lshl_add_u64 v[216:217], s[24:25], 0, v[134:135]
	s_addc_u32 s51, s25, 0
	s_add_i32 s52, s44, s34
	global_load_lds_dwordx4 v[216:217], off
	v_lshl_add_u64 v[218:219], s[50:51], 0, v[130:131]
	s_mov_b32 m0, s52
	v_lshl_add_u64 v[220:221], s[26:27], 0, v[132:133]
	global_load_lds_dwordx4 v[218:219], off
	v_lshl_add_u64 v[218:219], s[50:51], 0, v[134:135]
	s_add_i32 m0, s52, 0x2000
	s_nop 0
	global_load_lds_dwordx4 v[218:219], off
	v_lshl_add_u64 v[218:219], s[26:27], 0, v[128:129]
	s_mov_b32 m0, s21
	s_nop 0
	global_load_lds_dwordx4 v[218:219], off
	s_mov_b32 m0, s35
	s_nop 0
	global_load_lds_dwordx4 v[220:221], off
	s_waitcnt vmcnt(8)
	s_waitcnt lgkmcnt(0)
	s_setprio 1
	s_barrier
	v_mfma_f32_16x16x32_bf16 v[60:63], v[144:147], v[182:185], v[60:63]
	v_mfma_f32_16x16x32_bf16 v[56:59], v[158:161], v[182:185], v[56:59]
	v_mfma_f32_16x16x32_bf16 v[44:47], v[144:147], v[190:193], v[44:47]
	v_mfma_f32_16x16x32_bf16 v[40:43], v[158:161], v[190:193], v[40:43]
	v_mfma_f32_16x16x32_bf16 v[28:31], v[144:147], v[198:201], v[28:31]
	v_mfma_f32_16x16x32_bf16 v[24:27], v[158:161], v[198:201], v[24:27]
	v_mfma_f32_16x16x32_bf16 v[12:15], v[144:147], v[206:209], v[12:15]
	v_mfma_f32_16x16x32_bf16 v[8:11], v[158:161], v[206:209], v[8:11]
	v_mfma_f32_16x16x32_bf16 v[60:63], v[154:157], v[186:189], v[60:63]
	v_mfma_f32_16x16x32_bf16 v[56:59], v[162:165], v[186:189], v[56:59]
	v_mfma_f32_16x16x32_bf16 v[44:47], v[154:157], v[194:197], v[44:47]
	v_mfma_f32_16x16x32_bf16 v[40:43], v[162:165], v[194:197], v[40:43]
	v_mfma_f32_16x16x32_bf16 v[28:31], v[154:157], v[202:205], v[28:31]
	v_mfma_f32_16x16x32_bf16 v[24:27], v[162:165], v[202:205], v[24:27]
	v_mfma_f32_16x16x32_bf16 v[12:15], v[154:157], v[210:213], v[12:15]
	v_mfma_f32_16x16x32_bf16 v[8:11], v[162:165], v[210:213], v[8:11]
	v_mfma_f32_16x16x32_bf16 v[52:55], v[166:169], v[182:185], v[52:55]
	v_mfma_f32_16x16x32_bf16 v[48:51], v[174:177], v[182:185], v[48:51]
	v_mfma_f32_16x16x32_bf16 v[36:39], v[166:169], v[190:193], v[36:39]
	v_mfma_f32_16x16x32_bf16 v[32:35], v[174:177], v[190:193], v[32:35]
	v_mfma_f32_16x16x32_bf16 v[20:23], v[166:169], v[198:201], v[20:23]
	v_mfma_f32_16x16x32_bf16 v[16:19], v[174:177], v[198:201], v[16:19]
	v_mfma_f32_16x16x32_bf16 v[4:7], v[166:169], v[206:209], v[4:7]
	v_mfma_f32_16x16x32_bf16 v[0:3], v[174:177], v[206:209], v[0:3]
	v_mfma_f32_16x16x32_bf16 v[52:55], v[170:173], v[186:189], v[52:55]
	v_mfma_f32_16x16x32_bf16 v[48:51], v[178:181], v[186:189], v[48:51]
	v_mfma_f32_16x16x32_bf16 v[36:39], v[170:173], v[194:197], v[36:39]
	v_mfma_f32_16x16x32_bf16 v[32:35], v[178:181], v[194:197], v[32:35]
	v_mfma_f32_16x16x32_bf16 v[20:23], v[170:173], v[202:205], v[20:23]
	v_mfma_f32_16x16x32_bf16 v[16:19], v[178:181], v[202:205], v[16:19]
	v_mfma_f32_16x16x32_bf16 v[4:7], v[170:173], v[210:213], v[4:7]
	v_mfma_f32_16x16x32_bf16 v[0:3], v[178:181], v[210:213], v[0:3]
	s_setprio 0
	s_barrier
; #define PG8_STAGE(bufoff, gbase, voff) do { _Pragma("unroll") for (int _i = 0; _i < 2; ++_i) \
;         __builtin_amdgcn_global_load_lds((const unsigned*)((const char*)(gbase) + (voff)[_i]), (PG8_LAS unsigned*)(lds + (bufoff) + ldsw + _i * 8192), 16, 0, 0); } while (0)
; #define PG8_LDA(dst, b, h) do { _Pragma("unroll") for (int m = 0; m < 4; ++m) _Pragma("unroll") for (int k = 0; k < 2; ++k) dst[m][k] = *(const PG8_LAS bf16x8*)(lds + PG8_SA(b, h) + aoff + m * 2048 + k * 1024); } while (0)
; #define PG8_LDB(dst, b, h) do { _Pragma("unroll") for (int n = 0; n < 2; ++n) _Pragma("unroll") for (int k = 0; k < 2; ++k) dst[n][k] = *(const PG8_LAS bf16x8*)(lds + PG8_SB(b, h) + boff + n * 2048 + k * 1024); } while (0)
; #define PG8_MMA(ai, bj, At, Bt) do { __builtin_amdgcn_s_setprio(1); _Pragma("unroll") for (int m = 0; m < 4; ++m) _Pragma("unroll") for (int n = 0; n < 2; ++n) _Pragma("unroll") for (int k = 0; k < 2; ++k) \
;         acc[ai][bj][m][n] = __builtin_amdgcn_mfma_f32_16x16x32_bf16(Bt[n][k], At[m][k], acc[ai][bj][m][n], 0, 0, 0); __builtin_amdgcn_s_setprio(0); } while (0)
; #define PG8_WAIT_V(n) asm volatile("s_waitcnt vmcnt(" #n ")" ::: "memory")
; #define PG8_WAIT_L(n) asm volatile("s_waitcnt lgkmcnt(" #n ")" ::: "memory")
; #define PG8_BAR __builtin_amdgcn_s_barrier()
; template <class Epi, class Sched, bool ALIGN_EPI = false, bool SP2 = false>
; __device__ __forceinline__ void gemm_phase(PG8_LAS unsigned char* lds, const Gemm g, const Sched& S, const Epi& E, const int wave_in) {
;     ...
;         for (int t = 0; t < nt; t += 2) {
;             const bool last = (t == nt - 2);
;             const char* a1 = cA + (size_t)(t + 1) * kstep;
;             const char* a2 = last ? nA : cA + (size_t)(t + 2) * kstep; const char* b2 = last ? nB : cB + (size_t)(t + 2) * kstep;
;             const char* a3 = a2 + kstep; const char* b3 = b2 + kstep;
;     ...
;             PG8_LDB(B0, 1, 0); PG8_LDB(B1, 1, 1); PG8_SCHED; PG8_LDA(At, 1, 0); PG8_STAGE(PG8_SA(0, 1), a2 + hstepA, voffA);
;             PG8_WAIT_V(8); PG8_WAIT_L(0); PG8_BAR; PG8_MMA(0, 0, At, B0); PG8_MMA(0, 1, At, B1); PG8_BAR; PG8_SCHED;
;             PG8_LDA(At, 1, 1); PG8_STAGE(PG8_SB(1, 0), b3, voffB); PG8_STAGE(PG8_SB(1, 1), b3 + hstepB, voffB); PG8_STAGE(PG8_SA(1, 0), a3, voffA);
;             PG8_WAIT_V(8); PG8_WAIT_L(0); PG8_BAR; PG8_MMA(1, 0, At, B0); PG8_MMA(1, 1, At, B1); PG8_BAR; PG8_SCHED;
	s_add_i32 s50, 0, 0x18000
	s_add_i32 s51, 0, 0x1c000
	v_add_u32_e32 v162, s50, v149
	v_add_u32_e32 v178, s51, v149
	ds_read_b128 v[144:147], v162
	ds_read_b128 v[154:157], v162 offset:1024
	ds_read_b128 v[158:161], v162 offset:2048
	ds_read_b128 v[162:165], v162 offset:3072
	ds_read_b128 v[166:169], v178
	ds_read_b128 v[170:173], v178 offset:1024
	ds_read_b128 v[174:177], v178 offset:2048
	ds_read_b128 v[178:181], v178 offset:3072
	s_add_u32 s26, s26, 0x80000
	s_addc_u32 s27, s27, 0
	s_mov_b32 m0, s36
	v_lshl_add_u64 v[222:223], s[26:27], 0, v[128:129]
	ds_read_b128 v[182:185], v153 offset:32768
	ds_read_b128 v[186:189], v153 offset:33792
	ds_read_b128 v[190:193], v153 offset:34816
	ds_read_b128 v[194:197], v153 offset:35840
	ds_read_b128 v[198:201], v153 offset:36864
	ds_read_b128 v[202:205], v153 offset:37888
	ds_read_b128 v[206:209], v153 offset:38912
	ds_read_b128 v[210:213], v153 offset:39936
	global_load_lds_dwordx4 v[222:223], off
	v_lshl_add_u64 v[222:223], s[26:27], 0, v[132:133]
	s_mov_b32 m0, s37
	s_nop 0
	global_load_lds_dwordx4 v[222:223], off
	s_waitcnt vmcnt(8)
	s_waitcnt lgkmcnt(0)
	s_setprio 1
	s_barrier
	v_mfma_f32_16x16x32_bf16 v[124:127], v[144:147], v[182:185], v[124:127]
	v_mfma_f32_16x16x32_bf16 v[120:123], v[158:161], v[182:185], v[120:123]
	v_mfma_f32_16x16x32_bf16 v[108:111], v[144:147], v[190:193], v[108:111]
	v_mfma_f32_16x16x32_bf16 v[104:107], v[158:161], v[190:193], v[104:107]
	v_mfma_f32_16x16x32_bf16 v[92:95], v[144:147], v[198:201], v[92:95]
	v_mfma_f32_16x16x32_bf16 v[88:91], v[158:161], v[198:201], v[88:91]
	v_mfma_f32_16x16x32_bf16 v[76:79], v[144:147], v[206:209], v[76:79]
	v_mfma_f32_16x16x32_bf16 v[72:75], v[158:161], v[206:209], v[72:75]
	v_mfma_f32_16x16x32_bf16 v[124:127], v[154:157], v[186:189], v[124:127]
	v_mfma_f32_16x16x32_bf16 v[120:123], v[162:165], v[186:189], v[120:123]
	v_mfma_f32_16x16x32_bf16 v[108:111], v[154:157], v[194:197], v[108:111]
	v_mfma_f32_16x16x32_bf16 v[104:107], v[162:165], v[194:197], v[104:107]
	v_mfma_f32_16x16x32_bf16 v[92:95], v[154:157], v[202:205], v[92:95]
	v_mfma_f32_16x16x32_bf16 v[88:91], v[162:165], v[202:205], v[88:91]
	v_mfma_f32_16x16x32_bf16 v[76:79], v[154:157], v[210:213], v[76:79]
	v_mfma_f32_16x16x32_bf16 v[72:75], v[162:165], v[210:213], v[72:75]
	v_mfma_f32_16x16x32_bf16 v[116:119], v[166:169], v[182:185], v[116:119]
	v_mfma_f32_16x16x32_bf16 v[112:115], v[174:177], v[182:185], v[112:115]
	v_mfma_f32_16x16x32_bf16 v[100:103], v[166:169], v[190:193], v[100:103]
	v_mfma_f32_16x16x32_bf16 v[96:99], v[174:177], v[190:193], v[96:99]
	v_mfma_f32_16x16x32_bf16 v[84:87], v[166:169], v[198:201], v[84:87]
	v_mfma_f32_16x16x32_bf16 v[80:83], v[174:177], v[198:201], v[80:83]
	v_mfma_f32_16x16x32_bf16 v[68:71], v[166:169], v[206:209], v[68:71]
	v_mfma_f32_16x16x32_bf16 v[64:67], v[174:177], v[206:209], v[64:67]
	v_mfma_f32_16x16x32_bf16 v[116:119], v[170:173], v[186:189], v[116:119]
	v_mfma_f32_16x16x32_bf16 v[112:115], v[178:181], v[186:189], v[112:115]
	v_mfma_f32_16x16x32_bf16 v[100:103], v[170:173], v[194:197], v[100:103]
	v_mfma_f32_16x16x32_bf16 v[96:99], v[178:181], v[194:197], v[96:99]
	v_mfma_f32_16x16x32_bf16 v[84:87], v[170:173], v[202:205], v[84:87]
	v_mfma_f32_16x16x32_bf16 v[80:83], v[178:181], v[202:205], v[80:83]
	v_mfma_f32_16x16x32_bf16 v[68:71], v[170:173], v[210:213], v[68:71]
	v_mfma_f32_16x16x32_bf16 v[64:67], v[178:181], v[210:213], v[64:67]
	s_setprio 0
	s_barrier
	s_add_i32 s26, s50, s34
	v_lshl_add_u64 v[214:215], v[214:215], 0, s[8:9]
	s_mov_b32 m0, s26
	ds_read_b128 v[182:185], v153 offset:49152
	ds_read_b128 v[186:189], v153 offset:50176
	ds_read_b128 v[190:193], v153 offset:51200
	ds_read_b128 v[194:197], v153 offset:52224
	ds_read_b128 v[198:201], v153 offset:53248
	ds_read_b128 v[202:205], v153 offset:54272
	ds_read_b128 v[206:209], v153 offset:55296
	ds_read_b128 v[210:213], v153 offset:56320
	global_load_lds_dwordx4 v[214:215], off
	s_add_i32 m0, s26, 0x2000
	s_add_u32 s24, s24, 0x80080
	v_lshl_add_u64 v[214:215], v[216:217], 0, s[8:9]
	s_addc_u32 s25, s25, 0
	s_add_i32 s26, s51, s34
	global_load_lds_dwordx4 v[214:215], off
	v_lshl_add_u64 v[214:215], s[24:25], 0, v[130:131]
	s_mov_b32 m0, s26
	s_nop 0
	global_load_lds_dwordx4 v[214:215], off
	v_lshl_add_u64 v[214:215], s[24:25], 0, v[134:135]
	s_add_i32 m0, s26, 0x2000
	s_nop 0
	global_load_lds_dwordx4 v[214:215], off
	v_lshl_add_u64 v[214:215], v[218:219], 0, s[8:9]
	s_mov_b32 m0, s39
	s_nop 0
	global_load_lds_dwordx4 v[214:215], off
	v_lshl_add_u64 v[214:215], v[220:221], 0, s[8:9]
	s_mov_b32 m0, s40
	s_nop 0
	global_load_lds_dwordx4 v[214:215], off
	s_waitcnt vmcnt(8)
	s_waitcnt lgkmcnt(0)
	s_setprio 1
	s_barrier
	v_mfma_f32_16x16x32_bf16 v[60:63], v[144:147], v[182:185], v[60:63]
	v_mfma_f32_16x16x32_bf16 v[56:59], v[158:161], v[182:185], v[56:59]
	v_mfma_f32_16x16x32_bf16 v[44:47], v[144:147], v[190:193], v[44:47]
	v_mfma_f32_16x16x32_bf16 v[40:43], v[158:161], v[190:193], v[40:43]
	v_mfma_f32_16x16x32_bf16 v[28:31], v[144:147], v[198:201], v[28:31]
	v_mfma_f32_16x16x32_bf16 v[24:27], v[158:161], v[198:201], v[24:27]
	v_mfma_f32_16x16x32_bf16 v[12:15], v[144:147], v[206:209], v[12:15]
	v_mfma_f32_16x16x32_bf16 v[8:11], v[158:161], v[206:209], v[8:11]
	v_mfma_f32_16x16x32_bf16 v[60:63], v[154:157], v[186:189], v[60:63]
	v_mfma_f32_16x16x32_bf16 v[56:59], v[162:165], v[186:189], v[56:59]
	v_mfma_f32_16x16x32_bf16 v[44:47], v[154:157], v[194:197], v[44:47]
	v_mfma_f32_16x16x32_bf16 v[40:43], v[162:165], v[194:197], v[40:43]
	v_mfma_f32_16x16x32_bf16 v[28:31], v[154:157], v[202:205], v[28:31]
	v_mfma_f32_16x16x32_bf16 v[24:27], v[162:165], v[202:205], v[24:27]
	v_mfma_f32_16x16x32_bf16 v[12:15], v[154:157], v[210:213], v[12:15]
	v_mfma_f32_16x16x32_bf16 v[8:11], v[162:165], v[210:213], v[8:11]
	v_mfma_f32_16x16x32_bf16 v[52:55], v[166:169], v[182:185], v[52:55]
	v_mfma_f32_16x16x32_bf16 v[48:51], v[174:177], v[182:185], v[48:51]
	v_mfma_f32_16x16x32_bf16 v[36:39], v[166:169], v[190:193], v[36:39]
	v_mfma_f32_16x16x32_bf16 v[32:35], v[174:177], v[190:193], v[32:35]
	v_mfma_f32_16x16x32_bf16 v[20:23], v[166:169], v[198:201], v[20:23]
	v_mfma_f32_16x16x32_bf16 v[16:19], v[174:177], v[198:201], v[16:19]
	v_mfma_f32_16x16x32_bf16 v[4:7], v[166:169], v[206:209], v[4:7]
	v_mfma_f32_16x16x32_bf16 v[0:3], v[174:177], v[206:209], v[0:3]
	v_mfma_f32_16x16x32_bf16 v[52:55], v[170:173], v[186:189], v[52:55]
	v_mfma_f32_16x16x32_bf16 v[48:51], v[178:181], v[186:189], v[48:51]
	v_mfma_f32_16x16x32_bf16 v[36:39], v[170:173], v[194:197], v[36:39]
	v_mfma_f32_16x16x32_bf16 v[32:35], v[178:181], v[194:197], v[32:35]
	v_mfma_f32_16x16x32_bf16 v[20:23], v[170:173], v[202:205], v[20:23]
	v_mfma_f32_16x16x32_bf16 v[16:19], v[178:181], v[202:205], v[16:19]
	v_mfma_f32_16x16x32_bf16 v[4:7], v[170:173], v[210:213], v[4:7]
	v_mfma_f32_16x16x32_bf16 v[0:3], v[178:181], v[210:213], v[0:3]
	s_setprio 0
	s_barrier
	s_add_i32 s49, s49, 2
	s_add_u32 s22, s22, 0x100
	s_addc_u32 s23, s23, 0
	s_add_u32 s47, s47, 0x100
	s_addc_u32 s48, s48, 0
	s_cmp_gt_u32 s49, 29
	s_cbranch_scc0 .LBB0_158

;     __host__ __device__ bool next(int i, Unit& u) const { const bool ok = StaticOrder::next(i, u); u.pm = 0; u.pn = 0; return ok; }
; #define PG8_STAGE(bufoff, gbase, voff) do { _Pragma("unroll") for (int _i = 0; _i < 2; ++_i) \
;         __builtin_amdgcn_global_load_lds((const unsigned*)((const char*)(gbase) + (voff)[_i]), (PG8_LAS unsigned*)(lds + (bufoff) + ldsw + _i * 8192), 16, 0, 0); } while (0)
; #define PG8_BAR __builtin_amdgcn_s_barrier()
; template <class Epi, class Sched, bool ALIGN_EPI = false, bool SP2 = false>
; __device__ __forceinline__ void gemm_phase(PG8_LAS unsigned char* lds, const Gemm g, const Sched& S, const Epi& E, const int wave_in) {
;     ...
;     for (;;) {
;         const bool has_next = S.next(ui + 1, nxt);
;         const char* nA = has_next ? (const char*)g.A + (size_t)nxt.pm * tstepA : cA; const char* nB = has_next ? (const char*)g.Bt + (size_t)nxt.pn * tstepB : cB;
;         for (int t = 0; t < nt; t += 2) {
;             const bool last = (t == nt - 2);
;             const char* a1 = cA + (size_t)(t + 1) * kstep;
;             const char* a2 = last ? nA : cA + (size_t)(t + 2) * kstep; const char* b2 = last ? nB : cB + (size_t)(t + 2) * kstep;
;             const char* a3 = a2 + kstep; const char* b3 = b2 + kstep;
;             if (last && has_next) S.a_ready(nxt);
;             if constexpr (SP2) {
;             PG8_LDB(B0, 0, 0); PG8_LDB(B1, 0, 1); PG8_SCHED; PG8_LDA(At, 0, 0); PG8_STAGE(PG8_SA(1, 1), a1 + hstepA, voffA);
;             PG8_WAIT_V(8); PG8_WAIT_L(0); PG8_BAR; PG8_MMA(0, 0, At, B0); PG8_MMA(0, 1, At, B1); PG8_BAR; PG8_SCHED;
;             PG8_LDA(At, 0, 1); PG8_STAGE(PG8_SB(0, 0), b2, voffB); PG8_STAGE(PG8_SB(0, 1), b2 + hstepB, voffB); PG8_STAGE(PG8_SA(0, 0), a2, voffA);
;             PG8_WAIT_V(8); PG8_WAIT_L(0); PG8_BAR; PG8_MMA(1, 0, At, B0); PG8_MMA(1, 1, At, B1); PG8_BAR; PG8_SCHED;
;             PG8_LDB(B0, 1, 0); PG8_LDB(B1, 1, 1); PG8_SCHED; PG8_LDA(At, 1, 0); PG8_STAGE(PG8_SA(0, 1), a2 + hstepA, voffA);
;             PG8_WAIT_V(8); PG8_WAIT_L(0); PG8_BAR; PG8_MMA(0, 0, At, B0); PG8_MMA(0, 1, At, B1); PG8_BAR; PG8_SCHED;
;             PG8_LDA(At, 1, 1); PG8_STAGE(PG8_SB(1, 0), b3, voffB); PG8_STAGE(PG8_SB(1, 1), b3 + hstepB, voffB); PG8_STAGE(PG8_SA(1, 0), a3, voffA);
;             PG8_WAIT_V(8); PG8_WAIT_L(0); PG8_BAR; PG8_MMA(1, 0, At, B0); PG8_MMA(1, 1, At, B1); PG8_BAR; PG8_SCHED;
.LBB0_352:
	s_ashr_i32 s15, s14, 31
	s_lshl_b64 s[18:19], s[14:15], 20
	s_add_u32 s18, s30, s18
	s_addc_u32 s19, s31, s19
	s_and_b64 s[4:5], s[4:5], exec
	s_cselect_b32 s15, s19, s25
	s_cselect_b32 s21, s18, s24
	s_add_u32 s51, s24, 0x100
	v_mov_b32_e32 v0, 0
	s_addc_u32 s52, s25, 0
	s_mov_b32 s53, -2
	ds_read_b128 v[128:131], v168
	ds_read_b128 v[132:135], v168 offset:1024
	ds_read_b128 v[136:139], v168 offset:2048
	ds_read_b128 v[140:143], v168 offset:3072
	ds_read_b128 v[162:165], v169
	ds_read_b128 v[172:175], v169 offset:1024
	ds_read_b128 v[176:179], v169 offset:2048
	ds_read_b128 v[180:183], v169 offset:3072
	s_add_u32 s4, s22, 0x100
	s_addc_u32 s5, s23, 0
	s_cmp_eq_u32 s53, 28
	s_cselect_b32 s27, s17, s5
	s_cselect_b32 s26, s16, s4
	s_cselect_b32 s25, s15, s52
	s_cselect_b32 s24, s21, s51
	v_lshl_add_u64 v[216:217], s[22:23], 0, v[154:155]
	s_add_i32 m0, s37, 0xc000
	ds_read_b128 v[184:187], v170
	ds_read_b128 v[188:191], v170 offset:1024
	ds_read_b128 v[192:195], v170 offset:2048
	ds_read_b128 v[196:199], v170 offset:3072
	ds_read_b128 v[200:203], v170 offset:4096
	ds_read_b128 v[204:207], v170 offset:5120
	ds_read_b128 v[208:211], v170 offset:6144
	ds_read_b128 v[212:215], v170 offset:7168
	global_load_lds_dwordx4 v[216:217], off
	v_lshl_add_u64 v[216:217], s[22:23], 0, v[156:157]
	s_add_i32 m0, s37, 0xe000
	s_nop 0
	global_load_lds_dwordx4 v[216:217], off
	s_waitcnt vmcnt(8)
	s_waitcnt lgkmcnt(0)
	s_setprio 1
	s_barrier
	v_mfma_f32_16x16x32_bf16 v[124:127], v[128:131], v[184:187], 0
	v_mfma_f32_16x16x32_bf16 v[120:123], v[136:139], v[184:187], 0
	v_mfma_f32_16x16x32_bf16 v[116:119], v[128:131], v[192:195], 0
	v_mfma_f32_16x16x32_bf16 v[112:115], v[136:139], v[192:195], 0
	v_mfma_f32_16x16x32_bf16 v[92:95], v[128:131], v[200:203], 0
	v_mfma_f32_16x16x32_bf16 v[88:91], v[136:139], v[200:203], 0
	v_mfma_f32_16x16x32_bf16 v[84:87], v[128:131], v[208:211], 0
	v_mfma_f32_16x16x32_bf16 v[76:79], v[136:139], v[208:211], 0
	v_mfma_f32_16x16x32_bf16 v[124:127], v[132:135], v[188:191], v[124:127]
	v_mfma_f32_16x16x32_bf16 v[120:123], v[140:143], v[188:191], v[120:123]
	v_mfma_f32_16x16x32_bf16 v[116:119], v[132:135], v[196:199], v[116:119]
	v_mfma_f32_16x16x32_bf16 v[112:115], v[140:143], v[196:199], v[112:115]
	v_mfma_f32_16x16x32_bf16 v[92:95], v[132:135], v[204:207], v[92:95]
	v_mfma_f32_16x16x32_bf16 v[88:91], v[140:143], v[204:207], v[88:91]
	v_mfma_f32_16x16x32_bf16 v[84:87], v[132:135], v[212:215], v[84:87]
	v_mfma_f32_16x16x32_bf16 v[76:79], v[140:143], v[212:215], v[76:79]
	v_mfma_f32_16x16x32_bf16 v[108:111], v[162:165], v[184:187], 0
	v_mfma_f32_16x16x32_bf16 v[104:107], v[176:179], v[184:187], 0
	v_mfma_f32_16x16x32_bf16 v[100:103], v[162:165], v[192:195], 0
	v_mfma_f32_16x16x32_bf16 v[96:99], v[176:179], v[192:195], 0
	v_mfma_f32_16x16x32_bf16 v[80:83], v[162:165], v[200:203], 0
	v_mfma_f32_16x16x32_bf16 v[72:75], v[176:179], v[200:203], 0
	v_mfma_f32_16x16x32_bf16 v[68:71], v[162:165], v[208:211], 0
	v_mfma_f32_16x16x32_bf16 v[64:67], v[176:179], v[208:211], 0
	v_mfma_f32_16x16x32_bf16 v[108:111], v[172:175], v[188:191], v[108:111]
	v_mfma_f32_16x16x32_bf16 v[104:107], v[180:183], v[188:191], v[104:107]
	v_mfma_f32_16x16x32_bf16 v[100:103], v[172:175], v[196:199], v[100:103]
	v_mfma_f32_16x16x32_bf16 v[96:99], v[180:183], v[196:199], v[96:99]
	v_mfma_f32_16x16x32_bf16 v[80:83], v[172:175], v[204:207], v[80:83]
	v_mfma_f32_16x16x32_bf16 v[72:75], v[180:183], v[204:207], v[72:75]
	v_mfma_f32_16x16x32_bf16 v[68:71], v[172:175], v[212:215], v[68:71]
	v_mfma_f32_16x16x32_bf16 v[64:67], v[180:183], v[212:215], v[64:67]
	s_setprio 0
	s_barrier
	s_add_i32 s22, s47, s34
	v_lshl_add_u64 v[216:217], s[24:25], 0, v[148:149]
	s_mov_b32 m0, s22
	ds_read_b128 v[184:187], v170 offset:16384
	ds_read_b128 v[188:191], v170 offset:17408
	ds_read_b128 v[192:195], v170 offset:18432
	ds_read_b128 v[196:199], v170 offset:19456
	ds_read_b128 v[200:203], v170 offset:20480
	ds_read_b128 v[204:207], v170 offset:21504
	ds_read_b128 v[208:211], v170 offset:22528
	ds_read_b128 v[212:215], v170 offset:23552
	global_load_lds_dwordx4 v[216:217], off
	s_add_i32 m0, s22, 0x2000
	s_add_u32 s22, s24, 0x80000
	v_lshl_add_u64 v[218:219], s[24:25], 0, v[144:145]
	s_addc_u32 s23, s25, 0
	s_add_i32 s54, s48, s34
	global_load_lds_dwordx4 v[218:219], off
	v_lshl_add_u64 v[220:221], s[22:23], 0, v[148:149]
	s_mov_b32 m0, s54
	v_lshl_add_u64 v[222:223], s[26:27], 0, v[146:147]
	global_load_lds_dwordx4 v[220:221], off
	v_lshl_add_u64 v[220:221], s[22:23], 0, v[144:145]
	s_add_i32 m0, s54, 0x2000
	s_nop 0
	global_load_lds_dwordx4 v[220:221], off
	v_lshl_add_u64 v[220:221], s[26:27], 0, v[150:151]
	s_mov_b32 m0, s37
	s_nop 0
	global_load_lds_dwordx4 v[220:221], off
	s_mov_b32 m0, s38
	s_nop 0
	global_load_lds_dwordx4 v[222:223], off
	s_waitcnt vmcnt(8)
	s_waitcnt lgkmcnt(0)
	s_setprio 1
	s_barrier
; #define PG8_STAGE(bufoff, gbase, voff) do { _Pragma("unroll") for (int _i = 0; _i < 2; ++_i) \
;         __builtin_amdgcn_global_load_lds((const unsigned*)((const char*)(gbase) + (voff)[_i]), (PG8_LAS unsigned*)(lds + (bufoff) + ldsw + _i * 8192), 16, 0, 0); } while (0)
; #define PG8_LDA(dst, b, h) do { _Pragma("unroll") for (int m = 0; m < 4; ++m) _Pragma("unroll") for (int k = 0; k < 2; ++k) dst[m][k] = *(const PG8_LAS bf16x8*)(lds + PG8_SA(b, h) + aoff + m * 2048 + k * 1024); } while (0)
; #define PG8_LDB(dst, b, h) do { _Pragma("unroll") for (int n = 0; n < 2; ++n) _Pragma("unroll") for (int k = 0; k < 2; ++k) dst[n][k] = *(const PG8_LAS bf16x8*)(lds + PG8_SB(b, h) + boff + n * 2048 + k * 1024); } while (0)
; #define PG8_MMA(ai, bj, At, Bt) do { __builtin_amdgcn_s_setprio(1); _Pragma("unroll") for (int m = 0; m < 4; ++m) _Pragma("unroll") for (int n = 0; n < 2; ++n) _Pragma("unroll") for (int k = 0; k < 2; ++k) \
;         acc[ai][bj][m][n] = __builtin_amdgcn_mfma_f32_16x16x32_bf16(Bt[n][k], At[m][k], acc[ai][bj][m][n], 0, 0, 0); __builtin_amdgcn_s_setprio(0); } while (0)
; #define PG8_WAIT_V(n) asm volatile("s_waitcnt vmcnt(" #n ")" ::: "memory")
; #define PG8_WAIT_L(n) asm volatile("s_waitcnt lgkmcnt(" #n ")" ::: "memory")
; #define PG8_BAR __builtin_amdgcn_s_barrier()
; #define PG8_SCHED __builtin_amdgcn_sched_barrier(0)
; template <class Epi, class Sched, bool ALIGN_EPI = false, bool SP2 = false>
; __device__ __forceinline__ void gemm_phase(PG8_LAS unsigned char* lds, const Gemm g, const Sched& S, const Epi& E, const int wave_in) {
;     ...
;             PG8_WAIT_V(8); PG8_WAIT_L(0); PG8_BAR; PG8_MMA(0, 0, At, B0); PG8_MMA(0, 1, At, B1); PG8_BAR; PG8_SCHED;
;             PG8_LDA(At, 0, 1); PG8_STAGE(PG8_SB(0, 0), b2, voffB); PG8_STAGE(PG8_SB(0, 1), b2 + hstepB, voffB); PG8_STAGE(PG8_SA(0, 0), a2, voffA);
;             PG8_WAIT_V(8); PG8_WAIT_L(0); PG8_BAR; PG8_MMA(1, 0, At, B0); PG8_MMA(1, 1, At, B1); PG8_BAR; PG8_SCHED;
;             PG8_LDB(B0, 1, 0); PG8_LDB(B1, 1, 1); PG8_SCHED; PG8_LDA(At, 1, 0); PG8_STAGE(PG8_SA(0, 1), a2 + hstepA, voffA);
;             PG8_WAIT_V(8); PG8_WAIT_L(0); PG8_BAR; PG8_MMA(0, 0, At, B0); PG8_MMA(0, 1, At, B1); PG8_BAR; PG8_SCHED;
	v_mfma_f32_16x16x32_bf16 v[60:63], v[128:131], v[184:187], 0
	v_mfma_f32_16x16x32_bf16 v[56:59], v[136:139], v[184:187], 0
	v_mfma_f32_16x16x32_bf16 v[52:55], v[128:131], v[192:195], 0
	v_mfma_f32_16x16x32_bf16 v[44:47], v[136:139], v[192:195], 0
	v_mfma_f32_16x16x32_bf16 v[36:39], v[128:131], v[200:203], 0
	v_mfma_f32_16x16x32_bf16 v[28:31], v[136:139], v[200:203], 0
	v_mfma_f32_16x16x32_bf16 v[20:23], v[128:131], v[208:211], 0
	v_mfma_f32_16x16x32_bf16 v[12:15], v[136:139], v[208:211], 0
	v_mfma_f32_16x16x32_bf16 v[60:63], v[132:135], v[188:191], v[60:63]
	v_mfma_f32_16x16x32_bf16 v[56:59], v[140:143], v[188:191], v[56:59]
	v_mfma_f32_16x16x32_bf16 v[52:55], v[132:135], v[196:199], v[52:55]
	v_mfma_f32_16x16x32_bf16 v[44:47], v[140:143], v[196:199], v[44:47]
	v_mfma_f32_16x16x32_bf16 v[36:39], v[132:135], v[204:207], v[36:39]
	v_mfma_f32_16x16x32_bf16 v[28:31], v[140:143], v[204:207], v[28:31]
	v_mfma_f32_16x16x32_bf16 v[20:23], v[132:135], v[212:215], v[20:23]
	v_mfma_f32_16x16x32_bf16 v[12:15], v[140:143], v[212:215], v[12:15]
	v_mfma_f32_16x16x32_bf16 v[48:51], v[162:165], v[184:187], 0
	v_mfma_f32_16x16x32_bf16 v[40:43], v[176:179], v[184:187], 0
	v_mfma_f32_16x16x32_bf16 v[32:35], v[162:165], v[192:195], 0
	v_mfma_f32_16x16x32_bf16 v[24:27], v[176:179], v[192:195], 0
	v_mfma_f32_16x16x32_bf16 v[16:19], v[162:165], v[200:203], 0
	v_mfma_f32_16x16x32_bf16 v[8:11], v[176:179], v[200:203], 0
	v_mfma_f32_16x16x32_bf16 v[4:7], v[162:165], v[208:211], 0
	v_mfma_f32_16x16x32_bf16 v[0:3], v[176:179], v[208:211], 0
	v_mfma_f32_16x16x32_bf16 v[48:51], v[172:175], v[188:191], v[48:51]
	v_mfma_f32_16x16x32_bf16 v[40:43], v[180:183], v[188:191], v[40:43]
	v_mfma_f32_16x16x32_bf16 v[32:35], v[172:175], v[196:199], v[32:35]
	v_mfma_f32_16x16x32_bf16 v[24:27], v[180:183], v[196:199], v[24:27]
	v_mfma_f32_16x16x32_bf16 v[16:19], v[172:175], v[204:207], v[16:19]
	v_mfma_f32_16x16x32_bf16 v[8:11], v[180:183], v[204:207], v[8:11]
	v_mfma_f32_16x16x32_bf16 v[4:7], v[172:175], v[212:215], v[4:7]
	v_mfma_f32_16x16x32_bf16 v[0:3], v[180:183], v[212:215], v[0:3]
	s_setprio 0
	s_barrier
	s_add_i32 s54, 0, 0x18000
	s_add_i32 s55, 0, 0x1c000
	v_add_u32_e32 v140, s54, v166
	v_add_u32_e32 v171, s55, v166
	ds_read_b128 v[128:131], v140
	ds_read_b128 v[132:135], v140 offset:1024
	ds_read_b128 v[136:139], v140 offset:2048
	ds_read_b128 v[140:143], v140 offset:3072
	ds_read_b128 v[162:165], v171
	ds_read_b128 v[172:175], v171 offset:1024
	ds_read_b128 v[176:179], v171 offset:2048
	ds_read_b128 v[180:183], v171 offset:3072
	s_add_u32 s22, s26, 0x280000
	s_addc_u32 s23, s27, 0
	s_mov_b32 m0, s39
	v_lshl_add_u64 v[224:225], s[22:23], 0, v[150:151]
	ds_read_b128 v[184:187], v170 offset:32768
	ds_read_b128 v[188:191], v170 offset:33792
	ds_read_b128 v[192:195], v170 offset:34816
	ds_read_b128 v[196:199], v170 offset:35840
	ds_read_b128 v[200:203], v170 offset:36864
	ds_read_b128 v[204:207], v170 offset:37888
	ds_read_b128 v[208:211], v170 offset:38912
	ds_read_b128 v[212:215], v170 offset:39936
	global_load_lds_dwordx4 v[224:225], off
	v_lshl_add_u64 v[224:225], s[22:23], 0, v[146:147]
	s_mov_b32 m0, s40
	s_nop 0
	global_load_lds_dwordx4 v[224:225], off
	s_waitcnt vmcnt(8)
	s_waitcnt lgkmcnt(0)
	s_setprio 1
	s_barrier
	v_mfma_f32_16x16x32_bf16 v[124:127], v[128:131], v[184:187], v[124:127]
	v_mfma_f32_16x16x32_bf16 v[120:123], v[136:139], v[184:187], v[120:123]
	v_mfma_f32_16x16x32_bf16 v[116:119], v[128:131], v[192:195], v[116:119]
	v_mfma_f32_16x16x32_bf16 v[112:115], v[136:139], v[192:195], v[112:115]
	v_mfma_f32_16x16x32_bf16 v[92:95], v[128:131], v[200:203], v[92:95]
	v_mfma_f32_16x16x32_bf16 v[88:91], v[136:139], v[200:203], v[88:91]
	v_mfma_f32_16x16x32_bf16 v[84:87], v[128:131], v[208:211], v[84:87]
	v_mfma_f32_16x16x32_bf16 v[76:79], v[136:139], v[208:211], v[76:79]
	v_mfma_f32_16x16x32_bf16 v[124:127], v[132:135], v[188:191], v[124:127]
	v_mfma_f32_16x16x32_bf16 v[120:123], v[140:143], v[188:191], v[120:123]
	v_mfma_f32_16x16x32_bf16 v[116:119], v[132:135], v[196:199], v[116:119]
	v_mfma_f32_16x16x32_bf16 v[112:115], v[140:143], v[196:199], v[112:115]
	v_mfma_f32_16x16x32_bf16 v[92:95], v[132:135], v[204:207], v[92:95]
	v_mfma_f32_16x16x32_bf16 v[88:91], v[140:143], v[204:207], v[88:91]
	v_mfma_f32_16x16x32_bf16 v[84:87], v[132:135], v[212:215], v[84:87]
	v_mfma_f32_16x16x32_bf16 v[76:79], v[140:143], v[212:215], v[76:79]
	v_mfma_f32_16x16x32_bf16 v[108:111], v[162:165], v[184:187], v[108:111]
	v_mfma_f32_16x16x32_bf16 v[104:107], v[176:179], v[184:187], v[104:107]
	v_mfma_f32_16x16x32_bf16 v[100:103], v[162:165], v[192:195], v[100:103]
	v_mfma_f32_16x16x32_bf16 v[96:99], v[176:179], v[192:195], v[96:99]
	v_mfma_f32_16x16x32_bf16 v[80:83], v[162:165], v[200:203], v[80:83]
	v_mfma_f32_16x16x32_bf16 v[72:75], v[176:179], v[200:203], v[72:75]
	v_mfma_f32_16x16x32_bf16 v[68:71], v[162:165], v[208:211], v[68:71]
	v_mfma_f32_16x16x32_bf16 v[64:67], v[176:179], v[208:211], v[64:67]
	v_mfma_f32_16x16x32_bf16 v[108:111], v[172:175], v[188:191], v[108:111]
	v_mfma_f32_16x16x32_bf16 v[104:107], v[180:183], v[188:191], v[104:107]
	v_mfma_f32_16x16x32_bf16 v[100:103], v[172:175], v[196:199], v[100:103]
	v_mfma_f32_16x16x32_bf16 v[96:99], v[180:183], v[196:199], v[96:99]
	v_mfma_f32_16x16x32_bf16 v[80:83], v[172:175], v[204:207], v[80:83]
	v_mfma_f32_16x16x32_bf16 v[72:75], v[180:183], v[204:207], v[72:75]
	v_mfma_f32_16x16x32_bf16 v[68:71], v[172:175], v[212:215], v[68:71]
	v_mfma_f32_16x16x32_bf16 v[64:67], v[180:183], v[212:215], v[64:67]
	s_setprio 0
	s_barrier
; #define PG8_STAGE(bufoff, gbase, voff) do { _Pragma("unroll") for (int _i = 0; _i < 2; ++_i) \
;         __builtin_amdgcn_global_load_lds((const unsigned*)((const char*)(gbase) + (voff)[_i]), (PG8_LAS unsigned*)(lds + (bufoff) + ldsw + _i * 8192), 16, 0, 0); } while (0)
; #define PG8_LDA(dst, b, h) do { _Pragma("unroll") for (int m = 0; m < 4; ++m) _Pragma("unroll") for (int k = 0; k < 2; ++k) dst[m][k] = *(const PG8_LAS bf16x8*)(lds + PG8_SA(b, h) + aoff + m * 2048 + k * 1024); } while (0)
; #define PG8_LDB(dst, b, h) do { _Pragma("unroll") for (int n = 0; n < 2; ++n) _Pragma("unroll") for (int k = 0; k < 2; ++k) dst[n][k] = *(const PG8_LAS bf16x8*)(lds + PG8_SB(b, h) + boff + n * 2048 + k * 1024); } while (0)
; #define PG8_MMA(ai, bj, At, Bt) do { __builtin_amdgcn_s_setprio(1); _Pragma("unroll") for (int m = 0; m < 4; ++m) _Pragma("unroll") for (int n = 0; n < 2; ++n) _Pragma("unroll") for (int k = 0; k < 2; ++k) \
;         acc[ai][bj][m][n] = __builtin_amdgcn_mfma_f32_16x16x32_bf16(Bt[n][k], At[m][k], acc[ai][bj][m][n], 0, 0, 0); __builtin_amdgcn_s_setprio(0); } while (0)
; #define PG8_WAIT_V(n) asm volatile("s_waitcnt vmcnt(" #n ")" ::: "memory")
; #define PG8_WAIT_L(n) asm volatile("s_waitcnt lgkmcnt(" #n ")" ::: "memory")
; #define PG8_BAR __builtin_amdgcn_s_barrier()
; template <class Epi, class Sched, bool ALIGN_EPI = false, bool SP2 = false>
; __device__ __forceinline__ void gemm_phase(PG8_LAS unsigned char* lds, const Gemm g, const Sched& S, const Epi& E, const int wave_in) {
;     ...
;         for (int t = 0; t < nt; t += 2) {
;             const bool last = (t == nt - 2);
;             const char* a1 = cA + (size_t)(t + 1) * kstep;
;             const char* a2 = last ? nA : cA + (size_t)(t + 2) * kstep; const char* b2 = last ? nB : cB + (size_t)(t + 2) * kstep;
;             const char* a3 = a2 + kstep; const char* b3 = b2 + kstep;
;             if (last && has_next) S.a_ready(nxt);
;             if constexpr (SP2) {
;             PG8_LDB(B0, 0, 0); PG8_LDB(B1, 0, 1); PG8_SCHED; PG8_LDA(At, 0, 0); PG8_STAGE(PG8_SA(1, 1), a1 + hstepA, voffA);
;     ...
;             PG8_LDA(At, 1, 1); PG8_STAGE(PG8_SB(1, 0), b3, voffB); PG8_STAGE(PG8_SB(1, 1), b3 + hstepB, voffB); PG8_STAGE(PG8_SA(1, 0), a3, voffA);
;             PG8_WAIT_V(8); PG8_WAIT_L(0); PG8_BAR; PG8_MMA(1, 0, At, B0); PG8_MMA(1, 1, At, B1); PG8_BAR; PG8_SCHED;
	s_add_i32 s22, s54, s34
	v_lshl_add_u64 v[216:217], v[216:217], 0, s[10:11]
	s_mov_b32 m0, s22
	ds_read_b128 v[184:187], v170 offset:49152
	ds_read_b128 v[188:191], v170 offset:50176
	ds_read_b128 v[192:195], v170 offset:51200
	ds_read_b128 v[196:199], v170 offset:52224
	ds_read_b128 v[200:203], v170 offset:53248
	ds_read_b128 v[204:207], v170 offset:54272
	ds_read_b128 v[208:211], v170 offset:55296
	ds_read_b128 v[212:215], v170 offset:56320
	global_load_lds_dwordx4 v[216:217], off
	s_add_i32 m0, s22, 0x2000
	s_add_u32 s22, s24, 0x80080
	v_lshl_add_u64 v[216:217], v[218:219], 0, s[10:11]
	s_addc_u32 s23, s25, 0
	s_add_i32 s24, s55, s34
	global_load_lds_dwordx4 v[216:217], off
	v_lshl_add_u64 v[216:217], s[22:23], 0, v[148:149]
	s_mov_b32 m0, s24
	s_nop 0
	global_load_lds_dwordx4 v[216:217], off
	v_lshl_add_u64 v[216:217], s[22:23], 0, v[144:145]
	s_add_i32 m0, s24, 0x2000
	s_nop 0
	global_load_lds_dwordx4 v[216:217], off
	v_lshl_add_u64 v[216:217], v[220:221], 0, s[10:11]
	s_mov_b32 m0, s44
	s_nop 0
	global_load_lds_dwordx4 v[216:217], off
	v_lshl_add_u64 v[216:217], v[222:223], 0, s[10:11]
	s_mov_b32 m0, s45
	s_nop 0
	global_load_lds_dwordx4 v[216:217], off
	s_waitcnt vmcnt(8)
	s_waitcnt lgkmcnt(0)
	s_setprio 1
	s_barrier
	v_mfma_f32_16x16x32_bf16 v[60:63], v[128:131], v[184:187], v[60:63]
	v_mfma_f32_16x16x32_bf16 v[56:59], v[136:139], v[184:187], v[56:59]
	v_mfma_f32_16x16x32_bf16 v[52:55], v[128:131], v[192:195], v[52:55]
	v_mfma_f32_16x16x32_bf16 v[44:47], v[136:139], v[192:195], v[44:47]
	v_mfma_f32_16x16x32_bf16 v[36:39], v[128:131], v[200:203], v[36:39]
	v_mfma_f32_16x16x32_bf16 v[28:31], v[136:139], v[200:203], v[28:31]
	v_mfma_f32_16x16x32_bf16 v[20:23], v[128:131], v[208:211], v[20:23]
	v_mfma_f32_16x16x32_bf16 v[12:15], v[136:139], v[208:211], v[12:15]
	v_mfma_f32_16x16x32_bf16 v[60:63], v[132:135], v[188:191], v[60:63]
	v_mfma_f32_16x16x32_bf16 v[56:59], v[140:143], v[188:191], v[56:59]
	v_mfma_f32_16x16x32_bf16 v[52:55], v[132:135], v[196:199], v[52:55]
	v_mfma_f32_16x16x32_bf16 v[44:47], v[140:143], v[196:199], v[44:47]
	v_mfma_f32_16x16x32_bf16 v[36:39], v[132:135], v[204:207], v[36:39]
	v_mfma_f32_16x16x32_bf16 v[28:31], v[140:143], v[204:207], v[28:31]
	v_mfma_f32_16x16x32_bf16 v[20:23], v[132:135], v[212:215], v[20:23]
	v_mfma_f32_16x16x32_bf16 v[12:15], v[140:143], v[212:215], v[12:15]
	v_mfma_f32_16x16x32_bf16 v[48:51], v[162:165], v[184:187], v[48:51]
	v_mfma_f32_16x16x32_bf16 v[40:43], v[176:179], v[184:187], v[40:43]
	v_mfma_f32_16x16x32_bf16 v[32:35], v[162:165], v[192:195], v[32:35]
	v_mfma_f32_16x16x32_bf16 v[24:27], v[176:179], v[192:195], v[24:27]
	v_mfma_f32_16x16x32_bf16 v[16:19], v[162:165], v[200:203], v[16:19]
	v_mfma_f32_16x16x32_bf16 v[8:11], v[176:179], v[200:203], v[8:11]
	v_mfma_f32_16x16x32_bf16 v[4:7], v[162:165], v[208:211], v[4:7]
	v_mfma_f32_16x16x32_bf16 v[0:3], v[176:179], v[208:211], v[0:3]
	v_mfma_f32_16x16x32_bf16 v[48:51], v[172:175], v[188:191], v[48:51]
	v_mfma_f32_16x16x32_bf16 v[40:43], v[180:183], v[188:191], v[40:43]
	v_mfma_f32_16x16x32_bf16 v[32:35], v[172:175], v[196:199], v[32:35]
	v_mfma_f32_16x16x32_bf16 v[24:27], v[180:183], v[196:199], v[24:27]
	v_mfma_f32_16x16x32_bf16 v[16:19], v[172:175], v[204:207], v[16:19]
	v_mfma_f32_16x16x32_bf16 v[8:11], v[180:183], v[204:207], v[8:11]
	v_mfma_f32_16x16x32_bf16 v[4:7], v[172:175], v[212:215], v[4:7]
	v_mfma_f32_16x16x32_bf16 v[0:3], v[180:183], v[212:215], v[0:3]
	s_setprio 0
	s_barrier
	s_add_i32 s53, s53, 2
	s_add_u32 s51, s51, 0x100
	s_addc_u32 s52, s52, 0
	s_cmp_gt_u32 s53, 29
	s_mov_b64 s[22:23], s[4:5]
	s_cbranch_scc0 .LBB0_353
	s_branch .Lkx_4
.LBB0_353:
	ds_read_b128 v[128:131], v168
	ds_read_b128 v[132:135], v168 offset:1024
	ds_read_b128 v[136:139], v168 offset:2048
	ds_read_b128 v[140:143], v168 offset:3072
	ds_read_b128 v[162:165], v169
	ds_read_b128 v[172:175], v169 offset:1024
	ds_read_b128 v[176:179], v169 offset:2048
	ds_read_b128 v[180:183], v169 offset:3072
	s_add_u32 s4, s22, 0x100
	s_addc_u32 s5, s23, 0
	s_cmp_eq_u32 s53, 28
	s_cselect_b32 s27, s17, s5
	s_cselect_b32 s26, s16, s4
	s_cselect_b32 s25, s15, s52
	s_cselect_b32 s24, s21, s51
	v_lshl_add_u64 v[216:217], s[22:23], 0, v[154:155]
	s_add_i32 m0, s37, 0xc000
	ds_read_b128 v[184:187], v170
	ds_read_b128 v[188:191], v170 offset:1024
	ds_read_b128 v[192:195], v170 offset:2048
	ds_read_b128 v[196:199], v170 offset:3072
	ds_read_b128 v[200:203], v170 offset:4096
	ds_read_b128 v[204:207], v170 offset:5120
	ds_read_b128 v[208:211], v170 offset:6144
	ds_read_b128 v[212:215], v170 offset:7168
	global_load_lds_dwordx4 v[216:217], off
	v_lshl_add_u64 v[216:217], s[22:23], 0, v[156:157]
	s_add_i32 m0, s37, 0xe000
	s_nop 0
	global_load_lds_dwordx4 v[216:217], off
	s_waitcnt vmcnt(8)
	s_waitcnt lgkmcnt(0)
	s_setprio 1
	s_barrier
; #define PG8_STAGE(bufoff, gbase, voff) do { _Pragma("unroll") for (int _i = 0; _i < 2; ++_i) \
;         __builtin_amdgcn_global_load_lds((const unsigned*)((const char*)(gbase) + (voff)[_i]), (PG8_LAS unsigned*)(lds + (bufoff) + ldsw + _i * 8192), 16, 0, 0); } while (0)
; #define PG8_LDA(dst, b, h) do { _Pragma("unroll") for (int m = 0; m < 4; ++m) _Pragma("unroll") for (int k = 0; k < 2; ++k) dst[m][k] = *(const PG8_LAS bf16x8*)(lds + PG8_SA(b, h) + aoff + m * 2048 + k * 1024); } while (0)
; #define PG8_LDB(dst, b, h) do { _Pragma("unroll") for (int n = 0; n < 2; ++n) _Pragma("unroll") for (int k = 0; k < 2; ++k) dst[n][k] = *(const PG8_LAS bf16x8*)(lds + PG8_SB(b, h) + boff + n * 2048 + k * 1024); } while (0)
; #define PG8_MMA(ai, bj, At, Bt) do { __builtin_amdgcn_s_setprio(1); _Pragma("unroll") for (int m = 0; m < 4; ++m) _Pragma("unroll") for (int n = 0; n < 2; ++n) _Pragma("unroll") for (int k = 0; k < 2; ++k) \
;         acc[ai][bj][m][n] = __builtin_amdgcn_mfma_f32_16x16x32_bf16(Bt[n][k], At[m][k], acc[ai][bj][m][n], 0, 0, 0); __builtin_amdgcn_s_setprio(0); } while (0)
; #define PG8_BAR __builtin_amdgcn_s_barrier()
; template <class Epi, class Sched, bool ALIGN_EPI = false, bool SP2 = false>
; __device__ __forceinline__ void gemm_phase(PG8_LAS unsigned char* lds, const Gemm g, const Sched& S, const Epi& E, const int wave_in) {
;     ...
;             PG8_LDB(B0, 0, 0); PG8_LDB(B1, 0, 1); PG8_SCHED; PG8_LDA(At, 0, 0); PG8_STAGE(PG8_SA(1, 1), a1 + hstepA, voffA);
;             PG8_WAIT_V(8); PG8_WAIT_L(0); PG8_BAR; PG8_MMA(0, 0, At, B0); PG8_MMA(0, 1, At, B1); PG8_BAR; PG8_SCHED;
;             PG8_LDA(At, 0, 1); PG8_STAGE(PG8_SB(0, 0), b2, voffB); PG8_STAGE(PG8_SB(0, 1), b2 + hstepB, voffB); PG8_STAGE(PG8_SA(0, 0), a2, voffA);
;             PG8_WAIT_V(8); PG8_WAIT_L(0); PG8_BAR; PG8_MMA(1, 0, At, B0); PG8_MMA(1, 1, At, B1); PG8_BAR; PG8_SCHED;
;             PG8_LDB(B0, 1, 0); PG8_LDB(B1, 1, 1); PG8_SCHED; PG8_LDA(At, 1, 0); PG8_STAGE(PG8_SA(0, 1), a2 + hstepA, voffA);
;             PG8_WAIT_V(8); PG8_WAIT_L(0); PG8_BAR; PG8_MMA(0, 0, At, B0); PG8_MMA(0, 1, At, B1); PG8_BAR; PG8_SCHED;
;             PG8_LDA(At, 1, 1); PG8_STAGE(PG8_SB(1, 0), b3, voffB); PG8_STAGE(PG8_SB(1, 1), b3 + hstepB, voffB); PG8_STAGE(PG8_SA(1, 0), a3, voffA);
;             PG8_WAIT_V(8); PG8_WAIT_L(0); PG8_BAR; PG8_MMA(1, 0, At, B0); PG8_MMA(1, 1, At, B1); PG8_BAR; PG8_SCHED;
	v_mfma_f32_16x16x32_bf16 v[124:127], v[128:131], v[184:187], v[124:127]
	v_mfma_f32_16x16x32_bf16 v[120:123], v[136:139], v[184:187], v[120:123]
	v_mfma_f32_16x16x32_bf16 v[116:119], v[128:131], v[192:195], v[116:119]
	v_mfma_f32_16x16x32_bf16 v[112:115], v[136:139], v[192:195], v[112:115]
	v_mfma_f32_16x16x32_bf16 v[92:95], v[128:131], v[200:203], v[92:95]
	v_mfma_f32_16x16x32_bf16 v[88:91], v[136:139], v[200:203], v[88:91]
	v_mfma_f32_16x16x32_bf16 v[84:87], v[128:131], v[208:211], v[84:87]
	v_mfma_f32_16x16x32_bf16 v[76:79], v[136:139], v[208:211], v[76:79]
	v_mfma_f32_16x16x32_bf16 v[124:127], v[132:135], v[188:191], v[124:127]
	v_mfma_f32_16x16x32_bf16 v[120:123], v[140:143], v[188:191], v[120:123]
	v_mfma_f32_16x16x32_bf16 v[116:119], v[132:135], v[196:199], v[116:119]
	v_mfma_f32_16x16x32_bf16 v[112:115], v[140:143], v[196:199], v[112:115]
	v_mfma_f32_16x16x32_bf16 v[92:95], v[132:135], v[204:207], v[92:95]
	v_mfma_f32_16x16x32_bf16 v[88:91], v[140:143], v[204:207], v[88:91]
	v_mfma_f32_16x16x32_bf16 v[84:87], v[132:135], v[212:215], v[84:87]
	v_mfma_f32_16x16x32_bf16 v[76:79], v[140:143], v[212:215], v[76:79]
	v_mfma_f32_16x16x32_bf16 v[108:111], v[162:165], v[184:187], v[108:111]
	v_mfma_f32_16x16x32_bf16 v[104:107], v[176:179], v[184:187], v[104:107]
	v_mfma_f32_16x16x32_bf16 v[100:103], v[162:165], v[192:195], v[100:103]
	v_mfma_f32_16x16x32_bf16 v[96:99], v[176:179], v[192:195], v[96:99]
	v_mfma_f32_16x16x32_bf16 v[80:83], v[162:165], v[200:203], v[80:83]
	v_mfma_f32_16x16x32_bf16 v[72:75], v[176:179], v[200:203], v[72:75]
	v_mfma_f32_16x16x32_bf16 v[68:71], v[162:165], v[208:211], v[68:71]
	v_mfma_f32_16x16x32_bf16 v[64:67], v[176:179], v[208:211], v[64:67]
	v_mfma_f32_16x16x32_bf16 v[108:111], v[172:175], v[188:191], v[108:111]
	v_mfma_f32_16x16x32_bf16 v[104:107], v[180:183], v[188:191], v[104:107]
	v_mfma_f32_16x16x32_bf16 v[100:103], v[172:175], v[196:199], v[100:103]
	v_mfma_f32_16x16x32_bf16 v[96:99], v[180:183], v[196:199], v[96:99]
	v_mfma_f32_16x16x32_bf16 v[80:83], v[172:175], v[204:207], v[80:83]
	v_mfma_f32_16x16x32_bf16 v[72:75], v[180:183], v[204:207], v[72:75]
	v_mfma_f32_16x16x32_bf16 v[68:71], v[172:175], v[212:215], v[68:71]
	v_mfma_f32_16x16x32_bf16 v[64:67], v[180:183], v[212:215], v[64:67]
	s_setprio 0
	s_barrier
	s_add_i32 s22, s47, s34
	v_lshl_add_u64 v[216:217], s[24:25], 0, v[148:149]
	s_mov_b32 m0, s22
	ds_read_b128 v[184:187], v170 offset:16384
	ds_read_b128 v[188:191], v170 offset:17408
	ds_read_b128 v[192:195], v170 offset:18432
	ds_read_b128 v[196:199], v170 offset:19456
	ds_read_b128 v[200:203], v170 offset:20480
	ds_read_b128 v[204:207], v170 offset:21504
	ds_read_b128 v[208:211], v170 offset:22528
	ds_read_b128 v[212:215], v170 offset:23552
	global_load_lds_dwordx4 v[216:217], off
	s_add_i32 m0, s22, 0x2000
	s_add_u32 s22, s24, 0x80000
	v_lshl_add_u64 v[218:219], s[24:25], 0, v[144:145]
	s_addc_u32 s23, s25, 0
	s_add_i32 s54, s48, s34
	global_load_lds_dwordx4 v[218:219], off
	v_lshl_add_u64 v[220:221], s[22:23], 0, v[148:149]
	s_mov_b32 m0, s54
	v_lshl_add_u64 v[222:223], s[26:27], 0, v[146:147]
	global_load_lds_dwordx4 v[220:221], off
	v_lshl_add_u64 v[220:221], s[22:23], 0, v[144:145]
	s_add_i32 m0, s54, 0x2000
	s_nop 0
	global_load_lds_dwordx4 v[220:221], off
	v_lshl_add_u64 v[220:221], s[26:27], 0, v[150:151]
	s_mov_b32 m0, s37
	s_nop 0
	global_load_lds_dwordx4 v[220:221], off
	s_mov_b32 m0, s38
	s_nop 0
	global_load_lds_dwordx4 v[222:223], off
	s_waitcnt vmcnt(8)
	s_waitcnt lgkmcnt(0)
	s_setprio 1
	s_barrier
	v_mfma_f32_16x16x32_bf16 v[60:63], v[128:131], v[184:187], v[60:63]
	v_mfma_f32_16x16x32_bf16 v[56:59], v[136:139], v[184:187], v[56:59]
	v_mfma_f32_16x16x32_bf16 v[52:55], v[128:131], v[192:195], v[52:55]
	v_mfma_f32_16x16x32_bf16 v[44:47], v[136:139], v[192:195], v[44:47]
	v_mfma_f32_16x16x32_bf16 v[36:39], v[128:131], v[200:203], v[36:39]
	v_mfma_f32_16x16x32_bf16 v[28:31], v[136:139], v[200:203], v[28:31]
	v_mfma_f32_16x16x32_bf16 v[20:23], v[128:131], v[208:211], v[20:23]
	v_mfma_f32_16x16x32_bf16 v[12:15], v[136:139], v[208:211], v[12:15]
	v_mfma_f32_16x16x32_bf16 v[60:63], v[132:135], v[188:191], v[60:63]
	v_mfma_f32_16x16x32_bf16 v[56:59], v[140:143], v[188:191], v[56:59]
	v_mfma_f32_16x16x32_bf16 v[52:55], v[132:135], v[196:199], v[52:55]
	v_mfma_f32_16x16x32_bf16 v[44:47], v[140:143], v[196:199], v[44:47]
	v_mfma_f32_16x16x32_bf16 v[36:39], v[132:135], v[204:207], v[36:39]
	v_mfma_f32_16x16x32_bf16 v[28:31], v[140:143], v[204:207], v[28:31]
	v_mfma_f32_16x16x32_bf16 v[20:23], v[132:135], v[212:215], v[20:23]
	v_mfma_f32_16x16x32_bf16 v[12:15], v[140:143], v[212:215], v[12:15]
	v_mfma_f32_16x16x32_bf16 v[48:51], v[162:165], v[184:187], v[48:51]
	v_mfma_f32_16x16x32_bf16 v[40:43], v[176:179], v[184:187], v[40:43]
	v_mfma_f32_16x16x32_bf16 v[32:35], v[162:165], v[192:195], v[32:35]
	v_mfma_f32_16x16x32_bf16 v[24:27], v[176:179], v[192:195], v[24:27]
	v_mfma_f32_16x16x32_bf16 v[16:19], v[162:165], v[200:203], v[16:19]
	v_mfma_f32_16x16x32_bf16 v[8:11], v[176:179], v[200:203], v[8:11]
	v_mfma_f32_16x16x32_bf16 v[4:7], v[162:165], v[208:211], v[4:7]
	v_mfma_f32_16x16x32_bf16 v[0:3], v[176:179], v[208:211], v[0:3]
	v_mfma_f32_16x16x32_bf16 v[48:51], v[172:175], v[188:191], v[48:51]
	v_mfma_f32_16x16x32_bf16 v[40:43], v[180:183], v[188:191], v[40:43]
	v_mfma_f32_16x16x32_bf16 v[32:35], v[172:175], v[196:199], v[32:35]
	v_mfma_f32_16x16x32_bf16 v[24:27], v[180:183], v[196:199], v[24:27]
	v_mfma_f32_16x16x32_bf16 v[16:19], v[172:175], v[204:207], v[16:19]
	v_mfma_f32_16x16x32_bf16 v[8:11], v[180:183], v[204:207], v[8:11]
	v_mfma_f32_16x16x32_bf16 v[4:7], v[172:175], v[212:215], v[4:7]
	v_mfma_f32_16x16x32_bf16 v[0:3], v[180:183], v[212:215], v[0:3]
	s_setprio 0
	s_barrier
; #define PG8_STAGE(bufoff, gbase, voff) do { _Pragma("unroll") for (int _i = 0; _i < 2; ++_i) \
;         __builtin_amdgcn_global_load_lds((const unsigned*)((const char*)(gbase) + (voff)[_i]), (PG8_LAS unsigned*)(lds + (bufoff) + ldsw + _i * 8192), 16, 0, 0); } while (0)
; #define PG8_LDA(dst, b, h) do { _Pragma("unroll") for (int m = 0; m < 4; ++m) _Pragma("unroll") for (int k = 0; k < 2; ++k) dst[m][k] = *(const PG8_LAS bf16x8*)(lds + PG8_SA(b, h) + aoff + m * 2048 + k * 1024); } while (0)
; #define PG8_LDB(dst, b, h) do { _Pragma("unroll") for (int n = 0; n < 2; ++n) _Pragma("unroll") for (int k = 0; k < 2; ++k) dst[n][k] = *(const PG8_LAS bf16x8*)(lds + PG8_SB(b, h) + boff + n * 2048 + k * 1024); } while (0)
; #define PG8_MMA(ai, bj, At, Bt) do { __builtin_amdgcn_s_setprio(1); _Pragma("unroll") for (int m = 0; m < 4; ++m) _Pragma("unroll") for (int n = 0; n < 2; ++n) _Pragma("unroll") for (int k = 0; k < 2; ++k) \
;         acc[ai][bj][m][n] = __builtin_amdgcn_mfma_f32_16x16x32_bf16(Bt[n][k], At[m][k], acc[ai][bj][m][n], 0, 0, 0); __builtin_amdgcn_s_setprio(0); } while (0)
; #define PG8_WAIT_V(n) asm volatile("s_waitcnt vmcnt(" #n ")" ::: "memory")
; #define PG8_WAIT_L(n) asm volatile("s_waitcnt lgkmcnt(" #n ")" ::: "memory")
; #define PG8_BAR __builtin_amdgcn_s_barrier()
; template <class Epi, class Sched, bool ALIGN_EPI = false, bool SP2 = false>
; __device__ __forceinline__ void gemm_phase(PG8_LAS unsigned char* lds, const Gemm g, const Sched& S, const Epi& E, const int wave_in) {
;     ...
;         for (int t = 0; t < nt; t += 2) {
;             const bool last = (t == nt - 2);
;             const char* a1 = cA + (size_t)(t + 1) * kstep;
;             const char* a2 = last ? nA : cA + (size_t)(t + 2) * kstep; const char* b2 = last ? nB : cB + (size_t)(t + 2) * kstep;
;             const char* a3 = a2 + kstep; const char* b3 = b2 + kstep;
;     ...
;             PG8_LDB(B0, 1, 0); PG8_LDB(B1, 1, 1); PG8_SCHED; PG8_LDA(At, 1, 0); PG8_STAGE(PG8_SA(0, 1), a2 + hstepA, voffA);
;             PG8_WAIT_V(8); PG8_WAIT_L(0); PG8_BAR; PG8_MMA(0, 0, At, B0); PG8_MMA(0, 1, At, B1); PG8_BAR; PG8_SCHED;
;             PG8_LDA(At, 1, 1); PG8_STAGE(PG8_SB(1, 0), b3, voffB); PG8_STAGE(PG8_SB(1, 1), b3 + hstepB, voffB); PG8_STAGE(PG8_SA(1, 0), a3, voffA);
;             PG8_WAIT_V(8); PG8_WAIT_L(0); PG8_BAR; PG8_MMA(1, 0, At, B0); PG8_MMA(1, 1, At, B1); PG8_BAR; PG8_SCHED;
	s_add_i32 s54, 0, 0x18000
	s_add_i32 s55, 0, 0x1c000
	v_add_u32_e32 v140, s54, v166
	v_add_u32_e32 v171, s55, v166
	ds_read_b128 v[128:131], v140
	ds_read_b128 v[132:135], v140 offset:1024
	ds_read_b128 v[136:139], v140 offset:2048
	ds_read_b128 v[140:143], v140 offset:3072
	ds_read_b128 v[162:165], v171
	ds_read_b128 v[172:175], v171 offset:1024
	ds_read_b128 v[176:179], v171 offset:2048
	ds_read_b128 v[180:183], v171 offset:3072
	s_add_u32 s22, s26, 0x280000
	s_addc_u32 s23, s27, 0
	s_mov_b32 m0, s39
	v_lshl_add_u64 v[224:225], s[22:23], 0, v[150:151]
	ds_read_b128 v[184:187], v170 offset:32768
	ds_read_b128 v[188:191], v170 offset:33792
	ds_read_b128 v[192:195], v170 offset:34816
	ds_read_b128 v[196:199], v170 offset:35840
	ds_read_b128 v[200:203], v170 offset:36864
	ds_read_b128 v[204:207], v170 offset:37888
	ds_read_b128 v[208:211], v170 offset:38912
	ds_read_b128 v[212:215], v170 offset:39936
	global_load_lds_dwordx4 v[224:225], off
	v_lshl_add_u64 v[224:225], s[22:23], 0, v[146:147]
	s_mov_b32 m0, s40
	s_nop 0
	global_load_lds_dwordx4 v[224:225], off
	s_waitcnt vmcnt(8)
	s_waitcnt lgkmcnt(0)
	s_setprio 1
	s_barrier
	v_mfma_f32_16x16x32_bf16 v[124:127], v[128:131], v[184:187], v[124:127]
	v_mfma_f32_16x16x32_bf16 v[120:123], v[136:139], v[184:187], v[120:123]
	v_mfma_f32_16x16x32_bf16 v[116:119], v[128:131], v[192:195], v[116:119]
	v_mfma_f32_16x16x32_bf16 v[112:115], v[136:139], v[192:195], v[112:115]
	v_mfma_f32_16x16x32_bf16 v[92:95], v[128:131], v[200:203], v[92:95]
	v_mfma_f32_16x16x32_bf16 v[88:91], v[136:139], v[200:203], v[88:91]
	v_mfma_f32_16x16x32_bf16 v[84:87], v[128:131], v[208:211], v[84:87]
	v_mfma_f32_16x16x32_bf16 v[76:79], v[136:139], v[208:211], v[76:79]
	v_mfma_f32_16x16x32_bf16 v[124:127], v[132:135], v[188:191], v[124:127]
	v_mfma_f32_16x16x32_bf16 v[120:123], v[140:143], v[188:191], v[120:123]
	v_mfma_f32_16x16x32_bf16 v[116:119], v[132:135], v[196:199], v[116:119]
	v_mfma_f32_16x16x32_bf16 v[112:115], v[140:143], v[196:199], v[112:115]
	v_mfma_f32_16x16x32_bf16 v[92:95], v[132:135], v[204:207], v[92:95]
	v_mfma_f32_16x16x32_bf16 v[88:91], v[140:143], v[204:207], v[88:91]
	v_mfma_f32_16x16x32_bf16 v[84:87], v[132:135], v[212:215], v[84:87]
	v_mfma_f32_16x16x32_bf16 v[76:79], v[140:143], v[212:215], v[76:79]
	v_mfma_f32_16x16x32_bf16 v[108:111], v[162:165], v[184:187], v[108:111]
	v_mfma_f32_16x16x32_bf16 v[104:107], v[176:179], v[184:187], v[104:107]
	v_mfma_f32_16x16x32_bf16 v[100:103], v[162:165], v[192:195], v[100:103]
	v_mfma_f32_16x16x32_bf16 v[96:99], v[176:179], v[192:195], v[96:99]
	v_mfma_f32_16x16x32_bf16 v[80:83], v[162:165], v[200:203], v[80:83]
	v_mfma_f32_16x16x32_bf16 v[72:75], v[176:179], v[200:203], v[72:75]
	v_mfma_f32_16x16x32_bf16 v[68:71], v[162:165], v[208:211], v[68:71]
	v_mfma_f32_16x16x32_bf16 v[64:67], v[176:179], v[208:211], v[64:67]
	v_mfma_f32_16x16x32_bf16 v[108:111], v[172:175], v[188:191], v[108:111]
	v_mfma_f32_16x16x32_bf16 v[104:107], v[180:183], v[188:191], v[104:107]
	v_mfma_f32_16x16x32_bf16 v[100:103], v[172:175], v[196:199], v[100:103]
	v_mfma_f32_16x16x32_bf16 v[96:99], v[180:183], v[196:199], v[96:99]
	v_mfma_f32_16x16x32_bf16 v[80:83], v[172:175], v[204:207], v[80:83]
	v_mfma_f32_16x16x32_bf16 v[72:75], v[180:183], v[204:207], v[72:75]
	v_mfma_f32_16x16x32_bf16 v[68:71], v[172:175], v[212:215], v[68:71]
	v_mfma_f32_16x16x32_bf16 v[64:67], v[180:183], v[212:215], v[64:67]
	s_setprio 0
	s_barrier
	s_add_i32 s22, s54, s34
	v_lshl_add_u64 v[216:217], v[216:217], 0, s[10:11]
	s_mov_b32 m0, s22
	ds_read_b128 v[184:187], v170 offset:49152
	ds_read_b128 v[188:191], v170 offset:50176
	ds_read_b128 v[192:195], v170 offset:51200
	ds_read_b128 v[196:199], v170 offset:52224
	ds_read_b128 v[200:203], v170 offset:53248
	ds_read_b128 v[204:207], v170 offset:54272
	ds_read_b128 v[208:211], v170 offset:55296
	ds_read_b128 v[212:215], v170 offset:56320
	global_load_lds_dwordx4 v[216:217], off
	s_add_i32 m0, s22, 0x2000
	s_add_u32 s22, s24, 0x80080
	v_lshl_add_u64 v[216:217], v[218:219], 0, s[10:11]
	s_addc_u32 s23, s25, 0
	s_add_i32 s24, s55, s34
	global_load_lds_dwordx4 v[216:217], off
	v_lshl_add_u64 v[216:217], s[22:23], 0, v[148:149]
	s_mov_b32 m0, s24
	s_nop 0
	global_load_lds_dwordx4 v[216:217], off
	v_lshl_add_u64 v[216:217], s[22:23], 0, v[144:145]
	s_add_i32 m0, s24, 0x2000
	s_nop 0
	global_load_lds_dwordx4 v[216:217], off
	v_lshl_add_u64 v[216:217], v[220:221], 0, s[10:11]
	s_mov_b32 m0, s44
	s_nop 0
	global_load_lds_dwordx4 v[216:217], off
	v_lshl_add_u64 v[216:217], v[222:223], 0, s[10:11]
	s_mov_b32 m0, s45
	s_nop 0
	global_load_lds_dwordx4 v[216:217], off
	s_waitcnt vmcnt(8)
	s_waitcnt lgkmcnt(0)
	s_setprio 1
	s_barrier
	v_mfma_f32_16x16x32_bf16 v[60:63], v[128:131], v[184:187], v[60:63]
	v_mfma_f32_16x16x32_bf16 v[56:59], v[136:139], v[184:187], v[56:59]
	v_mfma_f32_16x16x32_bf16 v[52:55], v[128:131], v[192:195], v[52:55]
	v_mfma_f32_16x16x32_bf16 v[44:47], v[136:139], v[192:195], v[44:47]
	v_mfma_f32_16x16x32_bf16 v[36:39], v[128:131], v[200:203], v[36:39]
	v_mfma_f32_16x16x32_bf16 v[28:31], v[136:139], v[200:203], v[28:31]
	v_mfma_f32_16x16x32_bf16 v[20:23], v[128:131], v[208:211], v[20:23]
	v_mfma_f32_16x16x32_bf16 v[12:15], v[136:139], v[208:211], v[12:15]
	v_mfma_f32_16x16x32_bf16 v[60:63], v[132:135], v[188:191], v[60:63]
	v_mfma_f32_16x16x32_bf16 v[56:59], v[140:143], v[188:191], v[56:59]
	v_mfma_f32_16x16x32_bf16 v[52:55], v[132:135], v[196:199], v[52:55]
	v_mfma_f32_16x16x32_bf16 v[44:47], v[140:143], v[196:199], v[44:47]
	v_mfma_f32_16x16x32_bf16 v[36:39], v[132:135], v[204:207], v[36:39]
	v_mfma_f32_16x16x32_bf16 v[28:31], v[140:143], v[204:207], v[28:31]
	v_mfma_f32_16x16x32_bf16 v[20:23], v[132:135], v[212:215], v[20:23]
	v_mfma_f32_16x16x32_bf16 v[12:15], v[140:143], v[212:215], v[12:15]
	v_mfma_f32_16x16x32_bf16 v[48:51], v[162:165], v[184:187], v[48:51]
	v_mfma_f32_16x16x32_bf16 v[40:43], v[176:179], v[184:187], v[40:43]
	v_mfma_f32_16x16x32_bf16 v[32:35], v[162:165], v[192:195], v[32:35]
	v_mfma_f32_16x16x32_bf16 v[24:27], v[176:179], v[192:195], v[24:27]
	v_mfma_f32_16x16x32_bf16 v[16:19], v[162:165], v[200:203], v[16:19]
	v_mfma_f32_16x16x32_bf16 v[8:11], v[176:179], v[200:203], v[8:11]
	v_mfma_f32_16x16x32_bf16 v[4:7], v[162:165], v[208:211], v[4:7]
	v_mfma_f32_16x16x32_bf16 v[0:3], v[176:179], v[208:211], v[0:3]
	v_mfma_f32_16x16x32_bf16 v[48:51], v[172:175], v[188:191], v[48:51]
	v_mfma_f32_16x16x32_bf16 v[40:43], v[180:183], v[188:191], v[40:43]
	v_mfma_f32_16x16x32_bf16 v[32:35], v[172:175], v[196:199], v[32:35]
	v_mfma_f32_16x16x32_bf16 v[24:27], v[180:183], v[196:199], v[24:27]
	v_mfma_f32_16x16x32_bf16 v[16:19], v[172:175], v[204:207], v[16:19]
	v_mfma_f32_16x16x32_bf16 v[8:11], v[180:183], v[204:207], v[8:11]
	v_mfma_f32_16x16x32_bf16 v[4:7], v[172:175], v[212:215], v[4:7]
	v_mfma_f32_16x16x32_bf16 v[0:3], v[180:183], v[212:215], v[0:3]
	s_setprio 0
	s_barrier
	s_add_i32 s53, s53, 2
	s_add_u32 s51, s51, 0x100
	s_addc_u32 s52, s52, 0
	s_cmp_gt_u32 s53, 29
	s_mov_b64 s[22:23], s[4:5]
	s_cbranch_scc0 .LBB0_353

;     __host__ __device__ bool next(int i, Unit& u) const { const bool ok = StaticOrder::next(i, u); u.pm = 0; u.pn = 0; return ok; }
; #define PG8_STAGE(bufoff, gbase, voff) do { _Pragma("unroll") for (int _i = 0; _i < 2; ++_i) \
;         __builtin_amdgcn_global_load_lds((const unsigned*)((const char*)(gbase) + (voff)[_i]), (PG8_LAS unsigned*)(lds + (bufoff) + ldsw + _i * 8192), 16, 0, 0); } while (0)
; #define PG8_BAR __builtin_amdgcn_s_barrier()
; template <class Epi, class Sched, bool ALIGN_EPI = false, bool SP2 = false>
; __device__ __forceinline__ void gemm_phase(PG8_LAS unsigned char* lds, const Gemm g, const Sched& S, const Epi& E, const int wave_in) {
;     ...
;     for (;;) {
;         const bool has_next = S.next(ui + 1, nxt);
;         const char* nA = has_next ? (const char*)g.A + (size_t)nxt.pm * tstepA : cA; const char* nB = has_next ? (const char*)g.Bt + (size_t)nxt.pn * tstepB : cB;
;         for (int t = 0; t < nt; t += 2) {
;             const bool last = (t == nt - 2);
;             const char* a1 = cA + (size_t)(t + 1) * kstep;
;             const char* a2 = last ? nA : cA + (size_t)(t + 2) * kstep; const char* b2 = last ? nB : cB + (size_t)(t + 2) * kstep;
;             const char* a3 = a2 + kstep; const char* b3 = b2 + kstep;
;             if (last && has_next) S.a_ready(nxt);
;             if constexpr (SP2) {
;             PG8_LDB(B0, 0, 0); PG8_LDB(B1, 0, 1); PG8_SCHED; PG8_LDA(At, 0, 0); PG8_STAGE(PG8_SA(1, 1), a1 + hstepA, voffA);
;             PG8_WAIT_V(8); PG8_WAIT_L(0); PG8_BAR; PG8_MMA(0, 0, At, B0); PG8_MMA(0, 1, At, B1); PG8_BAR; PG8_SCHED;
;             PG8_LDA(At, 0, 1); PG8_STAGE(PG8_SB(0, 0), b2, voffB); PG8_STAGE(PG8_SB(0, 1), b2 + hstepB, voffB); PG8_STAGE(PG8_SA(0, 0), a2, voffA);
;             PG8_WAIT_V(8); PG8_WAIT_L(0); PG8_BAR; PG8_MMA(1, 0, At, B0); PG8_MMA(1, 1, At, B1); PG8_BAR; PG8_SCHED;
;             PG8_LDB(B0, 1, 0); PG8_LDB(B1, 1, 1); PG8_SCHED; PG8_LDA(At, 1, 0); PG8_STAGE(PG8_SA(0, 1), a2 + hstepA, voffA);
;             PG8_WAIT_V(8); PG8_WAIT_L(0); PG8_BAR; PG8_MMA(0, 0, At, B0); PG8_MMA(0, 1, At, B1); PG8_BAR; PG8_SCHED;
;             PG8_LDA(At, 1, 1); PG8_STAGE(PG8_SB(1, 0), b3, voffB); PG8_STAGE(PG8_SB(1, 1), b3 + hstepB, voffB); PG8_STAGE(PG8_SA(1, 0), a3, voffA);
;             PG8_WAIT_V(8); PG8_WAIT_L(0); PG8_BAR; PG8_MMA(1, 0, At, B0); PG8_MMA(1, 1, At, B1); PG8_BAR; PG8_SCHED;
.LBB0_478:
	s_ashr_i32 s41, s40, 31
	s_lshl_b64 s[42:43], s[40:41], 20
	s_add_u32 s42, s52, s42
	s_addc_u32 s43, s53, s43
	s_and_b64 s[44:45], s[10:11], exec
	s_cselect_b32 s1, s43, s47
	s_cselect_b32 s13, s42, s46
	s_ashr_i32 s39, s38, 31
	s_lshl_b64 s[44:45], s[38:39], 20
	s_add_u32 s44, s54, s44
	s_addc_u32 s45, s55, s45
	s_and_b64 s[50:51], s[10:11], exec
	s_cselect_b32 s39, s45, s49
	s_cselect_b32 s41, s44, s48
	s_add_u32 s46, s46, 0x80080
	s_addc_u32 s47, s47, 0
	s_add_u32 s72, s48, 0x100
	v_mov_b32_e32 v0, 0
	s_addc_u32 s73, s49, 0
	s_mov_b32 s74, -2
	ds_read_b128 v[44:47], v189
	ds_read_b128 v[48:51], v189 offset:1024
	ds_read_b128 v[52:55], v189 offset:2048
	ds_read_b128 v[56:59], v189 offset:3072
	ds_read_b128 v[60:63], v197
	ds_read_b128 v[64:67], v197 offset:1024
	ds_read_b128 v[80:83], v197 offset:2048
	ds_read_b128 v[84:87], v197 offset:3072
	s_add_u32 s48, s46, 0xfff80080
	s_addc_u32 s49, s47, -1
	s_cmp_eq_u32 s74, 28
	s_cselect_b32 s51, s1, s49
	s_cselect_b32 s50, s13, s48
	s_cselect_b32 s49, s39, s73
	s_cselect_b32 s48, s41, s72
	v_lshl_add_u64 v[224:225], s[46:47], 0, v[206:207]
	s_add_i32 m0, s57, 0xc000
	ds_read_b128 v[88:91], v199
	ds_read_b128 v[92:95], v199 offset:1024
	ds_read_b128 v[96:99], v199 offset:2048
	ds_read_b128 v[100:103], v199 offset:3072
	ds_read_b128 v[176:179], v199 offset:4096
	ds_read_b128 v[212:215], v199 offset:5120
	ds_read_b128 v[216:219], v199 offset:6144
	ds_read_b128 v[220:223], v199 offset:7168
	global_load_lds_dwordx4 v[224:225], off
	v_lshl_add_u64 v[224:225], s[46:47], 0, v[208:209]
	s_add_i32 m0, s57, 0xe000
	s_nop 0
	global_load_lds_dwordx4 v[224:225], off
	s_waitcnt vmcnt(8)
	s_waitcnt lgkmcnt(0)
	s_setprio 1
	s_barrier
	v_mfma_f32_16x16x32_bf16 v[172:175], v[44:47], v[88:91], 0
	v_mfma_f32_16x16x32_bf16 v[164:167], v[52:55], v[88:91], 0
	v_mfma_f32_16x16x32_bf16 v[156:159], v[44:47], v[96:99], 0
	v_mfma_f32_16x16x32_bf16 v[148:151], v[52:55], v[96:99], 0
	v_mfma_f32_16x16x32_bf16 v[140:143], v[44:47], v[176:179], 0
	v_mfma_f32_16x16x32_bf16 v[132:135], v[52:55], v[176:179], 0
	v_mfma_f32_16x16x32_bf16 v[124:127], v[44:47], v[216:219], 0
	v_mfma_f32_16x16x32_bf16 v[120:123], v[52:55], v[216:219], 0
	v_mfma_f32_16x16x32_bf16 v[172:175], v[48:51], v[92:95], v[172:175]
	v_mfma_f32_16x16x32_bf16 v[164:167], v[56:59], v[92:95], v[164:167]
	v_mfma_f32_16x16x32_bf16 v[156:159], v[48:51], v[100:103], v[156:159]
	v_mfma_f32_16x16x32_bf16 v[148:151], v[56:59], v[100:103], v[148:151]
	v_mfma_f32_16x16x32_bf16 v[140:143], v[48:51], v[212:215], v[140:143]
	v_mfma_f32_16x16x32_bf16 v[132:135], v[56:59], v[212:215], v[132:135]
	v_mfma_f32_16x16x32_bf16 v[124:127], v[48:51], v[220:223], v[124:127]
	v_mfma_f32_16x16x32_bf16 v[120:123], v[56:59], v[220:223], v[120:123]
	v_mfma_f32_16x16x32_bf16 v[168:171], v[60:63], v[88:91], 0
	v_mfma_f32_16x16x32_bf16 v[88:91], v[80:83], v[88:91], 0
	v_mfma_f32_16x16x32_bf16 v[168:171], v[64:67], v[92:95], v[168:171]
	v_mfma_f32_16x16x32_bf16 v[88:91], v[84:87], v[92:95], v[88:91]
	v_mfma_f32_16x16x32_bf16 v[92:95], v[60:63], v[96:99], 0
	v_mfma_f32_16x16x32_bf16 v[96:99], v[80:83], v[96:99], 0
	v_mfma_f32_16x16x32_bf16 v[128:131], v[80:83], v[176:179], 0
	v_mfma_f32_16x16x32_bf16 v[116:119], v[60:63], v[216:219], 0
	v_mfma_f32_16x16x32_bf16 v[112:115], v[80:83], v[216:219], 0
	v_mfma_f32_16x16x32_bf16 v[92:95], v[64:67], v[100:103], v[92:95]
	v_mfma_f32_16x16x32_bf16 v[96:99], v[84:87], v[100:103], v[96:99]
	v_mfma_f32_16x16x32_bf16 v[100:103], v[60:63], v[176:179], 0
	v_mfma_f32_16x16x32_bf16 v[128:131], v[84:87], v[212:215], v[128:131]
	v_mfma_f32_16x16x32_bf16 v[116:119], v[64:67], v[220:223], v[116:119]
	v_mfma_f32_16x16x32_bf16 v[112:115], v[84:87], v[220:223], v[112:115]
	v_mfma_f32_16x16x32_bf16 v[100:103], v[64:67], v[212:215], v[100:103]
	s_setprio 0
	s_barrier
	s_add_i32 s75, s68, s56
	v_lshl_add_u64 v[232:233], s[48:49], 0, v[182:183]
	s_mov_b32 m0, s75
	ds_read_b128 v[136:139], v199 offset:16384
	ds_read_b128 v[144:147], v199 offset:17408
	ds_read_b128 v[152:155], v199 offset:18432
	ds_read_b128 v[160:163], v199 offset:19456
	ds_read_b128 v[176:179], v199 offset:20480
	ds_read_b128 v[212:215], v199 offset:21504
	ds_read_b128 v[216:219], v199 offset:22528
	ds_read_b128 v[220:223], v199 offset:23552
	global_load_lds_dwordx4 v[232:233], off
	s_add_i32 m0, s75, 0x2000
	s_add_u32 s76, s48, 0x80000
	v_lshl_add_u64 v[234:235], s[48:49], 0, v[186:187]
	s_addc_u32 s77, s49, 0
	s_add_i32 s75, s69, s56
	global_load_lds_dwordx4 v[234:235], off
	v_lshl_add_u64 v[224:225], s[76:77], 0, v[182:183]
	s_mov_b32 m0, s75
	v_lshl_add_u64 v[236:237], s[50:51], 0, v[180:181]
	global_load_lds_dwordx4 v[224:225], off
	v_lshl_add_u64 v[224:225], s[76:77], 0, v[186:187]
	s_add_i32 m0, s75, 0x2000
	v_lshl_add_u64 v[238:239], s[50:51], 0, v[184:185]
	global_load_lds_dwordx4 v[224:225], off
	s_mov_b32 m0, s57
	s_nop 0
	global_load_lds_dwordx4 v[236:237], off
	s_mov_b32 m0, s58
	s_nop 0
	global_load_lds_dwordx4 v[238:239], off
	s_waitcnt vmcnt(8)
	s_waitcnt lgkmcnt(0)
	s_setprio 1
	s_barrier
; #define PG8_STAGE(bufoff, gbase, voff) do { _Pragma("unroll") for (int _i = 0; _i < 2; ++_i) \
;         __builtin_amdgcn_global_load_lds((const unsigned*)((const char*)(gbase) + (voff)[_i]), (PG8_LAS unsigned*)(lds + (bufoff) + ldsw + _i * 8192), 16, 0, 0); } while (0)
; #define PG8_LDA(dst, b, h) do { _Pragma("unroll") for (int m = 0; m < 4; ++m) _Pragma("unroll") for (int k = 0; k < 2; ++k) dst[m][k] = *(const PG8_LAS bf16x8*)(lds + PG8_SA(b, h) + aoff + m * 2048 + k * 1024); } while (0)
; #define PG8_LDB(dst, b, h) do { _Pragma("unroll") for (int n = 0; n < 2; ++n) _Pragma("unroll") for (int k = 0; k < 2; ++k) dst[n][k] = *(const PG8_LAS bf16x8*)(lds + PG8_SB(b, h) + boff + n * 2048 + k * 1024); } while (0)
; #define PG8_MMA(ai, bj, At, Bt) do { __builtin_amdgcn_s_setprio(1); _Pragma("unroll") for (int m = 0; m < 4; ++m) _Pragma("unroll") for (int n = 0; n < 2; ++n) _Pragma("unroll") for (int k = 0; k < 2; ++k) \
;         acc[ai][bj][m][n] = __builtin_amdgcn_mfma_f32_16x16x32_bf16(Bt[n][k], At[m][k], acc[ai][bj][m][n], 0, 0, 0); __builtin_amdgcn_s_setprio(0); } while (0)
; #define PG8_WAIT_V(n) asm volatile("s_waitcnt vmcnt(" #n ")" ::: "memory")
; #define PG8_WAIT_L(n) asm volatile("s_waitcnt lgkmcnt(" #n ")" ::: "memory")
; #define PG8_BAR __builtin_amdgcn_s_barrier()
; #define PG8_SCHED __builtin_amdgcn_sched_barrier(0)
; template <class Epi, class Sched, bool ALIGN_EPI = false, bool SP2 = false>
; __device__ __forceinline__ void gemm_phase(PG8_LAS unsigned char* lds, const Gemm g, const Sched& S, const Epi& E, const int wave_in) {
;     ...
;             PG8_WAIT_V(8); PG8_WAIT_L(0); PG8_BAR; PG8_MMA(0, 0, At, B0); PG8_MMA(0, 1, At, B1); PG8_BAR; PG8_SCHED;
;             PG8_LDA(At, 0, 1); PG8_STAGE(PG8_SB(0, 0), b2, voffB); PG8_STAGE(PG8_SB(0, 1), b2 + hstepB, voffB); PG8_STAGE(PG8_SA(0, 0), a2, voffA);
;             PG8_WAIT_V(8); PG8_WAIT_L(0); PG8_BAR; PG8_MMA(1, 0, At, B0); PG8_MMA(1, 1, At, B1); PG8_BAR; PG8_SCHED;
;             PG8_LDB(B0, 1, 0); PG8_LDB(B1, 1, 1); PG8_SCHED; PG8_LDA(At, 1, 0); PG8_STAGE(PG8_SA(0, 1), a2 + hstepA, voffA);
;             PG8_WAIT_V(8); PG8_WAIT_L(0); PG8_BAR; PG8_MMA(0, 0, At, B0); PG8_MMA(0, 1, At, B1); PG8_BAR; PG8_SCHED;
	v_mfma_f32_16x16x32_bf16 v[108:111], v[44:47], v[136:139], 0
	v_mfma_f32_16x16x32_bf16 v[76:79], v[52:55], v[136:139], 0
	v_mfma_f32_16x16x32_bf16 v[68:71], v[44:47], v[152:155], 0
	v_mfma_f32_16x16x32_bf16 v[36:39], v[52:55], v[152:155], 0
	v_mfma_f32_16x16x32_bf16 v[28:31], v[44:47], v[176:179], 0
	v_mfma_f32_16x16x32_bf16 v[20:23], v[52:55], v[176:179], 0
	v_mfma_f32_16x16x32_bf16 v[12:15], v[44:47], v[216:219], 0
	v_mfma_f32_16x16x32_bf16 v[8:11], v[52:55], v[216:219], 0
	v_mfma_f32_16x16x32_bf16 v[108:111], v[48:51], v[144:147], v[108:111]
	v_mfma_f32_16x16x32_bf16 v[76:79], v[56:59], v[144:147], v[76:79]
	v_mfma_f32_16x16x32_bf16 v[68:71], v[48:51], v[160:163], v[68:71]
	v_mfma_f32_16x16x32_bf16 v[36:39], v[56:59], v[160:163], v[36:39]
	v_mfma_f32_16x16x32_bf16 v[28:31], v[48:51], v[212:215], v[28:31]
	v_mfma_f32_16x16x32_bf16 v[20:23], v[56:59], v[212:215], v[20:23]
	v_mfma_f32_16x16x32_bf16 v[12:15], v[48:51], v[220:223], v[12:15]
	v_mfma_f32_16x16x32_bf16 v[8:11], v[56:59], v[220:223], v[8:11]
	v_mfma_f32_16x16x32_bf16 v[40:43], v[60:63], v[152:155], 0
	v_mfma_f32_16x16x32_bf16 v[32:35], v[80:83], v[152:155], 0
	v_mfma_f32_16x16x32_bf16 v[24:27], v[60:63], v[176:179], 0
	v_mfma_f32_16x16x32_bf16 v[16:19], v[80:83], v[176:179], 0
	v_mfma_f32_16x16x32_bf16 v[4:7], v[60:63], v[216:219], 0
	v_mfma_f32_16x16x32_bf16 v[0:3], v[80:83], v[216:219], 0
	v_mfma_f32_16x16x32_bf16 v[44:47], v[60:63], v[136:139], 0
	v_mfma_f32_16x16x32_bf16 v[48:51], v[80:83], v[136:139], 0
	v_mfma_f32_16x16x32_bf16 v[40:43], v[64:67], v[160:163], v[40:43]
	v_mfma_f32_16x16x32_bf16 v[32:35], v[84:87], v[160:163], v[32:35]
	v_mfma_f32_16x16x32_bf16 v[24:27], v[64:67], v[212:215], v[24:27]
	v_mfma_f32_16x16x32_bf16 v[16:19], v[84:87], v[212:215], v[16:19]
	v_mfma_f32_16x16x32_bf16 v[4:7], v[64:67], v[220:223], v[4:7]
	v_mfma_f32_16x16x32_bf16 v[0:3], v[84:87], v[220:223], v[0:3]
	v_mfma_f32_16x16x32_bf16 v[44:47], v[64:67], v[144:147], v[44:47]
	v_mfma_f32_16x16x32_bf16 v[48:51], v[84:87], v[144:147], v[48:51]
	s_setprio 0
	s_barrier
	s_add_i32 s75, 0, 0x18000
	s_add_i32 s76, 0, 0x1c000
	v_add_u32_e32 v64, s75, v195
	v_add_u32_e32 v72, s76, v195
	ds_read_b128 v[52:55], v64
	ds_read_b128 v[56:59], v64 offset:1024
	ds_read_b128 v[60:63], v64 offset:2048
	ds_read_b128 v[64:67], v64 offset:3072
	ds_read_b128 v[80:83], v72
	ds_read_b128 v[84:87], v72 offset:1024
	ds_read_b128 v[176:179], v72 offset:2048
	ds_read_b128 v[212:215], v72 offset:3072
	s_add_u32 s50, s50, 0x80000
	s_addc_u32 s51, s51, 0
	s_mov_b32 m0, s59
	v_lshl_add_u64 v[152:153], s[50:51], 0, v[180:181]
	ds_read_b128 v[72:75], v199 offset:32768
	ds_read_b128 v[104:107], v199 offset:33792
	ds_read_b128 v[136:139], v199 offset:34816
	ds_read_b128 v[144:147], v199 offset:35840
	ds_read_b128 v[216:219], v199 offset:36864
	ds_read_b128 v[220:223], v199 offset:37888
	ds_read_b128 v[224:227], v199 offset:38912
	ds_read_b128 v[228:231], v199 offset:39936
	global_load_lds_dwordx4 v[152:153], off
	v_lshl_add_u64 v[152:153], s[50:51], 0, v[184:185]
	s_mov_b32 m0, s60
	s_nop 0
	global_load_lds_dwordx4 v[152:153], off
	s_waitcnt vmcnt(8)
	s_waitcnt lgkmcnt(0)
	s_setprio 1
	s_barrier
	v_mfma_f32_16x16x32_bf16 v[152:155], v[52:55], v[72:75], v[172:175]
	v_mfma_f32_16x16x32_bf16 v[172:175], v[56:59], v[104:107], v[152:155]
	v_mfma_f32_16x16x32_bf16 v[152:155], v[60:63], v[72:75], v[164:167]
	v_mfma_f32_16x16x32_bf16 v[164:167], v[64:67], v[104:107], v[152:155]
	v_mfma_f32_16x16x32_bf16 v[152:155], v[52:55], v[136:139], v[156:159]
	v_mfma_f32_16x16x32_bf16 v[148:151], v[60:63], v[136:139], v[148:151]
	v_mfma_f32_16x16x32_bf16 v[140:143], v[52:55], v[216:219], v[140:143]
	v_mfma_f32_16x16x32_bf16 v[132:135], v[60:63], v[216:219], v[132:135]
	v_mfma_f32_16x16x32_bf16 v[124:127], v[52:55], v[224:227], v[124:127]
	v_mfma_f32_16x16x32_bf16 v[120:123], v[60:63], v[224:227], v[120:123]
	v_mfma_f32_16x16x32_bf16 v[156:159], v[56:59], v[144:147], v[152:155]
	v_mfma_f32_16x16x32_bf16 v[148:151], v[64:67], v[144:147], v[148:151]
	v_mfma_f32_16x16x32_bf16 v[140:143], v[56:59], v[220:223], v[140:143]
	v_mfma_f32_16x16x32_bf16 v[132:135], v[64:67], v[220:223], v[132:135]
	v_mfma_f32_16x16x32_bf16 v[124:127], v[56:59], v[228:231], v[124:127]
	v_mfma_f32_16x16x32_bf16 v[120:123], v[64:67], v[228:231], v[120:123]
	v_mfma_f32_16x16x32_bf16 v[152:155], v[80:83], v[72:75], v[168:171]
	v_mfma_f32_16x16x32_bf16 v[72:75], v[176:179], v[72:75], v[88:91]
	v_mfma_f32_16x16x32_bf16 v[160:163], v[212:215], v[104:107], v[72:75]
	v_mfma_f32_16x16x32_bf16 v[72:75], v[80:83], v[136:139], v[92:95]
	v_mfma_f32_16x16x32_bf16 v[168:171], v[84:87], v[104:107], v[152:155]
	v_mfma_f32_16x16x32_bf16 v[152:155], v[84:87], v[144:147], v[72:75]
	v_mfma_f32_16x16x32_bf16 v[72:75], v[176:179], v[136:139], v[96:99]
	v_mfma_f32_16x16x32_bf16 v[144:147], v[212:215], v[144:147], v[72:75]
	v_mfma_f32_16x16x32_bf16 v[72:75], v[80:83], v[216:219], v[100:103]
	v_mfma_f32_16x16x32_bf16 v[136:139], v[84:87], v[220:223], v[72:75]
	v_mfma_f32_16x16x32_bf16 v[72:75], v[176:179], v[216:219], v[128:131]
	v_mfma_f32_16x16x32_bf16 v[128:131], v[212:215], v[220:223], v[72:75]
	v_mfma_f32_16x16x32_bf16 v[72:75], v[80:83], v[224:227], v[116:119]
	v_mfma_f32_16x16x32_bf16 v[116:119], v[84:87], v[228:231], v[72:75]
	v_mfma_f32_16x16x32_bf16 v[72:75], v[176:179], v[224:227], v[112:115]
	v_mfma_f32_16x16x32_bf16 v[112:115], v[212:215], v[228:231], v[72:75]
	s_setprio 0
	s_barrier
; #define PG8_STAGE(bufoff, gbase, voff) do { _Pragma("unroll") for (int _i = 0; _i < 2; ++_i) \
;         __builtin_amdgcn_global_load_lds((const unsigned*)((const char*)(gbase) + (voff)[_i]), (PG8_LAS unsigned*)(lds + (bufoff) + ldsw + _i * 8192), 16, 0, 0); } while (0)
; #define PG8_LDA(dst, b, h) do { _Pragma("unroll") for (int m = 0; m < 4; ++m) _Pragma("unroll") for (int k = 0; k < 2; ++k) dst[m][k] = *(const PG8_LAS bf16x8*)(lds + PG8_SA(b, h) + aoff + m * 2048 + k * 1024); } while (0)
; #define PG8_LDB(dst, b, h) do { _Pragma("unroll") for (int n = 0; n < 2; ++n) _Pragma("unroll") for (int k = 0; k < 2; ++k) dst[n][k] = *(const PG8_LAS bf16x8*)(lds + PG8_SB(b, h) + boff + n * 2048 + k * 1024); } while (0)
; #define PG8_MMA(ai, bj, At, Bt) do { __builtin_amdgcn_s_setprio(1); _Pragma("unroll") for (int m = 0; m < 4; ++m) _Pragma("unroll") for (int n = 0; n < 2; ++n) _Pragma("unroll") for (int k = 0; k < 2; ++k) \
;         acc[ai][bj][m][n] = __builtin_amdgcn_mfma_f32_16x16x32_bf16(Bt[n][k], At[m][k], acc[ai][bj][m][n], 0, 0, 0); __builtin_amdgcn_s_setprio(0); } while (0)
; #define PG8_WAIT_V(n) asm volatile("s_waitcnt vmcnt(" #n ")" ::: "memory")
; #define PG8_WAIT_L(n) asm volatile("s_waitcnt lgkmcnt(" #n ")" ::: "memory")
; #define PG8_BAR __builtin_amdgcn_s_barrier()
; template <class Epi, class Sched, bool ALIGN_EPI = false, bool SP2 = false>
; __device__ __forceinline__ void gemm_phase(PG8_LAS unsigned char* lds, const Gemm g, const Sched& S, const Epi& E, const int wave_in) {
;     ...
;         for (int t = 0; t < nt; t += 2) {
;             const bool last = (t == nt - 2);
;             const char* a1 = cA + (size_t)(t + 1) * kstep;
;             const char* a2 = last ? nA : cA + (size_t)(t + 2) * kstep; const char* b2 = last ? nB : cB + (size_t)(t + 2) * kstep;
;             const char* a3 = a2 + kstep; const char* b3 = b2 + kstep;
;             if (last && has_next) S.a_ready(nxt);
;             if constexpr (SP2) {
;             PG8_LDB(B0, 0, 0); PG8_LDB(B1, 0, 1); PG8_SCHED; PG8_LDA(At, 0, 0); PG8_STAGE(PG8_SA(1, 1), a1 + hstepA, voffA);
;     ...
;             PG8_LDA(At, 1, 1); PG8_STAGE(PG8_SB(1, 0), b3, voffB); PG8_STAGE(PG8_SB(1, 1), b3 + hstepB, voffB); PG8_STAGE(PG8_SA(1, 0), a3, voffA);
;             PG8_WAIT_V(8); PG8_WAIT_L(0); PG8_BAR; PG8_MMA(1, 0, At, B0); PG8_MMA(1, 1, At, B1); PG8_BAR; PG8_SCHED;
	s_add_i32 s50, s75, s56
	v_lshl_add_u64 v[104:105], v[232:233], 0, s[22:23]
	s_mov_b32 m0, s50
	s_nop 1
	ds_read_b128 v[72:75], v199 offset:49152
	ds_read_b128 v[88:91], v199 offset:50176
	ds_read_b128 v[92:95], v199 offset:51200
	ds_read_b128 v[96:99], v199 offset:52224
	ds_read_b128 v[100:103], v199 offset:53248
	ds_read_b128 v[216:219], v199 offset:54272
	ds_read_b128 v[220:223], v199 offset:55296
	ds_read_b128 v[224:227], v199 offset:56320
	global_load_lds_dwordx4 v[104:105], off
	s_add_i32 m0, s50, 0x2000
	s_add_u32 s48, s48, 0x80080
	v_lshl_add_u64 v[104:105], v[234:235], 0, s[22:23]
	s_addc_u32 s49, s49, 0
	s_add_i32 s50, s76, s56
	global_load_lds_dwordx4 v[104:105], off
	v_lshl_add_u64 v[104:105], s[48:49], 0, v[182:183]
	s_mov_b32 m0, s50
	s_nop 0
	global_load_lds_dwordx4 v[104:105], off
	v_lshl_add_u64 v[104:105], s[48:49], 0, v[186:187]
	s_add_i32 m0, s50, 0x2000
	s_nop 0
	global_load_lds_dwordx4 v[104:105], off
	v_lshl_add_u64 v[104:105], v[236:237], 0, s[22:23]
	s_mov_b32 m0, s63
	s_nop 0
	global_load_lds_dwordx4 v[104:105], off
	v_lshl_add_u64 v[104:105], v[238:239], 0, s[22:23]
	s_mov_b32 m0, s64
	s_nop 0
	global_load_lds_dwordx4 v[104:105], off
	s_waitcnt vmcnt(8)
	s_waitcnt lgkmcnt(0)
	s_setprio 1
	s_barrier
	v_mfma_f32_16x16x32_bf16 v[104:107], v[52:55], v[72:75], v[108:111]
	v_mfma_f32_16x16x32_bf16 v[76:79], v[60:63], v[72:75], v[76:79]
	v_mfma_f32_16x16x32_bf16 v[68:71], v[52:55], v[92:95], v[68:71]
	v_mfma_f32_16x16x32_bf16 v[36:39], v[60:63], v[92:95], v[36:39]
	v_mfma_f32_16x16x32_bf16 v[28:31], v[52:55], v[100:103], v[28:31]
	v_mfma_f32_16x16x32_bf16 v[20:23], v[60:63], v[100:103], v[20:23]
	v_mfma_f32_16x16x32_bf16 v[12:15], v[52:55], v[220:223], v[12:15]
	v_mfma_f32_16x16x32_bf16 v[8:11], v[60:63], v[220:223], v[8:11]
	v_mfma_f32_16x16x32_bf16 v[108:111], v[56:59], v[88:91], v[104:107]
	v_mfma_f32_16x16x32_bf16 v[76:79], v[64:67], v[88:91], v[76:79]
	v_mfma_f32_16x16x32_bf16 v[68:71], v[56:59], v[96:99], v[68:71]
	v_mfma_f32_16x16x32_bf16 v[36:39], v[64:67], v[96:99], v[36:39]
	v_mfma_f32_16x16x32_bf16 v[28:31], v[56:59], v[216:219], v[28:31]
	v_mfma_f32_16x16x32_bf16 v[20:23], v[64:67], v[216:219], v[20:23]
	v_mfma_f32_16x16x32_bf16 v[12:15], v[56:59], v[224:227], v[12:15]
	v_mfma_f32_16x16x32_bf16 v[8:11], v[64:67], v[224:227], v[8:11]
	v_mfma_f32_16x16x32_bf16 v[44:47], v[80:83], v[72:75], v[44:47]
	v_mfma_f32_16x16x32_bf16 v[104:107], v[84:87], v[88:91], v[44:47]
	v_mfma_f32_16x16x32_bf16 v[44:47], v[176:179], v[72:75], v[48:51]
	v_mfma_f32_16x16x32_bf16 v[40:43], v[80:83], v[92:95], v[40:43]
	v_mfma_f32_16x16x32_bf16 v[32:35], v[176:179], v[92:95], v[32:35]
	v_mfma_f32_16x16x32_bf16 v[24:27], v[80:83], v[100:103], v[24:27]
	v_mfma_f32_16x16x32_bf16 v[16:19], v[176:179], v[100:103], v[16:19]
	v_mfma_f32_16x16x32_bf16 v[4:7], v[80:83], v[220:223], v[4:7]
	v_mfma_f32_16x16x32_bf16 v[0:3], v[176:179], v[220:223], v[0:3]
	v_mfma_f32_16x16x32_bf16 v[72:75], v[212:215], v[88:91], v[44:47]
	v_mfma_f32_16x16x32_bf16 v[40:43], v[84:87], v[96:99], v[40:43]
	v_mfma_f32_16x16x32_bf16 v[32:35], v[212:215], v[96:99], v[32:35]
	v_mfma_f32_16x16x32_bf16 v[24:27], v[84:87], v[216:219], v[24:27]
	v_mfma_f32_16x16x32_bf16 v[16:19], v[212:215], v[216:219], v[16:19]
	v_mfma_f32_16x16x32_bf16 v[4:7], v[84:87], v[224:227], v[4:7]
	v_mfma_f32_16x16x32_bf16 v[0:3], v[212:215], v[224:227], v[0:3]
	s_setprio 0
	s_barrier
	s_add_i32 s74, s74, 2
	s_add_u32 s46, s46, 0x100
	s_addc_u32 s47, s47, 0
	s_add_u32 s72, s72, 0x100
	s_addc_u32 s73, s73, 0
	s_cmp_gt_u32 s74, 29
	s_cbranch_scc0 .LBB0_479
	s_branch .Lkx_6
.LBB0_479:
	ds_read_b128 v[44:47], v189
	ds_read_b128 v[48:51], v189 offset:1024
	ds_read_b128 v[52:55], v189 offset:2048
	ds_read_b128 v[56:59], v189 offset:3072
	ds_read_b128 v[60:63], v197
	ds_read_b128 v[64:67], v197 offset:1024
	ds_read_b128 v[80:83], v197 offset:2048
	ds_read_b128 v[84:87], v197 offset:3072
	s_add_u32 s48, s46, 0xfff80080
	s_addc_u32 s49, s47, -1
	s_cmp_eq_u32 s74, 28
	s_cselect_b32 s51, s1, s49
	s_cselect_b32 s50, s13, s48
	s_cselect_b32 s49, s39, s73
	s_cselect_b32 s48, s41, s72
	v_lshl_add_u64 v[224:225], s[46:47], 0, v[206:207]
	s_add_i32 m0, s57, 0xc000
	ds_read_b128 v[88:91], v199
	ds_read_b128 v[92:95], v199 offset:1024
	ds_read_b128 v[96:99], v199 offset:2048
	ds_read_b128 v[100:103], v199 offset:3072
	ds_read_b128 v[176:179], v199 offset:4096
	ds_read_b128 v[212:215], v199 offset:5120
	ds_read_b128 v[216:219], v199 offset:6144
	ds_read_b128 v[220:223], v199 offset:7168
	global_load_lds_dwordx4 v[224:225], off
	v_lshl_add_u64 v[224:225], s[46:47], 0, v[208:209]
	s_add_i32 m0, s57, 0xe000
	s_nop 0
	global_load_lds_dwordx4 v[224:225], off
	s_waitcnt vmcnt(8)
	s_waitcnt lgkmcnt(0)
	s_setprio 1
	s_barrier
; #define PG8_STAGE(bufoff, gbase, voff) do { _Pragma("unroll") for (int _i = 0; _i < 2; ++_i) \
;         __builtin_amdgcn_global_load_lds((const unsigned*)((const char*)(gbase) + (voff)[_i]), (PG8_LAS unsigned*)(lds + (bufoff) + ldsw + _i * 8192), 16, 0, 0); } while (0)
; #define PG8_LDA(dst, b, h) do { _Pragma("unroll") for (int m = 0; m < 4; ++m) _Pragma("unroll") for (int k = 0; k < 2; ++k) dst[m][k] = *(const PG8_LAS bf16x8*)(lds + PG8_SA(b, h) + aoff + m * 2048 + k * 1024); } while (0)
; #define PG8_LDB(dst, b, h) do { _Pragma("unroll") for (int n = 0; n < 2; ++n) _Pragma("unroll") for (int k = 0; k < 2; ++k) dst[n][k] = *(const PG8_LAS bf16x8*)(lds + PG8_SB(b, h) + boff + n * 2048 + k * 1024); } while (0)
; #define PG8_MMA(ai, bj, At, Bt) do { __builtin_amdgcn_s_setprio(1); _Pragma("unroll") for (int m = 0; m < 4; ++m) _Pragma("unroll") for (int n = 0; n < 2; ++n) _Pragma("unroll") for (int k = 0; k < 2; ++k) \
;         acc[ai][bj][m][n] = __builtin_amdgcn_mfma_f32_16x16x32_bf16(Bt[n][k], At[m][k], acc[ai][bj][m][n], 0, 0, 0); __builtin_amdgcn_s_setprio(0); } while (0)
; #define PG8_BAR __builtin_amdgcn_s_barrier()
; template <class Epi, class Sched, bool ALIGN_EPI = false, bool SP2 = false>
; __device__ __forceinline__ void gemm_phase(PG8_LAS unsigned char* lds, const Gemm g, const Sched& S, const Epi& E, const int wave_in) {
;     ...
;             PG8_LDB(B0, 0, 0); PG8_LDB(B1, 0, 1); PG8_SCHED; PG8_LDA(At, 0, 0); PG8_STAGE(PG8_SA(1, 1), a1 + hstepA, voffA);
;             PG8_WAIT_V(8); PG8_WAIT_L(0); PG8_BAR; PG8_MMA(0, 0, At, B0); PG8_MMA(0, 1, At, B1); PG8_BAR; PG8_SCHED;
;             PG8_LDA(At, 0, 1); PG8_STAGE(PG8_SB(0, 0), b2, voffB); PG8_STAGE(PG8_SB(0, 1), b2 + hstepB, voffB); PG8_STAGE(PG8_SA(0, 0), a2, voffA);
;             PG8_WAIT_V(8); PG8_WAIT_L(0); PG8_BAR; PG8_MMA(1, 0, At, B0); PG8_MMA(1, 1, At, B1); PG8_BAR; PG8_SCHED;
;             PG8_LDB(B0, 1, 0); PG8_LDB(B1, 1, 1); PG8_SCHED; PG8_LDA(At, 1, 0); PG8_STAGE(PG8_SA(0, 1), a2 + hstepA, voffA);
;             PG8_WAIT_V(8); PG8_WAIT_L(0); PG8_BAR; PG8_MMA(0, 0, At, B0); PG8_MMA(0, 1, At, B1); PG8_BAR; PG8_SCHED;
;             PG8_LDA(At, 1, 1); PG8_STAGE(PG8_SB(1, 0), b3, voffB); PG8_STAGE(PG8_SB(1, 1), b3 + hstepB, voffB); PG8_STAGE(PG8_SA(1, 0), a3, voffA);
;             PG8_WAIT_V(8); PG8_WAIT_L(0); PG8_BAR; PG8_MMA(1, 0, At, B0); PG8_MMA(1, 1, At, B1); PG8_BAR; PG8_SCHED;
	v_mfma_f32_16x16x32_bf16 v[172:175], v[44:47], v[88:91], v[172:175]
	v_mfma_f32_16x16x32_bf16 v[164:167], v[52:55], v[88:91], v[164:167]
	v_mfma_f32_16x16x32_bf16 v[156:159], v[44:47], v[96:99], v[156:159]
	v_mfma_f32_16x16x32_bf16 v[148:151], v[52:55], v[96:99], v[148:151]
	v_mfma_f32_16x16x32_bf16 v[140:143], v[44:47], v[176:179], v[140:143]
	v_mfma_f32_16x16x32_bf16 v[132:135], v[52:55], v[176:179], v[132:135]
	v_mfma_f32_16x16x32_bf16 v[124:127], v[44:47], v[216:219], v[124:127]
	v_mfma_f32_16x16x32_bf16 v[120:123], v[52:55], v[216:219], v[120:123]
	v_mfma_f32_16x16x32_bf16 v[172:175], v[48:51], v[92:95], v[172:175]
	v_mfma_f32_16x16x32_bf16 v[164:167], v[56:59], v[92:95], v[164:167]
	v_mfma_f32_16x16x32_bf16 v[156:159], v[48:51], v[100:103], v[156:159]
	v_mfma_f32_16x16x32_bf16 v[148:151], v[56:59], v[100:103], v[148:151]
	v_mfma_f32_16x16x32_bf16 v[140:143], v[48:51], v[212:215], v[140:143]
	v_mfma_f32_16x16x32_bf16 v[132:135], v[56:59], v[212:215], v[132:135]
	v_mfma_f32_16x16x32_bf16 v[124:127], v[48:51], v[220:223], v[124:127]
	v_mfma_f32_16x16x32_bf16 v[120:123], v[56:59], v[220:223], v[120:123]
	v_mfma_f32_16x16x32_bf16 v[168:171], v[60:63], v[88:91], v[168:171]
	v_mfma_f32_16x16x32_bf16 v[88:91], v[80:83], v[88:91], v[160:163]
	v_mfma_f32_16x16x32_bf16 v[168:171], v[64:67], v[92:95], v[168:171]
	v_mfma_f32_16x16x32_bf16 v[88:91], v[84:87], v[92:95], v[88:91]
	v_mfma_f32_16x16x32_bf16 v[92:95], v[60:63], v[96:99], v[152:155]
	v_mfma_f32_16x16x32_bf16 v[96:99], v[80:83], v[96:99], v[144:147]
	v_mfma_f32_16x16x32_bf16 v[128:131], v[80:83], v[176:179], v[128:131]
	v_mfma_f32_16x16x32_bf16 v[116:119], v[60:63], v[216:219], v[116:119]
	v_mfma_f32_16x16x32_bf16 v[112:115], v[80:83], v[216:219], v[112:115]
	v_mfma_f32_16x16x32_bf16 v[92:95], v[64:67], v[100:103], v[92:95]
	v_mfma_f32_16x16x32_bf16 v[96:99], v[84:87], v[100:103], v[96:99]
	v_mfma_f32_16x16x32_bf16 v[100:103], v[60:63], v[176:179], v[136:139]
	v_mfma_f32_16x16x32_bf16 v[128:131], v[84:87], v[212:215], v[128:131]
	v_mfma_f32_16x16x32_bf16 v[116:119], v[64:67], v[220:223], v[116:119]
	v_mfma_f32_16x16x32_bf16 v[112:115], v[84:87], v[220:223], v[112:115]
	v_mfma_f32_16x16x32_bf16 v[100:103], v[64:67], v[212:215], v[100:103]
	s_setprio 0
	s_barrier
	s_add_i32 s75, s68, s56
	v_lshl_add_u64 v[232:233], s[48:49], 0, v[182:183]
	s_mov_b32 m0, s75
	ds_read_b128 v[136:139], v199 offset:16384
	ds_read_b128 v[144:147], v199 offset:17408
	ds_read_b128 v[152:155], v199 offset:18432
	ds_read_b128 v[160:163], v199 offset:19456
	ds_read_b128 v[176:179], v199 offset:20480
	ds_read_b128 v[212:215], v199 offset:21504
	ds_read_b128 v[216:219], v199 offset:22528
	ds_read_b128 v[220:223], v199 offset:23552
	global_load_lds_dwordx4 v[232:233], off
	s_add_i32 m0, s75, 0x2000
	s_add_u32 s76, s48, 0x80000
	v_lshl_add_u64 v[234:235], s[48:49], 0, v[186:187]
	s_addc_u32 s77, s49, 0
	s_add_i32 s75, s69, s56
	global_load_lds_dwordx4 v[234:235], off
	v_lshl_add_u64 v[224:225], s[76:77], 0, v[182:183]
	s_mov_b32 m0, s75
	v_lshl_add_u64 v[236:237], s[50:51], 0, v[180:181]
	global_load_lds_dwordx4 v[224:225], off
	v_lshl_add_u64 v[224:225], s[76:77], 0, v[186:187]
	s_add_i32 m0, s75, 0x2000
	v_lshl_add_u64 v[238:239], s[50:51], 0, v[184:185]
	global_load_lds_dwordx4 v[224:225], off
	s_mov_b32 m0, s57
	s_nop 0
	global_load_lds_dwordx4 v[236:237], off
	s_mov_b32 m0, s58
	s_nop 0
	global_load_lds_dwordx4 v[238:239], off
	s_waitcnt vmcnt(8)
	s_waitcnt lgkmcnt(0)
	s_setprio 1
	s_barrier
	v_mfma_f32_16x16x32_bf16 v[108:111], v[44:47], v[136:139], v[108:111]
	v_mfma_f32_16x16x32_bf16 v[76:79], v[52:55], v[136:139], v[76:79]
	v_mfma_f32_16x16x32_bf16 v[68:71], v[44:47], v[152:155], v[68:71]
	v_mfma_f32_16x16x32_bf16 v[36:39], v[52:55], v[152:155], v[36:39]
	v_mfma_f32_16x16x32_bf16 v[28:31], v[44:47], v[176:179], v[28:31]
	v_mfma_f32_16x16x32_bf16 v[20:23], v[52:55], v[176:179], v[20:23]
	v_mfma_f32_16x16x32_bf16 v[12:15], v[44:47], v[216:219], v[12:15]
	v_mfma_f32_16x16x32_bf16 v[8:11], v[52:55], v[216:219], v[8:11]
	v_mfma_f32_16x16x32_bf16 v[108:111], v[48:51], v[144:147], v[108:111]
	v_mfma_f32_16x16x32_bf16 v[76:79], v[56:59], v[144:147], v[76:79]
	v_mfma_f32_16x16x32_bf16 v[68:71], v[48:51], v[160:163], v[68:71]
	v_mfma_f32_16x16x32_bf16 v[36:39], v[56:59], v[160:163], v[36:39]
	v_mfma_f32_16x16x32_bf16 v[28:31], v[48:51], v[212:215], v[28:31]
	v_mfma_f32_16x16x32_bf16 v[20:23], v[56:59], v[212:215], v[20:23]
	v_mfma_f32_16x16x32_bf16 v[12:15], v[48:51], v[220:223], v[12:15]
	v_mfma_f32_16x16x32_bf16 v[8:11], v[56:59], v[220:223], v[8:11]
	v_mfma_f32_16x16x32_bf16 v[40:43], v[60:63], v[152:155], v[40:43]
	v_mfma_f32_16x16x32_bf16 v[32:35], v[80:83], v[152:155], v[32:35]
	v_mfma_f32_16x16x32_bf16 v[24:27], v[60:63], v[176:179], v[24:27]
	v_mfma_f32_16x16x32_bf16 v[16:19], v[80:83], v[176:179], v[16:19]
	v_mfma_f32_16x16x32_bf16 v[4:7], v[60:63], v[216:219], v[4:7]
	v_mfma_f32_16x16x32_bf16 v[0:3], v[80:83], v[216:219], v[0:3]
	v_mfma_f32_16x16x32_bf16 v[44:47], v[60:63], v[136:139], v[104:107]
	v_mfma_f32_16x16x32_bf16 v[48:51], v[80:83], v[136:139], v[72:75]
	v_mfma_f32_16x16x32_bf16 v[40:43], v[64:67], v[160:163], v[40:43]
	v_mfma_f32_16x16x32_bf16 v[32:35], v[84:87], v[160:163], v[32:35]
	v_mfma_f32_16x16x32_bf16 v[24:27], v[64:67], v[212:215], v[24:27]
	v_mfma_f32_16x16x32_bf16 v[16:19], v[84:87], v[212:215], v[16:19]
	v_mfma_f32_16x16x32_bf16 v[4:7], v[64:67], v[220:223], v[4:7]
	v_mfma_f32_16x16x32_bf16 v[0:3], v[84:87], v[220:223], v[0:3]
	v_mfma_f32_16x16x32_bf16 v[44:47], v[64:67], v[144:147], v[44:47]
	v_mfma_f32_16x16x32_bf16 v[48:51], v[84:87], v[144:147], v[48:51]
	s_setprio 0
	s_barrier
; #define PG8_STAGE(bufoff, gbase, voff) do { _Pragma("unroll") for (int _i = 0; _i < 2; ++_i) \
;         __builtin_amdgcn_global_load_lds((const unsigned*)((const char*)(gbase) + (voff)[_i]), (PG8_LAS unsigned*)(lds + (bufoff) + ldsw + _i * 8192), 16, 0, 0); } while (0)
; #define PG8_LDA(dst, b, h) do { _Pragma("unroll") for (int m = 0; m < 4; ++m) _Pragma("unroll") for (int k = 0; k < 2; ++k) dst[m][k] = *(const PG8_LAS bf16x8*)(lds + PG8_SA(b, h) + aoff + m * 2048 + k * 1024); } while (0)
; #define PG8_LDB(dst, b, h) do { _Pragma("unroll") for (int n = 0; n < 2; ++n) _Pragma("unroll") for (int k = 0; k < 2; ++k) dst[n][k] = *(const PG8_LAS bf16x8*)(lds + PG8_SB(b, h) + boff + n * 2048 + k * 1024); } while (0)
; #define PG8_MMA(ai, bj, At, Bt) do { __builtin_amdgcn_s_setprio(1); _Pragma("unroll") for (int m = 0; m < 4; ++m) _Pragma("unroll") for (int n = 0; n < 2; ++n) _Pragma("unroll") for (int k = 0; k < 2; ++k) \
;         acc[ai][bj][m][n] = __builtin_amdgcn_mfma_f32_16x16x32_bf16(Bt[n][k], At[m][k], acc[ai][bj][m][n], 0, 0, 0); __builtin_amdgcn_s_setprio(0); } while (0)
; #define PG8_WAIT_V(n) asm volatile("s_waitcnt vmcnt(" #n ")" ::: "memory")
; #define PG8_WAIT_L(n) asm volatile("s_waitcnt lgkmcnt(" #n ")" ::: "memory")
; #define PG8_BAR __builtin_amdgcn_s_barrier()
; template <class Epi, class Sched, bool ALIGN_EPI = false, bool SP2 = false>
; __device__ __forceinline__ void gemm_phase(PG8_LAS unsigned char* lds, const Gemm g, const Sched& S, const Epi& E, const int wave_in) {
;     ...
;         for (int t = 0; t < nt; t += 2) {
;             const bool last = (t == nt - 2);
;             const char* a1 = cA + (size_t)(t + 1) * kstep;
;             const char* a2 = last ? nA : cA + (size_t)(t + 2) * kstep; const char* b2 = last ? nB : cB + (size_t)(t + 2) * kstep;
;             const char* a3 = a2 + kstep; const char* b3 = b2 + kstep;
;     ...
;             PG8_LDB(B0, 1, 0); PG8_LDB(B1, 1, 1); PG8_SCHED; PG8_LDA(At, 1, 0); PG8_STAGE(PG8_SA(0, 1), a2 + hstepA, voffA);
;             PG8_WAIT_V(8); PG8_WAIT_L(0); PG8_BAR; PG8_MMA(0, 0, At, B0); PG8_MMA(0, 1, At, B1); PG8_BAR; PG8_SCHED;
;             PG8_LDA(At, 1, 1); PG8_STAGE(PG8_SB(1, 0), b3, voffB); PG8_STAGE(PG8_SB(1, 1), b3 + hstepB, voffB); PG8_STAGE(PG8_SA(1, 0), a3, voffA);
;             PG8_WAIT_V(8); PG8_WAIT_L(0); PG8_BAR; PG8_MMA(1, 0, At, B0); PG8_MMA(1, 1, At, B1); PG8_BAR; PG8_SCHED;
	s_add_i32 s75, 0, 0x18000
	s_add_i32 s76, 0, 0x1c000
	v_add_u32_e32 v64, s75, v195
	v_add_u32_e32 v72, s76, v195
	ds_read_b128 v[52:55], v64
	ds_read_b128 v[56:59], v64 offset:1024
	ds_read_b128 v[60:63], v64 offset:2048
	ds_read_b128 v[64:67], v64 offset:3072
	ds_read_b128 v[80:83], v72
	ds_read_b128 v[84:87], v72 offset:1024
	ds_read_b128 v[176:179], v72 offset:2048
	ds_read_b128 v[212:215], v72 offset:3072
	s_add_u32 s50, s50, 0x80000
	s_addc_u32 s51, s51, 0
	s_mov_b32 m0, s59
	v_lshl_add_u64 v[152:153], s[50:51], 0, v[180:181]
	ds_read_b128 v[72:75], v199 offset:32768
	ds_read_b128 v[104:107], v199 offset:33792
	ds_read_b128 v[136:139], v199 offset:34816
	ds_read_b128 v[144:147], v199 offset:35840
	ds_read_b128 v[216:219], v199 offset:36864
	ds_read_b128 v[220:223], v199 offset:37888
	ds_read_b128 v[224:227], v199 offset:38912
	ds_read_b128 v[228:231], v199 offset:39936
	global_load_lds_dwordx4 v[152:153], off
	v_lshl_add_u64 v[152:153], s[50:51], 0, v[184:185]
	s_mov_b32 m0, s60
	s_nop 0
	global_load_lds_dwordx4 v[152:153], off
	s_waitcnt vmcnt(8)
	s_waitcnt lgkmcnt(0)
	s_setprio 1
	s_barrier
	v_mfma_f32_16x16x32_bf16 v[152:155], v[52:55], v[72:75], v[172:175]
	v_mfma_f32_16x16x32_bf16 v[172:175], v[56:59], v[104:107], v[152:155]
	v_mfma_f32_16x16x32_bf16 v[152:155], v[60:63], v[72:75], v[164:167]
	v_mfma_f32_16x16x32_bf16 v[164:167], v[64:67], v[104:107], v[152:155]
	v_mfma_f32_16x16x32_bf16 v[152:155], v[52:55], v[136:139], v[156:159]
	v_mfma_f32_16x16x32_bf16 v[148:151], v[60:63], v[136:139], v[148:151]
	v_mfma_f32_16x16x32_bf16 v[140:143], v[52:55], v[216:219], v[140:143]
	v_mfma_f32_16x16x32_bf16 v[132:135], v[60:63], v[216:219], v[132:135]
	v_mfma_f32_16x16x32_bf16 v[124:127], v[52:55], v[224:227], v[124:127]
	v_mfma_f32_16x16x32_bf16 v[120:123], v[60:63], v[224:227], v[120:123]
	v_mfma_f32_16x16x32_bf16 v[156:159], v[56:59], v[144:147], v[152:155]
	v_mfma_f32_16x16x32_bf16 v[148:151], v[64:67], v[144:147], v[148:151]
	v_mfma_f32_16x16x32_bf16 v[140:143], v[56:59], v[220:223], v[140:143]
	v_mfma_f32_16x16x32_bf16 v[132:135], v[64:67], v[220:223], v[132:135]
	v_mfma_f32_16x16x32_bf16 v[124:127], v[56:59], v[228:231], v[124:127]
	v_mfma_f32_16x16x32_bf16 v[120:123], v[64:67], v[228:231], v[120:123]
	v_mfma_f32_16x16x32_bf16 v[152:155], v[80:83], v[72:75], v[168:171]
	v_mfma_f32_16x16x32_bf16 v[72:75], v[176:179], v[72:75], v[88:91]
	v_mfma_f32_16x16x32_bf16 v[160:163], v[212:215], v[104:107], v[72:75]
	v_mfma_f32_16x16x32_bf16 v[72:75], v[80:83], v[136:139], v[92:95]
	v_mfma_f32_16x16x32_bf16 v[168:171], v[84:87], v[104:107], v[152:155]
	v_mfma_f32_16x16x32_bf16 v[152:155], v[84:87], v[144:147], v[72:75]
	v_mfma_f32_16x16x32_bf16 v[72:75], v[176:179], v[136:139], v[96:99]
	v_mfma_f32_16x16x32_bf16 v[144:147], v[212:215], v[144:147], v[72:75]
	v_mfma_f32_16x16x32_bf16 v[72:75], v[80:83], v[216:219], v[100:103]
	v_mfma_f32_16x16x32_bf16 v[136:139], v[84:87], v[220:223], v[72:75]
	v_mfma_f32_16x16x32_bf16 v[72:75], v[176:179], v[216:219], v[128:131]
	v_mfma_f32_16x16x32_bf16 v[128:131], v[212:215], v[220:223], v[72:75]
	v_mfma_f32_16x16x32_bf16 v[72:75], v[80:83], v[224:227], v[116:119]
	v_mfma_f32_16x16x32_bf16 v[116:119], v[84:87], v[228:231], v[72:75]
	v_mfma_f32_16x16x32_bf16 v[72:75], v[176:179], v[224:227], v[112:115]
	v_mfma_f32_16x16x32_bf16 v[112:115], v[212:215], v[228:231], v[72:75]
	s_setprio 0
	s_barrier
	s_add_i32 s50, s75, s56
	v_lshl_add_u64 v[104:105], v[232:233], 0, s[22:23]
	s_mov_b32 m0, s50
	s_nop 1
	ds_read_b128 v[72:75], v199 offset:49152
	ds_read_b128 v[88:91], v199 offset:50176
	ds_read_b128 v[92:95], v199 offset:51200
	ds_read_b128 v[96:99], v199 offset:52224
	ds_read_b128 v[100:103], v199 offset:53248
	ds_read_b128 v[216:219], v199 offset:54272
	ds_read_b128 v[220:223], v199 offset:55296
	ds_read_b128 v[224:227], v199 offset:56320
	global_load_lds_dwordx4 v[104:105], off
	s_add_i32 m0, s50, 0x2000
	s_add_u32 s48, s48, 0x80080
	v_lshl_add_u64 v[104:105], v[234:235], 0, s[22:23]
	s_addc_u32 s49, s49, 0
	s_add_i32 s50, s76, s56
	global_load_lds_dwordx4 v[104:105], off
	v_lshl_add_u64 v[104:105], s[48:49], 0, v[182:183]
	s_mov_b32 m0, s50
	s_nop 0
	global_load_lds_dwordx4 v[104:105], off
	v_lshl_add_u64 v[104:105], s[48:49], 0, v[186:187]
	s_add_i32 m0, s50, 0x2000
	s_nop 0
	global_load_lds_dwordx4 v[104:105], off
	v_lshl_add_u64 v[104:105], v[236:237], 0, s[22:23]
	s_mov_b32 m0, s63
	s_nop 0
	global_load_lds_dwordx4 v[104:105], off
	v_lshl_add_u64 v[104:105], v[238:239], 0, s[22:23]
	s_mov_b32 m0, s64
	s_nop 0
	global_load_lds_dwordx4 v[104:105], off
	s_waitcnt vmcnt(8)
	s_waitcnt lgkmcnt(0)
	s_setprio 1
	s_barrier
	v_mfma_f32_16x16x32_bf16 v[104:107], v[52:55], v[72:75], v[108:111]
	v_mfma_f32_16x16x32_bf16 v[76:79], v[60:63], v[72:75], v[76:79]
	v_mfma_f32_16x16x32_bf16 v[68:71], v[52:55], v[92:95], v[68:71]
	v_mfma_f32_16x16x32_bf16 v[36:39], v[60:63], v[92:95], v[36:39]
	v_mfma_f32_16x16x32_bf16 v[28:31], v[52:55], v[100:103], v[28:31]
	v_mfma_f32_16x16x32_bf16 v[20:23], v[60:63], v[100:103], v[20:23]
	v_mfma_f32_16x16x32_bf16 v[12:15], v[52:55], v[220:223], v[12:15]
	v_mfma_f32_16x16x32_bf16 v[8:11], v[60:63], v[220:223], v[8:11]
	v_mfma_f32_16x16x32_bf16 v[108:111], v[56:59], v[88:91], v[104:107]
	v_mfma_f32_16x16x32_bf16 v[76:79], v[64:67], v[88:91], v[76:79]
	v_mfma_f32_16x16x32_bf16 v[68:71], v[56:59], v[96:99], v[68:71]
	v_mfma_f32_16x16x32_bf16 v[36:39], v[64:67], v[96:99], v[36:39]
	v_mfma_f32_16x16x32_bf16 v[28:31], v[56:59], v[216:219], v[28:31]
	v_mfma_f32_16x16x32_bf16 v[20:23], v[64:67], v[216:219], v[20:23]
	v_mfma_f32_16x16x32_bf16 v[12:15], v[56:59], v[224:227], v[12:15]
	v_mfma_f32_16x16x32_bf16 v[8:11], v[64:67], v[224:227], v[8:11]
	v_mfma_f32_16x16x32_bf16 v[44:47], v[80:83], v[72:75], v[44:47]
	v_mfma_f32_16x16x32_bf16 v[104:107], v[84:87], v[88:91], v[44:47]
	v_mfma_f32_16x16x32_bf16 v[44:47], v[176:179], v[72:75], v[48:51]
	v_mfma_f32_16x16x32_bf16 v[40:43], v[80:83], v[92:95], v[40:43]
	v_mfma_f32_16x16x32_bf16 v[32:35], v[176:179], v[92:95], v[32:35]
	v_mfma_f32_16x16x32_bf16 v[24:27], v[80:83], v[100:103], v[24:27]
	v_mfma_f32_16x16x32_bf16 v[16:19], v[176:179], v[100:103], v[16:19]
	v_mfma_f32_16x16x32_bf16 v[4:7], v[80:83], v[220:223], v[4:7]
	v_mfma_f32_16x16x32_bf16 v[0:3], v[176:179], v[220:223], v[0:3]
	v_mfma_f32_16x16x32_bf16 v[72:75], v[212:215], v[88:91], v[44:47]
	v_mfma_f32_16x16x32_bf16 v[40:43], v[84:87], v[96:99], v[40:43]
	v_mfma_f32_16x16x32_bf16 v[32:35], v[212:215], v[96:99], v[32:35]
	v_mfma_f32_16x16x32_bf16 v[24:27], v[84:87], v[216:219], v[24:27]
	v_mfma_f32_16x16x32_bf16 v[16:19], v[212:215], v[216:219], v[16:19]
	v_mfma_f32_16x16x32_bf16 v[4:7], v[84:87], v[224:227], v[4:7]
	v_mfma_f32_16x16x32_bf16 v[0:3], v[212:215], v[224:227], v[0:3]
	s_setprio 0
	s_barrier
	s_add_i32 s74, s74, 2
	s_add_u32 s46, s46, 0x100
	s_addc_u32 s47, s47, 0
	s_add_u32 s72, s72, 0x100
	s_addc_u32 s73, s73, 0
	s_cmp_gt_u32 s74, 29
	s_cbranch_scc0 .LBB0_479

;     __host__ __device__ bool next(int i, Unit& u) const { const bool ok = StaticOrder::next(i, u); u.pm = 0; u.pn = 0; return ok; }
; #define PG8_STAGE(bufoff, gbase, voff) do { _Pragma("unroll") for (int _i = 0; _i < 2; ++_i) \
;         __builtin_amdgcn_global_load_lds((const unsigned*)((const char*)(gbase) + (voff)[_i]), (PG8_LAS unsigned*)(lds + (bufoff) + ldsw + _i * 8192), 16, 0, 0); } while (0)
; #define PG8_BAR __builtin_amdgcn_s_barrier()
; template <class Epi, class Sched, bool ALIGN_EPI = false, bool SP2 = false>
; __device__ __forceinline__ void gemm_phase(PG8_LAS unsigned char* lds, const Gemm g, const Sched& S, const Epi& E, const int wave_in) {
;     ...
;     for (;;) {
;         const bool has_next = S.next(ui + 1, nxt);
;         const char* nA = has_next ? (const char*)g.A + (size_t)nxt.pm * tstepA : cA; const char* nB = has_next ? (const char*)g.Bt + (size_t)nxt.pn * tstepB : cB;
;         for (int t = 0; t < nt; t += 2) {
;             const bool last = (t == nt - 2);
;             const char* a1 = cA + (size_t)(t + 1) * kstep;
;             const char* a2 = last ? nA : cA + (size_t)(t + 2) * kstep; const char* b2 = last ? nB : cB + (size_t)(t + 2) * kstep;
;             const char* a3 = a2 + kstep; const char* b3 = b2 + kstep;
;             if (last && has_next) S.a_ready(nxt);
;             if constexpr (SP2) {
;             PG8_LDB(B0, 0, 0); PG8_LDB(B1, 0, 1); PG8_SCHED; PG8_LDA(At, 0, 0); PG8_STAGE(PG8_SA(1, 1), a1 + hstepA, voffA);
;             PG8_WAIT_V(8); PG8_WAIT_L(0); PG8_BAR; PG8_MMA(0, 0, At, B0); PG8_MMA(0, 1, At, B1); PG8_BAR; PG8_SCHED;
;             PG8_LDA(At, 0, 1); PG8_STAGE(PG8_SB(0, 0), b2, voffB); PG8_STAGE(PG8_SB(0, 1), b2 + hstepB, voffB); PG8_STAGE(PG8_SA(0, 0), a2, voffA);
;             PG8_WAIT_V(8); PG8_WAIT_L(0); PG8_BAR; PG8_MMA(1, 0, At, B0); PG8_MMA(1, 1, At, B1); PG8_BAR; PG8_SCHED;
;             PG8_LDB(B0, 1, 0); PG8_LDB(B1, 1, 1); PG8_SCHED; PG8_LDA(At, 1, 0); PG8_STAGE(PG8_SA(0, 1), a2 + hstepA, voffA);
;             PG8_WAIT_V(8); PG8_WAIT_L(0); PG8_BAR; PG8_MMA(0, 0, At, B0); PG8_MMA(0, 1, At, B1); PG8_BAR; PG8_SCHED;
;             PG8_LDA(At, 1, 1); PG8_STAGE(PG8_SB(1, 0), b3, voffB); PG8_STAGE(PG8_SB(1, 1), b3 + hstepB, voffB); PG8_STAGE(PG8_SA(1, 0), a3, voffA);
;             PG8_WAIT_V(8); PG8_WAIT_L(0); PG8_BAR; PG8_MMA(1, 0, At, B0); PG8_MMA(1, 1, At, B1); PG8_BAR; PG8_SCHED;
.LBB0_634:
	s_add_u32 s17, s20, 0x100
	v_mov_b32_e32 v0, 0
	s_addc_u32 s52, s21, 0
	s_mov_b32 s53, -2
	ds_read_b128 v[64:67], v230
	ds_read_b128 v[68:71], v230 offset:1024
	ds_read_b128 v[72:75], v230 offset:2048
	ds_read_b128 v[76:79], v230 offset:3072
	ds_read_b128 v[144:147], v231
	ds_read_b128 v[148:151], v231 offset:1024
	ds_read_b128 v[170:173], v231 offset:2048
	ds_read_b128 v[174:177], v231 offset:3072
	s_add_u32 s20, s18, 0x100
	s_addc_u32 s21, s19, 0
	s_cmpk_eq_i32 s53, 0x52
	s_cselect_b32 s25, s5, s21
	s_cselect_b32 s24, s4, s20
	s_cselect_b32 s23, s15, s52
	s_cselect_b32 s22, s14, s17
	v_lshl_add_u64 v[210:211], s[18:19], 0, v[162:163]
	s_add_i32 m0, s35, 0xc000
	ds_read_b128 v[178:181], v232
	ds_read_b128 v[182:185], v232 offset:1024
	ds_read_b128 v[186:189], v232 offset:2048
	ds_read_b128 v[190:193], v232 offset:3072
	ds_read_b128 v[194:197], v232 offset:4096
	ds_read_b128 v[198:201], v232 offset:5120
	ds_read_b128 v[202:205], v232 offset:6144
	ds_read_b128 v[206:209], v232 offset:7168
	global_load_lds_dwordx4 v[210:211], off
	v_lshl_add_u64 v[210:211], s[18:19], 0, v[164:165]
	s_add_i32 m0, s35, 0xe000
	s_nop 0
	global_load_lds_dwordx4 v[210:211], off
	s_waitcnt vmcnt(8)
	s_waitcnt lgkmcnt(0)
	s_setprio 1
	s_barrier
	v_mfma_f32_16x16x32_bf16 v[140:143], v[64:67], v[178:181], 0
	v_mfma_f32_16x16x32_bf16 v[136:139], v[72:75], v[178:181], 0
	v_mfma_f32_16x16x32_bf16 v[128:131], v[64:67], v[186:189], 0
	v_mfma_f32_16x16x32_bf16 v[120:123], v[72:75], v[186:189], 0
	v_mfma_f32_16x16x32_bf16 v[116:119], v[64:67], v[194:197], 0
	v_mfma_f32_16x16x32_bf16 v[112:115], v[72:75], v[194:197], 0
	v_mfma_f32_16x16x32_bf16 v[100:103], v[64:67], v[202:205], 0
	v_mfma_f32_16x16x32_bf16 v[96:99], v[72:75], v[202:205], 0
	v_mfma_f32_16x16x32_bf16 v[140:143], v[68:71], v[182:185], v[140:143]
	v_mfma_f32_16x16x32_bf16 v[136:139], v[76:79], v[182:185], v[136:139]
	v_mfma_f32_16x16x32_bf16 v[128:131], v[68:71], v[190:193], v[128:131]
	v_mfma_f32_16x16x32_bf16 v[120:123], v[76:79], v[190:193], v[120:123]
	v_mfma_f32_16x16x32_bf16 v[116:119], v[68:71], v[198:201], v[116:119]
	v_mfma_f32_16x16x32_bf16 v[112:115], v[76:79], v[198:201], v[112:115]
	v_mfma_f32_16x16x32_bf16 v[100:103], v[68:71], v[206:209], v[100:103]
	v_mfma_f32_16x16x32_bf16 v[96:99], v[76:79], v[206:209], v[96:99]
	v_mfma_f32_16x16x32_bf16 v[132:135], v[144:147], v[178:181], 0
	v_mfma_f32_16x16x32_bf16 v[124:127], v[170:173], v[178:181], 0
	v_mfma_f32_16x16x32_bf16 v[108:111], v[144:147], v[186:189], 0
	v_mfma_f32_16x16x32_bf16 v[104:107], v[170:173], v[186:189], 0
	v_mfma_f32_16x16x32_bf16 v[92:95], v[144:147], v[194:197], 0
	v_mfma_f32_16x16x32_bf16 v[88:91], v[170:173], v[194:197], 0
	v_mfma_f32_16x16x32_bf16 v[84:87], v[144:147], v[202:205], 0
	v_mfma_f32_16x16x32_bf16 v[80:83], v[170:173], v[202:205], 0
	v_mfma_f32_16x16x32_bf16 v[132:135], v[148:151], v[182:185], v[132:135]
	v_mfma_f32_16x16x32_bf16 v[124:127], v[174:177], v[182:185], v[124:127]
	v_mfma_f32_16x16x32_bf16 v[108:111], v[148:151], v[190:193], v[108:111]
	v_mfma_f32_16x16x32_bf16 v[104:107], v[174:177], v[190:193], v[104:107]
	v_mfma_f32_16x16x32_bf16 v[92:95], v[148:151], v[198:201], v[92:95]
	v_mfma_f32_16x16x32_bf16 v[88:91], v[174:177], v[198:201], v[88:91]
	v_mfma_f32_16x16x32_bf16 v[84:87], v[148:151], v[206:209], v[84:87]
	v_mfma_f32_16x16x32_bf16 v[80:83], v[174:177], v[206:209], v[80:83]
	s_setprio 0
	s_barrier
	s_add_i32 s18, s45, s30
	v_lshl_add_u64 v[210:211], s[22:23], 0, v[156:157]
	s_mov_b32 m0, s18
	ds_read_b128 v[178:181], v232 offset:16384
	ds_read_b128 v[182:185], v232 offset:17408
	ds_read_b128 v[186:189], v232 offset:18432
	ds_read_b128 v[190:193], v232 offset:19456
	ds_read_b128 v[194:197], v232 offset:20480
	ds_read_b128 v[198:201], v232 offset:21504
	ds_read_b128 v[202:205], v232 offset:22528
	ds_read_b128 v[206:209], v232 offset:23552
	global_load_lds_dwordx4 v[210:211], off
	s_add_i32 m0, s18, 0x2000
	s_add_u32 s18, s22, 0x158000
	v_lshl_add_u64 v[212:213], s[22:23], 0, v[152:153]
	s_addc_u32 s19, s23, 0
	s_add_i32 s54, s46, s30
	global_load_lds_dwordx4 v[212:213], off
	v_lshl_add_u64 v[214:215], s[18:19], 0, v[156:157]
	s_mov_b32 m0, s54
	v_lshl_add_u64 v[216:217], s[24:25], 0, v[154:155]
	global_load_lds_dwordx4 v[214:215], off
	v_lshl_add_u64 v[214:215], s[18:19], 0, v[152:153]
	s_add_i32 m0, s54, 0x2000
	s_nop 0
	global_load_lds_dwordx4 v[214:215], off
	v_lshl_add_u64 v[214:215], s[24:25], 0, v[158:159]
	s_mov_b32 m0, s35
	s_nop 0
	global_load_lds_dwordx4 v[214:215], off
	s_mov_b32 m0, s36
	s_nop 0
	global_load_lds_dwordx4 v[216:217], off
	s_waitcnt vmcnt(8)
	s_waitcnt lgkmcnt(0)
	s_setprio 1
	s_barrier
; #define PG8_STAGE(bufoff, gbase, voff) do { _Pragma("unroll") for (int _i = 0; _i < 2; ++_i) \
;         __builtin_amdgcn_global_load_lds((const unsigned*)((const char*)(gbase) + (voff)[_i]), (PG8_LAS unsigned*)(lds + (bufoff) + ldsw + _i * 8192), 16, 0, 0); } while (0)
; #define PG8_LDA(dst, b, h) do { _Pragma("unroll") for (int m = 0; m < 4; ++m) _Pragma("unroll") for (int k = 0; k < 2; ++k) dst[m][k] = *(const PG8_LAS bf16x8*)(lds + PG8_SA(b, h) + aoff + m * 2048 + k * 1024); } while (0)
; #define PG8_LDB(dst, b, h) do { _Pragma("unroll") for (int n = 0; n < 2; ++n) _Pragma("unroll") for (int k = 0; k < 2; ++k) dst[n][k] = *(const PG8_LAS bf16x8*)(lds + PG8_SB(b, h) + boff + n * 2048 + k * 1024); } while (0)
; #define PG8_MMA(ai, bj, At, Bt) do { __builtin_amdgcn_s_setprio(1); _Pragma("unroll") for (int m = 0; m < 4; ++m) _Pragma("unroll") for (int n = 0; n < 2; ++n) _Pragma("unroll") for (int k = 0; k < 2; ++k) \
;         acc[ai][bj][m][n] = __builtin_amdgcn_mfma_f32_16x16x32_bf16(Bt[n][k], At[m][k], acc[ai][bj][m][n], 0, 0, 0); __builtin_amdgcn_s_setprio(0); } while (0)
; #define PG8_WAIT_V(n) asm volatile("s_waitcnt vmcnt(" #n ")" ::: "memory")
; #define PG8_WAIT_L(n) asm volatile("s_waitcnt lgkmcnt(" #n ")" ::: "memory")
; #define PG8_BAR __builtin_amdgcn_s_barrier()
; #define PG8_SCHED __builtin_amdgcn_sched_barrier(0)
; template <class Epi, class Sched, bool ALIGN_EPI = false, bool SP2 = false>
; __device__ __forceinline__ void gemm_phase(PG8_LAS unsigned char* lds, const Gemm g, const Sched& S, const Epi& E, const int wave_in) {
;     ...
;             PG8_WAIT_V(8); PG8_WAIT_L(0); PG8_BAR; PG8_MMA(0, 0, At, B0); PG8_MMA(0, 1, At, B1); PG8_BAR; PG8_SCHED;
;             PG8_LDA(At, 0, 1); PG8_STAGE(PG8_SB(0, 0), b2, voffB); PG8_STAGE(PG8_SB(0, 1), b2 + hstepB, voffB); PG8_STAGE(PG8_SA(0, 0), a2, voffA);
;             PG8_WAIT_V(8); PG8_WAIT_L(0); PG8_BAR; PG8_MMA(1, 0, At, B0); PG8_MMA(1, 1, At, B1); PG8_BAR; PG8_SCHED;
;             PG8_LDB(B0, 1, 0); PG8_LDB(B1, 1, 1); PG8_SCHED; PG8_LDA(At, 1, 0); PG8_STAGE(PG8_SA(0, 1), a2 + hstepA, voffA);
;             PG8_WAIT_V(8); PG8_WAIT_L(0); PG8_BAR; PG8_MMA(0, 0, At, B0); PG8_MMA(0, 1, At, B1); PG8_BAR; PG8_SCHED;
	v_mfma_f32_16x16x32_bf16 v[60:63], v[64:67], v[178:181], 0
	v_mfma_f32_16x16x32_bf16 v[56:59], v[72:75], v[178:181], 0
	v_mfma_f32_16x16x32_bf16 v[48:51], v[64:67], v[186:189], 0
	v_mfma_f32_16x16x32_bf16 v[40:43], v[72:75], v[186:189], 0
	v_mfma_f32_16x16x32_bf16 v[32:35], v[64:67], v[194:197], 0
	v_mfma_f32_16x16x32_bf16 v[24:27], v[72:75], v[194:197], 0
	v_mfma_f32_16x16x32_bf16 v[16:19], v[64:67], v[202:205], 0
	v_mfma_f32_16x16x32_bf16 v[8:11], v[72:75], v[202:205], 0
	v_mfma_f32_16x16x32_bf16 v[60:63], v[68:71], v[182:185], v[60:63]
	v_mfma_f32_16x16x32_bf16 v[56:59], v[76:79], v[182:185], v[56:59]
	v_mfma_f32_16x16x32_bf16 v[48:51], v[68:71], v[190:193], v[48:51]
	v_mfma_f32_16x16x32_bf16 v[40:43], v[76:79], v[190:193], v[40:43]
	v_mfma_f32_16x16x32_bf16 v[32:35], v[68:71], v[198:201], v[32:35]
	v_mfma_f32_16x16x32_bf16 v[24:27], v[76:79], v[198:201], v[24:27]
	v_mfma_f32_16x16x32_bf16 v[16:19], v[68:71], v[206:209], v[16:19]
	v_mfma_f32_16x16x32_bf16 v[8:11], v[76:79], v[206:209], v[8:11]
	v_mfma_f32_16x16x32_bf16 v[52:55], v[144:147], v[178:181], 0
	v_mfma_f32_16x16x32_bf16 v[44:47], v[170:173], v[178:181], 0
	v_mfma_f32_16x16x32_bf16 v[36:39], v[144:147], v[186:189], 0
	v_mfma_f32_16x16x32_bf16 v[28:31], v[170:173], v[186:189], 0
	v_mfma_f32_16x16x32_bf16 v[20:23], v[144:147], v[194:197], 0
	v_mfma_f32_16x16x32_bf16 v[12:15], v[170:173], v[194:197], 0
	v_mfma_f32_16x16x32_bf16 v[4:7], v[144:147], v[202:205], 0
	v_mfma_f32_16x16x32_bf16 v[0:3], v[170:173], v[202:205], 0
	v_mfma_f32_16x16x32_bf16 v[52:55], v[148:151], v[182:185], v[52:55]
	v_mfma_f32_16x16x32_bf16 v[44:47], v[174:177], v[182:185], v[44:47]
	v_mfma_f32_16x16x32_bf16 v[36:39], v[148:151], v[190:193], v[36:39]
	v_mfma_f32_16x16x32_bf16 v[28:31], v[174:177], v[190:193], v[28:31]
	v_mfma_f32_16x16x32_bf16 v[20:23], v[148:151], v[198:201], v[20:23]
	v_mfma_f32_16x16x32_bf16 v[12:15], v[174:177], v[198:201], v[12:15]
	v_mfma_f32_16x16x32_bf16 v[4:7], v[148:151], v[206:209], v[4:7]
	v_mfma_f32_16x16x32_bf16 v[0:3], v[174:177], v[206:209], v[0:3]
	s_setprio 0
	s_barrier
	s_add_i32 s54, 0, 0x18000
	s_add_i32 s55, 0, 0x1c000
	v_add_u32_e32 v76, s54, v228
	v_add_u32_e32 v174, s55, v228
	ds_read_b128 v[64:67], v76
	ds_read_b128 v[68:71], v76 offset:1024
	ds_read_b128 v[72:75], v76 offset:2048
	ds_read_b128 v[76:79], v76 offset:3072
	ds_read_b128 v[144:147], v174
	ds_read_b128 v[148:151], v174 offset:1024
	ds_read_b128 v[170:173], v174 offset:2048
	ds_read_b128 v[174:177], v174 offset:3072
	s_add_u32 s18, s24, 0x158000
	s_addc_u32 s19, s25, 0
	s_mov_b32 m0, s37
	v_lshl_add_u64 v[218:219], s[18:19], 0, v[158:159]
	ds_read_b128 v[178:181], v232 offset:32768
	ds_read_b128 v[182:185], v232 offset:33792
	ds_read_b128 v[186:189], v232 offset:34816
	ds_read_b128 v[190:193], v232 offset:35840
	ds_read_b128 v[194:197], v232 offset:36864
	ds_read_b128 v[198:201], v232 offset:37888
	ds_read_b128 v[202:205], v232 offset:38912
	ds_read_b128 v[206:209], v232 offset:39936
	global_load_lds_dwordx4 v[218:219], off
	v_lshl_add_u64 v[218:219], s[18:19], 0, v[154:155]
	s_mov_b32 m0, s38
	s_nop 0
	global_load_lds_dwordx4 v[218:219], off
	s_waitcnt vmcnt(8)
	s_waitcnt lgkmcnt(0)
	s_setprio 1
	s_barrier
	v_mfma_f32_16x16x32_bf16 v[140:143], v[64:67], v[178:181], v[140:143]
	v_mfma_f32_16x16x32_bf16 v[136:139], v[72:75], v[178:181], v[136:139]
	v_mfma_f32_16x16x32_bf16 v[128:131], v[64:67], v[186:189], v[128:131]
	v_mfma_f32_16x16x32_bf16 v[120:123], v[72:75], v[186:189], v[120:123]
	v_mfma_f32_16x16x32_bf16 v[116:119], v[64:67], v[194:197], v[116:119]
	v_mfma_f32_16x16x32_bf16 v[112:115], v[72:75], v[194:197], v[112:115]
	v_mfma_f32_16x16x32_bf16 v[100:103], v[64:67], v[202:205], v[100:103]
	v_mfma_f32_16x16x32_bf16 v[96:99], v[72:75], v[202:205], v[96:99]
	v_mfma_f32_16x16x32_bf16 v[140:143], v[68:71], v[182:185], v[140:143]
	v_mfma_f32_16x16x32_bf16 v[136:139], v[76:79], v[182:185], v[136:139]
	v_mfma_f32_16x16x32_bf16 v[128:131], v[68:71], v[190:193], v[128:131]
	v_mfma_f32_16x16x32_bf16 v[120:123], v[76:79], v[190:193], v[120:123]
	v_mfma_f32_16x16x32_bf16 v[116:119], v[68:71], v[198:201], v[116:119]
	v_mfma_f32_16x16x32_bf16 v[112:115], v[76:79], v[198:201], v[112:115]
	v_mfma_f32_16x16x32_bf16 v[100:103], v[68:71], v[206:209], v[100:103]
	v_mfma_f32_16x16x32_bf16 v[96:99], v[76:79], v[206:209], v[96:99]
	v_mfma_f32_16x16x32_bf16 v[132:135], v[144:147], v[178:181], v[132:135]
	v_mfma_f32_16x16x32_bf16 v[124:127], v[170:173], v[178:181], v[124:127]
	v_mfma_f32_16x16x32_bf16 v[108:111], v[144:147], v[186:189], v[108:111]
	v_mfma_f32_16x16x32_bf16 v[104:107], v[170:173], v[186:189], v[104:107]
	v_mfma_f32_16x16x32_bf16 v[92:95], v[144:147], v[194:197], v[92:95]
	v_mfma_f32_16x16x32_bf16 v[88:91], v[170:173], v[194:197], v[88:91]
	v_mfma_f32_16x16x32_bf16 v[84:87], v[144:147], v[202:205], v[84:87]
	v_mfma_f32_16x16x32_bf16 v[80:83], v[170:173], v[202:205], v[80:83]
	v_mfma_f32_16x16x32_bf16 v[132:135], v[148:151], v[182:185], v[132:135]
	v_mfma_f32_16x16x32_bf16 v[124:127], v[174:177], v[182:185], v[124:127]
	v_mfma_f32_16x16x32_bf16 v[108:111], v[148:151], v[190:193], v[108:111]
	v_mfma_f32_16x16x32_bf16 v[104:107], v[174:177], v[190:193], v[104:107]
	v_mfma_f32_16x16x32_bf16 v[92:95], v[148:151], v[198:201], v[92:95]
	v_mfma_f32_16x16x32_bf16 v[88:91], v[174:177], v[198:201], v[88:91]
	v_mfma_f32_16x16x32_bf16 v[84:87], v[148:151], v[206:209], v[84:87]
	v_mfma_f32_16x16x32_bf16 v[80:83], v[174:177], v[206:209], v[80:83]
	s_setprio 0
	s_barrier
; #define PG8_STAGE(bufoff, gbase, voff) do { _Pragma("unroll") for (int _i = 0; _i < 2; ++_i) \
;         __builtin_amdgcn_global_load_lds((const unsigned*)((const char*)(gbase) + (voff)[_i]), (PG8_LAS unsigned*)(lds + (bufoff) + ldsw + _i * 8192), 16, 0, 0); } while (0)
; #define PG8_LDA(dst, b, h) do { _Pragma("unroll") for (int m = 0; m < 4; ++m) _Pragma("unroll") for (int k = 0; k < 2; ++k) dst[m][k] = *(const PG8_LAS bf16x8*)(lds + PG8_SA(b, h) + aoff + m * 2048 + k * 1024); } while (0)
; #define PG8_LDB(dst, b, h) do { _Pragma("unroll") for (int n = 0; n < 2; ++n) _Pragma("unroll") for (int k = 0; k < 2; ++k) dst[n][k] = *(const PG8_LAS bf16x8*)(lds + PG8_SB(b, h) + boff + n * 2048 + k * 1024); } while (0)
; #define PG8_MMA(ai, bj, At, Bt) do { __builtin_amdgcn_s_setprio(1); _Pragma("unroll") for (int m = 0; m < 4; ++m) _Pragma("unroll") for (int n = 0; n < 2; ++n) _Pragma("unroll") for (int k = 0; k < 2; ++k) \
;         acc[ai][bj][m][n] = __builtin_amdgcn_mfma_f32_16x16x32_bf16(Bt[n][k], At[m][k], acc[ai][bj][m][n], 0, 0, 0); __builtin_amdgcn_s_setprio(0); } while (0)
; #define PG8_WAIT_V(n) asm volatile("s_waitcnt vmcnt(" #n ")" ::: "memory")
; #define PG8_WAIT_L(n) asm volatile("s_waitcnt lgkmcnt(" #n ")" ::: "memory")
; #define PG8_BAR __builtin_amdgcn_s_barrier()
; template <class Epi, class Sched, bool ALIGN_EPI = false, bool SP2 = false>
; __device__ __forceinline__ void gemm_phase(PG8_LAS unsigned char* lds, const Gemm g, const Sched& S, const Epi& E, const int wave_in) {
;     ...
;         for (int t = 0; t < nt; t += 2) {
;             const bool last = (t == nt - 2);
;             const char* a1 = cA + (size_t)(t + 1) * kstep;
;             const char* a2 = last ? nA : cA + (size_t)(t + 2) * kstep; const char* b2 = last ? nB : cB + (size_t)(t + 2) * kstep;
;             const char* a3 = a2 + kstep; const char* b3 = b2 + kstep;
;             if (last && has_next) S.a_ready(nxt);
;             if constexpr (SP2) {
;             PG8_LDB(B0, 0, 0); PG8_LDB(B1, 0, 1); PG8_SCHED; PG8_LDA(At, 0, 0); PG8_STAGE(PG8_SA(1, 1), a1 + hstepA, voffA);
;     ...
;             PG8_LDA(At, 1, 1); PG8_STAGE(PG8_SB(1, 0), b3, voffB); PG8_STAGE(PG8_SB(1, 1), b3 + hstepB, voffB); PG8_STAGE(PG8_SA(1, 0), a3, voffA);
;             PG8_WAIT_V(8); PG8_WAIT_L(0); PG8_BAR; PG8_MMA(1, 0, At, B0); PG8_MMA(1, 1, At, B1); PG8_BAR; PG8_SCHED;
	s_add_i32 s18, s54, s30
	v_lshl_add_u64 v[210:211], v[210:211], 0, s[6:7]
	s_mov_b32 m0, s18
	ds_read_b128 v[178:181], v232 offset:49152
	ds_read_b128 v[182:185], v232 offset:50176
	ds_read_b128 v[186:189], v232 offset:51200
	ds_read_b128 v[190:193], v232 offset:52224
	ds_read_b128 v[194:197], v232 offset:53248
	ds_read_b128 v[198:201], v232 offset:54272
	ds_read_b128 v[202:205], v232 offset:55296
	ds_read_b128 v[206:209], v232 offset:56320
	global_load_lds_dwordx4 v[210:211], off
	s_add_i32 m0, s18, 0x2000
	s_add_u32 s18, s22, 0x158080
	v_lshl_add_u64 v[210:211], v[212:213], 0, s[6:7]
	s_addc_u32 s19, s23, 0
	s_add_i32 s22, s55, s30
	global_load_lds_dwordx4 v[210:211], off
	v_lshl_add_u64 v[210:211], s[18:19], 0, v[156:157]
	s_mov_b32 m0, s22
	s_nop 0
	global_load_lds_dwordx4 v[210:211], off
	v_lshl_add_u64 v[210:211], s[18:19], 0, v[152:153]
	s_add_i32 m0, s22, 0x2000
	s_nop 0
	global_load_lds_dwordx4 v[210:211], off
	v_lshl_add_u64 v[210:211], v[214:215], 0, s[6:7]
	s_mov_b32 m0, s42
	s_nop 0
	global_load_lds_dwordx4 v[210:211], off
	v_lshl_add_u64 v[210:211], v[216:217], 0, s[6:7]
	s_mov_b32 m0, s43
	s_nop 0
	global_load_lds_dwordx4 v[210:211], off
	s_waitcnt vmcnt(8)
	s_waitcnt lgkmcnt(0)
	s_setprio 1
	s_barrier
	v_mfma_f32_16x16x32_bf16 v[60:63], v[64:67], v[178:181], v[60:63]
	v_mfma_f32_16x16x32_bf16 v[56:59], v[72:75], v[178:181], v[56:59]
	v_mfma_f32_16x16x32_bf16 v[48:51], v[64:67], v[186:189], v[48:51]
	v_mfma_f32_16x16x32_bf16 v[40:43], v[72:75], v[186:189], v[40:43]
	v_mfma_f32_16x16x32_bf16 v[32:35], v[64:67], v[194:197], v[32:35]
	v_mfma_f32_16x16x32_bf16 v[24:27], v[72:75], v[194:197], v[24:27]
	v_mfma_f32_16x16x32_bf16 v[16:19], v[64:67], v[202:205], v[16:19]
	v_mfma_f32_16x16x32_bf16 v[8:11], v[72:75], v[202:205], v[8:11]
	v_mfma_f32_16x16x32_bf16 v[60:63], v[68:71], v[182:185], v[60:63]
	v_mfma_f32_16x16x32_bf16 v[56:59], v[76:79], v[182:185], v[56:59]
	v_mfma_f32_16x16x32_bf16 v[48:51], v[68:71], v[190:193], v[48:51]
	v_mfma_f32_16x16x32_bf16 v[40:43], v[76:79], v[190:193], v[40:43]
	v_mfma_f32_16x16x32_bf16 v[32:35], v[68:71], v[198:201], v[32:35]
	v_mfma_f32_16x16x32_bf16 v[24:27], v[76:79], v[198:201], v[24:27]
	v_mfma_f32_16x16x32_bf16 v[16:19], v[68:71], v[206:209], v[16:19]
	v_mfma_f32_16x16x32_bf16 v[8:11], v[76:79], v[206:209], v[8:11]
	v_mfma_f32_16x16x32_bf16 v[52:55], v[144:147], v[178:181], v[52:55]
	v_mfma_f32_16x16x32_bf16 v[44:47], v[170:173], v[178:181], v[44:47]
	v_mfma_f32_16x16x32_bf16 v[36:39], v[144:147], v[186:189], v[36:39]
	v_mfma_f32_16x16x32_bf16 v[28:31], v[170:173], v[186:189], v[28:31]
	v_mfma_f32_16x16x32_bf16 v[20:23], v[144:147], v[194:197], v[20:23]
	v_mfma_f32_16x16x32_bf16 v[12:15], v[170:173], v[194:197], v[12:15]
	v_mfma_f32_16x16x32_bf16 v[4:7], v[144:147], v[202:205], v[4:7]
	v_mfma_f32_16x16x32_bf16 v[0:3], v[170:173], v[202:205], v[0:3]
	v_mfma_f32_16x16x32_bf16 v[52:55], v[148:151], v[182:185], v[52:55]
	v_mfma_f32_16x16x32_bf16 v[44:47], v[174:177], v[182:185], v[44:47]
	v_mfma_f32_16x16x32_bf16 v[36:39], v[148:151], v[190:193], v[36:39]
	v_mfma_f32_16x16x32_bf16 v[28:31], v[174:177], v[190:193], v[28:31]
	v_mfma_f32_16x16x32_bf16 v[20:23], v[148:151], v[198:201], v[20:23]
	v_mfma_f32_16x16x32_bf16 v[12:15], v[174:177], v[198:201], v[12:15]
	v_mfma_f32_16x16x32_bf16 v[4:7], v[148:151], v[206:209], v[4:7]
	v_mfma_f32_16x16x32_bf16 v[0:3], v[174:177], v[206:209], v[0:3]
	s_setprio 0
	s_barrier
	s_add_i32 s53, s53, 2
	s_add_u32 s17, s17, 0x100
	s_addc_u32 s52, s52, 0
	s_cmpk_gt_u32 s53, 0x53
	s_mov_b64 s[18:19], s[20:21]
	s_cbranch_scc0 .LBB0_635
	s_branch .Lkx_8
.LBB0_635:
	ds_read_b128 v[64:67], v230
	ds_read_b128 v[68:71], v230 offset:1024
	ds_read_b128 v[72:75], v230 offset:2048
	ds_read_b128 v[76:79], v230 offset:3072
	ds_read_b128 v[144:147], v231
	ds_read_b128 v[148:151], v231 offset:1024
	ds_read_b128 v[170:173], v231 offset:2048
	ds_read_b128 v[174:177], v231 offset:3072
	s_add_u32 s20, s18, 0x100
	s_addc_u32 s21, s19, 0
	s_cmpk_eq_i32 s53, 0x52
	s_cselect_b32 s25, s5, s21
	s_cselect_b32 s24, s4, s20
	s_cselect_b32 s23, s15, s52
	s_cselect_b32 s22, s14, s17
	v_lshl_add_u64 v[210:211], s[18:19], 0, v[162:163]
	s_add_i32 m0, s35, 0xc000
	ds_read_b128 v[178:181], v232
	ds_read_b128 v[182:185], v232 offset:1024
	ds_read_b128 v[186:189], v232 offset:2048
	ds_read_b128 v[190:193], v232 offset:3072
	ds_read_b128 v[194:197], v232 offset:4096
	ds_read_b128 v[198:201], v232 offset:5120
	ds_read_b128 v[202:205], v232 offset:6144
	ds_read_b128 v[206:209], v232 offset:7168
	global_load_lds_dwordx4 v[210:211], off
	v_lshl_add_u64 v[210:211], s[18:19], 0, v[164:165]
	s_add_i32 m0, s35, 0xe000
	s_nop 0
	global_load_lds_dwordx4 v[210:211], off
	s_waitcnt vmcnt(8)
	s_waitcnt lgkmcnt(0)
	s_setprio 1
	s_barrier
; #define PG8_STAGE(bufoff, gbase, voff) do { _Pragma("unroll") for (int _i = 0; _i < 2; ++_i) \
;         __builtin_amdgcn_global_load_lds((const unsigned*)((const char*)(gbase) + (voff)[_i]), (PG8_LAS unsigned*)(lds + (bufoff) + ldsw + _i * 8192), 16, 0, 0); } while (0)
; #define PG8_LDA(dst, b, h) do { _Pragma("unroll") for (int m = 0; m < 4; ++m) _Pragma("unroll") for (int k = 0; k < 2; ++k) dst[m][k] = *(const PG8_LAS bf16x8*)(lds + PG8_SA(b, h) + aoff + m * 2048 + k * 1024); } while (0)
; #define PG8_LDB(dst, b, h) do { _Pragma("unroll") for (int n = 0; n < 2; ++n) _Pragma("unroll") for (int k = 0; k < 2; ++k) dst[n][k] = *(const PG8_LAS bf16x8*)(lds + PG8_SB(b, h) + boff + n * 2048 + k * 1024); } while (0)
; #define PG8_MMA(ai, bj, At, Bt) do { __builtin_amdgcn_s_setprio(1); _Pragma("unroll") for (int m = 0; m < 4; ++m) _Pragma("unroll") for (int n = 0; n < 2; ++n) _Pragma("unroll") for (int k = 0; k < 2; ++k) \
;         acc[ai][bj][m][n] = __builtin_amdgcn_mfma_f32_16x16x32_bf16(Bt[n][k], At[m][k], acc[ai][bj][m][n], 0, 0, 0); __builtin_amdgcn_s_setprio(0); } while (0)
; #define PG8_BAR __builtin_amdgcn_s_barrier()
; template <class Epi, class Sched, bool ALIGN_EPI = false, bool SP2 = false>
; __device__ __forceinline__ void gemm_phase(PG8_LAS unsigned char* lds, const Gemm g, const Sched& S, const Epi& E, const int wave_in) {
;     ...
;             PG8_LDB(B0, 0, 0); PG8_LDB(B1, 0, 1); PG8_SCHED; PG8_LDA(At, 0, 0); PG8_STAGE(PG8_SA(1, 1), a1 + hstepA, voffA);
;             PG8_WAIT_V(8); PG8_WAIT_L(0); PG8_BAR; PG8_MMA(0, 0, At, B0); PG8_MMA(0, 1, At, B1); PG8_BAR; PG8_SCHED;
;             PG8_LDA(At, 0, 1); PG8_STAGE(PG8_SB(0, 0), b2, voffB); PG8_STAGE(PG8_SB(0, 1), b2 + hstepB, voffB); PG8_STAGE(PG8_SA(0, 0), a2, voffA);
;             PG8_WAIT_V(8); PG8_WAIT_L(0); PG8_BAR; PG8_MMA(1, 0, At, B0); PG8_MMA(1, 1, At, B1); PG8_BAR; PG8_SCHED;
;             PG8_LDB(B0, 1, 0); PG8_LDB(B1, 1, 1); PG8_SCHED; PG8_LDA(At, 1, 0); PG8_STAGE(PG8_SA(0, 1), a2 + hstepA, voffA);
;             PG8_WAIT_V(8); PG8_WAIT_L(0); PG8_BAR; PG8_MMA(0, 0, At, B0); PG8_MMA(0, 1, At, B1); PG8_BAR; PG8_SCHED;
;             PG8_LDA(At, 1, 1); PG8_STAGE(PG8_SB(1, 0), b3, voffB); PG8_STAGE(PG8_SB(1, 1), b3 + hstepB, voffB); PG8_STAGE(PG8_SA(1, 0), a3, voffA);
;             PG8_WAIT_V(8); PG8_WAIT_L(0); PG8_BAR; PG8_MMA(1, 0, At, B0); PG8_MMA(1, 1, At, B1); PG8_BAR; PG8_SCHED;
	v_mfma_f32_16x16x32_bf16 v[140:143], v[64:67], v[178:181], v[140:143]
	v_mfma_f32_16x16x32_bf16 v[136:139], v[72:75], v[178:181], v[136:139]
	v_mfma_f32_16x16x32_bf16 v[128:131], v[64:67], v[186:189], v[128:131]
	v_mfma_f32_16x16x32_bf16 v[120:123], v[72:75], v[186:189], v[120:123]
	v_mfma_f32_16x16x32_bf16 v[116:119], v[64:67], v[194:197], v[116:119]
	v_mfma_f32_16x16x32_bf16 v[112:115], v[72:75], v[194:197], v[112:115]
	v_mfma_f32_16x16x32_bf16 v[100:103], v[64:67], v[202:205], v[100:103]
	v_mfma_f32_16x16x32_bf16 v[96:99], v[72:75], v[202:205], v[96:99]
	v_mfma_f32_16x16x32_bf16 v[140:143], v[68:71], v[182:185], v[140:143]
	v_mfma_f32_16x16x32_bf16 v[136:139], v[76:79], v[182:185], v[136:139]
	v_mfma_f32_16x16x32_bf16 v[128:131], v[68:71], v[190:193], v[128:131]
	v_mfma_f32_16x16x32_bf16 v[120:123], v[76:79], v[190:193], v[120:123]
	v_mfma_f32_16x16x32_bf16 v[116:119], v[68:71], v[198:201], v[116:119]
	v_mfma_f32_16x16x32_bf16 v[112:115], v[76:79], v[198:201], v[112:115]
	v_mfma_f32_16x16x32_bf16 v[100:103], v[68:71], v[206:209], v[100:103]
	v_mfma_f32_16x16x32_bf16 v[96:99], v[76:79], v[206:209], v[96:99]
	v_mfma_f32_16x16x32_bf16 v[132:135], v[144:147], v[178:181], v[132:135]
	v_mfma_f32_16x16x32_bf16 v[124:127], v[170:173], v[178:181], v[124:127]
	v_mfma_f32_16x16x32_bf16 v[108:111], v[144:147], v[186:189], v[108:111]
	v_mfma_f32_16x16x32_bf16 v[104:107], v[170:173], v[186:189], v[104:107]
	v_mfma_f32_16x16x32_bf16 v[92:95], v[144:147], v[194:197], v[92:95]
	v_mfma_f32_16x16x32_bf16 v[88:91], v[170:173], v[194:197], v[88:91]
	v_mfma_f32_16x16x32_bf16 v[84:87], v[144:147], v[202:205], v[84:87]
	v_mfma_f32_16x16x32_bf16 v[80:83], v[170:173], v[202:205], v[80:83]
	v_mfma_f32_16x16x32_bf16 v[132:135], v[148:151], v[182:185], v[132:135]
	v_mfma_f32_16x16x32_bf16 v[124:127], v[174:177], v[182:185], v[124:127]
	v_mfma_f32_16x16x32_bf16 v[108:111], v[148:151], v[190:193], v[108:111]
	v_mfma_f32_16x16x32_bf16 v[104:107], v[174:177], v[190:193], v[104:107]
	v_mfma_f32_16x16x32_bf16 v[92:95], v[148:151], v[198:201], v[92:95]
	v_mfma_f32_16x16x32_bf16 v[88:91], v[174:177], v[198:201], v[88:91]
	v_mfma_f32_16x16x32_bf16 v[84:87], v[148:151], v[206:209], v[84:87]
	v_mfma_f32_16x16x32_bf16 v[80:83], v[174:177], v[206:209], v[80:83]
	s_setprio 0
	s_barrier
	s_add_i32 s18, s45, s30
	v_lshl_add_u64 v[210:211], s[22:23], 0, v[156:157]
	s_mov_b32 m0, s18
	ds_read_b128 v[178:181], v232 offset:16384
	ds_read_b128 v[182:185], v232 offset:17408
	ds_read_b128 v[186:189], v232 offset:18432
	ds_read_b128 v[190:193], v232 offset:19456
	ds_read_b128 v[194:197], v232 offset:20480
	ds_read_b128 v[198:201], v232 offset:21504
	ds_read_b128 v[202:205], v232 offset:22528
	ds_read_b128 v[206:209], v232 offset:23552
	global_load_lds_dwordx4 v[210:211], off
	s_add_i32 m0, s18, 0x2000
	s_add_u32 s18, s22, 0x158000
	v_lshl_add_u64 v[212:213], s[22:23], 0, v[152:153]
	s_addc_u32 s19, s23, 0
	s_add_i32 s54, s46, s30
	global_load_lds_dwordx4 v[212:213], off
	v_lshl_add_u64 v[214:215], s[18:19], 0, v[156:157]
	s_mov_b32 m0, s54
	v_lshl_add_u64 v[216:217], s[24:25], 0, v[154:155]
	global_load_lds_dwordx4 v[214:215], off
	v_lshl_add_u64 v[214:215], s[18:19], 0, v[152:153]
	s_add_i32 m0, s54, 0x2000
	s_nop 0
	global_load_lds_dwordx4 v[214:215], off
	v_lshl_add_u64 v[214:215], s[24:25], 0, v[158:159]
	s_mov_b32 m0, s35
	s_nop 0
	global_load_lds_dwordx4 v[214:215], off
	s_mov_b32 m0, s36
	s_nop 0
	global_load_lds_dwordx4 v[216:217], off
	s_waitcnt vmcnt(8)
	s_waitcnt lgkmcnt(0)
	s_setprio 1
	s_barrier
	v_mfma_f32_16x16x32_bf16 v[60:63], v[64:67], v[178:181], v[60:63]
	v_mfma_f32_16x16x32_bf16 v[56:59], v[72:75], v[178:181], v[56:59]
	v_mfma_f32_16x16x32_bf16 v[48:51], v[64:67], v[186:189], v[48:51]
	v_mfma_f32_16x16x32_bf16 v[40:43], v[72:75], v[186:189], v[40:43]
	v_mfma_f32_16x16x32_bf16 v[32:35], v[64:67], v[194:197], v[32:35]
	v_mfma_f32_16x16x32_bf16 v[24:27], v[72:75], v[194:197], v[24:27]
	v_mfma_f32_16x16x32_bf16 v[16:19], v[64:67], v[202:205], v[16:19]
	v_mfma_f32_16x16x32_bf16 v[8:11], v[72:75], v[202:205], v[8:11]
	v_mfma_f32_16x16x32_bf16 v[60:63], v[68:71], v[182:185], v[60:63]
	v_mfma_f32_16x16x32_bf16 v[56:59], v[76:79], v[182:185], v[56:59]
	v_mfma_f32_16x16x32_bf16 v[48:51], v[68:71], v[190:193], v[48:51]
	v_mfma_f32_16x16x32_bf16 v[40:43], v[76:79], v[190:193], v[40:43]
	v_mfma_f32_16x16x32_bf16 v[32:35], v[68:71], v[198:201], v[32:35]
	v_mfma_f32_16x16x32_bf16 v[24:27], v[76:79], v[198:201], v[24:27]
	v_mfma_f32_16x16x32_bf16 v[16:19], v[68:71], v[206:209], v[16:19]
	v_mfma_f32_16x16x32_bf16 v[8:11], v[76:79], v[206:209], v[8:11]
	v_mfma_f32_16x16x32_bf16 v[52:55], v[144:147], v[178:181], v[52:55]
	v_mfma_f32_16x16x32_bf16 v[44:47], v[170:173], v[178:181], v[44:47]
	v_mfma_f32_16x16x32_bf16 v[36:39], v[144:147], v[186:189], v[36:39]
	v_mfma_f32_16x16x32_bf16 v[28:31], v[170:173], v[186:189], v[28:31]
	v_mfma_f32_16x16x32_bf16 v[20:23], v[144:147], v[194:197], v[20:23]
	v_mfma_f32_16x16x32_bf16 v[12:15], v[170:173], v[194:197], v[12:15]
	v_mfma_f32_16x16x32_bf16 v[4:7], v[144:147], v[202:205], v[4:7]
	v_mfma_f32_16x16x32_bf16 v[0:3], v[170:173], v[202:205], v[0:3]
	v_mfma_f32_16x16x32_bf16 v[52:55], v[148:151], v[182:185], v[52:55]
	v_mfma_f32_16x16x32_bf16 v[44:47], v[174:177], v[182:185], v[44:47]
	v_mfma_f32_16x16x32_bf16 v[36:39], v[148:151], v[190:193], v[36:39]
	v_mfma_f32_16x16x32_bf16 v[28:31], v[174:177], v[190:193], v[28:31]
	v_mfma_f32_16x16x32_bf16 v[20:23], v[148:151], v[198:201], v[20:23]
	v_mfma_f32_16x16x32_bf16 v[12:15], v[174:177], v[198:201], v[12:15]
	v_mfma_f32_16x16x32_bf16 v[4:7], v[148:151], v[206:209], v[4:7]
	v_mfma_f32_16x16x32_bf16 v[0:3], v[174:177], v[206:209], v[0:3]
	s_setprio 0
	s_barrier
; #define PG8_STAGE(bufoff, gbase, voff) do { _Pragma("unroll") for (int _i = 0; _i < 2; ++_i) \
;         __builtin_amdgcn_global_load_lds((const unsigned*)((const char*)(gbase) + (voff)[_i]), (PG8_LAS unsigned*)(lds + (bufoff) + ldsw + _i * 8192), 16, 0, 0); } while (0)
; #define PG8_LDA(dst, b, h) do { _Pragma("unroll") for (int m = 0; m < 4; ++m) _Pragma("unroll") for (int k = 0; k < 2; ++k) dst[m][k] = *(const PG8_LAS bf16x8*)(lds + PG8_SA(b, h) + aoff + m * 2048 + k * 1024); } while (0)
; #define PG8_LDB(dst, b, h) do { _Pragma("unroll") for (int n = 0; n < 2; ++n) _Pragma("unroll") for (int k = 0; k < 2; ++k) dst[n][k] = *(const PG8_LAS bf16x8*)(lds + PG8_SB(b, h) + boff + n * 2048 + k * 1024); } while (0)
; #define PG8_MMA(ai, bj, At, Bt) do { __builtin_amdgcn_s_setprio(1); _Pragma("unroll") for (int m = 0; m < 4; ++m) _Pragma("unroll") for (int n = 0; n < 2; ++n) _Pragma("unroll") for (int k = 0; k < 2; ++k) \
;         acc[ai][bj][m][n] = __builtin_amdgcn_mfma_f32_16x16x32_bf16(Bt[n][k], At[m][k], acc[ai][bj][m][n], 0, 0, 0); __builtin_amdgcn_s_setprio(0); } while (0)
; #define PG8_WAIT_V(n) asm volatile("s_waitcnt vmcnt(" #n ")" ::: "memory")
; #define PG8_WAIT_L(n) asm volatile("s_waitcnt lgkmcnt(" #n ")" ::: "memory")
; #define PG8_BAR __builtin_amdgcn_s_barrier()
; #define PG8_SCHED __builtin_amdgcn_sched_barrier(0)
; template <class Epi, class Sched, bool ALIGN_EPI = false, bool SP2 = false>
; __device__ __forceinline__ void gemm_phase(PG8_LAS unsigned char* lds, const Gemm g, const Sched& S, const Epi& E, const int wave_in) {
;     ...
;             PG8_LDB(B0, 1, 0); PG8_LDB(B1, 1, 1); PG8_SCHED; PG8_LDA(At, 1, 0); PG8_STAGE(PG8_SA(0, 1), a2 + hstepA, voffA);
;             PG8_WAIT_V(8); PG8_WAIT_L(0); PG8_BAR; PG8_MMA(0, 0, At, B0); PG8_MMA(0, 1, At, B1); PG8_BAR; PG8_SCHED;
;             PG8_LDA(At, 1, 1); PG8_STAGE(PG8_SB(1, 0), b3, voffB); PG8_STAGE(PG8_SB(1, 1), b3 + hstepB, voffB); PG8_STAGE(PG8_SA(1, 0), a3, voffA);
;             PG8_WAIT_V(8); PG8_WAIT_L(0); PG8_BAR; PG8_MMA(1, 0, At, B0); PG8_MMA(1, 1, At, B1); PG8_BAR; PG8_SCHED;
	s_add_i32 s54, 0, 0x18000
	s_add_i32 s55, 0, 0x1c000
	v_add_u32_e32 v76, s54, v228
	v_add_u32_e32 v174, s55, v228
	ds_read_b128 v[64:67], v76
	ds_read_b128 v[68:71], v76 offset:1024
	ds_read_b128 v[72:75], v76 offset:2048
	ds_read_b128 v[76:79], v76 offset:3072
	ds_read_b128 v[144:147], v174
	ds_read_b128 v[148:151], v174 offset:1024
	ds_read_b128 v[170:173], v174 offset:2048
	ds_read_b128 v[174:177], v174 offset:3072
	s_add_u32 s18, s24, 0x158000
	s_addc_u32 s19, s25, 0
	s_mov_b32 m0, s37
	v_lshl_add_u64 v[218:219], s[18:19], 0, v[158:159]
	ds_read_b128 v[178:181], v232 offset:32768
	ds_read_b128 v[182:185], v232 offset:33792
	ds_read_b128 v[186:189], v232 offset:34816
	ds_read_b128 v[190:193], v232 offset:35840
	ds_read_b128 v[194:197], v232 offset:36864
	ds_read_b128 v[198:201], v232 offset:37888
	ds_read_b128 v[202:205], v232 offset:38912
	ds_read_b128 v[206:209], v232 offset:39936
	global_load_lds_dwordx4 v[218:219], off
	v_lshl_add_u64 v[218:219], s[18:19], 0, v[154:155]
	s_mov_b32 m0, s38
	s_nop 0
	global_load_lds_dwordx4 v[218:219], off
	s_waitcnt vmcnt(8)
	s_waitcnt lgkmcnt(0)
	s_setprio 1
	s_barrier
	v_mfma_f32_16x16x32_bf16 v[140:143], v[64:67], v[178:181], v[140:143]
	v_mfma_f32_16x16x32_bf16 v[136:139], v[72:75], v[178:181], v[136:139]
	v_mfma_f32_16x16x32_bf16 v[128:131], v[64:67], v[186:189], v[128:131]
	v_mfma_f32_16x16x32_bf16 v[120:123], v[72:75], v[186:189], v[120:123]
	v_mfma_f32_16x16x32_bf16 v[116:119], v[64:67], v[194:197], v[116:119]
	v_mfma_f32_16x16x32_bf16 v[112:115], v[72:75], v[194:197], v[112:115]
	v_mfma_f32_16x16x32_bf16 v[100:103], v[64:67], v[202:205], v[100:103]
	v_mfma_f32_16x16x32_bf16 v[96:99], v[72:75], v[202:205], v[96:99]
	v_mfma_f32_16x16x32_bf16 v[140:143], v[68:71], v[182:185], v[140:143]
	v_mfma_f32_16x16x32_bf16 v[136:139], v[76:79], v[182:185], v[136:139]
	v_mfma_f32_16x16x32_bf16 v[128:131], v[68:71], v[190:193], v[128:131]
	v_mfma_f32_16x16x32_bf16 v[120:123], v[76:79], v[190:193], v[120:123]
	v_mfma_f32_16x16x32_bf16 v[116:119], v[68:71], v[198:201], v[116:119]
	v_mfma_f32_16x16x32_bf16 v[112:115], v[76:79], v[198:201], v[112:115]
	v_mfma_f32_16x16x32_bf16 v[100:103], v[68:71], v[206:209], v[100:103]
	v_mfma_f32_16x16x32_bf16 v[96:99], v[76:79], v[206:209], v[96:99]
	v_mfma_f32_16x16x32_bf16 v[132:135], v[144:147], v[178:181], v[132:135]
	v_mfma_f32_16x16x32_bf16 v[124:127], v[170:173], v[178:181], v[124:127]
	v_mfma_f32_16x16x32_bf16 v[108:111], v[144:147], v[186:189], v[108:111]
	v_mfma_f32_16x16x32_bf16 v[104:107], v[170:173], v[186:189], v[104:107]
	v_mfma_f32_16x16x32_bf16 v[92:95], v[144:147], v[194:197], v[92:95]
	v_mfma_f32_16x16x32_bf16 v[88:91], v[170:173], v[194:197], v[88:91]
	v_mfma_f32_16x16x32_bf16 v[84:87], v[144:147], v[202:205], v[84:87]
	v_mfma_f32_16x16x32_bf16 v[80:83], v[170:173], v[202:205], v[80:83]
	v_mfma_f32_16x16x32_bf16 v[132:135], v[148:151], v[182:185], v[132:135]
	v_mfma_f32_16x16x32_bf16 v[124:127], v[174:177], v[182:185], v[124:127]
	v_mfma_f32_16x16x32_bf16 v[108:111], v[148:151], v[190:193], v[108:111]
	v_mfma_f32_16x16x32_bf16 v[104:107], v[174:177], v[190:193], v[104:107]
	v_mfma_f32_16x16x32_bf16 v[92:95], v[148:151], v[198:201], v[92:95]
	v_mfma_f32_16x16x32_bf16 v[88:91], v[174:177], v[198:201], v[88:91]
	v_mfma_f32_16x16x32_bf16 v[84:87], v[148:151], v[206:209], v[84:87]
	v_mfma_f32_16x16x32_bf16 v[80:83], v[174:177], v[206:209], v[80:83]
	s_setprio 0
	s_barrier
	s_add_i32 s18, s54, s30
	v_lshl_add_u64 v[210:211], v[210:211], 0, s[6:7]
	s_mov_b32 m0, s18
	ds_read_b128 v[178:181], v232 offset:49152
	ds_read_b128 v[182:185], v232 offset:50176
	ds_read_b128 v[186:189], v232 offset:51200
	ds_read_b128 v[190:193], v232 offset:52224
	ds_read_b128 v[194:197], v232 offset:53248
	ds_read_b128 v[198:201], v232 offset:54272
	ds_read_b128 v[202:205], v232 offset:55296
	ds_read_b128 v[206:209], v232 offset:56320
	global_load_lds_dwordx4 v[210:211], off
	s_add_i32 m0, s18, 0x2000
	s_add_u32 s18, s22, 0x158080
	v_lshl_add_u64 v[210:211], v[212:213], 0, s[6:7]
	s_addc_u32 s19, s23, 0
	s_add_i32 s22, s55, s30
	global_load_lds_dwordx4 v[210:211], off
	v_lshl_add_u64 v[210:211], s[18:19], 0, v[156:157]
	s_mov_b32 m0, s22
	s_nop 0
	global_load_lds_dwordx4 v[210:211], off
	v_lshl_add_u64 v[210:211], s[18:19], 0, v[152:153]
	s_add_i32 m0, s22, 0x2000
	s_nop 0
	global_load_lds_dwordx4 v[210:211], off
	v_lshl_add_u64 v[210:211], v[214:215], 0, s[6:7]
	s_mov_b32 m0, s42
	s_nop 0
	global_load_lds_dwordx4 v[210:211], off
	v_lshl_add_u64 v[210:211], v[216:217], 0, s[6:7]
	s_mov_b32 m0, s43
	s_nop 0
	global_load_lds_dwordx4 v[210:211], off
	s_waitcnt vmcnt(8)
	s_waitcnt lgkmcnt(0)
	s_setprio 1
	s_barrier
	v_mfma_f32_16x16x32_bf16 v[60:63], v[64:67], v[178:181], v[60:63]
	v_mfma_f32_16x16x32_bf16 v[56:59], v[72:75], v[178:181], v[56:59]
	v_mfma_f32_16x16x32_bf16 v[48:51], v[64:67], v[186:189], v[48:51]
	v_mfma_f32_16x16x32_bf16 v[40:43], v[72:75], v[186:189], v[40:43]
	v_mfma_f32_16x16x32_bf16 v[32:35], v[64:67], v[194:197], v[32:35]
	v_mfma_f32_16x16x32_bf16 v[24:27], v[72:75], v[194:197], v[24:27]
	v_mfma_f32_16x16x32_bf16 v[16:19], v[64:67], v[202:205], v[16:19]
	v_mfma_f32_16x16x32_bf16 v[8:11], v[72:75], v[202:205], v[8:11]
	v_mfma_f32_16x16x32_bf16 v[60:63], v[68:71], v[182:185], v[60:63]
	v_mfma_f32_16x16x32_bf16 v[56:59], v[76:79], v[182:185], v[56:59]
	v_mfma_f32_16x16x32_bf16 v[48:51], v[68:71], v[190:193], v[48:51]
	v_mfma_f32_16x16x32_bf16 v[40:43], v[76:79], v[190:193], v[40:43]
	v_mfma_f32_16x16x32_bf16 v[32:35], v[68:71], v[198:201], v[32:35]
	v_mfma_f32_16x16x32_bf16 v[24:27], v[76:79], v[198:201], v[24:27]
	v_mfma_f32_16x16x32_bf16 v[16:19], v[68:71], v[206:209], v[16:19]
	v_mfma_f32_16x16x32_bf16 v[8:11], v[76:79], v[206:209], v[8:11]
	v_mfma_f32_16x16x32_bf16 v[52:55], v[144:147], v[178:181], v[52:55]
	v_mfma_f32_16x16x32_bf16 v[44:47], v[170:173], v[178:181], v[44:47]
	v_mfma_f32_16x16x32_bf16 v[36:39], v[144:147], v[186:189], v[36:39]
	v_mfma_f32_16x16x32_bf16 v[28:31], v[170:173], v[186:189], v[28:31]
	v_mfma_f32_16x16x32_bf16 v[20:23], v[144:147], v[194:197], v[20:23]
	v_mfma_f32_16x16x32_bf16 v[12:15], v[170:173], v[194:197], v[12:15]
	v_mfma_f32_16x16x32_bf16 v[4:7], v[144:147], v[202:205], v[4:7]
	v_mfma_f32_16x16x32_bf16 v[0:3], v[170:173], v[202:205], v[0:3]
	v_mfma_f32_16x16x32_bf16 v[52:55], v[148:151], v[182:185], v[52:55]
	v_mfma_f32_16x16x32_bf16 v[44:47], v[174:177], v[182:185], v[44:47]
	v_mfma_f32_16x16x32_bf16 v[36:39], v[148:151], v[190:193], v[36:39]
	v_mfma_f32_16x16x32_bf16 v[28:31], v[174:177], v[190:193], v[28:31]
	v_mfma_f32_16x16x32_bf16 v[20:23], v[148:151], v[198:201], v[20:23]
	v_mfma_f32_16x16x32_bf16 v[12:15], v[174:177], v[198:201], v[12:15]
	v_mfma_f32_16x16x32_bf16 v[4:7], v[148:151], v[206:209], v[4:7]
	v_mfma_f32_16x16x32_bf16 v[0:3], v[174:177], v[206:209], v[0:3]
	s_setprio 0
	s_barrier
	s_add_i32 s53, s53, 2
	s_add_u32 s17, s17, 0x100
	s_addc_u32 s52, s52, 0
	s_cmpk_gt_u32 s53, 0x53
	s_mov_b64 s[18:19], s[20:21]
	s_cbranch_scc0 .LBB0_635

;     __host__ __device__ bool next(int i, Unit& u) const { const bool ok = StaticOrder::next(i, u); u.pm = 0; u.pn = 0; return ok; }
; #define PG8_STAGE(bufoff, gbase, voff) do { _Pragma("unroll") for (int _i = 0; _i < 2; ++_i) \
;         __builtin_amdgcn_global_load_lds((const unsigned*)((const char*)(gbase) + (voff)[_i]), (PG8_LAS unsigned*)(lds + (bufoff) + ldsw + _i * 8192), 16, 0, 0); } while (0)
; #define PG8_LDA(dst, b, h) do { _Pragma("unroll") for (int m = 0; m < 4; ++m) _Pragma("unroll") for (int k = 0; k < 2; ++k) dst[m][k] = *(const PG8_LAS bf16x8*)(lds + PG8_SA(b, h) + aoff + m * 2048 + k * 1024); } while (0)
; #define PG8_LDB(dst, b, h) do { _Pragma("unroll") for (int n = 0; n < 2; ++n) _Pragma("unroll") for (int k = 0; k < 2; ++k) dst[n][k] = *(const PG8_LAS bf16x8*)(lds + PG8_SB(b, h) + boff + n * 2048 + k * 1024); } while (0)
; #define PG8_WAIT_V(n) asm volatile("s_waitcnt vmcnt(" #n ")" ::: "memory")
; #define PG8_BAR __builtin_amdgcn_s_barrier()
; template <class Epi, class Sched, bool ALIGN_EPI = false, bool SP2 = false>
; __device__ __forceinline__ void gemm_phase(PG8_LAS unsigned char* lds, const Gemm g, const Sched& S, const Epi& E, const int wave_in) {
;     ...
;         const bool has_next = S.next(ui + 1, nxt);
;         const char* nA = has_next ? (const char*)g.A + (size_t)nxt.pm * tstepA : cA; const char* nB = has_next ? (const char*)g.Bt + (size_t)nxt.pn * tstepB : cB;
;         for (int t = 0; t < nt; t += 2) {
;             const bool last = (t == nt - 2);
;             const char* a1 = cA + (size_t)(t + 1) * kstep;
;             const char* a2 = last ? nA : cA + (size_t)(t + 2) * kstep; const char* b2 = last ? nB : cB + (size_t)(t + 2) * kstep;
;             const char* a3 = a2 + kstep; const char* b3 = b2 + kstep;
;             if (last && has_next) S.a_ready(nxt);
;             if constexpr (SP2) {
;             PG8_LDB(B0, 0, 0); PG8_LDB(B1, 0, 1); PG8_SCHED; PG8_LDA(At, 0, 0); PG8_STAGE(PG8_SA(1, 1), a1 + hstepA, voffA);
;             PG8_WAIT_V(8); PG8_WAIT_L(0); PG8_BAR; PG8_MMA(0, 0, At, B0); PG8_MMA(0, 1, At, B1); PG8_BAR; PG8_SCHED;
;             PG8_LDA(At, 0, 1); PG8_STAGE(PG8_SB(0, 0), b2, voffB); PG8_STAGE(PG8_SB(0, 1), b2 + hstepB, voffB); PG8_STAGE(PG8_SA(0, 0), a2, voffA);
;             PG8_WAIT_V(8); PG8_WAIT_L(0); PG8_BAR; PG8_MMA(1, 0, At, B0); PG8_MMA(1, 1, At, B1); PG8_BAR; PG8_SCHED;
.LBB0_1092:
	s_ashr_i32 s15, s14, 31
	s_lshl_b64 s[18:19], s[14:15], 21
	s_add_u32 s18, s30, s18
	s_addc_u32 s19, s31, s19
	s_and_b64 s[4:5], s[4:5], exec
	s_cselect_b32 s15, s19, s25
	s_cselect_b32 s21, s18, s24
	s_add_u32 s53, s24, 0x100
	v_mov_b32_e32 v0, 0
	s_addc_u32 s54, s25, 0
	s_mov_b32 s55, -2
	ds_read_b128 v[128:131], v214
	ds_read_b128 v[132:135], v214 offset:1024
	ds_read_b128 v[136:139], v214 offset:2048
	ds_read_b128 v[140:143], v214 offset:3072
	ds_read_b128 v[162:165], v215
	ds_read_b128 v[166:169], v215 offset:1024
	ds_read_b128 v[170:173], v215 offset:2048
	ds_read_b128 v[174:177], v215 offset:3072
	s_add_u32 s4, s22, 0x100
	s_addc_u32 s5, s23, 0
	s_cmp_eq_u32 s55, 60
	s_cselect_b32 s27, s17, s5
	s_cselect_b32 s26, s16, s4
	s_cselect_b32 s25, s15, s54
	s_cselect_b32 s24, s21, s53
	v_lshl_add_u64 v[210:211], s[22:23], 0, v[154:155]
	s_add_i32 m0, s37, 0xc000
	ds_read_b128 v[178:181], v216
	ds_read_b128 v[182:185], v216 offset:1024
	ds_read_b128 v[186:189], v216 offset:2048
	ds_read_b128 v[190:193], v216 offset:3072
	ds_read_b128 v[194:197], v216 offset:4096
	ds_read_b128 v[198:201], v216 offset:5120
	ds_read_b128 v[202:205], v216 offset:6144
	ds_read_b128 v[206:209], v216 offset:7168
	global_load_lds_dwordx4 v[210:211], off
	v_lshl_add_u64 v[210:211], s[22:23], 0, v[156:157]
	s_add_i32 m0, s37, 0xe000
	s_nop 0
	global_load_lds_dwordx4 v[210:211], off
	s_waitcnt vmcnt(8)
	s_waitcnt lgkmcnt(0)
	s_setprio 1
	s_barrier
	v_mfma_f32_16x16x32_bf16 v[124:127], v[128:131], v[178:181], 0
	v_mfma_f32_16x16x32_bf16 v[120:123], v[136:139], v[178:181], 0
	v_mfma_f32_16x16x32_bf16 v[112:115], v[128:131], v[186:189], 0
	v_mfma_f32_16x16x32_bf16 v[104:107], v[136:139], v[186:189], 0
	v_mfma_f32_16x16x32_bf16 v[100:103], v[128:131], v[194:197], 0
	v_mfma_f32_16x16x32_bf16 v[96:99], v[136:139], v[194:197], 0
	v_mfma_f32_16x16x32_bf16 v[76:79], v[128:131], v[202:205], 0
	v_mfma_f32_16x16x32_bf16 v[72:75], v[136:139], v[202:205], 0
	v_mfma_f32_16x16x32_bf16 v[124:127], v[132:135], v[182:185], v[124:127]
	v_mfma_f32_16x16x32_bf16 v[120:123], v[140:143], v[182:185], v[120:123]
	v_mfma_f32_16x16x32_bf16 v[112:115], v[132:135], v[190:193], v[112:115]
	v_mfma_f32_16x16x32_bf16 v[104:107], v[140:143], v[190:193], v[104:107]
	v_mfma_f32_16x16x32_bf16 v[100:103], v[132:135], v[198:201], v[100:103]
	v_mfma_f32_16x16x32_bf16 v[96:99], v[140:143], v[198:201], v[96:99]
	v_mfma_f32_16x16x32_bf16 v[76:79], v[132:135], v[206:209], v[76:79]
	v_mfma_f32_16x16x32_bf16 v[72:75], v[140:143], v[206:209], v[72:75]
	v_mfma_f32_16x16x32_bf16 v[116:119], v[162:165], v[178:181], 0
	v_mfma_f32_16x16x32_bf16 v[108:111], v[170:173], v[178:181], 0
	v_mfma_f32_16x16x32_bf16 v[92:95], v[162:165], v[186:189], 0
	v_mfma_f32_16x16x32_bf16 v[88:91], v[170:173], v[186:189], 0
	v_mfma_f32_16x16x32_bf16 v[84:87], v[162:165], v[194:197], 0
	v_mfma_f32_16x16x32_bf16 v[80:83], v[170:173], v[194:197], 0
	v_mfma_f32_16x16x32_bf16 v[68:71], v[162:165], v[202:205], 0
	v_mfma_f32_16x16x32_bf16 v[64:67], v[170:173], v[202:205], 0
	v_mfma_f32_16x16x32_bf16 v[116:119], v[166:169], v[182:185], v[116:119]
	v_mfma_f32_16x16x32_bf16 v[108:111], v[174:177], v[182:185], v[108:111]
	v_mfma_f32_16x16x32_bf16 v[92:95], v[166:169], v[190:193], v[92:95]
	v_mfma_f32_16x16x32_bf16 v[88:91], v[174:177], v[190:193], v[88:91]
	v_mfma_f32_16x16x32_bf16 v[84:87], v[166:169], v[198:201], v[84:87]
	v_mfma_f32_16x16x32_bf16 v[80:83], v[174:177], v[198:201], v[80:83]
	v_mfma_f32_16x16x32_bf16 v[68:71], v[166:169], v[206:209], v[68:71]
	v_mfma_f32_16x16x32_bf16 v[64:67], v[174:177], v[206:209], v[64:67]
	s_setprio 0
	s_barrier
	s_add_i32 s22, s47, s34
	v_lshl_add_u64 v[210:211], s[24:25], 0, v[148:149]
	s_mov_b32 m0, s22
	ds_read_b128 v[178:181], v216 offset:16384
	ds_read_b128 v[182:185], v216 offset:17408
	ds_read_b128 v[186:189], v216 offset:18432
	ds_read_b128 v[190:193], v216 offset:19456
	ds_read_b128 v[194:197], v216 offset:20480
	ds_read_b128 v[198:201], v216 offset:21504
	ds_read_b128 v[202:205], v216 offset:22528
	ds_read_b128 v[206:209], v216 offset:23552
	global_load_lds_dwordx4 v[210:211], off
	s_add_i32 m0, s22, 0x2000
	s_add_u32 s22, s24, 0x100000
	v_lshl_add_u64 v[218:219], s[24:25], 0, v[144:145]
	s_addc_u32 s23, s25, 0
	s_add_i32 s56, s48, s34
	global_load_lds_dwordx4 v[218:219], off
	v_lshl_add_u64 v[220:221], s[22:23], 0, v[148:149]
	s_mov_b32 m0, s56
	v_lshl_add_u64 v[222:223], s[26:27], 0, v[146:147]
	global_load_lds_dwordx4 v[220:221], off
	v_lshl_add_u64 v[220:221], s[22:23], 0, v[144:145]
	s_add_i32 m0, s56, 0x2000
	s_nop 0
	global_load_lds_dwordx4 v[220:221], off
	v_lshl_add_u64 v[220:221], s[26:27], 0, v[150:151]
	s_mov_b32 m0, s37
	s_nop 0
	global_load_lds_dwordx4 v[220:221], off
	s_mov_b32 m0, s38
	s_nop 0
	global_load_lds_dwordx4 v[222:223], off
	s_waitcnt vmcnt(8)
	s_waitcnt lgkmcnt(0)
	s_setprio 1
	s_barrier
; #define PG8_STAGE(bufoff, gbase, voff) do { _Pragma("unroll") for (int _i = 0; _i < 2; ++_i) \
;         __builtin_amdgcn_global_load_lds((const unsigned*)((const char*)(gbase) + (voff)[_i]), (PG8_LAS unsigned*)(lds + (bufoff) + ldsw + _i * 8192), 16, 0, 0); } while (0)
; #define PG8_LDA(dst, b, h) do { _Pragma("unroll") for (int m = 0; m < 4; ++m) _Pragma("unroll") for (int k = 0; k < 2; ++k) dst[m][k] = *(const PG8_LAS bf16x8*)(lds + PG8_SA(b, h) + aoff + m * 2048 + k * 1024); } while (0)
; #define PG8_LDB(dst, b, h) do { _Pragma("unroll") for (int n = 0; n < 2; ++n) _Pragma("unroll") for (int k = 0; k < 2; ++k) dst[n][k] = *(const PG8_LAS bf16x8*)(lds + PG8_SB(b, h) + boff + n * 2048 + k * 1024); } while (0)
; #define PG8_MMA(ai, bj, At, Bt) do { __builtin_amdgcn_s_setprio(1); _Pragma("unroll") for (int m = 0; m < 4; ++m) _Pragma("unroll") for (int n = 0; n < 2; ++n) _Pragma("unroll") for (int k = 0; k < 2; ++k) \
;         acc[ai][bj][m][n] = __builtin_amdgcn_mfma_f32_16x16x32_bf16(Bt[n][k], At[m][k], acc[ai][bj][m][n], 0, 0, 0); __builtin_amdgcn_s_setprio(0); } while (0)
; #define PG8_WAIT_V(n) asm volatile("s_waitcnt vmcnt(" #n ")" ::: "memory")
; #define PG8_WAIT_L(n) asm volatile("s_waitcnt lgkmcnt(" #n ")" ::: "memory")
; #define PG8_BAR __builtin_amdgcn_s_barrier()
; #define PG8_SCHED __builtin_amdgcn_sched_barrier(0)
; template <class Epi, class Sched, bool ALIGN_EPI = false, bool SP2 = false>
; __device__ __forceinline__ void gemm_phase(PG8_LAS unsigned char* lds, const Gemm g, const Sched& S, const Epi& E, const int wave_in) {
;     ...
;             PG8_WAIT_V(8); PG8_WAIT_L(0); PG8_BAR; PG8_MMA(1, 0, At, B0); PG8_MMA(1, 1, At, B1); PG8_BAR; PG8_SCHED;
;             PG8_LDB(B0, 1, 0); PG8_LDB(B1, 1, 1); PG8_SCHED; PG8_LDA(At, 1, 0); PG8_STAGE(PG8_SA(0, 1), a2 + hstepA, voffA);
;             PG8_WAIT_V(8); PG8_WAIT_L(0); PG8_BAR; PG8_MMA(0, 0, At, B0); PG8_MMA(0, 1, At, B1); PG8_BAR; PG8_SCHED;
;             PG8_LDA(At, 1, 1); PG8_STAGE(PG8_SB(1, 0), b3, voffB); PG8_STAGE(PG8_SB(1, 1), b3 + hstepB, voffB); PG8_STAGE(PG8_SA(1, 0), a3, voffA);
;             PG8_WAIT_V(8); PG8_WAIT_L(0); PG8_BAR; PG8_MMA(1, 0, At, B0); PG8_MMA(1, 1, At, B1); PG8_BAR; PG8_SCHED;
	v_mfma_f32_16x16x32_bf16 v[60:63], v[128:131], v[178:181], 0
	v_mfma_f32_16x16x32_bf16 v[56:59], v[136:139], v[178:181], 0
	v_mfma_f32_16x16x32_bf16 v[48:51], v[128:131], v[186:189], 0
	v_mfma_f32_16x16x32_bf16 v[40:43], v[136:139], v[186:189], 0
	v_mfma_f32_16x16x32_bf16 v[32:35], v[128:131], v[194:197], 0
	v_mfma_f32_16x16x32_bf16 v[24:27], v[136:139], v[194:197], 0
	v_mfma_f32_16x16x32_bf16 v[16:19], v[128:131], v[202:205], 0
	v_mfma_f32_16x16x32_bf16 v[8:11], v[136:139], v[202:205], 0
	v_mfma_f32_16x16x32_bf16 v[60:63], v[132:135], v[182:185], v[60:63]
	v_mfma_f32_16x16x32_bf16 v[56:59], v[140:143], v[182:185], v[56:59]
	v_mfma_f32_16x16x32_bf16 v[48:51], v[132:135], v[190:193], v[48:51]
	v_mfma_f32_16x16x32_bf16 v[40:43], v[140:143], v[190:193], v[40:43]
	v_mfma_f32_16x16x32_bf16 v[32:35], v[132:135], v[198:201], v[32:35]
	v_mfma_f32_16x16x32_bf16 v[24:27], v[140:143], v[198:201], v[24:27]
	v_mfma_f32_16x16x32_bf16 v[16:19], v[132:135], v[206:209], v[16:19]
	v_mfma_f32_16x16x32_bf16 v[8:11], v[140:143], v[206:209], v[8:11]
	v_mfma_f32_16x16x32_bf16 v[52:55], v[162:165], v[178:181], 0
	v_mfma_f32_16x16x32_bf16 v[44:47], v[170:173], v[178:181], 0
	v_mfma_f32_16x16x32_bf16 v[36:39], v[162:165], v[186:189], 0
	v_mfma_f32_16x16x32_bf16 v[28:31], v[170:173], v[186:189], 0
	v_mfma_f32_16x16x32_bf16 v[20:23], v[162:165], v[194:197], 0
	v_mfma_f32_16x16x32_bf16 v[12:15], v[170:173], v[194:197], 0
	v_mfma_f32_16x16x32_bf16 v[4:7], v[162:165], v[202:205], 0
	v_mfma_f32_16x16x32_bf16 v[0:3], v[170:173], v[202:205], 0
	v_mfma_f32_16x16x32_bf16 v[52:55], v[166:169], v[182:185], v[52:55]
	v_mfma_f32_16x16x32_bf16 v[44:47], v[174:177], v[182:185], v[44:47]
	v_mfma_f32_16x16x32_bf16 v[36:39], v[166:169], v[190:193], v[36:39]
	v_mfma_f32_16x16x32_bf16 v[28:31], v[174:177], v[190:193], v[28:31]
	v_mfma_f32_16x16x32_bf16 v[20:23], v[166:169], v[198:201], v[20:23]
	v_mfma_f32_16x16x32_bf16 v[12:15], v[174:177], v[198:201], v[12:15]
	v_mfma_f32_16x16x32_bf16 v[4:7], v[166:169], v[206:209], v[4:7]
	v_mfma_f32_16x16x32_bf16 v[0:3], v[174:177], v[206:209], v[0:3]
	s_setprio 0
	s_barrier
	s_add_i32 s56, 0, 0x18000
	s_add_i32 s57, 0, 0x1c000
	v_add_u32_e32 v140, s56, v212
	v_add_u32_e32 v174, s57, v212
	ds_read_b128 v[128:131], v140
	ds_read_b128 v[132:135], v140 offset:1024
	ds_read_b128 v[136:139], v140 offset:2048
	ds_read_b128 v[140:143], v140 offset:3072
	ds_read_b128 v[162:165], v174
	ds_read_b128 v[166:169], v174 offset:1024
	ds_read_b128 v[170:173], v174 offset:2048
	ds_read_b128 v[174:177], v174 offset:3072
	s_add_u32 s22, s26, 0x310000
	s_addc_u32 s23, s27, 0
	s_mov_b32 m0, s39
	v_lshl_add_u64 v[224:225], s[22:23], 0, v[150:151]
	ds_read_b128 v[178:181], v216 offset:32768
	ds_read_b128 v[182:185], v216 offset:33792
	ds_read_b128 v[186:189], v216 offset:34816
	ds_read_b128 v[190:193], v216 offset:35840
	ds_read_b128 v[194:197], v216 offset:36864
	ds_read_b128 v[198:201], v216 offset:37888
	ds_read_b128 v[202:205], v216 offset:38912
	ds_read_b128 v[206:209], v216 offset:39936
	global_load_lds_dwordx4 v[224:225], off
	v_lshl_add_u64 v[224:225], s[22:23], 0, v[146:147]
	s_mov_b32 m0, s40
	s_nop 0
	global_load_lds_dwordx4 v[224:225], off
	s_waitcnt vmcnt(8)
	s_waitcnt lgkmcnt(0)
	s_setprio 1
	s_barrier
	v_mfma_f32_16x16x32_bf16 v[124:127], v[128:131], v[178:181], v[124:127]
	v_mfma_f32_16x16x32_bf16 v[120:123], v[136:139], v[178:181], v[120:123]
	v_mfma_f32_16x16x32_bf16 v[112:115], v[128:131], v[186:189], v[112:115]
	v_mfma_f32_16x16x32_bf16 v[104:107], v[136:139], v[186:189], v[104:107]
	v_mfma_f32_16x16x32_bf16 v[100:103], v[128:131], v[194:197], v[100:103]
	v_mfma_f32_16x16x32_bf16 v[96:99], v[136:139], v[194:197], v[96:99]
	v_mfma_f32_16x16x32_bf16 v[76:79], v[128:131], v[202:205], v[76:79]
	v_mfma_f32_16x16x32_bf16 v[72:75], v[136:139], v[202:205], v[72:75]
	v_mfma_f32_16x16x32_bf16 v[124:127], v[132:135], v[182:185], v[124:127]
	v_mfma_f32_16x16x32_bf16 v[120:123], v[140:143], v[182:185], v[120:123]
	v_mfma_f32_16x16x32_bf16 v[112:115], v[132:135], v[190:193], v[112:115]
	v_mfma_f32_16x16x32_bf16 v[104:107], v[140:143], v[190:193], v[104:107]
	v_mfma_f32_16x16x32_bf16 v[100:103], v[132:135], v[198:201], v[100:103]
	v_mfma_f32_16x16x32_bf16 v[96:99], v[140:143], v[198:201], v[96:99]
	v_mfma_f32_16x16x32_bf16 v[76:79], v[132:135], v[206:209], v[76:79]
	v_mfma_f32_16x16x32_bf16 v[72:75], v[140:143], v[206:209], v[72:75]
	v_mfma_f32_16x16x32_bf16 v[116:119], v[162:165], v[178:181], v[116:119]
	v_mfma_f32_16x16x32_bf16 v[108:111], v[170:173], v[178:181], v[108:111]
	v_mfma_f32_16x16x32_bf16 v[92:95], v[162:165], v[186:189], v[92:95]
	v_mfma_f32_16x16x32_bf16 v[88:91], v[170:173], v[186:189], v[88:91]
	v_mfma_f32_16x16x32_bf16 v[84:87], v[162:165], v[194:197], v[84:87]
	v_mfma_f32_16x16x32_bf16 v[80:83], v[170:173], v[194:197], v[80:83]
	v_mfma_f32_16x16x32_bf16 v[68:71], v[162:165], v[202:205], v[68:71]
	v_mfma_f32_16x16x32_bf16 v[64:67], v[170:173], v[202:205], v[64:67]
	v_mfma_f32_16x16x32_bf16 v[116:119], v[166:169], v[182:185], v[116:119]
	v_mfma_f32_16x16x32_bf16 v[108:111], v[174:177], v[182:185], v[108:111]
	v_mfma_f32_16x16x32_bf16 v[92:95], v[166:169], v[190:193], v[92:95]
	v_mfma_f32_16x16x32_bf16 v[88:91], v[174:177], v[190:193], v[88:91]
	v_mfma_f32_16x16x32_bf16 v[84:87], v[166:169], v[198:201], v[84:87]
	v_mfma_f32_16x16x32_bf16 v[80:83], v[174:177], v[198:201], v[80:83]
	v_mfma_f32_16x16x32_bf16 v[68:71], v[166:169], v[206:209], v[68:71]
	v_mfma_f32_16x16x32_bf16 v[64:67], v[174:177], v[206:209], v[64:67]
	s_setprio 0
	s_barrier
; #define PG8_STAGE(bufoff, gbase, voff) do { _Pragma("unroll") for (int _i = 0; _i < 2; ++_i) \
;         __builtin_amdgcn_global_load_lds((const unsigned*)((const char*)(gbase) + (voff)[_i]), (PG8_LAS unsigned*)(lds + (bufoff) + ldsw + _i * 8192), 16, 0, 0); } while (0)
; #define PG8_LDA(dst, b, h) do { _Pragma("unroll") for (int m = 0; m < 4; ++m) _Pragma("unroll") for (int k = 0; k < 2; ++k) dst[m][k] = *(const PG8_LAS bf16x8*)(lds + PG8_SA(b, h) + aoff + m * 2048 + k * 1024); } while (0)
; #define PG8_LDB(dst, b, h) do { _Pragma("unroll") for (int n = 0; n < 2; ++n) _Pragma("unroll") for (int k = 0; k < 2; ++k) dst[n][k] = *(const PG8_LAS bf16x8*)(lds + PG8_SB(b, h) + boff + n * 2048 + k * 1024); } while (0)
; #define PG8_WAIT_V(n) asm volatile("s_waitcnt vmcnt(" #n ")" ::: "memory")
; #define PG8_WAIT_L(n) asm volatile("s_waitcnt lgkmcnt(" #n ")" ::: "memory")
; #define PG8_BAR __builtin_amdgcn_s_barrier()
; template <class Epi, class Sched, bool ALIGN_EPI = false, bool SP2 = false>
; __device__ __forceinline__ void gemm_phase(PG8_LAS unsigned char* lds, const Gemm g, const Sched& S, const Epi& E, const int wave_in) {
;     ...
;         for (int t = 0; t < nt; t += 2) {
;             const bool last = (t == nt - 2);
;             const char* a1 = cA + (size_t)(t + 1) * kstep;
;             const char* a2 = last ? nA : cA + (size_t)(t + 2) * kstep; const char* b2 = last ? nB : cB + (size_t)(t + 2) * kstep;
;             const char* a3 = a2 + kstep; const char* b3 = b2 + kstep;
;             if (last && has_next) S.a_ready(nxt);
;             if constexpr (SP2) {
;             PG8_LDB(B0, 0, 0); PG8_LDB(B1, 0, 1); PG8_SCHED; PG8_LDA(At, 0, 0); PG8_STAGE(PG8_SA(1, 1), a1 + hstepA, voffA);
;             PG8_WAIT_V(8); PG8_WAIT_L(0); PG8_BAR; PG8_MMA(0, 0, At, B0); PG8_MMA(0, 1, At, B1); PG8_BAR; PG8_SCHED;
;             PG8_LDA(At, 0, 1); PG8_STAGE(PG8_SB(0, 0), b2, voffB); PG8_STAGE(PG8_SB(0, 1), b2 + hstepB, voffB); PG8_STAGE(PG8_SA(0, 0), a2, voffA);
;             PG8_WAIT_V(8); PG8_WAIT_L(0); PG8_BAR; PG8_MMA(1, 0, At, B0); PG8_MMA(1, 1, At, B1); PG8_BAR; PG8_SCHED;
;     ...
;             PG8_LDA(At, 1, 1); PG8_STAGE(PG8_SB(1, 0), b3, voffB); PG8_STAGE(PG8_SB(1, 1), b3 + hstepB, voffB); PG8_STAGE(PG8_SA(1, 0), a3, voffA);
;             PG8_WAIT_V(8); PG8_WAIT_L(0); PG8_BAR; PG8_MMA(1, 0, At, B0); PG8_MMA(1, 1, At, B1); PG8_BAR; PG8_SCHED;
	s_add_i32 s22, s56, s34
	v_lshl_add_u64 v[210:211], v[210:211], 0, s[6:7]
	s_mov_b32 m0, s22
	ds_read_b128 v[178:181], v216 offset:49152
	ds_read_b128 v[182:185], v216 offset:50176
	ds_read_b128 v[186:189], v216 offset:51200
	ds_read_b128 v[190:193], v216 offset:52224
	ds_read_b128 v[194:197], v216 offset:53248
	ds_read_b128 v[198:201], v216 offset:54272
	ds_read_b128 v[202:205], v216 offset:55296
	ds_read_b128 v[206:209], v216 offset:56320
	global_load_lds_dwordx4 v[210:211], off
	s_add_i32 m0, s22, 0x2000
	s_add_u32 s22, s24, 0x100080
	v_lshl_add_u64 v[210:211], v[218:219], 0, s[6:7]
	s_addc_u32 s23, s25, 0
	s_add_i32 s24, s57, s34
	global_load_lds_dwordx4 v[210:211], off
	v_lshl_add_u64 v[210:211], s[22:23], 0, v[148:149]
	s_mov_b32 m0, s24
	s_nop 0
	global_load_lds_dwordx4 v[210:211], off
	v_lshl_add_u64 v[210:211], s[22:23], 0, v[144:145]
	s_add_i32 m0, s24, 0x2000
	s_nop 0
	global_load_lds_dwordx4 v[210:211], off
	v_lshl_add_u64 v[210:211], v[220:221], 0, s[6:7]
	s_mov_b32 m0, s44
	s_nop 0
	global_load_lds_dwordx4 v[210:211], off
	v_lshl_add_u64 v[210:211], v[222:223], 0, s[6:7]
	s_mov_b32 m0, s45
	s_nop 0
	global_load_lds_dwordx4 v[210:211], off
	s_waitcnt vmcnt(8)
	s_waitcnt lgkmcnt(0)
	s_setprio 1
	s_barrier
	v_mfma_f32_16x16x32_bf16 v[60:63], v[128:131], v[178:181], v[60:63]
	v_mfma_f32_16x16x32_bf16 v[56:59], v[136:139], v[178:181], v[56:59]
	v_mfma_f32_16x16x32_bf16 v[48:51], v[128:131], v[186:189], v[48:51]
	v_mfma_f32_16x16x32_bf16 v[40:43], v[136:139], v[186:189], v[40:43]
	v_mfma_f32_16x16x32_bf16 v[32:35], v[128:131], v[194:197], v[32:35]
	v_mfma_f32_16x16x32_bf16 v[24:27], v[136:139], v[194:197], v[24:27]
	v_mfma_f32_16x16x32_bf16 v[16:19], v[128:131], v[202:205], v[16:19]
	v_mfma_f32_16x16x32_bf16 v[8:11], v[136:139], v[202:205], v[8:11]
	v_mfma_f32_16x16x32_bf16 v[60:63], v[132:135], v[182:185], v[60:63]
	v_mfma_f32_16x16x32_bf16 v[56:59], v[140:143], v[182:185], v[56:59]
	v_mfma_f32_16x16x32_bf16 v[48:51], v[132:135], v[190:193], v[48:51]
	v_mfma_f32_16x16x32_bf16 v[40:43], v[140:143], v[190:193], v[40:43]
	v_mfma_f32_16x16x32_bf16 v[32:35], v[132:135], v[198:201], v[32:35]
	v_mfma_f32_16x16x32_bf16 v[24:27], v[140:143], v[198:201], v[24:27]
	v_mfma_f32_16x16x32_bf16 v[16:19], v[132:135], v[206:209], v[16:19]
	v_mfma_f32_16x16x32_bf16 v[8:11], v[140:143], v[206:209], v[8:11]
	v_mfma_f32_16x16x32_bf16 v[52:55], v[162:165], v[178:181], v[52:55]
	v_mfma_f32_16x16x32_bf16 v[44:47], v[170:173], v[178:181], v[44:47]
	v_mfma_f32_16x16x32_bf16 v[36:39], v[162:165], v[186:189], v[36:39]
	v_mfma_f32_16x16x32_bf16 v[28:31], v[170:173], v[186:189], v[28:31]
	v_mfma_f32_16x16x32_bf16 v[20:23], v[162:165], v[194:197], v[20:23]
	v_mfma_f32_16x16x32_bf16 v[12:15], v[170:173], v[194:197], v[12:15]
	v_mfma_f32_16x16x32_bf16 v[4:7], v[162:165], v[202:205], v[4:7]
	v_mfma_f32_16x16x32_bf16 v[0:3], v[170:173], v[202:205], v[0:3]
	v_mfma_f32_16x16x32_bf16 v[52:55], v[166:169], v[182:185], v[52:55]
	v_mfma_f32_16x16x32_bf16 v[44:47], v[174:177], v[182:185], v[44:47]
	v_mfma_f32_16x16x32_bf16 v[36:39], v[166:169], v[190:193], v[36:39]
	v_mfma_f32_16x16x32_bf16 v[28:31], v[174:177], v[190:193], v[28:31]
	v_mfma_f32_16x16x32_bf16 v[20:23], v[166:169], v[198:201], v[20:23]
	v_mfma_f32_16x16x32_bf16 v[12:15], v[174:177], v[198:201], v[12:15]
	v_mfma_f32_16x16x32_bf16 v[4:7], v[166:169], v[206:209], v[4:7]
	v_mfma_f32_16x16x32_bf16 v[0:3], v[174:177], v[206:209], v[0:3]
	s_setprio 0
	s_barrier
	s_add_i32 s55, s55, 2
	s_add_u32 s53, s53, 0x100
	s_addc_u32 s54, s54, 0
	s_cmp_gt_u32 s55, 61
	s_mov_b64 s[22:23], s[4:5]
	s_cbranch_scc0 .LBB0_1093
	s_branch .Lkx_12
.LBB0_1093:
	ds_read_b128 v[128:131], v214
	ds_read_b128 v[132:135], v214 offset:1024
	ds_read_b128 v[136:139], v214 offset:2048
	ds_read_b128 v[140:143], v214 offset:3072
	ds_read_b128 v[162:165], v215
	ds_read_b128 v[166:169], v215 offset:1024
	ds_read_b128 v[170:173], v215 offset:2048
	ds_read_b128 v[174:177], v215 offset:3072
	s_add_u32 s4, s22, 0x100
	s_addc_u32 s5, s23, 0
	s_cmp_eq_u32 s55, 60
	s_cselect_b32 s27, s17, s5
	s_cselect_b32 s26, s16, s4
	s_cselect_b32 s25, s15, s54
	s_cselect_b32 s24, s21, s53
	v_lshl_add_u64 v[210:211], s[22:23], 0, v[154:155]
	s_add_i32 m0, s37, 0xc000
	ds_read_b128 v[178:181], v216
	ds_read_b128 v[182:185], v216 offset:1024
	ds_read_b128 v[186:189], v216 offset:2048
	ds_read_b128 v[190:193], v216 offset:3072
	ds_read_b128 v[194:197], v216 offset:4096
	ds_read_b128 v[198:201], v216 offset:5120
	ds_read_b128 v[202:205], v216 offset:6144
	ds_read_b128 v[206:209], v216 offset:7168
	global_load_lds_dwordx4 v[210:211], off
	v_lshl_add_u64 v[210:211], s[22:23], 0, v[156:157]
	s_add_i32 m0, s37, 0xe000
	s_nop 0
	global_load_lds_dwordx4 v[210:211], off
	s_waitcnt vmcnt(8)
	s_waitcnt lgkmcnt(0)
	s_setprio 1
	s_barrier
; #define PG8_STAGE(bufoff, gbase, voff) do { _Pragma("unroll") for (int _i = 0; _i < 2; ++_i) \
;         __builtin_amdgcn_global_load_lds((const unsigned*)((const char*)(gbase) + (voff)[_i]), (PG8_LAS unsigned*)(lds + (bufoff) + ldsw + _i * 8192), 16, 0, 0); } while (0)
; #define PG8_LDA(dst, b, h) do { _Pragma("unroll") for (int m = 0; m < 4; ++m) _Pragma("unroll") for (int k = 0; k < 2; ++k) dst[m][k] = *(const PG8_LAS bf16x8*)(lds + PG8_SA(b, h) + aoff + m * 2048 + k * 1024); } while (0)
; #define PG8_LDB(dst, b, h) do { _Pragma("unroll") for (int n = 0; n < 2; ++n) _Pragma("unroll") for (int k = 0; k < 2; ++k) dst[n][k] = *(const PG8_LAS bf16x8*)(lds + PG8_SB(b, h) + boff + n * 2048 + k * 1024); } while (0)
; #define PG8_MMA(ai, bj, At, Bt) do { __builtin_amdgcn_s_setprio(1); _Pragma("unroll") for (int m = 0; m < 4; ++m) _Pragma("unroll") for (int n = 0; n < 2; ++n) _Pragma("unroll") for (int k = 0; k < 2; ++k) \
;         acc[ai][bj][m][n] = __builtin_amdgcn_mfma_f32_16x16x32_bf16(Bt[n][k], At[m][k], acc[ai][bj][m][n], 0, 0, 0); __builtin_amdgcn_s_setprio(0); } while (0)
; #define PG8_WAIT_V(n) asm volatile("s_waitcnt vmcnt(" #n ")" ::: "memory")
; #define PG8_WAIT_L(n) asm volatile("s_waitcnt lgkmcnt(" #n ")" ::: "memory")
; #define PG8_BAR __builtin_amdgcn_s_barrier()
; #define PG8_SCHED __builtin_amdgcn_sched_barrier(0)
; template <class Epi, class Sched, bool ALIGN_EPI = false, bool SP2 = false>
; __device__ __forceinline__ void gemm_phase(PG8_LAS unsigned char* lds, const Gemm g, const Sched& S, const Epi& E, const int wave_in) {
;     ...
;             PG8_LDB(B0, 0, 0); PG8_LDB(B1, 0, 1); PG8_SCHED; PG8_LDA(At, 0, 0); PG8_STAGE(PG8_SA(1, 1), a1 + hstepA, voffA);
;             PG8_WAIT_V(8); PG8_WAIT_L(0); PG8_BAR; PG8_MMA(0, 0, At, B0); PG8_MMA(0, 1, At, B1); PG8_BAR; PG8_SCHED;
;             PG8_LDA(At, 0, 1); PG8_STAGE(PG8_SB(0, 0), b2, voffB); PG8_STAGE(PG8_SB(0, 1), b2 + hstepB, voffB); PG8_STAGE(PG8_SA(0, 0), a2, voffA);
;             PG8_WAIT_V(8); PG8_WAIT_L(0); PG8_BAR; PG8_MMA(1, 0, At, B0); PG8_MMA(1, 1, At, B1); PG8_BAR; PG8_SCHED;
;             PG8_LDB(B0, 1, 0); PG8_LDB(B1, 1, 1); PG8_SCHED; PG8_LDA(At, 1, 0); PG8_STAGE(PG8_SA(0, 1), a2 + hstepA, voffA);
;             PG8_WAIT_V(8); PG8_WAIT_L(0); PG8_BAR; PG8_MMA(0, 0, At, B0); PG8_MMA(0, 1, At, B1); PG8_BAR; PG8_SCHED;
	v_mfma_f32_16x16x32_bf16 v[124:127], v[128:131], v[178:181], v[124:127]
	v_mfma_f32_16x16x32_bf16 v[120:123], v[136:139], v[178:181], v[120:123]
	v_mfma_f32_16x16x32_bf16 v[112:115], v[128:131], v[186:189], v[112:115]
	v_mfma_f32_16x16x32_bf16 v[104:107], v[136:139], v[186:189], v[104:107]
	v_mfma_f32_16x16x32_bf16 v[100:103], v[128:131], v[194:197], v[100:103]
	v_mfma_f32_16x16x32_bf16 v[96:99], v[136:139], v[194:197], v[96:99]
	v_mfma_f32_16x16x32_bf16 v[76:79], v[128:131], v[202:205], v[76:79]
	v_mfma_f32_16x16x32_bf16 v[72:75], v[136:139], v[202:205], v[72:75]
	v_mfma_f32_16x16x32_bf16 v[124:127], v[132:135], v[182:185], v[124:127]
	v_mfma_f32_16x16x32_bf16 v[120:123], v[140:143], v[182:185], v[120:123]
	v_mfma_f32_16x16x32_bf16 v[112:115], v[132:135], v[190:193], v[112:115]
	v_mfma_f32_16x16x32_bf16 v[104:107], v[140:143], v[190:193], v[104:107]
	v_mfma_f32_16x16x32_bf16 v[100:103], v[132:135], v[198:201], v[100:103]
	v_mfma_f32_16x16x32_bf16 v[96:99], v[140:143], v[198:201], v[96:99]
	v_mfma_f32_16x16x32_bf16 v[76:79], v[132:135], v[206:209], v[76:79]
	v_mfma_f32_16x16x32_bf16 v[72:75], v[140:143], v[206:209], v[72:75]
	v_mfma_f32_16x16x32_bf16 v[116:119], v[162:165], v[178:181], v[116:119]
	v_mfma_f32_16x16x32_bf16 v[108:111], v[170:173], v[178:181], v[108:111]
	v_mfma_f32_16x16x32_bf16 v[92:95], v[162:165], v[186:189], v[92:95]
	v_mfma_f32_16x16x32_bf16 v[88:91], v[170:173], v[186:189], v[88:91]
	v_mfma_f32_16x16x32_bf16 v[84:87], v[162:165], v[194:197], v[84:87]
	v_mfma_f32_16x16x32_bf16 v[80:83], v[170:173], v[194:197], v[80:83]
	v_mfma_f32_16x16x32_bf16 v[68:71], v[162:165], v[202:205], v[68:71]
	v_mfma_f32_16x16x32_bf16 v[64:67], v[170:173], v[202:205], v[64:67]
	v_mfma_f32_16x16x32_bf16 v[116:119], v[166:169], v[182:185], v[116:119]
	v_mfma_f32_16x16x32_bf16 v[108:111], v[174:177], v[182:185], v[108:111]
	v_mfma_f32_16x16x32_bf16 v[92:95], v[166:169], v[190:193], v[92:95]
	v_mfma_f32_16x16x32_bf16 v[88:91], v[174:177], v[190:193], v[88:91]
	v_mfma_f32_16x16x32_bf16 v[84:87], v[166:169], v[198:201], v[84:87]
	v_mfma_f32_16x16x32_bf16 v[80:83], v[174:177], v[198:201], v[80:83]
	v_mfma_f32_16x16x32_bf16 v[68:71], v[166:169], v[206:209], v[68:71]
	v_mfma_f32_16x16x32_bf16 v[64:67], v[174:177], v[206:209], v[64:67]
	s_setprio 0
	s_barrier
	s_add_i32 s22, s47, s34
	v_lshl_add_u64 v[210:211], s[24:25], 0, v[148:149]
	s_mov_b32 m0, s22
	ds_read_b128 v[178:181], v216 offset:16384
	ds_read_b128 v[182:185], v216 offset:17408
	ds_read_b128 v[186:189], v216 offset:18432
	ds_read_b128 v[190:193], v216 offset:19456
	ds_read_b128 v[194:197], v216 offset:20480
	ds_read_b128 v[198:201], v216 offset:21504
	ds_read_b128 v[202:205], v216 offset:22528
	ds_read_b128 v[206:209], v216 offset:23552
	global_load_lds_dwordx4 v[210:211], off
	s_add_i32 m0, s22, 0x2000
	s_add_u32 s22, s24, 0x100000
	v_lshl_add_u64 v[218:219], s[24:25], 0, v[144:145]
	s_addc_u32 s23, s25, 0
	s_add_i32 s56, s48, s34
	global_load_lds_dwordx4 v[218:219], off
	v_lshl_add_u64 v[220:221], s[22:23], 0, v[148:149]
	s_mov_b32 m0, s56
	v_lshl_add_u64 v[222:223], s[26:27], 0, v[146:147]
	global_load_lds_dwordx4 v[220:221], off
	v_lshl_add_u64 v[220:221], s[22:23], 0, v[144:145]
	s_add_i32 m0, s56, 0x2000
	s_nop 0
	global_load_lds_dwordx4 v[220:221], off
	v_lshl_add_u64 v[220:221], s[26:27], 0, v[150:151]
	s_mov_b32 m0, s37
	s_nop 0
	global_load_lds_dwordx4 v[220:221], off
	s_mov_b32 m0, s38
	s_nop 0
	global_load_lds_dwordx4 v[222:223], off
	s_waitcnt vmcnt(8)
	s_waitcnt lgkmcnt(0)
	s_setprio 1
	s_barrier
	v_mfma_f32_16x16x32_bf16 v[60:63], v[128:131], v[178:181], v[60:63]
	v_mfma_f32_16x16x32_bf16 v[56:59], v[136:139], v[178:181], v[56:59]
	v_mfma_f32_16x16x32_bf16 v[48:51], v[128:131], v[186:189], v[48:51]
	v_mfma_f32_16x16x32_bf16 v[40:43], v[136:139], v[186:189], v[40:43]
	v_mfma_f32_16x16x32_bf16 v[32:35], v[128:131], v[194:197], v[32:35]
	v_mfma_f32_16x16x32_bf16 v[24:27], v[136:139], v[194:197], v[24:27]
	v_mfma_f32_16x16x32_bf16 v[16:19], v[128:131], v[202:205], v[16:19]
	v_mfma_f32_16x16x32_bf16 v[8:11], v[136:139], v[202:205], v[8:11]
	v_mfma_f32_16x16x32_bf16 v[60:63], v[132:135], v[182:185], v[60:63]
	v_mfma_f32_16x16x32_bf16 v[56:59], v[140:143], v[182:185], v[56:59]
	v_mfma_f32_16x16x32_bf16 v[48:51], v[132:135], v[190:193], v[48:51]
	v_mfma_f32_16x16x32_bf16 v[40:43], v[140:143], v[190:193], v[40:43]
	v_mfma_f32_16x16x32_bf16 v[32:35], v[132:135], v[198:201], v[32:35]
	v_mfma_f32_16x16x32_bf16 v[24:27], v[140:143], v[198:201], v[24:27]
	v_mfma_f32_16x16x32_bf16 v[16:19], v[132:135], v[206:209], v[16:19]
	v_mfma_f32_16x16x32_bf16 v[8:11], v[140:143], v[206:209], v[8:11]
	v_mfma_f32_16x16x32_bf16 v[52:55], v[162:165], v[178:181], v[52:55]
	v_mfma_f32_16x16x32_bf16 v[44:47], v[170:173], v[178:181], v[44:47]
	v_mfma_f32_16x16x32_bf16 v[36:39], v[162:165], v[186:189], v[36:39]
	v_mfma_f32_16x16x32_bf16 v[28:31], v[170:173], v[186:189], v[28:31]
	v_mfma_f32_16x16x32_bf16 v[20:23], v[162:165], v[194:197], v[20:23]
	v_mfma_f32_16x16x32_bf16 v[12:15], v[170:173], v[194:197], v[12:15]
	v_mfma_f32_16x16x32_bf16 v[4:7], v[162:165], v[202:205], v[4:7]
	v_mfma_f32_16x16x32_bf16 v[0:3], v[170:173], v[202:205], v[0:3]
	v_mfma_f32_16x16x32_bf16 v[52:55], v[166:169], v[182:185], v[52:55]
	v_mfma_f32_16x16x32_bf16 v[44:47], v[174:177], v[182:185], v[44:47]
	v_mfma_f32_16x16x32_bf16 v[36:39], v[166:169], v[190:193], v[36:39]
	v_mfma_f32_16x16x32_bf16 v[28:31], v[174:177], v[190:193], v[28:31]
	v_mfma_f32_16x16x32_bf16 v[20:23], v[166:169], v[198:201], v[20:23]
	v_mfma_f32_16x16x32_bf16 v[12:15], v[174:177], v[198:201], v[12:15]
	v_mfma_f32_16x16x32_bf16 v[4:7], v[166:169], v[206:209], v[4:7]
	v_mfma_f32_16x16x32_bf16 v[0:3], v[174:177], v[206:209], v[0:3]
	s_setprio 0
	s_barrier
; #define PG8_STAGE(bufoff, gbase, voff) do { _Pragma("unroll") for (int _i = 0; _i < 2; ++_i) \
;         __builtin_amdgcn_global_load_lds((const unsigned*)((const char*)(gbase) + (voff)[_i]), (PG8_LAS unsigned*)(lds + (bufoff) + ldsw + _i * 8192), 16, 0, 0); } while (0)
; #define PG8_LDA(dst, b, h) do { _Pragma("unroll") for (int m = 0; m < 4; ++m) _Pragma("unroll") for (int k = 0; k < 2; ++k) dst[m][k] = *(const PG8_LAS bf16x8*)(lds + PG8_SA(b, h) + aoff + m * 2048 + k * 1024); } while (0)
; #define PG8_LDB(dst, b, h) do { _Pragma("unroll") for (int n = 0; n < 2; ++n) _Pragma("unroll") for (int k = 0; k < 2; ++k) dst[n][k] = *(const PG8_LAS bf16x8*)(lds + PG8_SB(b, h) + boff + n * 2048 + k * 1024); } while (0)
; #define PG8_MMA(ai, bj, At, Bt) do { __builtin_amdgcn_s_setprio(1); _Pragma("unroll") for (int m = 0; m < 4; ++m) _Pragma("unroll") for (int n = 0; n < 2; ++n) _Pragma("unroll") for (int k = 0; k < 2; ++k) \
;         acc[ai][bj][m][n] = __builtin_amdgcn_mfma_f32_16x16x32_bf16(Bt[n][k], At[m][k], acc[ai][bj][m][n], 0, 0, 0); __builtin_amdgcn_s_setprio(0); } while (0)
; #define PG8_WAIT_V(n) asm volatile("s_waitcnt vmcnt(" #n ")" ::: "memory")
; #define PG8_WAIT_L(n) asm volatile("s_waitcnt lgkmcnt(" #n ")" ::: "memory")
; #define PG8_BAR __builtin_amdgcn_s_barrier()
; #define PG8_SCHED __builtin_amdgcn_sched_barrier(0)
; template <class Epi, class Sched, bool ALIGN_EPI = false, bool SP2 = false>
; __device__ __forceinline__ void gemm_phase(PG8_LAS unsigned char* lds, const Gemm g, const Sched& S, const Epi& E, const int wave_in) {
;     ...
;             PG8_LDB(B0, 1, 0); PG8_LDB(B1, 1, 1); PG8_SCHED; PG8_LDA(At, 1, 0); PG8_STAGE(PG8_SA(0, 1), a2 + hstepA, voffA);
;             PG8_WAIT_V(8); PG8_WAIT_L(0); PG8_BAR; PG8_MMA(0, 0, At, B0); PG8_MMA(0, 1, At, B1); PG8_BAR; PG8_SCHED;
;             PG8_LDA(At, 1, 1); PG8_STAGE(PG8_SB(1, 0), b3, voffB); PG8_STAGE(PG8_SB(1, 1), b3 + hstepB, voffB); PG8_STAGE(PG8_SA(1, 0), a3, voffA);
;             PG8_WAIT_V(8); PG8_WAIT_L(0); PG8_BAR; PG8_MMA(1, 0, At, B0); PG8_MMA(1, 1, At, B1); PG8_BAR; PG8_SCHED;
	s_add_i32 s56, 0, 0x18000
	s_add_i32 s57, 0, 0x1c000
	v_add_u32_e32 v140, s56, v212
	v_add_u32_e32 v174, s57, v212
	ds_read_b128 v[128:131], v140
	ds_read_b128 v[132:135], v140 offset:1024
	ds_read_b128 v[136:139], v140 offset:2048
	ds_read_b128 v[140:143], v140 offset:3072
	ds_read_b128 v[162:165], v174
	ds_read_b128 v[166:169], v174 offset:1024
	ds_read_b128 v[170:173], v174 offset:2048
	ds_read_b128 v[174:177], v174 offset:3072
	s_add_u32 s22, s26, 0x310000
	s_addc_u32 s23, s27, 0
	s_mov_b32 m0, s39
	v_lshl_add_u64 v[224:225], s[22:23], 0, v[150:151]
	ds_read_b128 v[178:181], v216 offset:32768
	ds_read_b128 v[182:185], v216 offset:33792
	ds_read_b128 v[186:189], v216 offset:34816
	ds_read_b128 v[190:193], v216 offset:35840
	ds_read_b128 v[194:197], v216 offset:36864
	ds_read_b128 v[198:201], v216 offset:37888
	ds_read_b128 v[202:205], v216 offset:38912
	ds_read_b128 v[206:209], v216 offset:39936
	global_load_lds_dwordx4 v[224:225], off
	v_lshl_add_u64 v[224:225], s[22:23], 0, v[146:147]
	s_mov_b32 m0, s40
	s_nop 0
	global_load_lds_dwordx4 v[224:225], off
	s_waitcnt vmcnt(8)
	s_waitcnt lgkmcnt(0)
	s_setprio 1
	s_barrier
	v_mfma_f32_16x16x32_bf16 v[124:127], v[128:131], v[178:181], v[124:127]
	v_mfma_f32_16x16x32_bf16 v[120:123], v[136:139], v[178:181], v[120:123]
	v_mfma_f32_16x16x32_bf16 v[112:115], v[128:131], v[186:189], v[112:115]
	v_mfma_f32_16x16x32_bf16 v[104:107], v[136:139], v[186:189], v[104:107]
	v_mfma_f32_16x16x32_bf16 v[100:103], v[128:131], v[194:197], v[100:103]
	v_mfma_f32_16x16x32_bf16 v[96:99], v[136:139], v[194:197], v[96:99]
	v_mfma_f32_16x16x32_bf16 v[76:79], v[128:131], v[202:205], v[76:79]
	v_mfma_f32_16x16x32_bf16 v[72:75], v[136:139], v[202:205], v[72:75]
	v_mfma_f32_16x16x32_bf16 v[124:127], v[132:135], v[182:185], v[124:127]
	v_mfma_f32_16x16x32_bf16 v[120:123], v[140:143], v[182:185], v[120:123]
	v_mfma_f32_16x16x32_bf16 v[112:115], v[132:135], v[190:193], v[112:115]
	v_mfma_f32_16x16x32_bf16 v[104:107], v[140:143], v[190:193], v[104:107]
	v_mfma_f32_16x16x32_bf16 v[100:103], v[132:135], v[198:201], v[100:103]
	v_mfma_f32_16x16x32_bf16 v[96:99], v[140:143], v[198:201], v[96:99]
	v_mfma_f32_16x16x32_bf16 v[76:79], v[132:135], v[206:209], v[76:79]
	v_mfma_f32_16x16x32_bf16 v[72:75], v[140:143], v[206:209], v[72:75]
	v_mfma_f32_16x16x32_bf16 v[116:119], v[162:165], v[178:181], v[116:119]
	v_mfma_f32_16x16x32_bf16 v[108:111], v[170:173], v[178:181], v[108:111]
	v_mfma_f32_16x16x32_bf16 v[92:95], v[162:165], v[186:189], v[92:95]
	v_mfma_f32_16x16x32_bf16 v[88:91], v[170:173], v[186:189], v[88:91]
	v_mfma_f32_16x16x32_bf16 v[84:87], v[162:165], v[194:197], v[84:87]
	v_mfma_f32_16x16x32_bf16 v[80:83], v[170:173], v[194:197], v[80:83]
	v_mfma_f32_16x16x32_bf16 v[68:71], v[162:165], v[202:205], v[68:71]
	v_mfma_f32_16x16x32_bf16 v[64:67], v[170:173], v[202:205], v[64:67]
	v_mfma_f32_16x16x32_bf16 v[116:119], v[166:169], v[182:185], v[116:119]
	v_mfma_f32_16x16x32_bf16 v[108:111], v[174:177], v[182:185], v[108:111]
	v_mfma_f32_16x16x32_bf16 v[92:95], v[166:169], v[190:193], v[92:95]
	v_mfma_f32_16x16x32_bf16 v[88:91], v[174:177], v[190:193], v[88:91]
	v_mfma_f32_16x16x32_bf16 v[84:87], v[166:169], v[198:201], v[84:87]
	v_mfma_f32_16x16x32_bf16 v[80:83], v[174:177], v[198:201], v[80:83]
	v_mfma_f32_16x16x32_bf16 v[68:71], v[166:169], v[206:209], v[68:71]
	v_mfma_f32_16x16x32_bf16 v[64:67], v[174:177], v[206:209], v[64:67]
	s_setprio 0
	s_barrier
	s_add_i32 s22, s56, s34
	v_lshl_add_u64 v[210:211], v[210:211], 0, s[6:7]
	s_mov_b32 m0, s22
	ds_read_b128 v[178:181], v216 offset:49152
	ds_read_b128 v[182:185], v216 offset:50176
	ds_read_b128 v[186:189], v216 offset:51200
	ds_read_b128 v[190:193], v216 offset:52224
	ds_read_b128 v[194:197], v216 offset:53248
	ds_read_b128 v[198:201], v216 offset:54272
	ds_read_b128 v[202:205], v216 offset:55296
	ds_read_b128 v[206:209], v216 offset:56320
	global_load_lds_dwordx4 v[210:211], off
	s_add_i32 m0, s22, 0x2000
	s_add_u32 s22, s24, 0x100080
	v_lshl_add_u64 v[210:211], v[218:219], 0, s[6:7]
	s_addc_u32 s23, s25, 0
	s_add_i32 s24, s57, s34
	global_load_lds_dwordx4 v[210:211], off
	v_lshl_add_u64 v[210:211], s[22:23], 0, v[148:149]
	s_mov_b32 m0, s24
	s_nop 0
	global_load_lds_dwordx4 v[210:211], off
	v_lshl_add_u64 v[210:211], s[22:23], 0, v[144:145]
	s_add_i32 m0, s24, 0x2000
	s_nop 0
	global_load_lds_dwordx4 v[210:211], off
	v_lshl_add_u64 v[210:211], v[220:221], 0, s[6:7]
	s_mov_b32 m0, s44
	s_nop 0
	global_load_lds_dwordx4 v[210:211], off
	v_lshl_add_u64 v[210:211], v[222:223], 0, s[6:7]
	s_mov_b32 m0, s45
	s_nop 0
	global_load_lds_dwordx4 v[210:211], off
	s_waitcnt vmcnt(8)
	s_waitcnt lgkmcnt(0)
	s_setprio 1
	s_barrier
	v_mfma_f32_16x16x32_bf16 v[60:63], v[128:131], v[178:181], v[60:63]
	v_mfma_f32_16x16x32_bf16 v[56:59], v[136:139], v[178:181], v[56:59]
	v_mfma_f32_16x16x32_bf16 v[48:51], v[128:131], v[186:189], v[48:51]
	v_mfma_f32_16x16x32_bf16 v[40:43], v[136:139], v[186:189], v[40:43]
	v_mfma_f32_16x16x32_bf16 v[32:35], v[128:131], v[194:197], v[32:35]
	v_mfma_f32_16x16x32_bf16 v[24:27], v[136:139], v[194:197], v[24:27]
	v_mfma_f32_16x16x32_bf16 v[16:19], v[128:131], v[202:205], v[16:19]
	v_mfma_f32_16x16x32_bf16 v[8:11], v[136:139], v[202:205], v[8:11]
	v_mfma_f32_16x16x32_bf16 v[60:63], v[132:135], v[182:185], v[60:63]
	v_mfma_f32_16x16x32_bf16 v[56:59], v[140:143], v[182:185], v[56:59]
	v_mfma_f32_16x16x32_bf16 v[48:51], v[132:135], v[190:193], v[48:51]
	v_mfma_f32_16x16x32_bf16 v[40:43], v[140:143], v[190:193], v[40:43]
	v_mfma_f32_16x16x32_bf16 v[32:35], v[132:135], v[198:201], v[32:35]
	v_mfma_f32_16x16x32_bf16 v[24:27], v[140:143], v[198:201], v[24:27]
	v_mfma_f32_16x16x32_bf16 v[16:19], v[132:135], v[206:209], v[16:19]
	v_mfma_f32_16x16x32_bf16 v[8:11], v[140:143], v[206:209], v[8:11]
	v_mfma_f32_16x16x32_bf16 v[52:55], v[162:165], v[178:181], v[52:55]
	v_mfma_f32_16x16x32_bf16 v[44:47], v[170:173], v[178:181], v[44:47]
	v_mfma_f32_16x16x32_bf16 v[36:39], v[162:165], v[186:189], v[36:39]
	v_mfma_f32_16x16x32_bf16 v[28:31], v[170:173], v[186:189], v[28:31]
	v_mfma_f32_16x16x32_bf16 v[20:23], v[162:165], v[194:197], v[20:23]
	v_mfma_f32_16x16x32_bf16 v[12:15], v[170:173], v[194:197], v[12:15]
	v_mfma_f32_16x16x32_bf16 v[4:7], v[162:165], v[202:205], v[4:7]
	v_mfma_f32_16x16x32_bf16 v[0:3], v[170:173], v[202:205], v[0:3]
	v_mfma_f32_16x16x32_bf16 v[52:55], v[166:169], v[182:185], v[52:55]
	v_mfma_f32_16x16x32_bf16 v[44:47], v[174:177], v[182:185], v[44:47]
	v_mfma_f32_16x16x32_bf16 v[36:39], v[166:169], v[190:193], v[36:39]
	v_mfma_f32_16x16x32_bf16 v[28:31], v[174:177], v[190:193], v[28:31]
	v_mfma_f32_16x16x32_bf16 v[20:23], v[166:169], v[198:201], v[20:23]
	v_mfma_f32_16x16x32_bf16 v[12:15], v[174:177], v[198:201], v[12:15]
	v_mfma_f32_16x16x32_bf16 v[4:7], v[166:169], v[206:209], v[4:7]
	v_mfma_f32_16x16x32_bf16 v[0:3], v[174:177], v[206:209], v[0:3]
	s_setprio 0
	s_barrier
	s_add_i32 s55, s55, 2
	s_add_u32 s53, s53, 0x100
	s_addc_u32 s54, s54, 0
	s_cmp_gt_u32 s55, 61
	s_mov_b64 s[22:23], s[4:5]
	s_cbranch_scc0 .LBB0_1093

;     __host__ __device__ bool next(int i, Unit& u) const { const bool ok = StaticOrder::next(i, u); u.pm = 0; u.pn = 0; return ok; }
; #define PG8_STAGE(bufoff, gbase, voff) do { _Pragma("unroll") for (int _i = 0; _i < 2; ++_i) \
;         __builtin_amdgcn_global_load_lds((const unsigned*)((const char*)(gbase) + (voff)[_i]), (PG8_LAS unsigned*)(lds + (bufoff) + ldsw + _i * 8192), 16, 0, 0); } while (0)
; #define PG8_LDA(dst, b, h) do { _Pragma("unroll") for (int m = 0; m < 4; ++m) _Pragma("unroll") for (int k = 0; k < 2; ++k) dst[m][k] = *(const PG8_LAS bf16x8*)(lds + PG8_SA(b, h) + aoff + m * 2048 + k * 1024); } while (0)
; #define PG8_LDB(dst, b, h) do { _Pragma("unroll") for (int n = 0; n < 2; ++n) _Pragma("unroll") for (int k = 0; k < 2; ++k) dst[n][k] = *(const PG8_LAS bf16x8*)(lds + PG8_SB(b, h) + boff + n * 2048 + k * 1024); } while (0)
; #define PG8_WAIT_V(n) asm volatile("s_waitcnt vmcnt(" #n ")" ::: "memory")
; #define PG8_BAR __builtin_amdgcn_s_barrier()
; template <class Epi, class Sched, bool ALIGN_EPI = false, bool SP2 = false>
; __device__ __forceinline__ void gemm_phase(PG8_LAS unsigned char* lds, const Gemm g, const Sched& S, const Epi& E, const int wave_in) {
;     ...
;         const bool has_next = S.next(ui + 1, nxt);
;         const char* nA = has_next ? (const char*)g.A + (size_t)nxt.pm * tstepA : cA; const char* nB = has_next ? (const char*)g.Bt + (size_t)nxt.pn * tstepB : cB;
;         for (int t = 0; t < nt; t += 2) {
;             const bool last = (t == nt - 2);
;             const char* a1 = cA + (size_t)(t + 1) * kstep;
;             const char* a2 = last ? nA : cA + (size_t)(t + 2) * kstep; const char* b2 = last ? nB : cB + (size_t)(t + 2) * kstep;
;             const char* a3 = a2 + kstep; const char* b3 = b2 + kstep;
;             if (last && has_next) S.a_ready(nxt);
;             if constexpr (SP2) {
;             PG8_LDB(B0, 0, 0); PG8_LDB(B1, 0, 1); PG8_SCHED; PG8_LDA(At, 0, 0); PG8_STAGE(PG8_SA(1, 1), a1 + hstepA, voffA);
;             PG8_WAIT_V(8); PG8_WAIT_L(0); PG8_BAR; PG8_MMA(0, 0, At, B0); PG8_MMA(0, 1, At, B1); PG8_BAR; PG8_SCHED;
;             PG8_LDA(At, 0, 1); PG8_STAGE(PG8_SB(0, 0), b2, voffB); PG8_STAGE(PG8_SB(0, 1), b2 + hstepB, voffB); PG8_STAGE(PG8_SA(0, 0), a2, voffA);
;             PG8_WAIT_V(8); PG8_WAIT_L(0); PG8_BAR; PG8_MMA(1, 0, At, B0); PG8_MMA(1, 1, At, B1); PG8_BAR; PG8_SCHED;
.LBB0_1374:
	s_add_u32 s17, s20, 0x100
	v_mov_b32_e32 v0, 0
	s_addc_u32 s53, s21, 0
	s_mov_b32 s54, -2
	ds_read_b128 v[128:131], v214
	ds_read_b128 v[132:135], v214 offset:1024
	ds_read_b128 v[136:139], v214 offset:2048
	ds_read_b128 v[140:143], v214 offset:3072
	ds_read_b128 v[162:165], v215
	ds_read_b128 v[166:169], v215 offset:1024
	ds_read_b128 v[170:173], v215 offset:2048
	ds_read_b128 v[174:177], v215 offset:3072
	s_add_u32 s20, s18, 0x100
	s_addc_u32 s21, s19, 0
	s_cmpk_eq_i32 s54, 0x52
	s_cselect_b32 s25, s5, s21
	s_cselect_b32 s24, s4, s20
	s_cselect_b32 s23, s15, s53
	s_cselect_b32 s22, s14, s17
	v_lshl_add_u64 v[210:211], s[18:19], 0, v[154:155]
	s_add_i32 m0, s35, 0xc000
	ds_read_b128 v[178:181], v216
	ds_read_b128 v[182:185], v216 offset:1024
	ds_read_b128 v[186:189], v216 offset:2048
	ds_read_b128 v[190:193], v216 offset:3072
	ds_read_b128 v[194:197], v216 offset:4096
	ds_read_b128 v[198:201], v216 offset:5120
	ds_read_b128 v[202:205], v216 offset:6144
	ds_read_b128 v[206:209], v216 offset:7168
	global_load_lds_dwordx4 v[210:211], off
	v_lshl_add_u64 v[210:211], s[18:19], 0, v[156:157]
	s_add_i32 m0, s35, 0xe000
	s_nop 0
	global_load_lds_dwordx4 v[210:211], off
	s_waitcnt vmcnt(8)
	s_waitcnt lgkmcnt(0)
	s_setprio 1
	s_barrier
	v_mfma_f32_16x16x32_bf16 v[124:127], v[128:131], v[178:181], 0
	v_mfma_f32_16x16x32_bf16 v[120:123], v[136:139], v[178:181], 0
	v_mfma_f32_16x16x32_bf16 v[112:115], v[128:131], v[186:189], 0
	v_mfma_f32_16x16x32_bf16 v[104:107], v[136:139], v[186:189], 0
	v_mfma_f32_16x16x32_bf16 v[100:103], v[128:131], v[194:197], 0
	v_mfma_f32_16x16x32_bf16 v[96:99], v[136:139], v[194:197], 0
	v_mfma_f32_16x16x32_bf16 v[76:79], v[128:131], v[202:205], 0
	v_mfma_f32_16x16x32_bf16 v[72:75], v[136:139], v[202:205], 0
	v_mfma_f32_16x16x32_bf16 v[124:127], v[132:135], v[182:185], v[124:127]
	v_mfma_f32_16x16x32_bf16 v[120:123], v[140:143], v[182:185], v[120:123]
	v_mfma_f32_16x16x32_bf16 v[112:115], v[132:135], v[190:193], v[112:115]
	v_mfma_f32_16x16x32_bf16 v[104:107], v[140:143], v[190:193], v[104:107]
	v_mfma_f32_16x16x32_bf16 v[100:103], v[132:135], v[198:201], v[100:103]
	v_mfma_f32_16x16x32_bf16 v[96:99], v[140:143], v[198:201], v[96:99]
	v_mfma_f32_16x16x32_bf16 v[76:79], v[132:135], v[206:209], v[76:79]
	v_mfma_f32_16x16x32_bf16 v[72:75], v[140:143], v[206:209], v[72:75]
	v_mfma_f32_16x16x32_bf16 v[116:119], v[162:165], v[178:181], 0
	v_mfma_f32_16x16x32_bf16 v[108:111], v[170:173], v[178:181], 0
	v_mfma_f32_16x16x32_bf16 v[92:95], v[162:165], v[186:189], 0
	v_mfma_f32_16x16x32_bf16 v[88:91], v[170:173], v[186:189], 0
	v_mfma_f32_16x16x32_bf16 v[84:87], v[162:165], v[194:197], 0
	v_mfma_f32_16x16x32_bf16 v[80:83], v[170:173], v[194:197], 0
	v_mfma_f32_16x16x32_bf16 v[68:71], v[162:165], v[202:205], 0
	v_mfma_f32_16x16x32_bf16 v[64:67], v[170:173], v[202:205], 0
	v_mfma_f32_16x16x32_bf16 v[116:119], v[166:169], v[182:185], v[116:119]
	v_mfma_f32_16x16x32_bf16 v[108:111], v[174:177], v[182:185], v[108:111]
	v_mfma_f32_16x16x32_bf16 v[92:95], v[166:169], v[190:193], v[92:95]
	v_mfma_f32_16x16x32_bf16 v[88:91], v[174:177], v[190:193], v[88:91]
	v_mfma_f32_16x16x32_bf16 v[84:87], v[166:169], v[198:201], v[84:87]
	v_mfma_f32_16x16x32_bf16 v[80:83], v[174:177], v[198:201], v[80:83]
	v_mfma_f32_16x16x32_bf16 v[68:71], v[166:169], v[206:209], v[68:71]
	v_mfma_f32_16x16x32_bf16 v[64:67], v[174:177], v[206:209], v[64:67]
	s_setprio 0
	s_barrier
	s_add_i32 s18, s45, s30
	v_lshl_add_u64 v[210:211], s[22:23], 0, v[148:149]
	s_mov_b32 m0, s18
	ds_read_b128 v[178:181], v216 offset:16384
	ds_read_b128 v[182:185], v216 offset:17408
	ds_read_b128 v[186:189], v216 offset:18432
	ds_read_b128 v[190:193], v216 offset:19456
	ds_read_b128 v[194:197], v216 offset:20480
	ds_read_b128 v[198:201], v216 offset:21504
	ds_read_b128 v[202:205], v216 offset:22528
	ds_read_b128 v[206:209], v216 offset:23552
	global_load_lds_dwordx4 v[210:211], off
	s_add_i32 m0, s18, 0x2000
	s_add_u32 s18, s22, 0x158000
	v_lshl_add_u64 v[218:219], s[22:23], 0, v[144:145]
	s_addc_u32 s19, s23, 0
	s_add_i32 s55, s46, s30
	global_load_lds_dwordx4 v[218:219], off
	v_lshl_add_u64 v[220:221], s[18:19], 0, v[148:149]
	s_mov_b32 m0, s55
	v_lshl_add_u64 v[222:223], s[24:25], 0, v[146:147]
	global_load_lds_dwordx4 v[220:221], off
	v_lshl_add_u64 v[220:221], s[18:19], 0, v[144:145]
	s_add_i32 m0, s55, 0x2000
	s_nop 0
	global_load_lds_dwordx4 v[220:221], off
	v_lshl_add_u64 v[220:221], s[24:25], 0, v[150:151]
	s_mov_b32 m0, s35
	s_nop 0
	global_load_lds_dwordx4 v[220:221], off
	s_mov_b32 m0, s36
	s_nop 0
	global_load_lds_dwordx4 v[222:223], off
	s_waitcnt vmcnt(8)
	s_waitcnt lgkmcnt(0)
	s_setprio 1
	s_barrier
; #define PG8_STAGE(bufoff, gbase, voff) do { _Pragma("unroll") for (int _i = 0; _i < 2; ++_i) \
;         __builtin_amdgcn_global_load_lds((const unsigned*)((const char*)(gbase) + (voff)[_i]), (PG8_LAS unsigned*)(lds + (bufoff) + ldsw + _i * 8192), 16, 0, 0); } while (0)
; #define PG8_LDA(dst, b, h) do { _Pragma("unroll") for (int m = 0; m < 4; ++m) _Pragma("unroll") for (int k = 0; k < 2; ++k) dst[m][k] = *(const PG8_LAS bf16x8*)(lds + PG8_SA(b, h) + aoff + m * 2048 + k * 1024); } while (0)
; #define PG8_LDB(dst, b, h) do { _Pragma("unroll") for (int n = 0; n < 2; ++n) _Pragma("unroll") for (int k = 0; k < 2; ++k) dst[n][k] = *(const PG8_LAS bf16x8*)(lds + PG8_SB(b, h) + boff + n * 2048 + k * 1024); } while (0)
; #define PG8_MMA(ai, bj, At, Bt) do { __builtin_amdgcn_s_setprio(1); _Pragma("unroll") for (int m = 0; m < 4; ++m) _Pragma("unroll") for (int n = 0; n < 2; ++n) _Pragma("unroll") for (int k = 0; k < 2; ++k) \
;         acc[ai][bj][m][n] = __builtin_amdgcn_mfma_f32_16x16x32_bf16(Bt[n][k], At[m][k], acc[ai][bj][m][n], 0, 0, 0); __builtin_amdgcn_s_setprio(0); } while (0)
; #define PG8_WAIT_V(n) asm volatile("s_waitcnt vmcnt(" #n ")" ::: "memory")
; #define PG8_WAIT_L(n) asm volatile("s_waitcnt lgkmcnt(" #n ")" ::: "memory")
; #define PG8_BAR __builtin_amdgcn_s_barrier()
; #define PG8_SCHED __builtin_amdgcn_sched_barrier(0)
; template <class Epi, class Sched, bool ALIGN_EPI = false, bool SP2 = false>
; __device__ __forceinline__ void gemm_phase(PG8_LAS unsigned char* lds, const Gemm g, const Sched& S, const Epi& E, const int wave_in) {
;     ...
;             PG8_WAIT_V(8); PG8_WAIT_L(0); PG8_BAR; PG8_MMA(1, 0, At, B0); PG8_MMA(1, 1, At, B1); PG8_BAR; PG8_SCHED;
;             PG8_LDB(B0, 1, 0); PG8_LDB(B1, 1, 1); PG8_SCHED; PG8_LDA(At, 1, 0); PG8_STAGE(PG8_SA(0, 1), a2 + hstepA, voffA);
;             PG8_WAIT_V(8); PG8_WAIT_L(0); PG8_BAR; PG8_MMA(0, 0, At, B0); PG8_MMA(0, 1, At, B1); PG8_BAR; PG8_SCHED;
	v_mfma_f32_16x16x32_bf16 v[60:63], v[128:131], v[178:181], 0
	v_mfma_f32_16x16x32_bf16 v[56:59], v[136:139], v[178:181], 0
	v_mfma_f32_16x16x32_bf16 v[48:51], v[128:131], v[186:189], 0
	v_mfma_f32_16x16x32_bf16 v[40:43], v[136:139], v[186:189], 0
	v_mfma_f32_16x16x32_bf16 v[32:35], v[128:131], v[194:197], 0
	v_mfma_f32_16x16x32_bf16 v[24:27], v[136:139], v[194:197], 0
	v_mfma_f32_16x16x32_bf16 v[16:19], v[128:131], v[202:205], 0
	v_mfma_f32_16x16x32_bf16 v[8:11], v[136:139], v[202:205], 0
	v_mfma_f32_16x16x32_bf16 v[60:63], v[132:135], v[182:185], v[60:63]
	v_mfma_f32_16x16x32_bf16 v[56:59], v[140:143], v[182:185], v[56:59]
	v_mfma_f32_16x16x32_bf16 v[48:51], v[132:135], v[190:193], v[48:51]
	v_mfma_f32_16x16x32_bf16 v[40:43], v[140:143], v[190:193], v[40:43]
	v_mfma_f32_16x16x32_bf16 v[32:35], v[132:135], v[198:201], v[32:35]
	v_mfma_f32_16x16x32_bf16 v[24:27], v[140:143], v[198:201], v[24:27]
	v_mfma_f32_16x16x32_bf16 v[16:19], v[132:135], v[206:209], v[16:19]
	v_mfma_f32_16x16x32_bf16 v[8:11], v[140:143], v[206:209], v[8:11]
	v_mfma_f32_16x16x32_bf16 v[52:55], v[162:165], v[178:181], 0
	v_mfma_f32_16x16x32_bf16 v[44:47], v[170:173], v[178:181], 0
	v_mfma_f32_16x16x32_bf16 v[36:39], v[162:165], v[186:189], 0
	v_mfma_f32_16x16x32_bf16 v[28:31], v[170:173], v[186:189], 0
	v_mfma_f32_16x16x32_bf16 v[20:23], v[162:165], v[194:197], 0
	v_mfma_f32_16x16x32_bf16 v[12:15], v[170:173], v[194:197], 0
	v_mfma_f32_16x16x32_bf16 v[4:7], v[162:165], v[202:205], 0
	v_mfma_f32_16x16x32_bf16 v[0:3], v[170:173], v[202:205], 0
	v_mfma_f32_16x16x32_bf16 v[52:55], v[166:169], v[182:185], v[52:55]
	v_mfma_f32_16x16x32_bf16 v[44:47], v[174:177], v[182:185], v[44:47]
	v_mfma_f32_16x16x32_bf16 v[36:39], v[166:169], v[190:193], v[36:39]
	v_mfma_f32_16x16x32_bf16 v[28:31], v[174:177], v[190:193], v[28:31]
	v_mfma_f32_16x16x32_bf16 v[20:23], v[166:169], v[198:201], v[20:23]
	v_mfma_f32_16x16x32_bf16 v[12:15], v[174:177], v[198:201], v[12:15]
	v_mfma_f32_16x16x32_bf16 v[4:7], v[166:169], v[206:209], v[4:7]
	v_mfma_f32_16x16x32_bf16 v[0:3], v[174:177], v[206:209], v[0:3]
	s_setprio 0
	s_barrier
	s_add_i32 s55, 0, 0x18000
	s_add_i32 s56, 0, 0x1c000
	v_add_u32_e32 v140, s55, v212
	v_add_u32_e32 v174, s56, v212
	ds_read_b128 v[128:131], v140
	ds_read_b128 v[132:135], v140 offset:1024
	ds_read_b128 v[136:139], v140 offset:2048
	ds_read_b128 v[140:143], v140 offset:3072
	ds_read_b128 v[162:165], v174
	ds_read_b128 v[166:169], v174 offset:1024
	ds_read_b128 v[170:173], v174 offset:2048
	ds_read_b128 v[174:177], v174 offset:3072
	s_add_u32 s18, s24, 0x158000
	s_addc_u32 s19, s25, 0
	s_mov_b32 m0, s37
	v_lshl_add_u64 v[224:225], s[18:19], 0, v[150:151]
	ds_read_b128 v[178:181], v216 offset:32768
	ds_read_b128 v[182:185], v216 offset:33792
	ds_read_b128 v[186:189], v216 offset:34816
	ds_read_b128 v[190:193], v216 offset:35840
	ds_read_b128 v[194:197], v216 offset:36864
	ds_read_b128 v[198:201], v216 offset:37888
	ds_read_b128 v[202:205], v216 offset:38912
	ds_read_b128 v[206:209], v216 offset:39936
	global_load_lds_dwordx4 v[224:225], off
	v_lshl_add_u64 v[224:225], s[18:19], 0, v[146:147]
	s_mov_b32 m0, s38
	s_nop 0
	global_load_lds_dwordx4 v[224:225], off
	s_waitcnt vmcnt(8)
	s_waitcnt lgkmcnt(0)
	s_setprio 1
	s_barrier
	v_mfma_f32_16x16x32_bf16 v[124:127], v[128:131], v[178:181], v[124:127]
	v_mfma_f32_16x16x32_bf16 v[120:123], v[136:139], v[178:181], v[120:123]
	v_mfma_f32_16x16x32_bf16 v[112:115], v[128:131], v[186:189], v[112:115]
	v_mfma_f32_16x16x32_bf16 v[104:107], v[136:139], v[186:189], v[104:107]
	v_mfma_f32_16x16x32_bf16 v[100:103], v[128:131], v[194:197], v[100:103]
	v_mfma_f32_16x16x32_bf16 v[96:99], v[136:139], v[194:197], v[96:99]
	v_mfma_f32_16x16x32_bf16 v[76:79], v[128:131], v[202:205], v[76:79]
	v_mfma_f32_16x16x32_bf16 v[72:75], v[136:139], v[202:205], v[72:75]
	v_mfma_f32_16x16x32_bf16 v[124:127], v[132:135], v[182:185], v[124:127]
	v_mfma_f32_16x16x32_bf16 v[120:123], v[140:143], v[182:185], v[120:123]
	v_mfma_f32_16x16x32_bf16 v[112:115], v[132:135], v[190:193], v[112:115]
	v_mfma_f32_16x16x32_bf16 v[104:107], v[140:143], v[190:193], v[104:107]
	v_mfma_f32_16x16x32_bf16 v[100:103], v[132:135], v[198:201], v[100:103]
	v_mfma_f32_16x16x32_bf16 v[96:99], v[140:143], v[198:201], v[96:99]
	v_mfma_f32_16x16x32_bf16 v[76:79], v[132:135], v[206:209], v[76:79]
	v_mfma_f32_16x16x32_bf16 v[72:75], v[140:143], v[206:209], v[72:75]
	v_mfma_f32_16x16x32_bf16 v[116:119], v[162:165], v[178:181], v[116:119]
	v_mfma_f32_16x16x32_bf16 v[108:111], v[170:173], v[178:181], v[108:111]
	v_mfma_f32_16x16x32_bf16 v[92:95], v[162:165], v[186:189], v[92:95]
	v_mfma_f32_16x16x32_bf16 v[88:91], v[170:173], v[186:189], v[88:91]
	v_mfma_f32_16x16x32_bf16 v[84:87], v[162:165], v[194:197], v[84:87]
	v_mfma_f32_16x16x32_bf16 v[80:83], v[170:173], v[194:197], v[80:83]
	v_mfma_f32_16x16x32_bf16 v[68:71], v[162:165], v[202:205], v[68:71]
	v_mfma_f32_16x16x32_bf16 v[64:67], v[170:173], v[202:205], v[64:67]
	v_mfma_f32_16x16x32_bf16 v[116:119], v[166:169], v[182:185], v[116:119]
	v_mfma_f32_16x16x32_bf16 v[108:111], v[174:177], v[182:185], v[108:111]
	v_mfma_f32_16x16x32_bf16 v[92:95], v[166:169], v[190:193], v[92:95]
	v_mfma_f32_16x16x32_bf16 v[88:91], v[174:177], v[190:193], v[88:91]
	v_mfma_f32_16x16x32_bf16 v[84:87], v[166:169], v[198:201], v[84:87]
	v_mfma_f32_16x16x32_bf16 v[80:83], v[174:177], v[198:201], v[80:83]
	v_mfma_f32_16x16x32_bf16 v[68:71], v[166:169], v[206:209], v[68:71]
	v_mfma_f32_16x16x32_bf16 v[64:67], v[174:177], v[206:209], v[64:67]
	s_setprio 0
	s_barrier
; #define PG8_STAGE(bufoff, gbase, voff) do { _Pragma("unroll") for (int _i = 0; _i < 2; ++_i) \
;         __builtin_amdgcn_global_load_lds((const unsigned*)((const char*)(gbase) + (voff)[_i]), (PG8_LAS unsigned*)(lds + (bufoff) + ldsw + _i * 8192), 16, 0, 0); } while (0)
; #define PG8_LDA(dst, b, h) do { _Pragma("unroll") for (int m = 0; m < 4; ++m) _Pragma("unroll") for (int k = 0; k < 2; ++k) dst[m][k] = *(const PG8_LAS bf16x8*)(lds + PG8_SA(b, h) + aoff + m * 2048 + k * 1024); } while (0)
; #define PG8_LDB(dst, b, h) do { _Pragma("unroll") for (int n = 0; n < 2; ++n) _Pragma("unroll") for (int k = 0; k < 2; ++k) dst[n][k] = *(const PG8_LAS bf16x8*)(lds + PG8_SB(b, h) + boff + n * 2048 + k * 1024); } while (0)
; #define PG8_WAIT_V(n) asm volatile("s_waitcnt vmcnt(" #n ")" ::: "memory")
; #define PG8_WAIT_L(n) asm volatile("s_waitcnt lgkmcnt(" #n ")" ::: "memory")
; #define PG8_BAR __builtin_amdgcn_s_barrier()
; template <class Epi, class Sched, bool ALIGN_EPI = false, bool SP2 = false>
; __device__ __forceinline__ void gemm_phase(PG8_LAS unsigned char* lds, const Gemm g, const Sched& S, const Epi& E, const int wave_in) {
;     ...
;         for (int t = 0; t < nt; t += 2) {
;             const bool last = (t == nt - 2);
;             const char* a1 = cA + (size_t)(t + 1) * kstep;
;             const char* a2 = last ? nA : cA + (size_t)(t + 2) * kstep; const char* b2 = last ? nB : cB + (size_t)(t + 2) * kstep;
;             const char* a3 = a2 + kstep; const char* b3 = b2 + kstep;
;             if (last && has_next) S.a_ready(nxt);
;             if constexpr (SP2) {
;             PG8_LDB(B0, 0, 0); PG8_LDB(B1, 0, 1); PG8_SCHED; PG8_LDA(At, 0, 0); PG8_STAGE(PG8_SA(1, 1), a1 + hstepA, voffA);
;             PG8_WAIT_V(8); PG8_WAIT_L(0); PG8_BAR; PG8_MMA(0, 0, At, B0); PG8_MMA(0, 1, At, B1); PG8_BAR; PG8_SCHED;
;             PG8_LDA(At, 0, 1); PG8_STAGE(PG8_SB(0, 0), b2, voffB); PG8_STAGE(PG8_SB(0, 1), b2 + hstepB, voffB); PG8_STAGE(PG8_SA(0, 0), a2, voffA);
;             PG8_WAIT_V(8); PG8_WAIT_L(0); PG8_BAR; PG8_MMA(1, 0, At, B0); PG8_MMA(1, 1, At, B1); PG8_BAR; PG8_SCHED;
;     ...
;             PG8_LDA(At, 1, 1); PG8_STAGE(PG8_SB(1, 0), b3, voffB); PG8_STAGE(PG8_SB(1, 1), b3 + hstepB, voffB); PG8_STAGE(PG8_SA(1, 0), a3, voffA);
;             PG8_WAIT_V(8); PG8_WAIT_L(0); PG8_BAR; PG8_MMA(1, 0, At, B0); PG8_MMA(1, 1, At, B1); PG8_BAR; PG8_SCHED;
	s_add_i32 s18, s55, s30
	v_lshl_add_u64 v[210:211], v[210:211], 0, s[6:7]
	s_mov_b32 m0, s18
	ds_read_b128 v[178:181], v216 offset:49152
	ds_read_b128 v[182:185], v216 offset:50176
	ds_read_b128 v[186:189], v216 offset:51200
	ds_read_b128 v[190:193], v216 offset:52224
	ds_read_b128 v[194:197], v216 offset:53248
	ds_read_b128 v[198:201], v216 offset:54272
	ds_read_b128 v[202:205], v216 offset:55296
	ds_read_b128 v[206:209], v216 offset:56320
	global_load_lds_dwordx4 v[210:211], off
	s_add_i32 m0, s18, 0x2000
	s_add_u32 s18, s22, 0x158080
	v_lshl_add_u64 v[210:211], v[218:219], 0, s[6:7]
	s_addc_u32 s19, s23, 0
	s_add_i32 s22, s56, s30
	global_load_lds_dwordx4 v[210:211], off
	v_lshl_add_u64 v[210:211], s[18:19], 0, v[148:149]
	s_mov_b32 m0, s22
	s_nop 0
	global_load_lds_dwordx4 v[210:211], off
	v_lshl_add_u64 v[210:211], s[18:19], 0, v[144:145]
	s_add_i32 m0, s22, 0x2000
	s_nop 0
	global_load_lds_dwordx4 v[210:211], off
	v_lshl_add_u64 v[210:211], v[220:221], 0, s[6:7]
	s_mov_b32 m0, s42
	s_nop 0
	global_load_lds_dwordx4 v[210:211], off
	v_lshl_add_u64 v[210:211], v[222:223], 0, s[6:7]
	s_mov_b32 m0, s43
	s_nop 0
	global_load_lds_dwordx4 v[210:211], off
	s_waitcnt vmcnt(8)
	s_waitcnt lgkmcnt(0)
	s_setprio 1
	s_barrier
	v_mfma_f32_16x16x32_bf16 v[60:63], v[128:131], v[178:181], v[60:63]
	v_mfma_f32_16x16x32_bf16 v[56:59], v[136:139], v[178:181], v[56:59]
	v_mfma_f32_16x16x32_bf16 v[48:51], v[128:131], v[186:189], v[48:51]
	v_mfma_f32_16x16x32_bf16 v[40:43], v[136:139], v[186:189], v[40:43]
	v_mfma_f32_16x16x32_bf16 v[32:35], v[128:131], v[194:197], v[32:35]
	v_mfma_f32_16x16x32_bf16 v[24:27], v[136:139], v[194:197], v[24:27]
	v_mfma_f32_16x16x32_bf16 v[16:19], v[128:131], v[202:205], v[16:19]
	v_mfma_f32_16x16x32_bf16 v[8:11], v[136:139], v[202:205], v[8:11]
	v_mfma_f32_16x16x32_bf16 v[60:63], v[132:135], v[182:185], v[60:63]
	v_mfma_f32_16x16x32_bf16 v[56:59], v[140:143], v[182:185], v[56:59]
	v_mfma_f32_16x16x32_bf16 v[48:51], v[132:135], v[190:193], v[48:51]
	v_mfma_f32_16x16x32_bf16 v[40:43], v[140:143], v[190:193], v[40:43]
	v_mfma_f32_16x16x32_bf16 v[32:35], v[132:135], v[198:201], v[32:35]
	v_mfma_f32_16x16x32_bf16 v[24:27], v[140:143], v[198:201], v[24:27]
	v_mfma_f32_16x16x32_bf16 v[16:19], v[132:135], v[206:209], v[16:19]
	v_mfma_f32_16x16x32_bf16 v[8:11], v[140:143], v[206:209], v[8:11]
	v_mfma_f32_16x16x32_bf16 v[52:55], v[162:165], v[178:181], v[52:55]
	v_mfma_f32_16x16x32_bf16 v[44:47], v[170:173], v[178:181], v[44:47]
	v_mfma_f32_16x16x32_bf16 v[36:39], v[162:165], v[186:189], v[36:39]
	v_mfma_f32_16x16x32_bf16 v[28:31], v[170:173], v[186:189], v[28:31]
	v_mfma_f32_16x16x32_bf16 v[20:23], v[162:165], v[194:197], v[20:23]
	v_mfma_f32_16x16x32_bf16 v[12:15], v[170:173], v[194:197], v[12:15]
	v_mfma_f32_16x16x32_bf16 v[4:7], v[162:165], v[202:205], v[4:7]
	v_mfma_f32_16x16x32_bf16 v[0:3], v[170:173], v[202:205], v[0:3]
	v_mfma_f32_16x16x32_bf16 v[52:55], v[166:169], v[182:185], v[52:55]
	v_mfma_f32_16x16x32_bf16 v[44:47], v[174:177], v[182:185], v[44:47]
	v_mfma_f32_16x16x32_bf16 v[36:39], v[166:169], v[190:193], v[36:39]
	v_mfma_f32_16x16x32_bf16 v[28:31], v[174:177], v[190:193], v[28:31]
	v_mfma_f32_16x16x32_bf16 v[20:23], v[166:169], v[198:201], v[20:23]
	v_mfma_f32_16x16x32_bf16 v[12:15], v[174:177], v[198:201], v[12:15]
	v_mfma_f32_16x16x32_bf16 v[4:7], v[166:169], v[206:209], v[4:7]
	v_mfma_f32_16x16x32_bf16 v[0:3], v[174:177], v[206:209], v[0:3]
	s_setprio 0
	s_barrier
	s_add_i32 s54, s54, 2
	s_add_u32 s17, s17, 0x100
	s_addc_u32 s53, s53, 0
	s_cmpk_gt_u32 s54, 0x53
	s_mov_b64 s[18:19], s[20:21]
	s_cbranch_scc0 .LBB0_1375
	s_branch .Lkx_16
.LBB0_1375:
	ds_read_b128 v[128:131], v214
	ds_read_b128 v[132:135], v214 offset:1024
	ds_read_b128 v[136:139], v214 offset:2048
	ds_read_b128 v[140:143], v214 offset:3072
	ds_read_b128 v[162:165], v215
	ds_read_b128 v[166:169], v215 offset:1024
	ds_read_b128 v[170:173], v215 offset:2048
	ds_read_b128 v[174:177], v215 offset:3072
	s_add_u32 s20, s18, 0x100
	s_addc_u32 s21, s19, 0
	s_cmpk_eq_i32 s54, 0x52
	s_cselect_b32 s25, s5, s21
	s_cselect_b32 s24, s4, s20
	s_cselect_b32 s23, s15, s53
	s_cselect_b32 s22, s14, s17
	v_lshl_add_u64 v[210:211], s[18:19], 0, v[154:155]
	s_add_i32 m0, s35, 0xc000
	ds_read_b128 v[178:181], v216
	ds_read_b128 v[182:185], v216 offset:1024
	ds_read_b128 v[186:189], v216 offset:2048
	ds_read_b128 v[190:193], v216 offset:3072
	ds_read_b128 v[194:197], v216 offset:4096
	ds_read_b128 v[198:201], v216 offset:5120
	ds_read_b128 v[202:205], v216 offset:6144
	ds_read_b128 v[206:209], v216 offset:7168
	global_load_lds_dwordx4 v[210:211], off
	v_lshl_add_u64 v[210:211], s[18:19], 0, v[156:157]
	s_add_i32 m0, s35, 0xe000
	s_nop 0
	global_load_lds_dwordx4 v[210:211], off
	s_waitcnt vmcnt(8)
	s_waitcnt lgkmcnt(0)
	s_setprio 1
	s_barrier
; #define PG8_STAGE(bufoff, gbase, voff) do { _Pragma("unroll") for (int _i = 0; _i < 2; ++_i) \
;         __builtin_amdgcn_global_load_lds((const unsigned*)((const char*)(gbase) + (voff)[_i]), (PG8_LAS unsigned*)(lds + (bufoff) + ldsw + _i * 8192), 16, 0, 0); } while (0)
; #define PG8_LDA(dst, b, h) do { _Pragma("unroll") for (int m = 0; m < 4; ++m) _Pragma("unroll") for (int k = 0; k < 2; ++k) dst[m][k] = *(const PG8_LAS bf16x8*)(lds + PG8_SA(b, h) + aoff + m * 2048 + k * 1024); } while (0)
; #define PG8_LDB(dst, b, h) do { _Pragma("unroll") for (int n = 0; n < 2; ++n) _Pragma("unroll") for (int k = 0; k < 2; ++k) dst[n][k] = *(const PG8_LAS bf16x8*)(lds + PG8_SB(b, h) + boff + n * 2048 + k * 1024); } while (0)
; #define PG8_MMA(ai, bj, At, Bt) do { __builtin_amdgcn_s_setprio(1); _Pragma("unroll") for (int m = 0; m < 4; ++m) _Pragma("unroll") for (int n = 0; n < 2; ++n) _Pragma("unroll") for (int k = 0; k < 2; ++k) \
;         acc[ai][bj][m][n] = __builtin_amdgcn_mfma_f32_16x16x32_bf16(Bt[n][k], At[m][k], acc[ai][bj][m][n], 0, 0, 0); __builtin_amdgcn_s_setprio(0); } while (0)
; #define PG8_WAIT_V(n) asm volatile("s_waitcnt vmcnt(" #n ")" ::: "memory")
; #define PG8_WAIT_L(n) asm volatile("s_waitcnt lgkmcnt(" #n ")" ::: "memory")
; #define PG8_BAR __builtin_amdgcn_s_barrier()
; #define PG8_SCHED __builtin_amdgcn_sched_barrier(0)
; template <class Epi, class Sched, bool ALIGN_EPI = false, bool SP2 = false>
; __device__ __forceinline__ void gemm_phase(PG8_LAS unsigned char* lds, const Gemm g, const Sched& S, const Epi& E, const int wave_in) {
;     ...
;             PG8_LDB(B0, 0, 0); PG8_LDB(B1, 0, 1); PG8_SCHED; PG8_LDA(At, 0, 0); PG8_STAGE(PG8_SA(1, 1), a1 + hstepA, voffA);
;             PG8_WAIT_V(8); PG8_WAIT_L(0); PG8_BAR; PG8_MMA(0, 0, At, B0); PG8_MMA(0, 1, At, B1); PG8_BAR; PG8_SCHED;
;             PG8_LDA(At, 0, 1); PG8_STAGE(PG8_SB(0, 0), b2, voffB); PG8_STAGE(PG8_SB(0, 1), b2 + hstepB, voffB); PG8_STAGE(PG8_SA(0, 0), a2, voffA);
;             PG8_WAIT_V(8); PG8_WAIT_L(0); PG8_BAR; PG8_MMA(1, 0, At, B0); PG8_MMA(1, 1, At, B1); PG8_BAR; PG8_SCHED;
;             PG8_LDB(B0, 1, 0); PG8_LDB(B1, 1, 1); PG8_SCHED; PG8_LDA(At, 1, 0); PG8_STAGE(PG8_SA(0, 1), a2 + hstepA, voffA);
;             PG8_WAIT_V(8); PG8_WAIT_L(0); PG8_BAR; PG8_MMA(0, 0, At, B0); PG8_MMA(0, 1, At, B1); PG8_BAR; PG8_SCHED;
	v_mfma_f32_16x16x32_bf16 v[124:127], v[128:131], v[178:181], v[124:127]
	v_mfma_f32_16x16x32_bf16 v[120:123], v[136:139], v[178:181], v[120:123]
	v_mfma_f32_16x16x32_bf16 v[112:115], v[128:131], v[186:189], v[112:115]
	v_mfma_f32_16x16x32_bf16 v[104:107], v[136:139], v[186:189], v[104:107]
	v_mfma_f32_16x16x32_bf16 v[100:103], v[128:131], v[194:197], v[100:103]
	v_mfma_f32_16x16x32_bf16 v[96:99], v[136:139], v[194:197], v[96:99]
	v_mfma_f32_16x16x32_bf16 v[76:79], v[128:131], v[202:205], v[76:79]
	v_mfma_f32_16x16x32_bf16 v[72:75], v[136:139], v[202:205], v[72:75]
	v_mfma_f32_16x16x32_bf16 v[124:127], v[132:135], v[182:185], v[124:127]
	v_mfma_f32_16x16x32_bf16 v[120:123], v[140:143], v[182:185], v[120:123]
	v_mfma_f32_16x16x32_bf16 v[112:115], v[132:135], v[190:193], v[112:115]
	v_mfma_f32_16x16x32_bf16 v[104:107], v[140:143], v[190:193], v[104:107]
	v_mfma_f32_16x16x32_bf16 v[100:103], v[132:135], v[198:201], v[100:103]
	v_mfma_f32_16x16x32_bf16 v[96:99], v[140:143], v[198:201], v[96:99]
	v_mfma_f32_16x16x32_bf16 v[76:79], v[132:135], v[206:209], v[76:79]
	v_mfma_f32_16x16x32_bf16 v[72:75], v[140:143], v[206:209], v[72:75]
	v_mfma_f32_16x16x32_bf16 v[116:119], v[162:165], v[178:181], v[116:119]
	v_mfma_f32_16x16x32_bf16 v[108:111], v[170:173], v[178:181], v[108:111]
	v_mfma_f32_16x16x32_bf16 v[92:95], v[162:165], v[186:189], v[92:95]
	v_mfma_f32_16x16x32_bf16 v[88:91], v[170:173], v[186:189], v[88:91]
	v_mfma_f32_16x16x32_bf16 v[84:87], v[162:165], v[194:197], v[84:87]
	v_mfma_f32_16x16x32_bf16 v[80:83], v[170:173], v[194:197], v[80:83]
	v_mfma_f32_16x16x32_bf16 v[68:71], v[162:165], v[202:205], v[68:71]
	v_mfma_f32_16x16x32_bf16 v[64:67], v[170:173], v[202:205], v[64:67]
	v_mfma_f32_16x16x32_bf16 v[116:119], v[166:169], v[182:185], v[116:119]
	v_mfma_f32_16x16x32_bf16 v[108:111], v[174:177], v[182:185], v[108:111]
	v_mfma_f32_16x16x32_bf16 v[92:95], v[166:169], v[190:193], v[92:95]
	v_mfma_f32_16x16x32_bf16 v[88:91], v[174:177], v[190:193], v[88:91]
	v_mfma_f32_16x16x32_bf16 v[84:87], v[166:169], v[198:201], v[84:87]
	v_mfma_f32_16x16x32_bf16 v[80:83], v[174:177], v[198:201], v[80:83]
	v_mfma_f32_16x16x32_bf16 v[68:71], v[166:169], v[206:209], v[68:71]
	v_mfma_f32_16x16x32_bf16 v[64:67], v[174:177], v[206:209], v[64:67]
	s_setprio 0
	s_barrier
	s_add_i32 s18, s45, s30
	v_lshl_add_u64 v[210:211], s[22:23], 0, v[148:149]
	s_mov_b32 m0, s18
	ds_read_b128 v[178:181], v216 offset:16384
	ds_read_b128 v[182:185], v216 offset:17408
	ds_read_b128 v[186:189], v216 offset:18432
	ds_read_b128 v[190:193], v216 offset:19456
	ds_read_b128 v[194:197], v216 offset:20480
	ds_read_b128 v[198:201], v216 offset:21504
	ds_read_b128 v[202:205], v216 offset:22528
	ds_read_b128 v[206:209], v216 offset:23552
	global_load_lds_dwordx4 v[210:211], off
	s_add_i32 m0, s18, 0x2000
	s_add_u32 s18, s22, 0x158000
	v_lshl_add_u64 v[218:219], s[22:23], 0, v[144:145]
	s_addc_u32 s19, s23, 0
	s_add_i32 s55, s46, s30
	global_load_lds_dwordx4 v[218:219], off
	v_lshl_add_u64 v[220:221], s[18:19], 0, v[148:149]
	s_mov_b32 m0, s55
	v_lshl_add_u64 v[222:223], s[24:25], 0, v[146:147]
	global_load_lds_dwordx4 v[220:221], off
	v_lshl_add_u64 v[220:221], s[18:19], 0, v[144:145]
	s_add_i32 m0, s55, 0x2000
	s_nop 0
	global_load_lds_dwordx4 v[220:221], off
	v_lshl_add_u64 v[220:221], s[24:25], 0, v[150:151]
	s_mov_b32 m0, s35
	s_nop 0
	global_load_lds_dwordx4 v[220:221], off
	s_mov_b32 m0, s36
	s_nop 0
	global_load_lds_dwordx4 v[222:223], off
	s_waitcnt vmcnt(8)
	s_waitcnt lgkmcnt(0)
	s_setprio 1
	s_barrier
	v_mfma_f32_16x16x32_bf16 v[60:63], v[128:131], v[178:181], v[60:63]
	v_mfma_f32_16x16x32_bf16 v[56:59], v[136:139], v[178:181], v[56:59]
	v_mfma_f32_16x16x32_bf16 v[48:51], v[128:131], v[186:189], v[48:51]
	v_mfma_f32_16x16x32_bf16 v[40:43], v[136:139], v[186:189], v[40:43]
	v_mfma_f32_16x16x32_bf16 v[32:35], v[128:131], v[194:197], v[32:35]
	v_mfma_f32_16x16x32_bf16 v[24:27], v[136:139], v[194:197], v[24:27]
	v_mfma_f32_16x16x32_bf16 v[16:19], v[128:131], v[202:205], v[16:19]
	v_mfma_f32_16x16x32_bf16 v[8:11], v[136:139], v[202:205], v[8:11]
	v_mfma_f32_16x16x32_bf16 v[60:63], v[132:135], v[182:185], v[60:63]
	v_mfma_f32_16x16x32_bf16 v[56:59], v[140:143], v[182:185], v[56:59]
	v_mfma_f32_16x16x32_bf16 v[48:51], v[132:135], v[190:193], v[48:51]
	v_mfma_f32_16x16x32_bf16 v[40:43], v[140:143], v[190:193], v[40:43]
	v_mfma_f32_16x16x32_bf16 v[32:35], v[132:135], v[198:201], v[32:35]
	v_mfma_f32_16x16x32_bf16 v[24:27], v[140:143], v[198:201], v[24:27]
	v_mfma_f32_16x16x32_bf16 v[16:19], v[132:135], v[206:209], v[16:19]
	v_mfma_f32_16x16x32_bf16 v[8:11], v[140:143], v[206:209], v[8:11]
	v_mfma_f32_16x16x32_bf16 v[52:55], v[162:165], v[178:181], v[52:55]
	v_mfma_f32_16x16x32_bf16 v[44:47], v[170:173], v[178:181], v[44:47]
	v_mfma_f32_16x16x32_bf16 v[36:39], v[162:165], v[186:189], v[36:39]
	v_mfma_f32_16x16x32_bf16 v[28:31], v[170:173], v[186:189], v[28:31]
	v_mfma_f32_16x16x32_bf16 v[20:23], v[162:165], v[194:197], v[20:23]
	v_mfma_f32_16x16x32_bf16 v[12:15], v[170:173], v[194:197], v[12:15]
	v_mfma_f32_16x16x32_bf16 v[4:7], v[162:165], v[202:205], v[4:7]
	v_mfma_f32_16x16x32_bf16 v[0:3], v[170:173], v[202:205], v[0:3]
	v_mfma_f32_16x16x32_bf16 v[52:55], v[166:169], v[182:185], v[52:55]
	v_mfma_f32_16x16x32_bf16 v[44:47], v[174:177], v[182:185], v[44:47]
	v_mfma_f32_16x16x32_bf16 v[36:39], v[166:169], v[190:193], v[36:39]
	v_mfma_f32_16x16x32_bf16 v[28:31], v[174:177], v[190:193], v[28:31]
	v_mfma_f32_16x16x32_bf16 v[20:23], v[166:169], v[198:201], v[20:23]
	v_mfma_f32_16x16x32_bf16 v[12:15], v[174:177], v[198:201], v[12:15]
	v_mfma_f32_16x16x32_bf16 v[4:7], v[166:169], v[206:209], v[4:7]
	v_mfma_f32_16x16x32_bf16 v[0:3], v[174:177], v[206:209], v[0:3]
	s_setprio 0
	s_barrier
; #define PG8_STAGE(bufoff, gbase, voff) do { _Pragma("unroll") for (int _i = 0; _i < 2; ++_i) \
;         __builtin_amdgcn_global_load_lds((const unsigned*)((const char*)(gbase) + (voff)[_i]), (PG8_LAS unsigned*)(lds + (bufoff) + ldsw + _i * 8192), 16, 0, 0); } while (0)
; #define PG8_LDA(dst, b, h) do { _Pragma("unroll") for (int m = 0; m < 4; ++m) _Pragma("unroll") for (int k = 0; k < 2; ++k) dst[m][k] = *(const PG8_LAS bf16x8*)(lds + PG8_SA(b, h) + aoff + m * 2048 + k * 1024); } while (0)
; #define PG8_LDB(dst, b, h) do { _Pragma("unroll") for (int n = 0; n < 2; ++n) _Pragma("unroll") for (int k = 0; k < 2; ++k) dst[n][k] = *(const PG8_LAS bf16x8*)(lds + PG8_SB(b, h) + boff + n * 2048 + k * 1024); } while (0)
; #define PG8_MMA(ai, bj, At, Bt) do { __builtin_amdgcn_s_setprio(1); _Pragma("unroll") for (int m = 0; m < 4; ++m) _Pragma("unroll") for (int n = 0; n < 2; ++n) _Pragma("unroll") for (int k = 0; k < 2; ++k) \
;         acc[ai][bj][m][n] = __builtin_amdgcn_mfma_f32_16x16x32_bf16(Bt[n][k], At[m][k], acc[ai][bj][m][n], 0, 0, 0); __builtin_amdgcn_s_setprio(0); } while (0)
; #define PG8_WAIT_V(n) asm volatile("s_waitcnt vmcnt(" #n ")" ::: "memory")
; #define PG8_WAIT_L(n) asm volatile("s_waitcnt lgkmcnt(" #n ")" ::: "memory")
; #define PG8_BAR __builtin_amdgcn_s_barrier()
; #define PG8_SCHED __builtin_amdgcn_sched_barrier(0)
; template <class Epi, class Sched, bool ALIGN_EPI = false, bool SP2 = false>
; __device__ __forceinline__ void gemm_phase(PG8_LAS unsigned char* lds, const Gemm g, const Sched& S, const Epi& E, const int wave_in) {
;     ...
;             PG8_LDB(B0, 1, 0); PG8_LDB(B1, 1, 1); PG8_SCHED; PG8_LDA(At, 1, 0); PG8_STAGE(PG8_SA(0, 1), a2 + hstepA, voffA);
;             PG8_WAIT_V(8); PG8_WAIT_L(0); PG8_BAR; PG8_MMA(0, 0, At, B0); PG8_MMA(0, 1, At, B1); PG8_BAR; PG8_SCHED;
;             PG8_LDA(At, 1, 1); PG8_STAGE(PG8_SB(1, 0), b3, voffB); PG8_STAGE(PG8_SB(1, 1), b3 + hstepB, voffB); PG8_STAGE(PG8_SA(1, 0), a3, voffA);
;             PG8_WAIT_V(8); PG8_WAIT_L(0); PG8_BAR; PG8_MMA(1, 0, At, B0); PG8_MMA(1, 1, At, B1); PG8_BAR; PG8_SCHED;
	s_add_i32 s55, 0, 0x18000
	s_add_i32 s56, 0, 0x1c000
	v_add_u32_e32 v140, s55, v212
	v_add_u32_e32 v174, s56, v212
	ds_read_b128 v[128:131], v140
	ds_read_b128 v[132:135], v140 offset:1024
	ds_read_b128 v[136:139], v140 offset:2048
	ds_read_b128 v[140:143], v140 offset:3072
	ds_read_b128 v[162:165], v174
	ds_read_b128 v[166:169], v174 offset:1024
	ds_read_b128 v[170:173], v174 offset:2048
	ds_read_b128 v[174:177], v174 offset:3072
	s_add_u32 s18, s24, 0x158000
	s_addc_u32 s19, s25, 0
	s_mov_b32 m0, s37
	v_lshl_add_u64 v[224:225], s[18:19], 0, v[150:151]
	ds_read_b128 v[178:181], v216 offset:32768
	ds_read_b128 v[182:185], v216 offset:33792
	ds_read_b128 v[186:189], v216 offset:34816
	ds_read_b128 v[190:193], v216 offset:35840
	ds_read_b128 v[194:197], v216 offset:36864
	ds_read_b128 v[198:201], v216 offset:37888
	ds_read_b128 v[202:205], v216 offset:38912
	ds_read_b128 v[206:209], v216 offset:39936
	global_load_lds_dwordx4 v[224:225], off
	v_lshl_add_u64 v[224:225], s[18:19], 0, v[146:147]
	s_mov_b32 m0, s38
	s_nop 0
	global_load_lds_dwordx4 v[224:225], off
	s_waitcnt vmcnt(8)
	s_waitcnt lgkmcnt(0)
	s_setprio 1
	s_barrier
	v_mfma_f32_16x16x32_bf16 v[124:127], v[128:131], v[178:181], v[124:127]
	v_mfma_f32_16x16x32_bf16 v[120:123], v[136:139], v[178:181], v[120:123]
	v_mfma_f32_16x16x32_bf16 v[112:115], v[128:131], v[186:189], v[112:115]
	v_mfma_f32_16x16x32_bf16 v[104:107], v[136:139], v[186:189], v[104:107]
	v_mfma_f32_16x16x32_bf16 v[100:103], v[128:131], v[194:197], v[100:103]
	v_mfma_f32_16x16x32_bf16 v[96:99], v[136:139], v[194:197], v[96:99]
	v_mfma_f32_16x16x32_bf16 v[76:79], v[128:131], v[202:205], v[76:79]
	v_mfma_f32_16x16x32_bf16 v[72:75], v[136:139], v[202:205], v[72:75]
	v_mfma_f32_16x16x32_bf16 v[124:127], v[132:135], v[182:185], v[124:127]
	v_mfma_f32_16x16x32_bf16 v[120:123], v[140:143], v[182:185], v[120:123]
	v_mfma_f32_16x16x32_bf16 v[112:115], v[132:135], v[190:193], v[112:115]
	v_mfma_f32_16x16x32_bf16 v[104:107], v[140:143], v[190:193], v[104:107]
	v_mfma_f32_16x16x32_bf16 v[100:103], v[132:135], v[198:201], v[100:103]
	v_mfma_f32_16x16x32_bf16 v[96:99], v[140:143], v[198:201], v[96:99]
	v_mfma_f32_16x16x32_bf16 v[76:79], v[132:135], v[206:209], v[76:79]
	v_mfma_f32_16x16x32_bf16 v[72:75], v[140:143], v[206:209], v[72:75]
	v_mfma_f32_16x16x32_bf16 v[116:119], v[162:165], v[178:181], v[116:119]
	v_mfma_f32_16x16x32_bf16 v[108:111], v[170:173], v[178:181], v[108:111]
	v_mfma_f32_16x16x32_bf16 v[92:95], v[162:165], v[186:189], v[92:95]
	v_mfma_f32_16x16x32_bf16 v[88:91], v[170:173], v[186:189], v[88:91]
	v_mfma_f32_16x16x32_bf16 v[84:87], v[162:165], v[194:197], v[84:87]
	v_mfma_f32_16x16x32_bf16 v[80:83], v[170:173], v[194:197], v[80:83]
	v_mfma_f32_16x16x32_bf16 v[68:71], v[162:165], v[202:205], v[68:71]
	v_mfma_f32_16x16x32_bf16 v[64:67], v[170:173], v[202:205], v[64:67]
	v_mfma_f32_16x16x32_bf16 v[116:119], v[166:169], v[182:185], v[116:119]
	v_mfma_f32_16x16x32_bf16 v[108:111], v[174:177], v[182:185], v[108:111]
	v_mfma_f32_16x16x32_bf16 v[92:95], v[166:169], v[190:193], v[92:95]
	v_mfma_f32_16x16x32_bf16 v[88:91], v[174:177], v[190:193], v[88:91]
	v_mfma_f32_16x16x32_bf16 v[84:87], v[166:169], v[198:201], v[84:87]
	v_mfma_f32_16x16x32_bf16 v[80:83], v[174:177], v[198:201], v[80:83]
	v_mfma_f32_16x16x32_bf16 v[68:71], v[166:169], v[206:209], v[68:71]
	v_mfma_f32_16x16x32_bf16 v[64:67], v[174:177], v[206:209], v[64:67]
	s_setprio 0
	s_barrier
	s_add_i32 s18, s55, s30
	v_lshl_add_u64 v[210:211], v[210:211], 0, s[6:7]
	s_mov_b32 m0, s18
	ds_read_b128 v[178:181], v216 offset:49152
	ds_read_b128 v[182:185], v216 offset:50176
	ds_read_b128 v[186:189], v216 offset:51200
	ds_read_b128 v[190:193], v216 offset:52224
	ds_read_b128 v[194:197], v216 offset:53248
	ds_read_b128 v[198:201], v216 offset:54272
	ds_read_b128 v[202:205], v216 offset:55296
	ds_read_b128 v[206:209], v216 offset:56320
	global_load_lds_dwordx4 v[210:211], off
	s_add_i32 m0, s18, 0x2000
	s_add_u32 s18, s22, 0x158080
	v_lshl_add_u64 v[210:211], v[218:219], 0, s[6:7]
	s_addc_u32 s19, s23, 0
	s_add_i32 s22, s56, s30
	global_load_lds_dwordx4 v[210:211], off
	v_lshl_add_u64 v[210:211], s[18:19], 0, v[148:149]
	s_mov_b32 m0, s22
	s_nop 0
	global_load_lds_dwordx4 v[210:211], off
	v_lshl_add_u64 v[210:211], s[18:19], 0, v[144:145]
	s_add_i32 m0, s22, 0x2000
	s_nop 0
	global_load_lds_dwordx4 v[210:211], off
	v_lshl_add_u64 v[210:211], v[220:221], 0, s[6:7]
	s_mov_b32 m0, s42
	s_nop 0
	global_load_lds_dwordx4 v[210:211], off
	v_lshl_add_u64 v[210:211], v[222:223], 0, s[6:7]
	s_mov_b32 m0, s43
	s_nop 0
	global_load_lds_dwordx4 v[210:211], off
	s_waitcnt vmcnt(8)
	s_waitcnt lgkmcnt(0)
	s_setprio 1
	s_barrier
	v_mfma_f32_16x16x32_bf16 v[60:63], v[128:131], v[178:181], v[60:63]
	v_mfma_f32_16x16x32_bf16 v[56:59], v[136:139], v[178:181], v[56:59]
	v_mfma_f32_16x16x32_bf16 v[48:51], v[128:131], v[186:189], v[48:51]
	v_mfma_f32_16x16x32_bf16 v[40:43], v[136:139], v[186:189], v[40:43]
	v_mfma_f32_16x16x32_bf16 v[32:35], v[128:131], v[194:197], v[32:35]
	v_mfma_f32_16x16x32_bf16 v[24:27], v[136:139], v[194:197], v[24:27]
	v_mfma_f32_16x16x32_bf16 v[16:19], v[128:131], v[202:205], v[16:19]
	v_mfma_f32_16x16x32_bf16 v[8:11], v[136:139], v[202:205], v[8:11]
	v_mfma_f32_16x16x32_bf16 v[60:63], v[132:135], v[182:185], v[60:63]
	v_mfma_f32_16x16x32_bf16 v[56:59], v[140:143], v[182:185], v[56:59]
	v_mfma_f32_16x16x32_bf16 v[48:51], v[132:135], v[190:193], v[48:51]
	v_mfma_f32_16x16x32_bf16 v[40:43], v[140:143], v[190:193], v[40:43]
	v_mfma_f32_16x16x32_bf16 v[32:35], v[132:135], v[198:201], v[32:35]
	v_mfma_f32_16x16x32_bf16 v[24:27], v[140:143], v[198:201], v[24:27]
	v_mfma_f32_16x16x32_bf16 v[16:19], v[132:135], v[206:209], v[16:19]
	v_mfma_f32_16x16x32_bf16 v[8:11], v[140:143], v[206:209], v[8:11]
	v_mfma_f32_16x16x32_bf16 v[52:55], v[162:165], v[178:181], v[52:55]
	v_mfma_f32_16x16x32_bf16 v[44:47], v[170:173], v[178:181], v[44:47]
	v_mfma_f32_16x16x32_bf16 v[36:39], v[162:165], v[186:189], v[36:39]
	v_mfma_f32_16x16x32_bf16 v[28:31], v[170:173], v[186:189], v[28:31]
	v_mfma_f32_16x16x32_bf16 v[20:23], v[162:165], v[194:197], v[20:23]
	v_mfma_f32_16x16x32_bf16 v[12:15], v[170:173], v[194:197], v[12:15]
	v_mfma_f32_16x16x32_bf16 v[4:7], v[162:165], v[202:205], v[4:7]
	v_mfma_f32_16x16x32_bf16 v[0:3], v[170:173], v[202:205], v[0:3]
	v_mfma_f32_16x16x32_bf16 v[52:55], v[166:169], v[182:185], v[52:55]
	v_mfma_f32_16x16x32_bf16 v[44:47], v[174:177], v[182:185], v[44:47]
	v_mfma_f32_16x16x32_bf16 v[36:39], v[166:169], v[190:193], v[36:39]
	v_mfma_f32_16x16x32_bf16 v[28:31], v[174:177], v[190:193], v[28:31]
	v_mfma_f32_16x16x32_bf16 v[20:23], v[166:169], v[198:201], v[20:23]
	v_mfma_f32_16x16x32_bf16 v[12:15], v[174:177], v[198:201], v[12:15]
	v_mfma_f32_16x16x32_bf16 v[4:7], v[166:169], v[206:209], v[4:7]
	v_mfma_f32_16x16x32_bf16 v[0:3], v[174:177], v[206:209], v[0:3]
	s_setprio 0
	s_barrier
	s_add_i32 s54, s54, 2
	s_add_u32 s17, s17, 0x100
	s_addc_u32 s53, s53, 0
	s_cmpk_gt_u32 s54, 0x53
	s_mov_b64 s[18:19], s[20:21]
	s_cbranch_scc0 .LBB0_1375

;     __host__ __device__ bool next(int i, Unit& u) const { const bool ok = StaticOrder::next(i, u); u.pm = 0; u.pn = 0; return ok; }
; #define PG8_STAGE(bufoff, gbase, voff) do { _Pragma("unroll") for (int _i = 0; _i < 2; ++_i) \
;         __builtin_amdgcn_global_load_lds((const unsigned*)((const char*)(gbase) + (voff)[_i]), (PG8_LAS unsigned*)(lds + (bufoff) + ldsw + _i * 8192), 16, 0, 0); } while (0)
; #define PG8_LDA(dst, b, h) do { _Pragma("unroll") for (int m = 0; m < 4; ++m) _Pragma("unroll") for (int k = 0; k < 2; ++k) dst[m][k] = *(const PG8_LAS bf16x8*)(lds + PG8_SA(b, h) + aoff + m * 2048 + k * 1024); } while (0)
; #define PG8_LDB(dst, b, h) do { _Pragma("unroll") for (int n = 0; n < 2; ++n) _Pragma("unroll") for (int k = 0; k < 2; ++k) dst[n][k] = *(const PG8_LAS bf16x8*)(lds + PG8_SB(b, h) + boff + n * 2048 + k * 1024); } while (0)
; #define PG8_WAIT_V(n) asm volatile("s_waitcnt vmcnt(" #n ")" ::: "memory")
; #define PG8_BAR __builtin_amdgcn_s_barrier()
; template <class Epi, class Sched, bool ALIGN_EPI = false, bool SP2 = false>
; __device__ __forceinline__ void gemm_phase(PG8_LAS unsigned char* lds, const Gemm g, const Sched& S, const Epi& E, const int wave_in) {
;     ...
;         const bool has_next = S.next(ui + 1, nxt);
;         const char* nA = has_next ? (const char*)g.A + (size_t)nxt.pm * tstepA : cA; const char* nB = has_next ? (const char*)g.Bt + (size_t)nxt.pn * tstepB : cB;
;         for (int t = 0; t < nt; t += 2) {
;             const bool last = (t == nt - 2);
;             const char* a1 = cA + (size_t)(t + 1) * kstep;
;             const char* a2 = last ? nA : cA + (size_t)(t + 2) * kstep; const char* b2 = last ? nB : cB + (size_t)(t + 2) * kstep;
;             const char* a3 = a2 + kstep; const char* b3 = b2 + kstep;
;             if (last && has_next) S.a_ready(nxt);
;             if constexpr (SP2) {
;             PG8_LDB(B0, 0, 0); PG8_LDB(B1, 0, 1); PG8_SCHED; PG8_LDA(At, 0, 0); PG8_STAGE(PG8_SA(1, 1), a1 + hstepA, voffA);
;             PG8_WAIT_V(8); PG8_WAIT_L(0); PG8_BAR; PG8_MMA(0, 0, At, B0); PG8_MMA(0, 1, At, B1); PG8_BAR; PG8_SCHED;
;             PG8_LDA(At, 0, 1); PG8_STAGE(PG8_SB(0, 0), b2, voffB); PG8_STAGE(PG8_SB(0, 1), b2 + hstepB, voffB); PG8_STAGE(PG8_SA(0, 0), a2, voffA);
;             PG8_WAIT_V(8); PG8_WAIT_L(0); PG8_BAR; PG8_MMA(1, 0, At, B0); PG8_MMA(1, 1, At, B1); PG8_BAR; PG8_SCHED;
.LBB0_1512:
	s_ashr_i32 s13, s12, 31
	s_lshl_b64 s[14:15], s[12:13], 20
	s_add_u32 s14, s26, s14
	s_addc_u32 s15, s27, s15
	s_and_b64 s[16:17], s[2:3], exec
	s_cselect_b32 s13, s15, s21
	s_cselect_b32 s46, s14, s20
	s_ashr_i32 s11, s10, 31
	s_lshl_b64 s[16:17], s[10:11], 20
	s_add_u32 s16, s28, s16
	s_addc_u32 s17, s29, s17
	s_and_b64 s[24:25], s[2:3], exec
	s_cselect_b32 s11, s17, s23
	s_cselect_b32 s47, s16, s22
	s_add_u32 s20, s20, 0x80080
	s_addc_u32 s21, s21, 0
	s_add_u32 s48, s22, 0x100
	v_mov_b32_e32 v0, 0
	s_addc_u32 s49, s23, 0
	s_mov_b32 s50, -2
	ds_read_b128 v[144:147], v151
	ds_read_b128 v[154:157], v151 offset:1024
	ds_read_b128 v[158:161], v151 offset:2048
	ds_read_b128 v[162:165], v151 offset:3072
	ds_read_b128 v[166:169], v152
	ds_read_b128 v[170:173], v152 offset:1024
	ds_read_b128 v[174:177], v152 offset:2048
	ds_read_b128 v[178:181], v152 offset:3072
	s_add_u32 s22, s20, 0xfff80080
	s_addc_u32 s23, s21, -1
	s_cmp_eq_u32 s50, 28
	s_cselect_b32 s25, s13, s23
	s_cselect_b32 s24, s46, s22
	s_cselect_b32 s23, s11, s49
	s_cselect_b32 s22, s47, s48
	v_lshl_add_u64 v[214:215], s[20:21], 0, v[136:137]
	s_add_i32 m0, s19, 0xc000
	ds_read_b128 v[182:185], v153
	ds_read_b128 v[186:189], v153 offset:1024
	ds_read_b128 v[190:193], v153 offset:2048
	ds_read_b128 v[194:197], v153 offset:3072
	ds_read_b128 v[198:201], v153 offset:4096
	ds_read_b128 v[202:205], v153 offset:5120
	ds_read_b128 v[206:209], v153 offset:6144
	ds_read_b128 v[210:213], v153 offset:7168
	global_load_lds_dwordx4 v[214:215], off
	v_lshl_add_u64 v[214:215], s[20:21], 0, v[138:139]
	s_add_i32 m0, s19, 0xe000
	s_nop 0
	global_load_lds_dwordx4 v[214:215], off
	s_waitcnt vmcnt(8)
	s_waitcnt lgkmcnt(0)
	s_setprio 1
	s_barrier
	v_mfma_f32_16x16x32_bf16 v[124:127], v[144:147], v[182:185], 0
	v_mfma_f32_16x16x32_bf16 v[120:123], v[158:161], v[182:185], 0
	v_mfma_f32_16x16x32_bf16 v[116:119], v[144:147], v[190:193], 0
	v_mfma_f32_16x16x32_bf16 v[108:111], v[158:161], v[190:193], 0
	v_mfma_f32_16x16x32_bf16 v[100:103], v[144:147], v[198:201], 0
	v_mfma_f32_16x16x32_bf16 v[92:95], v[158:161], v[198:201], 0
	v_mfma_f32_16x16x32_bf16 v[84:87], v[144:147], v[206:209], 0
	v_mfma_f32_16x16x32_bf16 v[76:79], v[158:161], v[206:209], 0
	v_mfma_f32_16x16x32_bf16 v[124:127], v[154:157], v[186:189], v[124:127]
	v_mfma_f32_16x16x32_bf16 v[120:123], v[162:165], v[186:189], v[120:123]
	v_mfma_f32_16x16x32_bf16 v[116:119], v[154:157], v[194:197], v[116:119]
	v_mfma_f32_16x16x32_bf16 v[108:111], v[162:165], v[194:197], v[108:111]
	v_mfma_f32_16x16x32_bf16 v[100:103], v[154:157], v[202:205], v[100:103]
	v_mfma_f32_16x16x32_bf16 v[92:95], v[162:165], v[202:205], v[92:95]
	v_mfma_f32_16x16x32_bf16 v[84:87], v[154:157], v[210:213], v[84:87]
	v_mfma_f32_16x16x32_bf16 v[76:79], v[162:165], v[210:213], v[76:79]
	v_mfma_f32_16x16x32_bf16 v[112:115], v[166:169], v[182:185], 0
	v_mfma_f32_16x16x32_bf16 v[104:107], v[174:177], v[182:185], 0
	v_mfma_f32_16x16x32_bf16 v[96:99], v[166:169], v[190:193], 0
	v_mfma_f32_16x16x32_bf16 v[88:91], v[174:177], v[190:193], 0
	v_mfma_f32_16x16x32_bf16 v[80:83], v[166:169], v[198:201], 0
	v_mfma_f32_16x16x32_bf16 v[72:75], v[174:177], v[198:201], 0
	v_mfma_f32_16x16x32_bf16 v[68:71], v[166:169], v[206:209], 0
	v_mfma_f32_16x16x32_bf16 v[64:67], v[174:177], v[206:209], 0
	v_mfma_f32_16x16x32_bf16 v[112:115], v[170:173], v[186:189], v[112:115]
	v_mfma_f32_16x16x32_bf16 v[104:107], v[178:181], v[186:189], v[104:107]
	v_mfma_f32_16x16x32_bf16 v[96:99], v[170:173], v[194:197], v[96:99]
	v_mfma_f32_16x16x32_bf16 v[88:91], v[178:181], v[194:197], v[88:91]
	v_mfma_f32_16x16x32_bf16 v[80:83], v[170:173], v[202:205], v[80:83]
	v_mfma_f32_16x16x32_bf16 v[72:75], v[178:181], v[202:205], v[72:75]
	v_mfma_f32_16x16x32_bf16 v[68:71], v[170:173], v[210:213], v[68:71]
	v_mfma_f32_16x16x32_bf16 v[64:67], v[178:181], v[210:213], v[64:67]
	s_setprio 0
	s_barrier
	s_add_i32 s51, s42, s30
	v_lshl_add_u64 v[214:215], s[22:23], 0, v[132:133]
	s_mov_b32 m0, s51
	ds_read_b128 v[182:185], v153 offset:16384
	ds_read_b128 v[186:189], v153 offset:17408
	ds_read_b128 v[190:193], v153 offset:18432
	ds_read_b128 v[194:197], v153 offset:19456
	ds_read_b128 v[198:201], v153 offset:20480
	ds_read_b128 v[202:205], v153 offset:21504
	ds_read_b128 v[206:209], v153 offset:22528
	ds_read_b128 v[210:213], v153 offset:23552
	global_load_lds_dwordx4 v[214:215], off
	s_add_i32 m0, s51, 0x2000
	s_add_u32 s52, s22, 0x80000
	v_lshl_add_u64 v[216:217], s[22:23], 0, v[128:129]
	s_addc_u32 s53, s23, 0
	s_add_i32 s51, s43, s30
	global_load_lds_dwordx4 v[216:217], off
	v_lshl_add_u64 v[218:219], s[52:53], 0, v[132:133]
	s_mov_b32 m0, s51
	v_lshl_add_u64 v[220:221], s[24:25], 0, v[130:131]
	global_load_lds_dwordx4 v[218:219], off
	v_lshl_add_u64 v[218:219], s[52:53], 0, v[128:129]
	s_add_i32 m0, s51, 0x2000
	s_nop 0
	global_load_lds_dwordx4 v[218:219], off
	v_lshl_add_u64 v[218:219], s[24:25], 0, v[134:135]
	s_mov_b32 m0, s19
	s_nop 0
	global_load_lds_dwordx4 v[218:219], off
	s_mov_b32 m0, s35
	s_nop 0
	global_load_lds_dwordx4 v[220:221], off
	s_waitcnt vmcnt(8)
	s_waitcnt lgkmcnt(0)
	s_setprio 1
	s_barrier
; #define PG8_STAGE(bufoff, gbase, voff) do { _Pragma("unroll") for (int _i = 0; _i < 2; ++_i) \
;         __builtin_amdgcn_global_load_lds((const unsigned*)((const char*)(gbase) + (voff)[_i]), (PG8_LAS unsigned*)(lds + (bufoff) + ldsw + _i * 8192), 16, 0, 0); } while (0)
; #define PG8_LDA(dst, b, h) do { _Pragma("unroll") for (int m = 0; m < 4; ++m) _Pragma("unroll") for (int k = 0; k < 2; ++k) dst[m][k] = *(const PG8_LAS bf16x8*)(lds + PG8_SA(b, h) + aoff + m * 2048 + k * 1024); } while (0)
; #define PG8_LDB(dst, b, h) do { _Pragma("unroll") for (int n = 0; n < 2; ++n) _Pragma("unroll") for (int k = 0; k < 2; ++k) dst[n][k] = *(const PG8_LAS bf16x8*)(lds + PG8_SB(b, h) + boff + n * 2048 + k * 1024); } while (0)
; #define PG8_MMA(ai, bj, At, Bt) do { __builtin_amdgcn_s_setprio(1); _Pragma("unroll") for (int m = 0; m < 4; ++m) _Pragma("unroll") for (int n = 0; n < 2; ++n) _Pragma("unroll") for (int k = 0; k < 2; ++k) \
;         acc[ai][bj][m][n] = __builtin_amdgcn_mfma_f32_16x16x32_bf16(Bt[n][k], At[m][k], acc[ai][bj][m][n], 0, 0, 0); __builtin_amdgcn_s_setprio(0); } while (0)
; #define PG8_WAIT_V(n) asm volatile("s_waitcnt vmcnt(" #n ")" ::: "memory")
; #define PG8_WAIT_L(n) asm volatile("s_waitcnt lgkmcnt(" #n ")" ::: "memory")
; #define PG8_BAR __builtin_amdgcn_s_barrier()
; #define PG8_SCHED __builtin_amdgcn_sched_barrier(0)
; template <class Epi, class Sched, bool ALIGN_EPI = false, bool SP2 = false>
; __device__ __forceinline__ void gemm_phase(PG8_LAS unsigned char* lds, const Gemm g, const Sched& S, const Epi& E, const int wave_in) {
;     ...
;             PG8_WAIT_V(8); PG8_WAIT_L(0); PG8_BAR; PG8_MMA(1, 0, At, B0); PG8_MMA(1, 1, At, B1); PG8_BAR; PG8_SCHED;
;             PG8_LDB(B0, 1, 0); PG8_LDB(B1, 1, 1); PG8_SCHED; PG8_LDA(At, 1, 0); PG8_STAGE(PG8_SA(0, 1), a2 + hstepA, voffA);
;             PG8_WAIT_V(8); PG8_WAIT_L(0); PG8_BAR; PG8_MMA(0, 0, At, B0); PG8_MMA(0, 1, At, B1); PG8_BAR; PG8_SCHED;
	v_mfma_f32_16x16x32_bf16 v[60:63], v[144:147], v[182:185], 0
	v_mfma_f32_16x16x32_bf16 v[56:59], v[158:161], v[182:185], 0
	v_mfma_f32_16x16x32_bf16 v[52:55], v[144:147], v[190:193], 0
	v_mfma_f32_16x16x32_bf16 v[44:47], v[158:161], v[190:193], 0
	v_mfma_f32_16x16x32_bf16 v[36:39], v[144:147], v[198:201], 0
	v_mfma_f32_16x16x32_bf16 v[28:31], v[158:161], v[198:201], 0
	v_mfma_f32_16x16x32_bf16 v[20:23], v[144:147], v[206:209], 0
	v_mfma_f32_16x16x32_bf16 v[12:15], v[158:161], v[206:209], 0
	v_mfma_f32_16x16x32_bf16 v[60:63], v[154:157], v[186:189], v[60:63]
	v_mfma_f32_16x16x32_bf16 v[56:59], v[162:165], v[186:189], v[56:59]
	v_mfma_f32_16x16x32_bf16 v[52:55], v[154:157], v[194:197], v[52:55]
	v_mfma_f32_16x16x32_bf16 v[44:47], v[162:165], v[194:197], v[44:47]
	v_mfma_f32_16x16x32_bf16 v[36:39], v[154:157], v[202:205], v[36:39]
	v_mfma_f32_16x16x32_bf16 v[28:31], v[162:165], v[202:205], v[28:31]
	v_mfma_f32_16x16x32_bf16 v[20:23], v[154:157], v[210:213], v[20:23]
	v_mfma_f32_16x16x32_bf16 v[12:15], v[162:165], v[210:213], v[12:15]
	v_mfma_f32_16x16x32_bf16 v[48:51], v[166:169], v[182:185], 0
	v_mfma_f32_16x16x32_bf16 v[40:43], v[174:177], v[182:185], 0
	v_mfma_f32_16x16x32_bf16 v[32:35], v[166:169], v[190:193], 0
	v_mfma_f32_16x16x32_bf16 v[24:27], v[174:177], v[190:193], 0
	v_mfma_f32_16x16x32_bf16 v[16:19], v[166:169], v[198:201], 0
	v_mfma_f32_16x16x32_bf16 v[8:11], v[174:177], v[198:201], 0
	v_mfma_f32_16x16x32_bf16 v[4:7], v[166:169], v[206:209], 0
	v_mfma_f32_16x16x32_bf16 v[0:3], v[174:177], v[206:209], 0
	v_mfma_f32_16x16x32_bf16 v[48:51], v[170:173], v[186:189], v[48:51]
	v_mfma_f32_16x16x32_bf16 v[40:43], v[178:181], v[186:189], v[40:43]
	v_mfma_f32_16x16x32_bf16 v[32:35], v[170:173], v[194:197], v[32:35]
	v_mfma_f32_16x16x32_bf16 v[24:27], v[178:181], v[194:197], v[24:27]
	v_mfma_f32_16x16x32_bf16 v[16:19], v[170:173], v[202:205], v[16:19]
	v_mfma_f32_16x16x32_bf16 v[8:11], v[178:181], v[202:205], v[8:11]
	v_mfma_f32_16x16x32_bf16 v[4:7], v[170:173], v[210:213], v[4:7]
	v_mfma_f32_16x16x32_bf16 v[0:3], v[178:181], v[210:213], v[0:3]
	s_setprio 0
	s_barrier
	s_add_i32 s51, 0, 0x18000
	s_add_i32 s52, 0, 0x1c000
	v_add_u32_e32 v162, s51, v149
	v_add_u32_e32 v178, s52, v149
	ds_read_b128 v[144:147], v162
	ds_read_b128 v[154:157], v162 offset:1024
	ds_read_b128 v[158:161], v162 offset:2048
	ds_read_b128 v[162:165], v162 offset:3072
	ds_read_b128 v[166:169], v178
	ds_read_b128 v[170:173], v178 offset:1024
	ds_read_b128 v[174:177], v178 offset:2048
	ds_read_b128 v[178:181], v178 offset:3072
	s_add_u32 s24, s24, 0x80000
	s_addc_u32 s25, s25, 0
	s_mov_b32 m0, s36
	v_lshl_add_u64 v[222:223], s[24:25], 0, v[134:135]
	ds_read_b128 v[182:185], v153 offset:32768
	ds_read_b128 v[186:189], v153 offset:33792
	ds_read_b128 v[190:193], v153 offset:34816
	ds_read_b128 v[194:197], v153 offset:35840
	ds_read_b128 v[198:201], v153 offset:36864
	ds_read_b128 v[202:205], v153 offset:37888
	ds_read_b128 v[206:209], v153 offset:38912
	ds_read_b128 v[210:213], v153 offset:39936
	global_load_lds_dwordx4 v[222:223], off
	v_lshl_add_u64 v[222:223], s[24:25], 0, v[130:131]
	s_mov_b32 m0, s37
	s_nop 0
	global_load_lds_dwordx4 v[222:223], off
	s_waitcnt vmcnt(8)
	s_waitcnt lgkmcnt(0)
	s_setprio 1
	s_barrier
	v_mfma_f32_16x16x32_bf16 v[124:127], v[144:147], v[182:185], v[124:127]
	v_mfma_f32_16x16x32_bf16 v[120:123], v[158:161], v[182:185], v[120:123]
	v_mfma_f32_16x16x32_bf16 v[116:119], v[144:147], v[190:193], v[116:119]
	v_mfma_f32_16x16x32_bf16 v[108:111], v[158:161], v[190:193], v[108:111]
	v_mfma_f32_16x16x32_bf16 v[100:103], v[144:147], v[198:201], v[100:103]
	v_mfma_f32_16x16x32_bf16 v[92:95], v[158:161], v[198:201], v[92:95]
	v_mfma_f32_16x16x32_bf16 v[84:87], v[144:147], v[206:209], v[84:87]
	v_mfma_f32_16x16x32_bf16 v[76:79], v[158:161], v[206:209], v[76:79]
	v_mfma_f32_16x16x32_bf16 v[124:127], v[154:157], v[186:189], v[124:127]
	v_mfma_f32_16x16x32_bf16 v[120:123], v[162:165], v[186:189], v[120:123]
	v_mfma_f32_16x16x32_bf16 v[116:119], v[154:157], v[194:197], v[116:119]
	v_mfma_f32_16x16x32_bf16 v[108:111], v[162:165], v[194:197], v[108:111]
	v_mfma_f32_16x16x32_bf16 v[100:103], v[154:157], v[202:205], v[100:103]
	v_mfma_f32_16x16x32_bf16 v[92:95], v[162:165], v[202:205], v[92:95]
	v_mfma_f32_16x16x32_bf16 v[84:87], v[154:157], v[210:213], v[84:87]
	v_mfma_f32_16x16x32_bf16 v[76:79], v[162:165], v[210:213], v[76:79]
	v_mfma_f32_16x16x32_bf16 v[112:115], v[166:169], v[182:185], v[112:115]
	v_mfma_f32_16x16x32_bf16 v[104:107], v[174:177], v[182:185], v[104:107]
	v_mfma_f32_16x16x32_bf16 v[96:99], v[166:169], v[190:193], v[96:99]
	v_mfma_f32_16x16x32_bf16 v[88:91], v[174:177], v[190:193], v[88:91]
	v_mfma_f32_16x16x32_bf16 v[80:83], v[166:169], v[198:201], v[80:83]
	v_mfma_f32_16x16x32_bf16 v[72:75], v[174:177], v[198:201], v[72:75]
	v_mfma_f32_16x16x32_bf16 v[68:71], v[166:169], v[206:209], v[68:71]
	v_mfma_f32_16x16x32_bf16 v[64:67], v[174:177], v[206:209], v[64:67]
	v_mfma_f32_16x16x32_bf16 v[112:115], v[170:173], v[186:189], v[112:115]
	v_mfma_f32_16x16x32_bf16 v[104:107], v[178:181], v[186:189], v[104:107]
	v_mfma_f32_16x16x32_bf16 v[96:99], v[170:173], v[194:197], v[96:99]
	v_mfma_f32_16x16x32_bf16 v[88:91], v[178:181], v[194:197], v[88:91]
	v_mfma_f32_16x16x32_bf16 v[80:83], v[170:173], v[202:205], v[80:83]
	v_mfma_f32_16x16x32_bf16 v[72:75], v[178:181], v[202:205], v[72:75]
	v_mfma_f32_16x16x32_bf16 v[68:71], v[170:173], v[210:213], v[68:71]
	v_mfma_f32_16x16x32_bf16 v[64:67], v[178:181], v[210:213], v[64:67]
	s_setprio 0
	s_barrier
; #define PG8_STAGE(bufoff, gbase, voff) do { _Pragma("unroll") for (int _i = 0; _i < 2; ++_i) \
;         __builtin_amdgcn_global_load_lds((const unsigned*)((const char*)(gbase) + (voff)[_i]), (PG8_LAS unsigned*)(lds + (bufoff) + ldsw + _i * 8192), 16, 0, 0); } while (0)
; #define PG8_LDA(dst, b, h) do { _Pragma("unroll") for (int m = 0; m < 4; ++m) _Pragma("unroll") for (int k = 0; k < 2; ++k) dst[m][k] = *(const PG8_LAS bf16x8*)(lds + PG8_SA(b, h) + aoff + m * 2048 + k * 1024); } while (0)
; #define PG8_LDB(dst, b, h) do { _Pragma("unroll") for (int n = 0; n < 2; ++n) _Pragma("unroll") for (int k = 0; k < 2; ++k) dst[n][k] = *(const PG8_LAS bf16x8*)(lds + PG8_SB(b, h) + boff + n * 2048 + k * 1024); } while (0)
; #define PG8_WAIT_V(n) asm volatile("s_waitcnt vmcnt(" #n ")" ::: "memory")
; #define PG8_WAIT_L(n) asm volatile("s_waitcnt lgkmcnt(" #n ")" ::: "memory")
; #define PG8_BAR __builtin_amdgcn_s_barrier()
; template <class Epi, class Sched, bool ALIGN_EPI = false, bool SP2 = false>
; __device__ __forceinline__ void gemm_phase(PG8_LAS unsigned char* lds, const Gemm g, const Sched& S, const Epi& E, const int wave_in) {
;     ...
;         for (int t = 0; t < nt; t += 2) {
;             const bool last = (t == nt - 2);
;             const char* a1 = cA + (size_t)(t + 1) * kstep;
;             const char* a2 = last ? nA : cA + (size_t)(t + 2) * kstep; const char* b2 = last ? nB : cB + (size_t)(t + 2) * kstep;
;             const char* a3 = a2 + kstep; const char* b3 = b2 + kstep;
;             if (last && has_next) S.a_ready(nxt);
;             if constexpr (SP2) {
;             PG8_LDB(B0, 0, 0); PG8_LDB(B1, 0, 1); PG8_SCHED; PG8_LDA(At, 0, 0); PG8_STAGE(PG8_SA(1, 1), a1 + hstepA, voffA);
;             PG8_WAIT_V(8); PG8_WAIT_L(0); PG8_BAR; PG8_MMA(0, 0, At, B0); PG8_MMA(0, 1, At, B1); PG8_BAR; PG8_SCHED;
;             PG8_LDA(At, 0, 1); PG8_STAGE(PG8_SB(0, 0), b2, voffB); PG8_STAGE(PG8_SB(0, 1), b2 + hstepB, voffB); PG8_STAGE(PG8_SA(0, 0), a2, voffA);
;             PG8_WAIT_V(8); PG8_WAIT_L(0); PG8_BAR; PG8_MMA(1, 0, At, B0); PG8_MMA(1, 1, At, B1); PG8_BAR; PG8_SCHED;
;     ...
;             PG8_LDA(At, 1, 1); PG8_STAGE(PG8_SB(1, 0), b3, voffB); PG8_STAGE(PG8_SB(1, 1), b3 + hstepB, voffB); PG8_STAGE(PG8_SA(1, 0), a3, voffA);
;             PG8_WAIT_V(8); PG8_WAIT_L(0); PG8_BAR; PG8_MMA(1, 0, At, B0); PG8_MMA(1, 1, At, B1); PG8_BAR; PG8_SCHED;
	s_add_i32 s24, s51, s30
	v_lshl_add_u64 v[214:215], v[214:215], 0, s[6:7]
	s_mov_b32 m0, s24
	ds_read_b128 v[182:185], v153 offset:49152
	ds_read_b128 v[186:189], v153 offset:50176
	ds_read_b128 v[190:193], v153 offset:51200
	ds_read_b128 v[194:197], v153 offset:52224
	ds_read_b128 v[198:201], v153 offset:53248
	ds_read_b128 v[202:205], v153 offset:54272
	ds_read_b128 v[206:209], v153 offset:55296
	ds_read_b128 v[210:213], v153 offset:56320
	global_load_lds_dwordx4 v[214:215], off
	s_add_i32 m0, s24, 0x2000
	s_add_u32 s22, s22, 0x80080
	v_lshl_add_u64 v[214:215], v[216:217], 0, s[6:7]
	s_addc_u32 s23, s23, 0
	s_add_i32 s24, s52, s30
	global_load_lds_dwordx4 v[214:215], off
	v_lshl_add_u64 v[214:215], s[22:23], 0, v[132:133]
	s_mov_b32 m0, s24
	s_nop 0
	global_load_lds_dwordx4 v[214:215], off
	v_lshl_add_u64 v[214:215], s[22:23], 0, v[128:129]
	s_add_i32 m0, s24, 0x2000
	s_nop 0
	global_load_lds_dwordx4 v[214:215], off
	v_lshl_add_u64 v[214:215], v[218:219], 0, s[6:7]
	s_mov_b32 m0, s39
	s_nop 0
	global_load_lds_dwordx4 v[214:215], off
	v_lshl_add_u64 v[214:215], v[220:221], 0, s[6:7]
	s_mov_b32 m0, s40
	s_nop 0
	global_load_lds_dwordx4 v[214:215], off
	s_waitcnt vmcnt(8)
	s_waitcnt lgkmcnt(0)
	s_setprio 1
	s_barrier
	v_mfma_f32_16x16x32_bf16 v[60:63], v[144:147], v[182:185], v[60:63]
	v_mfma_f32_16x16x32_bf16 v[56:59], v[158:161], v[182:185], v[56:59]
	v_mfma_f32_16x16x32_bf16 v[52:55], v[144:147], v[190:193], v[52:55]
	v_mfma_f32_16x16x32_bf16 v[44:47], v[158:161], v[190:193], v[44:47]
	v_mfma_f32_16x16x32_bf16 v[36:39], v[144:147], v[198:201], v[36:39]
	v_mfma_f32_16x16x32_bf16 v[28:31], v[158:161], v[198:201], v[28:31]
	v_mfma_f32_16x16x32_bf16 v[20:23], v[144:147], v[206:209], v[20:23]
	v_mfma_f32_16x16x32_bf16 v[12:15], v[158:161], v[206:209], v[12:15]
	v_mfma_f32_16x16x32_bf16 v[60:63], v[154:157], v[186:189], v[60:63]
	v_mfma_f32_16x16x32_bf16 v[56:59], v[162:165], v[186:189], v[56:59]
	v_mfma_f32_16x16x32_bf16 v[52:55], v[154:157], v[194:197], v[52:55]
	v_mfma_f32_16x16x32_bf16 v[44:47], v[162:165], v[194:197], v[44:47]
	v_mfma_f32_16x16x32_bf16 v[36:39], v[154:157], v[202:205], v[36:39]
	v_mfma_f32_16x16x32_bf16 v[28:31], v[162:165], v[202:205], v[28:31]
	v_mfma_f32_16x16x32_bf16 v[20:23], v[154:157], v[210:213], v[20:23]
	v_mfma_f32_16x16x32_bf16 v[12:15], v[162:165], v[210:213], v[12:15]
	v_mfma_f32_16x16x32_bf16 v[48:51], v[166:169], v[182:185], v[48:51]
	v_mfma_f32_16x16x32_bf16 v[40:43], v[174:177], v[182:185], v[40:43]
	v_mfma_f32_16x16x32_bf16 v[32:35], v[166:169], v[190:193], v[32:35]
	v_mfma_f32_16x16x32_bf16 v[24:27], v[174:177], v[190:193], v[24:27]
	v_mfma_f32_16x16x32_bf16 v[16:19], v[166:169], v[198:201], v[16:19]
	v_mfma_f32_16x16x32_bf16 v[8:11], v[174:177], v[198:201], v[8:11]
	v_mfma_f32_16x16x32_bf16 v[4:7], v[166:169], v[206:209], v[4:7]
	v_mfma_f32_16x16x32_bf16 v[0:3], v[174:177], v[206:209], v[0:3]
	v_mfma_f32_16x16x32_bf16 v[48:51], v[170:173], v[186:189], v[48:51]
	v_mfma_f32_16x16x32_bf16 v[40:43], v[178:181], v[186:189], v[40:43]
	v_mfma_f32_16x16x32_bf16 v[32:35], v[170:173], v[194:197], v[32:35]
	v_mfma_f32_16x16x32_bf16 v[24:27], v[178:181], v[194:197], v[24:27]
	v_mfma_f32_16x16x32_bf16 v[16:19], v[170:173], v[202:205], v[16:19]
	v_mfma_f32_16x16x32_bf16 v[8:11], v[178:181], v[202:205], v[8:11]
	v_mfma_f32_16x16x32_bf16 v[4:7], v[170:173], v[210:213], v[4:7]
	v_mfma_f32_16x16x32_bf16 v[0:3], v[178:181], v[210:213], v[0:3]
	s_setprio 0
	s_barrier
	s_add_i32 s50, s50, 2
	s_add_u32 s20, s20, 0x100
	s_addc_u32 s21, s21, 0
	s_add_u32 s48, s48, 0x100
	s_addc_u32 s49, s49, 0
	s_cmp_gt_u32 s50, 29
	s_cbranch_scc0 .LBB0_1513
	s_branch .Lkx_18
.LBB0_1513:
	ds_read_b128 v[144:147], v151
	ds_read_b128 v[154:157], v151 offset:1024
	ds_read_b128 v[158:161], v151 offset:2048
	ds_read_b128 v[162:165], v151 offset:3072
	ds_read_b128 v[166:169], v152
	ds_read_b128 v[170:173], v152 offset:1024
	ds_read_b128 v[174:177], v152 offset:2048
	ds_read_b128 v[178:181], v152 offset:3072
	s_add_u32 s22, s20, 0xfff80080
	s_addc_u32 s23, s21, -1
	s_cmp_eq_u32 s50, 28
	s_cselect_b32 s25, s13, s23
	s_cselect_b32 s24, s46, s22
	s_cselect_b32 s23, s11, s49
	s_cselect_b32 s22, s47, s48
	v_lshl_add_u64 v[214:215], s[20:21], 0, v[136:137]
	s_add_i32 m0, s19, 0xc000
	ds_read_b128 v[182:185], v153
	ds_read_b128 v[186:189], v153 offset:1024
	ds_read_b128 v[190:193], v153 offset:2048
	ds_read_b128 v[194:197], v153 offset:3072
	ds_read_b128 v[198:201], v153 offset:4096
	ds_read_b128 v[202:205], v153 offset:5120
	ds_read_b128 v[206:209], v153 offset:6144
	ds_read_b128 v[210:213], v153 offset:7168
	global_load_lds_dwordx4 v[214:215], off
	v_lshl_add_u64 v[214:215], s[20:21], 0, v[138:139]
	s_add_i32 m0, s19, 0xe000
	s_nop 0
	global_load_lds_dwordx4 v[214:215], off
	s_waitcnt vmcnt(8)
	s_waitcnt lgkmcnt(0)
	s_setprio 1
	s_barrier
; #define PG8_STAGE(bufoff, gbase, voff) do { _Pragma("unroll") for (int _i = 0; _i < 2; ++_i) \
;         __builtin_amdgcn_global_load_lds((const unsigned*)((const char*)(gbase) + (voff)[_i]), (PG8_LAS unsigned*)(lds + (bufoff) + ldsw + _i * 8192), 16, 0, 0); } while (0)
; #define PG8_LDA(dst, b, h) do { _Pragma("unroll") for (int m = 0; m < 4; ++m) _Pragma("unroll") for (int k = 0; k < 2; ++k) dst[m][k] = *(const PG8_LAS bf16x8*)(lds + PG8_SA(b, h) + aoff + m * 2048 + k * 1024); } while (0)
; #define PG8_LDB(dst, b, h) do { _Pragma("unroll") for (int n = 0; n < 2; ++n) _Pragma("unroll") for (int k = 0; k < 2; ++k) dst[n][k] = *(const PG8_LAS bf16x8*)(lds + PG8_SB(b, h) + boff + n * 2048 + k * 1024); } while (0)
; #define PG8_MMA(ai, bj, At, Bt) do { __builtin_amdgcn_s_setprio(1); _Pragma("unroll") for (int m = 0; m < 4; ++m) _Pragma("unroll") for (int n = 0; n < 2; ++n) _Pragma("unroll") for (int k = 0; k < 2; ++k) \
;         acc[ai][bj][m][n] = __builtin_amdgcn_mfma_f32_16x16x32_bf16(Bt[n][k], At[m][k], acc[ai][bj][m][n], 0, 0, 0); __builtin_amdgcn_s_setprio(0); } while (0)
; #define PG8_WAIT_V(n) asm volatile("s_waitcnt vmcnt(" #n ")" ::: "memory")
; #define PG8_WAIT_L(n) asm volatile("s_waitcnt lgkmcnt(" #n ")" ::: "memory")
; #define PG8_BAR __builtin_amdgcn_s_barrier()
; #define PG8_SCHED __builtin_amdgcn_sched_barrier(0)
; template <class Epi, class Sched, bool ALIGN_EPI = false, bool SP2 = false>
; __device__ __forceinline__ void gemm_phase(PG8_LAS unsigned char* lds, const Gemm g, const Sched& S, const Epi& E, const int wave_in) {
;     ...
;             PG8_LDB(B0, 0, 0); PG8_LDB(B1, 0, 1); PG8_SCHED; PG8_LDA(At, 0, 0); PG8_STAGE(PG8_SA(1, 1), a1 + hstepA, voffA);
;             PG8_WAIT_V(8); PG8_WAIT_L(0); PG8_BAR; PG8_MMA(0, 0, At, B0); PG8_MMA(0, 1, At, B1); PG8_BAR; PG8_SCHED;
;             PG8_LDA(At, 0, 1); PG8_STAGE(PG8_SB(0, 0), b2, voffB); PG8_STAGE(PG8_SB(0, 1), b2 + hstepB, voffB); PG8_STAGE(PG8_SA(0, 0), a2, voffA);
;             PG8_WAIT_V(8); PG8_WAIT_L(0); PG8_BAR; PG8_MMA(1, 0, At, B0); PG8_MMA(1, 1, At, B1); PG8_BAR; PG8_SCHED;
;             PG8_LDB(B0, 1, 0); PG8_LDB(B1, 1, 1); PG8_SCHED; PG8_LDA(At, 1, 0); PG8_STAGE(PG8_SA(0, 1), a2 + hstepA, voffA);
;             PG8_WAIT_V(8); PG8_WAIT_L(0); PG8_BAR; PG8_MMA(0, 0, At, B0); PG8_MMA(0, 1, At, B1); PG8_BAR; PG8_SCHED;
	v_mfma_f32_16x16x32_bf16 v[124:127], v[144:147], v[182:185], v[124:127]
	v_mfma_f32_16x16x32_bf16 v[120:123], v[158:161], v[182:185], v[120:123]
	v_mfma_f32_16x16x32_bf16 v[116:119], v[144:147], v[190:193], v[116:119]
	v_mfma_f32_16x16x32_bf16 v[108:111], v[158:161], v[190:193], v[108:111]
	v_mfma_f32_16x16x32_bf16 v[100:103], v[144:147], v[198:201], v[100:103]
	v_mfma_f32_16x16x32_bf16 v[92:95], v[158:161], v[198:201], v[92:95]
	v_mfma_f32_16x16x32_bf16 v[84:87], v[144:147], v[206:209], v[84:87]
	v_mfma_f32_16x16x32_bf16 v[76:79], v[158:161], v[206:209], v[76:79]
	v_mfma_f32_16x16x32_bf16 v[124:127], v[154:157], v[186:189], v[124:127]
	v_mfma_f32_16x16x32_bf16 v[120:123], v[162:165], v[186:189], v[120:123]
	v_mfma_f32_16x16x32_bf16 v[116:119], v[154:157], v[194:197], v[116:119]
	v_mfma_f32_16x16x32_bf16 v[108:111], v[162:165], v[194:197], v[108:111]
	v_mfma_f32_16x16x32_bf16 v[100:103], v[154:157], v[202:205], v[100:103]
	v_mfma_f32_16x16x32_bf16 v[92:95], v[162:165], v[202:205], v[92:95]
	v_mfma_f32_16x16x32_bf16 v[84:87], v[154:157], v[210:213], v[84:87]
	v_mfma_f32_16x16x32_bf16 v[76:79], v[162:165], v[210:213], v[76:79]
	v_mfma_f32_16x16x32_bf16 v[112:115], v[166:169], v[182:185], v[112:115]
	v_mfma_f32_16x16x32_bf16 v[104:107], v[174:177], v[182:185], v[104:107]
	v_mfma_f32_16x16x32_bf16 v[96:99], v[166:169], v[190:193], v[96:99]
	v_mfma_f32_16x16x32_bf16 v[88:91], v[174:177], v[190:193], v[88:91]
	v_mfma_f32_16x16x32_bf16 v[80:83], v[166:169], v[198:201], v[80:83]
	v_mfma_f32_16x16x32_bf16 v[72:75], v[174:177], v[198:201], v[72:75]
	v_mfma_f32_16x16x32_bf16 v[68:71], v[166:169], v[206:209], v[68:71]
	v_mfma_f32_16x16x32_bf16 v[64:67], v[174:177], v[206:209], v[64:67]
	v_mfma_f32_16x16x32_bf16 v[112:115], v[170:173], v[186:189], v[112:115]
	v_mfma_f32_16x16x32_bf16 v[104:107], v[178:181], v[186:189], v[104:107]
	v_mfma_f32_16x16x32_bf16 v[96:99], v[170:173], v[194:197], v[96:99]
	v_mfma_f32_16x16x32_bf16 v[88:91], v[178:181], v[194:197], v[88:91]
	v_mfma_f32_16x16x32_bf16 v[80:83], v[170:173], v[202:205], v[80:83]
	v_mfma_f32_16x16x32_bf16 v[72:75], v[178:181], v[202:205], v[72:75]
	v_mfma_f32_16x16x32_bf16 v[68:71], v[170:173], v[210:213], v[68:71]
	v_mfma_f32_16x16x32_bf16 v[64:67], v[178:181], v[210:213], v[64:67]
	s_setprio 0
	s_barrier
	s_add_i32 s51, s42, s30
	v_lshl_add_u64 v[214:215], s[22:23], 0, v[132:133]
	s_mov_b32 m0, s51
	ds_read_b128 v[182:185], v153 offset:16384
	ds_read_b128 v[186:189], v153 offset:17408
	ds_read_b128 v[190:193], v153 offset:18432
	ds_read_b128 v[194:197], v153 offset:19456
	ds_read_b128 v[198:201], v153 offset:20480
	ds_read_b128 v[202:205], v153 offset:21504
	ds_read_b128 v[206:209], v153 offset:22528
	ds_read_b128 v[210:213], v153 offset:23552
	global_load_lds_dwordx4 v[214:215], off
	s_add_i32 m0, s51, 0x2000
	s_add_u32 s52, s22, 0x80000
	v_lshl_add_u64 v[216:217], s[22:23], 0, v[128:129]
	s_addc_u32 s53, s23, 0
	s_add_i32 s51, s43, s30
	global_load_lds_dwordx4 v[216:217], off
	v_lshl_add_u64 v[218:219], s[52:53], 0, v[132:133]
	s_mov_b32 m0, s51
	v_lshl_add_u64 v[220:221], s[24:25], 0, v[130:131]
	global_load_lds_dwordx4 v[218:219], off
	v_lshl_add_u64 v[218:219], s[52:53], 0, v[128:129]
	s_add_i32 m0, s51, 0x2000
	s_nop 0
	global_load_lds_dwordx4 v[218:219], off
	v_lshl_add_u64 v[218:219], s[24:25], 0, v[134:135]
	s_mov_b32 m0, s19
	s_nop 0
	global_load_lds_dwordx4 v[218:219], off
	s_mov_b32 m0, s35
	s_nop 0
	global_load_lds_dwordx4 v[220:221], off
	s_waitcnt vmcnt(8)
	s_waitcnt lgkmcnt(0)
	s_setprio 1
	s_barrier
	v_mfma_f32_16x16x32_bf16 v[60:63], v[144:147], v[182:185], v[60:63]
	v_mfma_f32_16x16x32_bf16 v[56:59], v[158:161], v[182:185], v[56:59]
	v_mfma_f32_16x16x32_bf16 v[52:55], v[144:147], v[190:193], v[52:55]
	v_mfma_f32_16x16x32_bf16 v[44:47], v[158:161], v[190:193], v[44:47]
	v_mfma_f32_16x16x32_bf16 v[36:39], v[144:147], v[198:201], v[36:39]
	v_mfma_f32_16x16x32_bf16 v[28:31], v[158:161], v[198:201], v[28:31]
	v_mfma_f32_16x16x32_bf16 v[20:23], v[144:147], v[206:209], v[20:23]
	v_mfma_f32_16x16x32_bf16 v[12:15], v[158:161], v[206:209], v[12:15]
	v_mfma_f32_16x16x32_bf16 v[60:63], v[154:157], v[186:189], v[60:63]
	v_mfma_f32_16x16x32_bf16 v[56:59], v[162:165], v[186:189], v[56:59]
	v_mfma_f32_16x16x32_bf16 v[52:55], v[154:157], v[194:197], v[52:55]
	v_mfma_f32_16x16x32_bf16 v[44:47], v[162:165], v[194:197], v[44:47]
	v_mfma_f32_16x16x32_bf16 v[36:39], v[154:157], v[202:205], v[36:39]
	v_mfma_f32_16x16x32_bf16 v[28:31], v[162:165], v[202:205], v[28:31]
	v_mfma_f32_16x16x32_bf16 v[20:23], v[154:157], v[210:213], v[20:23]
	v_mfma_f32_16x16x32_bf16 v[12:15], v[162:165], v[210:213], v[12:15]
	v_mfma_f32_16x16x32_bf16 v[48:51], v[166:169], v[182:185], v[48:51]
	v_mfma_f32_16x16x32_bf16 v[40:43], v[174:177], v[182:185], v[40:43]
	v_mfma_f32_16x16x32_bf16 v[32:35], v[166:169], v[190:193], v[32:35]
	v_mfma_f32_16x16x32_bf16 v[24:27], v[174:177], v[190:193], v[24:27]
	v_mfma_f32_16x16x32_bf16 v[16:19], v[166:169], v[198:201], v[16:19]
	v_mfma_f32_16x16x32_bf16 v[8:11], v[174:177], v[198:201], v[8:11]
	v_mfma_f32_16x16x32_bf16 v[4:7], v[166:169], v[206:209], v[4:7]
	v_mfma_f32_16x16x32_bf16 v[0:3], v[174:177], v[206:209], v[0:3]
	v_mfma_f32_16x16x32_bf16 v[48:51], v[170:173], v[186:189], v[48:51]
	v_mfma_f32_16x16x32_bf16 v[40:43], v[178:181], v[186:189], v[40:43]
	v_mfma_f32_16x16x32_bf16 v[32:35], v[170:173], v[194:197], v[32:35]
	v_mfma_f32_16x16x32_bf16 v[24:27], v[178:181], v[194:197], v[24:27]
	v_mfma_f32_16x16x32_bf16 v[16:19], v[170:173], v[202:205], v[16:19]
	v_mfma_f32_16x16x32_bf16 v[8:11], v[178:181], v[202:205], v[8:11]
	v_mfma_f32_16x16x32_bf16 v[4:7], v[170:173], v[210:213], v[4:7]
	v_mfma_f32_16x16x32_bf16 v[0:3], v[178:181], v[210:213], v[0:3]
	s_setprio 0
	s_barrier
; #define PG8_STAGE(bufoff, gbase, voff) do { _Pragma("unroll") for (int _i = 0; _i < 2; ++_i) \
;         __builtin_amdgcn_global_load_lds((const unsigned*)((const char*)(gbase) + (voff)[_i]), (PG8_LAS unsigned*)(lds + (bufoff) + ldsw + _i * 8192), 16, 0, 0); } while (0)
; #define PG8_LDA(dst, b, h) do { _Pragma("unroll") for (int m = 0; m < 4; ++m) _Pragma("unroll") for (int k = 0; k < 2; ++k) dst[m][k] = *(const PG8_LAS bf16x8*)(lds + PG8_SA(b, h) + aoff + m * 2048 + k * 1024); } while (0)
; #define PG8_LDB(dst, b, h) do { _Pragma("unroll") for (int n = 0; n < 2; ++n) _Pragma("unroll") for (int k = 0; k < 2; ++k) dst[n][k] = *(const PG8_LAS bf16x8*)(lds + PG8_SB(b, h) + boff + n * 2048 + k * 1024); } while (0)
; #define PG8_MMA(ai, bj, At, Bt) do { __builtin_amdgcn_s_setprio(1); _Pragma("unroll") for (int m = 0; m < 4; ++m) _Pragma("unroll") for (int n = 0; n < 2; ++n) _Pragma("unroll") for (int k = 0; k < 2; ++k) \
;         acc[ai][bj][m][n] = __builtin_amdgcn_mfma_f32_16x16x32_bf16(Bt[n][k], At[m][k], acc[ai][bj][m][n], 0, 0, 0); __builtin_amdgcn_s_setprio(0); } while (0)
; #define PG8_WAIT_V(n) asm volatile("s_waitcnt vmcnt(" #n ")" ::: "memory")
; #define PG8_WAIT_L(n) asm volatile("s_waitcnt lgkmcnt(" #n ")" ::: "memory")
; #define PG8_BAR __builtin_amdgcn_s_barrier()
; #define PG8_SCHED __builtin_amdgcn_sched_barrier(0)
; template <class Epi, class Sched, bool ALIGN_EPI = false, bool SP2 = false>
; __device__ __forceinline__ void gemm_phase(PG8_LAS unsigned char* lds, const Gemm g, const Sched& S, const Epi& E, const int wave_in) {
;     ...
;             PG8_LDB(B0, 1, 0); PG8_LDB(B1, 1, 1); PG8_SCHED; PG8_LDA(At, 1, 0); PG8_STAGE(PG8_SA(0, 1), a2 + hstepA, voffA);
;             PG8_WAIT_V(8); PG8_WAIT_L(0); PG8_BAR; PG8_MMA(0, 0, At, B0); PG8_MMA(0, 1, At, B1); PG8_BAR; PG8_SCHED;
	s_add_i32 s51, 0, 0x18000
	s_add_i32 s52, 0, 0x1c000
	v_add_u32_e32 v162, s51, v149
	v_add_u32_e32 v178, s52, v149
	ds_read_b128 v[144:147], v162
	ds_read_b128 v[154:157], v162 offset:1024
	ds_read_b128 v[158:161], v162 offset:2048
	ds_read_b128 v[162:165], v162 offset:3072
	ds_read_b128 v[166:169], v178
	ds_read_b128 v[170:173], v178 offset:1024
	ds_read_b128 v[174:177], v178 offset:2048
	ds_read_b128 v[178:181], v178 offset:3072
	s_add_u32 s24, s24, 0x80000
	s_addc_u32 s25, s25, 0
	s_mov_b32 m0, s36
	v_lshl_add_u64 v[222:223], s[24:25], 0, v[134:135]
	ds_read_b128 v[182:185], v153 offset:32768
	ds_read_b128 v[186:189], v153 offset:33792
	ds_read_b128 v[190:193], v153 offset:34816
	ds_read_b128 v[194:197], v153 offset:35840
	ds_read_b128 v[198:201], v153 offset:36864
	ds_read_b128 v[202:205], v153 offset:37888
	ds_read_b128 v[206:209], v153 offset:38912
	ds_read_b128 v[210:213], v153 offset:39936
	global_load_lds_dwordx4 v[222:223], off
	v_lshl_add_u64 v[222:223], s[24:25], 0, v[130:131]
	s_mov_b32 m0, s37
	s_nop 0
	global_load_lds_dwordx4 v[222:223], off
	s_waitcnt vmcnt(8)
	s_waitcnt lgkmcnt(0)
	s_setprio 1
	s_barrier
	v_mfma_f32_16x16x32_bf16 v[124:127], v[144:147], v[182:185], v[124:127]
	v_mfma_f32_16x16x32_bf16 v[120:123], v[158:161], v[182:185], v[120:123]
	v_mfma_f32_16x16x32_bf16 v[116:119], v[144:147], v[190:193], v[116:119]
	v_mfma_f32_16x16x32_bf16 v[108:111], v[158:161], v[190:193], v[108:111]
	v_mfma_f32_16x16x32_bf16 v[100:103], v[144:147], v[198:201], v[100:103]
	v_mfma_f32_16x16x32_bf16 v[92:95], v[158:161], v[198:201], v[92:95]
	v_mfma_f32_16x16x32_bf16 v[84:87], v[144:147], v[206:209], v[84:87]
	v_mfma_f32_16x16x32_bf16 v[76:79], v[158:161], v[206:209], v[76:79]
	v_mfma_f32_16x16x32_bf16 v[124:127], v[154:157], v[186:189], v[124:127]
	v_mfma_f32_16x16x32_bf16 v[120:123], v[162:165], v[186:189], v[120:123]
	v_mfma_f32_16x16x32_bf16 v[116:119], v[154:157], v[194:197], v[116:119]
	v_mfma_f32_16x16x32_bf16 v[108:111], v[162:165], v[194:197], v[108:111]
	v_mfma_f32_16x16x32_bf16 v[100:103], v[154:157], v[202:205], v[100:103]
	v_mfma_f32_16x16x32_bf16 v[92:95], v[162:165], v[202:205], v[92:95]
	v_mfma_f32_16x16x32_bf16 v[84:87], v[154:157], v[210:213], v[84:87]
	v_mfma_f32_16x16x32_bf16 v[76:79], v[162:165], v[210:213], v[76:79]
	v_mfma_f32_16x16x32_bf16 v[112:115], v[166:169], v[182:185], v[112:115]
	v_mfma_f32_16x16x32_bf16 v[104:107], v[174:177], v[182:185], v[104:107]
	v_mfma_f32_16x16x32_bf16 v[96:99], v[166:169], v[190:193], v[96:99]
	v_mfma_f32_16x16x32_bf16 v[88:91], v[174:177], v[190:193], v[88:91]
	v_mfma_f32_16x16x32_bf16 v[80:83], v[166:169], v[198:201], v[80:83]
	v_mfma_f32_16x16x32_bf16 v[72:75], v[174:177], v[198:201], v[72:75]
	v_mfma_f32_16x16x32_bf16 v[68:71], v[166:169], v[206:209], v[68:71]
	v_mfma_f32_16x16x32_bf16 v[64:67], v[174:177], v[206:209], v[64:67]
	v_mfma_f32_16x16x32_bf16 v[112:115], v[170:173], v[186:189], v[112:115]
	v_mfma_f32_16x16x32_bf16 v[104:107], v[178:181], v[186:189], v[104:107]
	v_mfma_f32_16x16x32_bf16 v[96:99], v[170:173], v[194:197], v[96:99]
	v_mfma_f32_16x16x32_bf16 v[88:91], v[178:181], v[194:197], v[88:91]
	v_mfma_f32_16x16x32_bf16 v[80:83], v[170:173], v[202:205], v[80:83]
	v_mfma_f32_16x16x32_bf16 v[72:75], v[178:181], v[202:205], v[72:75]
	v_mfma_f32_16x16x32_bf16 v[68:71], v[170:173], v[210:213], v[68:71]
	v_mfma_f32_16x16x32_bf16 v[64:67], v[178:181], v[210:213], v[64:67]
	s_setprio 0
	s_barrier
; #define PG8_STAGE(bufoff, gbase, voff) do { _Pragma("unroll") for (int _i = 0; _i < 2; ++_i) \
;         __builtin_amdgcn_global_load_lds((const unsigned*)((const char*)(gbase) + (voff)[_i]), (PG8_LAS unsigned*)(lds + (bufoff) + ldsw + _i * 8192), 16, 0, 0); } while (0)
; #define PG8_LDA(dst, b, h) do { _Pragma("unroll") for (int m = 0; m < 4; ++m) _Pragma("unroll") for (int k = 0; k < 2; ++k) dst[m][k] = *(const PG8_LAS bf16x8*)(lds + PG8_SA(b, h) + aoff + m * 2048 + k * 1024); } while (0)
; #define PG8_MMA(ai, bj, At, Bt) do { __builtin_amdgcn_s_setprio(1); _Pragma("unroll") for (int m = 0; m < 4; ++m) _Pragma("unroll") for (int n = 0; n < 2; ++n) _Pragma("unroll") for (int k = 0; k < 2; ++k) \
;         acc[ai][bj][m][n] = __builtin_amdgcn_mfma_f32_16x16x32_bf16(Bt[n][k], At[m][k], acc[ai][bj][m][n], 0, 0, 0); __builtin_amdgcn_s_setprio(0); } while (0)
; #define PG8_WAIT_V(n) asm volatile("s_waitcnt vmcnt(" #n ")" ::: "memory")
; #define PG8_WAIT_L(n) asm volatile("s_waitcnt lgkmcnt(" #n ")" ::: "memory")
; #define PG8_BAR __builtin_amdgcn_s_barrier()
; #define PG8_SCHED __builtin_amdgcn_sched_barrier(0)
; template <class Epi, class Sched, bool ALIGN_EPI = false, bool SP2 = false>
; __device__ __forceinline__ void gemm_phase(PG8_LAS unsigned char* lds, const Gemm g, const Sched& S, const Epi& E, const int wave_in) {
;     ...
;         for (int t = 0; t < nt; t += 2) {
;     ...
;             PG8_LDA(At, 1, 1); PG8_STAGE(PG8_SB(1, 0), b3, voffB); PG8_STAGE(PG8_SB(1, 1), b3 + hstepB, voffB); PG8_STAGE(PG8_SA(1, 0), a3, voffA);
;             PG8_WAIT_V(8); PG8_WAIT_L(0); PG8_BAR; PG8_MMA(1, 0, At, B0); PG8_MMA(1, 1, At, B1); PG8_BAR; PG8_SCHED;
	s_add_i32 s24, s51, s30
	v_lshl_add_u64 v[214:215], v[214:215], 0, s[6:7]
	s_mov_b32 m0, s24
	ds_read_b128 v[182:185], v153 offset:49152
	ds_read_b128 v[186:189], v153 offset:50176
	ds_read_b128 v[190:193], v153 offset:51200
	ds_read_b128 v[194:197], v153 offset:52224
	ds_read_b128 v[198:201], v153 offset:53248
	ds_read_b128 v[202:205], v153 offset:54272
	ds_read_b128 v[206:209], v153 offset:55296
	ds_read_b128 v[210:213], v153 offset:56320
	global_load_lds_dwordx4 v[214:215], off
	s_add_i32 m0, s24, 0x2000
	s_add_u32 s22, s22, 0x80080
	v_lshl_add_u64 v[214:215], v[216:217], 0, s[6:7]
	s_addc_u32 s23, s23, 0
	s_add_i32 s24, s52, s30
	global_load_lds_dwordx4 v[214:215], off
	v_lshl_add_u64 v[214:215], s[22:23], 0, v[132:133]
	s_mov_b32 m0, s24
	s_nop 0
	global_load_lds_dwordx4 v[214:215], off
	v_lshl_add_u64 v[214:215], s[22:23], 0, v[128:129]
	s_add_i32 m0, s24, 0x2000
	s_nop 0
	global_load_lds_dwordx4 v[214:215], off
	v_lshl_add_u64 v[214:215], v[218:219], 0, s[6:7]
	s_mov_b32 m0, s39
	s_nop 0
	global_load_lds_dwordx4 v[214:215], off
	v_lshl_add_u64 v[214:215], v[220:221], 0, s[6:7]
	s_mov_b32 m0, s40
	s_nop 0
	global_load_lds_dwordx4 v[214:215], off
	s_waitcnt vmcnt(8)
	s_waitcnt lgkmcnt(0)
	s_setprio 1
	s_barrier
	v_mfma_f32_16x16x32_bf16 v[60:63], v[144:147], v[182:185], v[60:63]
	v_mfma_f32_16x16x32_bf16 v[56:59], v[158:161], v[182:185], v[56:59]
	v_mfma_f32_16x16x32_bf16 v[52:55], v[144:147], v[190:193], v[52:55]
	v_mfma_f32_16x16x32_bf16 v[44:47], v[158:161], v[190:193], v[44:47]
	v_mfma_f32_16x16x32_bf16 v[36:39], v[144:147], v[198:201], v[36:39]
	v_mfma_f32_16x16x32_bf16 v[28:31], v[158:161], v[198:201], v[28:31]
	v_mfma_f32_16x16x32_bf16 v[20:23], v[144:147], v[206:209], v[20:23]
	v_mfma_f32_16x16x32_bf16 v[12:15], v[158:161], v[206:209], v[12:15]
	v_mfma_f32_16x16x32_bf16 v[60:63], v[154:157], v[186:189], v[60:63]
	v_mfma_f32_16x16x32_bf16 v[56:59], v[162:165], v[186:189], v[56:59]
	v_mfma_f32_16x16x32_bf16 v[52:55], v[154:157], v[194:197], v[52:55]
	v_mfma_f32_16x16x32_bf16 v[44:47], v[162:165], v[194:197], v[44:47]
	v_mfma_f32_16x16x32_bf16 v[36:39], v[154:157], v[202:205], v[36:39]
	v_mfma_f32_16x16x32_bf16 v[28:31], v[162:165], v[202:205], v[28:31]
	v_mfma_f32_16x16x32_bf16 v[20:23], v[154:157], v[210:213], v[20:23]
	v_mfma_f32_16x16x32_bf16 v[12:15], v[162:165], v[210:213], v[12:15]
	v_mfma_f32_16x16x32_bf16 v[48:51], v[166:169], v[182:185], v[48:51]
	v_mfma_f32_16x16x32_bf16 v[40:43], v[174:177], v[182:185], v[40:43]
	v_mfma_f32_16x16x32_bf16 v[32:35], v[166:169], v[190:193], v[32:35]
	v_mfma_f32_16x16x32_bf16 v[24:27], v[174:177], v[190:193], v[24:27]
	v_mfma_f32_16x16x32_bf16 v[16:19], v[166:169], v[198:201], v[16:19]
	v_mfma_f32_16x16x32_bf16 v[8:11], v[174:177], v[198:201], v[8:11]
	v_mfma_f32_16x16x32_bf16 v[4:7], v[166:169], v[206:209], v[4:7]
	v_mfma_f32_16x16x32_bf16 v[0:3], v[174:177], v[206:209], v[0:3]
	v_mfma_f32_16x16x32_bf16 v[48:51], v[170:173], v[186:189], v[48:51]
	v_mfma_f32_16x16x32_bf16 v[40:43], v[178:181], v[186:189], v[40:43]
	v_mfma_f32_16x16x32_bf16 v[32:35], v[170:173], v[194:197], v[32:35]
	v_mfma_f32_16x16x32_bf16 v[24:27], v[178:181], v[194:197], v[24:27]
	v_mfma_f32_16x16x32_bf16 v[16:19], v[170:173], v[202:205], v[16:19]
	v_mfma_f32_16x16x32_bf16 v[8:11], v[178:181], v[202:205], v[8:11]
	v_mfma_f32_16x16x32_bf16 v[4:7], v[170:173], v[210:213], v[4:7]
	v_mfma_f32_16x16x32_bf16 v[0:3], v[178:181], v[210:213], v[0:3]
	s_setprio 0
	s_barrier
	s_add_i32 s50, s50, 2
	s_add_u32 s20, s20, 0x100
	s_addc_u32 s21, s21, 0
	s_add_u32 s48, s48, 0x100
	s_addc_u32 s49, s49, 0
	s_cmp_gt_u32 s50, 29
	s_cbranch_scc0 .LBB0_1513

;     __host__ __device__ bool next(int i, Unit& u) const { const bool ok = StaticOrder::next(i, u); u.pm = 0; u.pn = 0; return ok; }
; #define PG8_STAGE(bufoff, gbase, voff) do { _Pragma("unroll") for (int _i = 0; _i < 2; ++_i) \
;         __builtin_amdgcn_global_load_lds((const unsigned*)((const char*)(gbase) + (voff)[_i]), (PG8_LAS unsigned*)(lds + (bufoff) + ldsw + _i * 8192), 16, 0, 0); } while (0)
; #define PG8_LDA(dst, b, h) do { _Pragma("unroll") for (int m = 0; m < 4; ++m) _Pragma("unroll") for (int k = 0; k < 2; ++k) dst[m][k] = *(const PG8_LAS bf16x8*)(lds + PG8_SA(b, h) + aoff + m * 2048 + k * 1024); } while (0)
; #define PG8_LDB(dst, b, h) do { _Pragma("unroll") for (int n = 0; n < 2; ++n) _Pragma("unroll") for (int k = 0; k < 2; ++k) dst[n][k] = *(const PG8_LAS bf16x8*)(lds + PG8_SB(b, h) + boff + n * 2048 + k * 1024); } while (0)
; #define PG8_WAIT_V(n) asm volatile("s_waitcnt vmcnt(" #n ")" ::: "memory")
; #define PG8_BAR __builtin_amdgcn_s_barrier()
; template <class Epi, class Sched, bool ALIGN_EPI = false, bool SP2 = false>
; __device__ __forceinline__ void gemm_phase(PG8_LAS unsigned char* lds, const Gemm g, const Sched& S, const Epi& E, const int wave_in) {
;     ...
;         const bool has_next = S.next(ui + 1, nxt);
;         const char* nA = has_next ? (const char*)g.A + (size_t)nxt.pm * tstepA : cA; const char* nB = has_next ? (const char*)g.Bt + (size_t)nxt.pn * tstepB : cB;
;         for (int t = 0; t < nt; t += 2) {
;             const bool last = (t == nt - 2);
;             const char* a1 = cA + (size_t)(t + 1) * kstep;
;             const char* a2 = last ? nA : cA + (size_t)(t + 2) * kstep; const char* b2 = last ? nB : cB + (size_t)(t + 2) * kstep;
;             const char* a3 = a2 + kstep; const char* b3 = b2 + kstep;
;             if (last && has_next) S.a_ready(nxt);
;             if constexpr (SP2) {
;             PG8_LDB(B0, 0, 0); PG8_LDB(B1, 0, 1); PG8_SCHED; PG8_LDA(At, 0, 0); PG8_STAGE(PG8_SA(1, 1), a1 + hstepA, voffA);
;             PG8_WAIT_V(8); PG8_WAIT_L(0); PG8_BAR; PG8_MMA(0, 0, At, B0); PG8_MMA(0, 1, At, B1); PG8_BAR; PG8_SCHED;
;             PG8_LDA(At, 0, 1); PG8_STAGE(PG8_SB(0, 0), b2, voffB); PG8_STAGE(PG8_SB(0, 1), b2 + hstepB, voffB); PG8_STAGE(PG8_SA(0, 0), a2, voffA);
;             PG8_WAIT_V(8); PG8_WAIT_L(0); PG8_BAR; PG8_MMA(1, 0, At, B0); PG8_MMA(1, 1, At, B1); PG8_BAR; PG8_SCHED;
.LBB0_1824:
	s_ashr_i32 s19, s18, 31
	s_lshl_b64 s[20:21], s[18:19], 20
	s_add_u32 s20, s34, s20
	s_addc_u32 s21, s35, s21
	s_and_b64 s[22:23], s[2:3], exec
	s_cselect_b32 s19, s21, s27
	s_cselect_b32 s25, s20, s26
	s_ashr_i32 s17, s16, 31
	s_lshl_b64 s[22:23], s[16:17], 20
	s_add_u32 s22, s36, s22
	s_addc_u32 s23, s37, s23
	s_and_b64 s[30:31], s[2:3], exec
	s_cselect_b32 s17, s23, s29
	s_cselect_b32 s58, s22, s28
	s_add_u32 s26, s26, 0x80080
	s_addc_u32 s27, s27, 0
	s_add_u32 s59, s28, 0x100
	v_mov_b32_e32 v0, 0
	s_addc_u32 s60, s29, 0
	s_mov_b32 s61, -2
	s_waitcnt vmcnt(0)
	ds_read_b128 v[128:131], v214
	ds_read_b128 v[132:135], v214 offset:1024
	ds_read_b128 v[136:139], v214 offset:2048
	ds_read_b128 v[140:143], v214 offset:3072
	ds_read_b128 v[162:165], v215
	ds_read_b128 v[166:169], v215 offset:1024
	ds_read_b128 v[170:173], v215 offset:2048
	ds_read_b128 v[174:177], v215 offset:3072
	s_add_u32 s28, s26, 0xfff80080
	s_addc_u32 s29, s27, -1
	s_cmp_eq_u32 s61, 28
	s_cselect_b32 s31, s19, s29
	s_cselect_b32 s30, s25, s28
	s_cselect_b32 s29, s17, s60
	s_cselect_b32 s28, s58, s59
	v_lshl_add_u64 v[210:211], s[26:27], 0, v[154:155]
	s_add_i32 m0, s41, 0xc000
	ds_read_b128 v[178:181], v216
	ds_read_b128 v[182:185], v216 offset:1024
	ds_read_b128 v[186:189], v216 offset:2048
	ds_read_b128 v[190:193], v216 offset:3072
	ds_read_b128 v[194:197], v216 offset:4096
	ds_read_b128 v[198:201], v216 offset:5120
	ds_read_b128 v[202:205], v216 offset:6144
	ds_read_b128 v[206:209], v216 offset:7168
	global_load_lds_dwordx4 v[210:211], off
	v_lshl_add_u64 v[210:211], s[26:27], 0, v[156:157]
	s_add_i32 m0, s41, 0xe000
	s_nop 0
	global_load_lds_dwordx4 v[210:211], off
	s_waitcnt vmcnt(8)
	s_waitcnt lgkmcnt(0)
	s_setprio 1
	s_barrier
	v_mfma_f32_16x16x32_bf16 v[124:127], v[128:131], v[178:181], 0
	v_mfma_f32_16x16x32_bf16 v[120:123], v[136:139], v[178:181], 0
	v_mfma_f32_16x16x32_bf16 v[112:115], v[128:131], v[186:189], 0
	v_mfma_f32_16x16x32_bf16 v[104:107], v[136:139], v[186:189], 0
	v_mfma_f32_16x16x32_bf16 v[100:103], v[128:131], v[194:197], 0
	v_mfma_f32_16x16x32_bf16 v[96:99], v[136:139], v[194:197], 0
	v_mfma_f32_16x16x32_bf16 v[76:79], v[128:131], v[202:205], 0
	v_mfma_f32_16x16x32_bf16 v[72:75], v[136:139], v[202:205], 0
	v_mfma_f32_16x16x32_bf16 v[124:127], v[132:135], v[182:185], v[124:127]
	v_mfma_f32_16x16x32_bf16 v[120:123], v[140:143], v[182:185], v[120:123]
	v_mfma_f32_16x16x32_bf16 v[112:115], v[132:135], v[190:193], v[112:115]
	v_mfma_f32_16x16x32_bf16 v[104:107], v[140:143], v[190:193], v[104:107]
	v_mfma_f32_16x16x32_bf16 v[100:103], v[132:135], v[198:201], v[100:103]
	v_mfma_f32_16x16x32_bf16 v[96:99], v[140:143], v[198:201], v[96:99]
	v_mfma_f32_16x16x32_bf16 v[76:79], v[132:135], v[206:209], v[76:79]
	v_mfma_f32_16x16x32_bf16 v[72:75], v[140:143], v[206:209], v[72:75]
	v_mfma_f32_16x16x32_bf16 v[116:119], v[162:165], v[178:181], 0
	v_mfma_f32_16x16x32_bf16 v[108:111], v[170:173], v[178:181], 0
	v_mfma_f32_16x16x32_bf16 v[92:95], v[162:165], v[186:189], 0
	v_mfma_f32_16x16x32_bf16 v[88:91], v[170:173], v[186:189], 0
	v_mfma_f32_16x16x32_bf16 v[84:87], v[162:165], v[194:197], 0
	v_mfma_f32_16x16x32_bf16 v[80:83], v[170:173], v[194:197], 0
	v_mfma_f32_16x16x32_bf16 v[68:71], v[162:165], v[202:205], 0
	v_mfma_f32_16x16x32_bf16 v[64:67], v[170:173], v[202:205], 0
	v_mfma_f32_16x16x32_bf16 v[116:119], v[166:169], v[182:185], v[116:119]
	v_mfma_f32_16x16x32_bf16 v[108:111], v[174:177], v[182:185], v[108:111]
	v_mfma_f32_16x16x32_bf16 v[92:95], v[166:169], v[190:193], v[92:95]
	v_mfma_f32_16x16x32_bf16 v[88:91], v[174:177], v[190:193], v[88:91]
	v_mfma_f32_16x16x32_bf16 v[84:87], v[166:169], v[198:201], v[84:87]
	v_mfma_f32_16x16x32_bf16 v[80:83], v[174:177], v[198:201], v[80:83]
	v_mfma_f32_16x16x32_bf16 v[68:71], v[166:169], v[206:209], v[68:71]
	v_mfma_f32_16x16x32_bf16 v[64:67], v[174:177], v[206:209], v[64:67]
	s_setprio 0
	s_barrier
	s_add_i32 s62, s51, s38
	v_lshl_add_u64 v[210:211], s[28:29], 0, v[148:149]
	s_mov_b32 m0, s62
	ds_read_b128 v[178:181], v216 offset:16384
	ds_read_b128 v[182:185], v216 offset:17408
	ds_read_b128 v[186:189], v216 offset:18432
	ds_read_b128 v[190:193], v216 offset:19456
	ds_read_b128 v[194:197], v216 offset:20480
	ds_read_b128 v[198:201], v216 offset:21504
	ds_read_b128 v[202:205], v216 offset:22528
	ds_read_b128 v[206:209], v216 offset:23552
	global_load_lds_dwordx4 v[210:211], off
	s_add_i32 m0, s62, 0x2000
	s_add_u32 s62, s28, 0x80000
	v_lshl_add_u64 v[218:219], s[28:29], 0, v[144:145]
	s_addc_u32 s63, s29, 0
	s_add_i32 s64, s52, s38
	global_load_lds_dwordx4 v[218:219], off
	v_lshl_add_u64 v[220:221], s[62:63], 0, v[148:149]
	s_mov_b32 m0, s64
	v_lshl_add_u64 v[222:223], s[30:31], 0, v[146:147]
	global_load_lds_dwordx4 v[220:221], off
	v_lshl_add_u64 v[220:221], s[62:63], 0, v[144:145]
	s_add_i32 m0, s64, 0x2000
	s_nop 0
	global_load_lds_dwordx4 v[220:221], off
	v_lshl_add_u64 v[220:221], s[30:31], 0, v[150:151]
	s_mov_b32 m0, s41
	s_nop 0
	global_load_lds_dwordx4 v[220:221], off
	s_mov_b32 m0, s42
	s_nop 0
	global_load_lds_dwordx4 v[222:223], off
	s_waitcnt vmcnt(8)
	s_waitcnt lgkmcnt(0)
	s_setprio 1
	s_barrier
; #define PG8_STAGE(bufoff, gbase, voff) do { _Pragma("unroll") for (int _i = 0; _i < 2; ++_i) \
;         __builtin_amdgcn_global_load_lds((const unsigned*)((const char*)(gbase) + (voff)[_i]), (PG8_LAS unsigned*)(lds + (bufoff) + ldsw + _i * 8192), 16, 0, 0); } while (0)
; #define PG8_LDA(dst, b, h) do { _Pragma("unroll") for (int m = 0; m < 4; ++m) _Pragma("unroll") for (int k = 0; k < 2; ++k) dst[m][k] = *(const PG8_LAS bf16x8*)(lds + PG8_SA(b, h) + aoff + m * 2048 + k * 1024); } while (0)
; #define PG8_LDB(dst, b, h) do { _Pragma("unroll") for (int n = 0; n < 2; ++n) _Pragma("unroll") for (int k = 0; k < 2; ++k) dst[n][k] = *(const PG8_LAS bf16x8*)(lds + PG8_SB(b, h) + boff + n * 2048 + k * 1024); } while (0)
; #define PG8_MMA(ai, bj, At, Bt) do { __builtin_amdgcn_s_setprio(1); _Pragma("unroll") for (int m = 0; m < 4; ++m) _Pragma("unroll") for (int n = 0; n < 2; ++n) _Pragma("unroll") for (int k = 0; k < 2; ++k) \
;         acc[ai][bj][m][n] = __builtin_amdgcn_mfma_f32_16x16x32_bf16(Bt[n][k], At[m][k], acc[ai][bj][m][n], 0, 0, 0); __builtin_amdgcn_s_setprio(0); } while (0)
; #define PG8_WAIT_V(n) asm volatile("s_waitcnt vmcnt(" #n ")" ::: "memory")
; #define PG8_WAIT_L(n) asm volatile("s_waitcnt lgkmcnt(" #n ")" ::: "memory")
; #define PG8_BAR __builtin_amdgcn_s_barrier()
; #define PG8_SCHED __builtin_amdgcn_sched_barrier(0)
; template <class Epi, class Sched, bool ALIGN_EPI = false, bool SP2 = false>
; __device__ __forceinline__ void gemm_phase(PG8_LAS unsigned char* lds, const Gemm g, const Sched& S, const Epi& E, const int wave_in) {
;     ...
;             PG8_WAIT_V(8); PG8_WAIT_L(0); PG8_BAR; PG8_MMA(1, 0, At, B0); PG8_MMA(1, 1, At, B1); PG8_BAR; PG8_SCHED;
;             PG8_LDB(B0, 1, 0); PG8_LDB(B1, 1, 1); PG8_SCHED; PG8_LDA(At, 1, 0); PG8_STAGE(PG8_SA(0, 1), a2 + hstepA, voffA);
;             PG8_WAIT_V(8); PG8_WAIT_L(0); PG8_BAR; PG8_MMA(0, 0, At, B0); PG8_MMA(0, 1, At, B1); PG8_BAR; PG8_SCHED;
	v_mfma_f32_16x16x32_bf16 v[60:63], v[128:131], v[178:181], 0
	v_mfma_f32_16x16x32_bf16 v[56:59], v[136:139], v[178:181], 0
	v_mfma_f32_16x16x32_bf16 v[48:51], v[128:131], v[186:189], 0
	v_mfma_f32_16x16x32_bf16 v[40:43], v[136:139], v[186:189], 0
	v_mfma_f32_16x16x32_bf16 v[32:35], v[128:131], v[194:197], 0
	v_mfma_f32_16x16x32_bf16 v[24:27], v[136:139], v[194:197], 0
	v_mfma_f32_16x16x32_bf16 v[16:19], v[128:131], v[202:205], 0
	v_mfma_f32_16x16x32_bf16 v[8:11], v[136:139], v[202:205], 0
	v_mfma_f32_16x16x32_bf16 v[60:63], v[132:135], v[182:185], v[60:63]
	v_mfma_f32_16x16x32_bf16 v[56:59], v[140:143], v[182:185], v[56:59]
	v_mfma_f32_16x16x32_bf16 v[48:51], v[132:135], v[190:193], v[48:51]
	v_mfma_f32_16x16x32_bf16 v[40:43], v[140:143], v[190:193], v[40:43]
	v_mfma_f32_16x16x32_bf16 v[32:35], v[132:135], v[198:201], v[32:35]
	v_mfma_f32_16x16x32_bf16 v[24:27], v[140:143], v[198:201], v[24:27]
	v_mfma_f32_16x16x32_bf16 v[16:19], v[132:135], v[206:209], v[16:19]
	v_mfma_f32_16x16x32_bf16 v[8:11], v[140:143], v[206:209], v[8:11]
	v_mfma_f32_16x16x32_bf16 v[52:55], v[162:165], v[178:181], 0
	v_mfma_f32_16x16x32_bf16 v[44:47], v[170:173], v[178:181], 0
	v_mfma_f32_16x16x32_bf16 v[36:39], v[162:165], v[186:189], 0
	v_mfma_f32_16x16x32_bf16 v[28:31], v[170:173], v[186:189], 0
	v_mfma_f32_16x16x32_bf16 v[20:23], v[162:165], v[194:197], 0
	v_mfma_f32_16x16x32_bf16 v[12:15], v[170:173], v[194:197], 0
	v_mfma_f32_16x16x32_bf16 v[4:7], v[162:165], v[202:205], 0
	v_mfma_f32_16x16x32_bf16 v[0:3], v[170:173], v[202:205], 0
	v_mfma_f32_16x16x32_bf16 v[52:55], v[166:169], v[182:185], v[52:55]
	v_mfma_f32_16x16x32_bf16 v[44:47], v[174:177], v[182:185], v[44:47]
	v_mfma_f32_16x16x32_bf16 v[36:39], v[166:169], v[190:193], v[36:39]
	v_mfma_f32_16x16x32_bf16 v[28:31], v[174:177], v[190:193], v[28:31]
	v_mfma_f32_16x16x32_bf16 v[20:23], v[166:169], v[198:201], v[20:23]
	v_mfma_f32_16x16x32_bf16 v[12:15], v[174:177], v[198:201], v[12:15]
	v_mfma_f32_16x16x32_bf16 v[4:7], v[166:169], v[206:209], v[4:7]
	v_mfma_f32_16x16x32_bf16 v[0:3], v[174:177], v[206:209], v[0:3]
	s_setprio 0
	s_barrier
	s_add_i32 s62, 0, 0x18000
	s_add_i32 s63, 0, 0x1c000
	v_add_u32_e32 v140, s62, v212
	v_add_u32_e32 v174, s63, v212
	ds_read_b128 v[128:131], v140
	ds_read_b128 v[132:135], v140 offset:1024
	ds_read_b128 v[136:139], v140 offset:2048
	ds_read_b128 v[140:143], v140 offset:3072
	ds_read_b128 v[162:165], v174
	ds_read_b128 v[166:169], v174 offset:1024
	ds_read_b128 v[170:173], v174 offset:2048
	ds_read_b128 v[174:177], v174 offset:3072
	s_add_u32 s30, s30, 0x80000
	s_addc_u32 s31, s31, 0
	s_mov_b32 m0, s43
	v_lshl_add_u64 v[224:225], s[30:31], 0, v[150:151]
	ds_read_b128 v[178:181], v216 offset:32768
	ds_read_b128 v[182:185], v216 offset:33792
	ds_read_b128 v[186:189], v216 offset:34816
	ds_read_b128 v[190:193], v216 offset:35840
	ds_read_b128 v[194:197], v216 offset:36864
	ds_read_b128 v[198:201], v216 offset:37888
	ds_read_b128 v[202:205], v216 offset:38912
	ds_read_b128 v[206:209], v216 offset:39936
	global_load_lds_dwordx4 v[224:225], off
	v_lshl_add_u64 v[224:225], s[30:31], 0, v[146:147]
	s_mov_b32 m0, s44
	s_nop 0
	global_load_lds_dwordx4 v[224:225], off
	s_waitcnt vmcnt(8)
	s_waitcnt lgkmcnt(0)
	s_setprio 1
	s_barrier
	v_mfma_f32_16x16x32_bf16 v[124:127], v[128:131], v[178:181], v[124:127]
	v_mfma_f32_16x16x32_bf16 v[120:123], v[136:139], v[178:181], v[120:123]
	v_mfma_f32_16x16x32_bf16 v[112:115], v[128:131], v[186:189], v[112:115]
	v_mfma_f32_16x16x32_bf16 v[104:107], v[136:139], v[186:189], v[104:107]
	v_mfma_f32_16x16x32_bf16 v[100:103], v[128:131], v[194:197], v[100:103]
	v_mfma_f32_16x16x32_bf16 v[96:99], v[136:139], v[194:197], v[96:99]
	v_mfma_f32_16x16x32_bf16 v[76:79], v[128:131], v[202:205], v[76:79]
	v_mfma_f32_16x16x32_bf16 v[72:75], v[136:139], v[202:205], v[72:75]
	v_mfma_f32_16x16x32_bf16 v[124:127], v[132:135], v[182:185], v[124:127]
	v_mfma_f32_16x16x32_bf16 v[120:123], v[140:143], v[182:185], v[120:123]
	v_mfma_f32_16x16x32_bf16 v[112:115], v[132:135], v[190:193], v[112:115]
	v_mfma_f32_16x16x32_bf16 v[104:107], v[140:143], v[190:193], v[104:107]
	v_mfma_f32_16x16x32_bf16 v[100:103], v[132:135], v[198:201], v[100:103]
	v_mfma_f32_16x16x32_bf16 v[96:99], v[140:143], v[198:201], v[96:99]
	v_mfma_f32_16x16x32_bf16 v[76:79], v[132:135], v[206:209], v[76:79]
	v_mfma_f32_16x16x32_bf16 v[72:75], v[140:143], v[206:209], v[72:75]
	v_mfma_f32_16x16x32_bf16 v[116:119], v[162:165], v[178:181], v[116:119]
	v_mfma_f32_16x16x32_bf16 v[108:111], v[170:173], v[178:181], v[108:111]
	v_mfma_f32_16x16x32_bf16 v[92:95], v[162:165], v[186:189], v[92:95]
	v_mfma_f32_16x16x32_bf16 v[88:91], v[170:173], v[186:189], v[88:91]
	v_mfma_f32_16x16x32_bf16 v[84:87], v[162:165], v[194:197], v[84:87]
	v_mfma_f32_16x16x32_bf16 v[80:83], v[170:173], v[194:197], v[80:83]
	v_mfma_f32_16x16x32_bf16 v[68:71], v[162:165], v[202:205], v[68:71]
	v_mfma_f32_16x16x32_bf16 v[64:67], v[170:173], v[202:205], v[64:67]
	v_mfma_f32_16x16x32_bf16 v[116:119], v[166:169], v[182:185], v[116:119]
	v_mfma_f32_16x16x32_bf16 v[108:111], v[174:177], v[182:185], v[108:111]
	v_mfma_f32_16x16x32_bf16 v[92:95], v[166:169], v[190:193], v[92:95]
	v_mfma_f32_16x16x32_bf16 v[88:91], v[174:177], v[190:193], v[88:91]
	v_mfma_f32_16x16x32_bf16 v[84:87], v[166:169], v[198:201], v[84:87]
	v_mfma_f32_16x16x32_bf16 v[80:83], v[174:177], v[198:201], v[80:83]
	v_mfma_f32_16x16x32_bf16 v[68:71], v[166:169], v[206:209], v[68:71]
	v_mfma_f32_16x16x32_bf16 v[64:67], v[174:177], v[206:209], v[64:67]
	s_setprio 0
	s_barrier
; #define PG8_STAGE(bufoff, gbase, voff) do { _Pragma("unroll") for (int _i = 0; _i < 2; ++_i) \
;         __builtin_amdgcn_global_load_lds((const unsigned*)((const char*)(gbase) + (voff)[_i]), (PG8_LAS unsigned*)(lds + (bufoff) + ldsw + _i * 8192), 16, 0, 0); } while (0)
; #define PG8_LDA(dst, b, h) do { _Pragma("unroll") for (int m = 0; m < 4; ++m) _Pragma("unroll") for (int k = 0; k < 2; ++k) dst[m][k] = *(const PG8_LAS bf16x8*)(lds + PG8_SA(b, h) + aoff + m * 2048 + k * 1024); } while (0)
; #define PG8_LDB(dst, b, h) do { _Pragma("unroll") for (int n = 0; n < 2; ++n) _Pragma("unroll") for (int k = 0; k < 2; ++k) dst[n][k] = *(const PG8_LAS bf16x8*)(lds + PG8_SB(b, h) + boff + n * 2048 + k * 1024); } while (0)
; #define PG8_WAIT_V(n) asm volatile("s_waitcnt vmcnt(" #n ")" ::: "memory")
; #define PG8_WAIT_L(n) asm volatile("s_waitcnt lgkmcnt(" #n ")" ::: "memory")
; #define PG8_BAR __builtin_amdgcn_s_barrier()
; template <class Epi, class Sched, bool ALIGN_EPI = false, bool SP2 = false>
; __device__ __forceinline__ void gemm_phase(PG8_LAS unsigned char* lds, const Gemm g, const Sched& S, const Epi& E, const int wave_in) {
;     ...
;         for (int t = 0; t < nt; t += 2) {
;             const bool last = (t == nt - 2);
;             const char* a1 = cA + (size_t)(t + 1) * kstep;
;             const char* a2 = last ? nA : cA + (size_t)(t + 2) * kstep; const char* b2 = last ? nB : cB + (size_t)(t + 2) * kstep;
;             const char* a3 = a2 + kstep; const char* b3 = b2 + kstep;
;             if (last && has_next) S.a_ready(nxt);
;             if constexpr (SP2) {
;             PG8_LDB(B0, 0, 0); PG8_LDB(B1, 0, 1); PG8_SCHED; PG8_LDA(At, 0, 0); PG8_STAGE(PG8_SA(1, 1), a1 + hstepA, voffA);
;             PG8_WAIT_V(8); PG8_WAIT_L(0); PG8_BAR; PG8_MMA(0, 0, At, B0); PG8_MMA(0, 1, At, B1); PG8_BAR; PG8_SCHED;
;             PG8_LDA(At, 0, 1); PG8_STAGE(PG8_SB(0, 0), b2, voffB); PG8_STAGE(PG8_SB(0, 1), b2 + hstepB, voffB); PG8_STAGE(PG8_SA(0, 0), a2, voffA);
;             PG8_WAIT_V(8); PG8_WAIT_L(0); PG8_BAR; PG8_MMA(1, 0, At, B0); PG8_MMA(1, 1, At, B1); PG8_BAR; PG8_SCHED;
;     ...
;             PG8_LDA(At, 1, 1); PG8_STAGE(PG8_SB(1, 0), b3, voffB); PG8_STAGE(PG8_SB(1, 1), b3 + hstepB, voffB); PG8_STAGE(PG8_SA(1, 0), a3, voffA);
;             PG8_WAIT_V(8); PG8_WAIT_L(0); PG8_BAR; PG8_MMA(1, 0, At, B0); PG8_MMA(1, 1, At, B1); PG8_BAR; PG8_SCHED;
	s_add_i32 s30, s62, s38
	v_lshl_add_u64 v[210:211], v[210:211], 0, s[6:7]
	s_mov_b32 m0, s30
	ds_read_b128 v[178:181], v216 offset:49152
	ds_read_b128 v[182:185], v216 offset:50176
	ds_read_b128 v[186:189], v216 offset:51200
	ds_read_b128 v[190:193], v216 offset:52224
	ds_read_b128 v[194:197], v216 offset:53248
	ds_read_b128 v[198:201], v216 offset:54272
	ds_read_b128 v[202:205], v216 offset:55296
	ds_read_b128 v[206:209], v216 offset:56320
	global_load_lds_dwordx4 v[210:211], off
	s_add_i32 m0, s30, 0x2000
	s_add_u32 s28, s28, 0x80080
	v_lshl_add_u64 v[210:211], v[218:219], 0, s[6:7]
	s_addc_u32 s29, s29, 0
	s_add_i32 s30, s63, s38
	global_load_lds_dwordx4 v[210:211], off
	v_lshl_add_u64 v[210:211], s[28:29], 0, v[148:149]
	s_mov_b32 m0, s30
	s_nop 0
	global_load_lds_dwordx4 v[210:211], off
	v_lshl_add_u64 v[210:211], s[28:29], 0, v[144:145]
	s_add_i32 m0, s30, 0x2000
	s_nop 0
	global_load_lds_dwordx4 v[210:211], off
	v_lshl_add_u64 v[210:211], v[220:221], 0, s[6:7]
	s_mov_b32 m0, s48
	s_nop 0
	global_load_lds_dwordx4 v[210:211], off
	v_lshl_add_u64 v[210:211], v[222:223], 0, s[6:7]
	s_mov_b32 m0, s49
	s_nop 0
	global_load_lds_dwordx4 v[210:211], off
	s_waitcnt vmcnt(8)
	s_waitcnt lgkmcnt(0)
	s_setprio 1
	s_barrier
	v_mfma_f32_16x16x32_bf16 v[60:63], v[128:131], v[178:181], v[60:63]
	v_mfma_f32_16x16x32_bf16 v[56:59], v[136:139], v[178:181], v[56:59]
	v_mfma_f32_16x16x32_bf16 v[48:51], v[128:131], v[186:189], v[48:51]
	v_mfma_f32_16x16x32_bf16 v[40:43], v[136:139], v[186:189], v[40:43]
	v_mfma_f32_16x16x32_bf16 v[32:35], v[128:131], v[194:197], v[32:35]
	v_mfma_f32_16x16x32_bf16 v[24:27], v[136:139], v[194:197], v[24:27]
	v_mfma_f32_16x16x32_bf16 v[16:19], v[128:131], v[202:205], v[16:19]
	v_mfma_f32_16x16x32_bf16 v[8:11], v[136:139], v[202:205], v[8:11]
	v_mfma_f32_16x16x32_bf16 v[60:63], v[132:135], v[182:185], v[60:63]
	v_mfma_f32_16x16x32_bf16 v[56:59], v[140:143], v[182:185], v[56:59]
	v_mfma_f32_16x16x32_bf16 v[48:51], v[132:135], v[190:193], v[48:51]
	v_mfma_f32_16x16x32_bf16 v[40:43], v[140:143], v[190:193], v[40:43]
	v_mfma_f32_16x16x32_bf16 v[32:35], v[132:135], v[198:201], v[32:35]
	v_mfma_f32_16x16x32_bf16 v[24:27], v[140:143], v[198:201], v[24:27]
	v_mfma_f32_16x16x32_bf16 v[16:19], v[132:135], v[206:209], v[16:19]
	v_mfma_f32_16x16x32_bf16 v[8:11], v[140:143], v[206:209], v[8:11]
	v_mfma_f32_16x16x32_bf16 v[52:55], v[162:165], v[178:181], v[52:55]
	v_mfma_f32_16x16x32_bf16 v[44:47], v[170:173], v[178:181], v[44:47]
	v_mfma_f32_16x16x32_bf16 v[36:39], v[162:165], v[186:189], v[36:39]
	v_mfma_f32_16x16x32_bf16 v[28:31], v[170:173], v[186:189], v[28:31]
	v_mfma_f32_16x16x32_bf16 v[20:23], v[162:165], v[194:197], v[20:23]
	v_mfma_f32_16x16x32_bf16 v[12:15], v[170:173], v[194:197], v[12:15]
	v_mfma_f32_16x16x32_bf16 v[4:7], v[162:165], v[202:205], v[4:7]
	v_mfma_f32_16x16x32_bf16 v[0:3], v[170:173], v[202:205], v[0:3]
	v_mfma_f32_16x16x32_bf16 v[52:55], v[166:169], v[182:185], v[52:55]
	v_mfma_f32_16x16x32_bf16 v[44:47], v[174:177], v[182:185], v[44:47]
	v_mfma_f32_16x16x32_bf16 v[36:39], v[166:169], v[190:193], v[36:39]
	v_mfma_f32_16x16x32_bf16 v[28:31], v[174:177], v[190:193], v[28:31]
	v_mfma_f32_16x16x32_bf16 v[20:23], v[166:169], v[198:201], v[20:23]
	v_mfma_f32_16x16x32_bf16 v[12:15], v[174:177], v[198:201], v[12:15]
	v_mfma_f32_16x16x32_bf16 v[4:7], v[166:169], v[206:209], v[4:7]
	v_mfma_f32_16x16x32_bf16 v[0:3], v[174:177], v[206:209], v[0:3]
	s_setprio 0
	s_barrier
	s_add_i32 s61, s61, 2
	s_add_u32 s26, s26, 0x100
	s_addc_u32 s27, s27, 0
	s_add_u32 s59, s59, 0x100
	s_addc_u32 s60, s60, 0
	s_cmp_gt_u32 s61, 29
	s_cbranch_scc0 .LBB0_1825
	s_branch .Lkx_20
.LBB0_1825:
	ds_read_b128 v[128:131], v214
	ds_read_b128 v[132:135], v214 offset:1024
	ds_read_b128 v[136:139], v214 offset:2048
	ds_read_b128 v[140:143], v214 offset:3072
	ds_read_b128 v[162:165], v215
	ds_read_b128 v[166:169], v215 offset:1024
	ds_read_b128 v[170:173], v215 offset:2048
	ds_read_b128 v[174:177], v215 offset:3072
	s_add_u32 s28, s26, 0xfff80080
	s_addc_u32 s29, s27, -1
	s_cmp_eq_u32 s61, 28
	s_cselect_b32 s31, s19, s29
	s_cselect_b32 s30, s25, s28
	s_cselect_b32 s29, s17, s60
	s_cselect_b32 s28, s58, s59
	v_lshl_add_u64 v[210:211], s[26:27], 0, v[154:155]
	s_add_i32 m0, s41, 0xc000
	ds_read_b128 v[178:181], v216
	ds_read_b128 v[182:185], v216 offset:1024
	ds_read_b128 v[186:189], v216 offset:2048
	ds_read_b128 v[190:193], v216 offset:3072
	ds_read_b128 v[194:197], v216 offset:4096
	ds_read_b128 v[198:201], v216 offset:5120
	ds_read_b128 v[202:205], v216 offset:6144
	ds_read_b128 v[206:209], v216 offset:7168
	global_load_lds_dwordx4 v[210:211], off
	v_lshl_add_u64 v[210:211], s[26:27], 0, v[156:157]
	s_add_i32 m0, s41, 0xe000
	s_nop 0
	global_load_lds_dwordx4 v[210:211], off
	s_waitcnt vmcnt(8)
	s_waitcnt lgkmcnt(0)
	s_setprio 1
	s_barrier
; #define PG8_STAGE(bufoff, gbase, voff) do { _Pragma("unroll") for (int _i = 0; _i < 2; ++_i) \
;         __builtin_amdgcn_global_load_lds((const unsigned*)((const char*)(gbase) + (voff)[_i]), (PG8_LAS unsigned*)(lds + (bufoff) + ldsw + _i * 8192), 16, 0, 0); } while (0)
; #define PG8_LDA(dst, b, h) do { _Pragma("unroll") for (int m = 0; m < 4; ++m) _Pragma("unroll") for (int k = 0; k < 2; ++k) dst[m][k] = *(const PG8_LAS bf16x8*)(lds + PG8_SA(b, h) + aoff + m * 2048 + k * 1024); } while (0)
; #define PG8_LDB(dst, b, h) do { _Pragma("unroll") for (int n = 0; n < 2; ++n) _Pragma("unroll") for (int k = 0; k < 2; ++k) dst[n][k] = *(const PG8_LAS bf16x8*)(lds + PG8_SB(b, h) + boff + n * 2048 + k * 1024); } while (0)
; #define PG8_MMA(ai, bj, At, Bt) do { __builtin_amdgcn_s_setprio(1); _Pragma("unroll") for (int m = 0; m < 4; ++m) _Pragma("unroll") for (int n = 0; n < 2; ++n) _Pragma("unroll") for (int k = 0; k < 2; ++k) \
;         acc[ai][bj][m][n] = __builtin_amdgcn_mfma_f32_16x16x32_bf16(Bt[n][k], At[m][k], acc[ai][bj][m][n], 0, 0, 0); __builtin_amdgcn_s_setprio(0); } while (0)
; #define PG8_WAIT_V(n) asm volatile("s_waitcnt vmcnt(" #n ")" ::: "memory")
; #define PG8_WAIT_L(n) asm volatile("s_waitcnt lgkmcnt(" #n ")" ::: "memory")
; #define PG8_BAR __builtin_amdgcn_s_barrier()
; #define PG8_SCHED __builtin_amdgcn_sched_barrier(0)
; template <class Epi, class Sched, bool ALIGN_EPI = false, bool SP2 = false>
; __device__ __forceinline__ void gemm_phase(PG8_LAS unsigned char* lds, const Gemm g, const Sched& S, const Epi& E, const int wave_in) {
;     ...
;             PG8_LDB(B0, 0, 0); PG8_LDB(B1, 0, 1); PG8_SCHED; PG8_LDA(At, 0, 0); PG8_STAGE(PG8_SA(1, 1), a1 + hstepA, voffA);
;             PG8_WAIT_V(8); PG8_WAIT_L(0); PG8_BAR; PG8_MMA(0, 0, At, B0); PG8_MMA(0, 1, At, B1); PG8_BAR; PG8_SCHED;
;             PG8_LDA(At, 0, 1); PG8_STAGE(PG8_SB(0, 0), b2, voffB); PG8_STAGE(PG8_SB(0, 1), b2 + hstepB, voffB); PG8_STAGE(PG8_SA(0, 0), a2, voffA);
;             PG8_WAIT_V(8); PG8_WAIT_L(0); PG8_BAR; PG8_MMA(1, 0, At, B0); PG8_MMA(1, 1, At, B1); PG8_BAR; PG8_SCHED;
;             PG8_LDB(B0, 1, 0); PG8_LDB(B1, 1, 1); PG8_SCHED; PG8_LDA(At, 1, 0); PG8_STAGE(PG8_SA(0, 1), a2 + hstepA, voffA);
;             PG8_WAIT_V(8); PG8_WAIT_L(0); PG8_BAR; PG8_MMA(0, 0, At, B0); PG8_MMA(0, 1, At, B1); PG8_BAR; PG8_SCHED;
	v_mfma_f32_16x16x32_bf16 v[124:127], v[128:131], v[178:181], v[124:127]
	v_mfma_f32_16x16x32_bf16 v[120:123], v[136:139], v[178:181], v[120:123]
	v_mfma_f32_16x16x32_bf16 v[112:115], v[128:131], v[186:189], v[112:115]
	v_mfma_f32_16x16x32_bf16 v[104:107], v[136:139], v[186:189], v[104:107]
	v_mfma_f32_16x16x32_bf16 v[100:103], v[128:131], v[194:197], v[100:103]
	v_mfma_f32_16x16x32_bf16 v[96:99], v[136:139], v[194:197], v[96:99]
	v_mfma_f32_16x16x32_bf16 v[76:79], v[128:131], v[202:205], v[76:79]
	v_mfma_f32_16x16x32_bf16 v[72:75], v[136:139], v[202:205], v[72:75]
	v_mfma_f32_16x16x32_bf16 v[124:127], v[132:135], v[182:185], v[124:127]
	v_mfma_f32_16x16x32_bf16 v[120:123], v[140:143], v[182:185], v[120:123]
	v_mfma_f32_16x16x32_bf16 v[112:115], v[132:135], v[190:193], v[112:115]
	v_mfma_f32_16x16x32_bf16 v[104:107], v[140:143], v[190:193], v[104:107]
	v_mfma_f32_16x16x32_bf16 v[100:103], v[132:135], v[198:201], v[100:103]
	v_mfma_f32_16x16x32_bf16 v[96:99], v[140:143], v[198:201], v[96:99]
	v_mfma_f32_16x16x32_bf16 v[76:79], v[132:135], v[206:209], v[76:79]
	v_mfma_f32_16x16x32_bf16 v[72:75], v[140:143], v[206:209], v[72:75]
	v_mfma_f32_16x16x32_bf16 v[116:119], v[162:165], v[178:181], v[116:119]
	v_mfma_f32_16x16x32_bf16 v[108:111], v[170:173], v[178:181], v[108:111]
	v_mfma_f32_16x16x32_bf16 v[92:95], v[162:165], v[186:189], v[92:95]
	v_mfma_f32_16x16x32_bf16 v[88:91], v[170:173], v[186:189], v[88:91]
	v_mfma_f32_16x16x32_bf16 v[84:87], v[162:165], v[194:197], v[84:87]
	v_mfma_f32_16x16x32_bf16 v[80:83], v[170:173], v[194:197], v[80:83]
	v_mfma_f32_16x16x32_bf16 v[68:71], v[162:165], v[202:205], v[68:71]
	v_mfma_f32_16x16x32_bf16 v[64:67], v[170:173], v[202:205], v[64:67]
	v_mfma_f32_16x16x32_bf16 v[116:119], v[166:169], v[182:185], v[116:119]
	v_mfma_f32_16x16x32_bf16 v[108:111], v[174:177], v[182:185], v[108:111]
	v_mfma_f32_16x16x32_bf16 v[92:95], v[166:169], v[190:193], v[92:95]
	v_mfma_f32_16x16x32_bf16 v[88:91], v[174:177], v[190:193], v[88:91]
	v_mfma_f32_16x16x32_bf16 v[84:87], v[166:169], v[198:201], v[84:87]
	v_mfma_f32_16x16x32_bf16 v[80:83], v[174:177], v[198:201], v[80:83]
	v_mfma_f32_16x16x32_bf16 v[68:71], v[166:169], v[206:209], v[68:71]
	v_mfma_f32_16x16x32_bf16 v[64:67], v[174:177], v[206:209], v[64:67]
	s_setprio 0
	s_barrier
	s_add_i32 s62, s51, s38
	v_lshl_add_u64 v[210:211], s[28:29], 0, v[148:149]
	s_mov_b32 m0, s62
	ds_read_b128 v[178:181], v216 offset:16384
	ds_read_b128 v[182:185], v216 offset:17408
	ds_read_b128 v[186:189], v216 offset:18432
	ds_read_b128 v[190:193], v216 offset:19456
	ds_read_b128 v[194:197], v216 offset:20480
	ds_read_b128 v[198:201], v216 offset:21504
	ds_read_b128 v[202:205], v216 offset:22528
	ds_read_b128 v[206:209], v216 offset:23552
	global_load_lds_dwordx4 v[210:211], off
	s_add_i32 m0, s62, 0x2000
	s_add_u32 s62, s28, 0x80000
	v_lshl_add_u64 v[218:219], s[28:29], 0, v[144:145]
	s_addc_u32 s63, s29, 0
	s_add_i32 s64, s52, s38
	global_load_lds_dwordx4 v[218:219], off
	v_lshl_add_u64 v[220:221], s[62:63], 0, v[148:149]
	s_mov_b32 m0, s64
	v_lshl_add_u64 v[222:223], s[30:31], 0, v[146:147]
	global_load_lds_dwordx4 v[220:221], off
	v_lshl_add_u64 v[220:221], s[62:63], 0, v[144:145]
	s_add_i32 m0, s64, 0x2000
	s_nop 0
	global_load_lds_dwordx4 v[220:221], off
	v_lshl_add_u64 v[220:221], s[30:31], 0, v[150:151]
	s_mov_b32 m0, s41
	s_nop 0
	global_load_lds_dwordx4 v[220:221], off
	s_mov_b32 m0, s42
	s_nop 0
	global_load_lds_dwordx4 v[222:223], off
	s_waitcnt vmcnt(8)
	s_waitcnt lgkmcnt(0)
	s_setprio 1
	s_barrier
	v_mfma_f32_16x16x32_bf16 v[60:63], v[128:131], v[178:181], v[60:63]
	v_mfma_f32_16x16x32_bf16 v[56:59], v[136:139], v[178:181], v[56:59]
	v_mfma_f32_16x16x32_bf16 v[48:51], v[128:131], v[186:189], v[48:51]
	v_mfma_f32_16x16x32_bf16 v[40:43], v[136:139], v[186:189], v[40:43]
	v_mfma_f32_16x16x32_bf16 v[32:35], v[128:131], v[194:197], v[32:35]
	v_mfma_f32_16x16x32_bf16 v[24:27], v[136:139], v[194:197], v[24:27]
	v_mfma_f32_16x16x32_bf16 v[16:19], v[128:131], v[202:205], v[16:19]
	v_mfma_f32_16x16x32_bf16 v[8:11], v[136:139], v[202:205], v[8:11]
	v_mfma_f32_16x16x32_bf16 v[60:63], v[132:135], v[182:185], v[60:63]
	v_mfma_f32_16x16x32_bf16 v[56:59], v[140:143], v[182:185], v[56:59]
	v_mfma_f32_16x16x32_bf16 v[48:51], v[132:135], v[190:193], v[48:51]
	v_mfma_f32_16x16x32_bf16 v[40:43], v[140:143], v[190:193], v[40:43]
	v_mfma_f32_16x16x32_bf16 v[32:35], v[132:135], v[198:201], v[32:35]
	v_mfma_f32_16x16x32_bf16 v[24:27], v[140:143], v[198:201], v[24:27]
	v_mfma_f32_16x16x32_bf16 v[16:19], v[132:135], v[206:209], v[16:19]
	v_mfma_f32_16x16x32_bf16 v[8:11], v[140:143], v[206:209], v[8:11]
	v_mfma_f32_16x16x32_bf16 v[52:55], v[162:165], v[178:181], v[52:55]
	v_mfma_f32_16x16x32_bf16 v[44:47], v[170:173], v[178:181], v[44:47]
	v_mfma_f32_16x16x32_bf16 v[36:39], v[162:165], v[186:189], v[36:39]
	v_mfma_f32_16x16x32_bf16 v[28:31], v[170:173], v[186:189], v[28:31]
	v_mfma_f32_16x16x32_bf16 v[20:23], v[162:165], v[194:197], v[20:23]
	v_mfma_f32_16x16x32_bf16 v[12:15], v[170:173], v[194:197], v[12:15]
	v_mfma_f32_16x16x32_bf16 v[4:7], v[162:165], v[202:205], v[4:7]
	v_mfma_f32_16x16x32_bf16 v[0:3], v[170:173], v[202:205], v[0:3]
	v_mfma_f32_16x16x32_bf16 v[52:55], v[166:169], v[182:185], v[52:55]
	v_mfma_f32_16x16x32_bf16 v[44:47], v[174:177], v[182:185], v[44:47]
	v_mfma_f32_16x16x32_bf16 v[36:39], v[166:169], v[190:193], v[36:39]
	v_mfma_f32_16x16x32_bf16 v[28:31], v[174:177], v[190:193], v[28:31]
	v_mfma_f32_16x16x32_bf16 v[20:23], v[166:169], v[198:201], v[20:23]
	v_mfma_f32_16x16x32_bf16 v[12:15], v[174:177], v[198:201], v[12:15]
	v_mfma_f32_16x16x32_bf16 v[4:7], v[166:169], v[206:209], v[4:7]
	v_mfma_f32_16x16x32_bf16 v[0:3], v[174:177], v[206:209], v[0:3]
	s_setprio 0
	s_barrier
; #define PG8_STAGE(bufoff, gbase, voff) do { _Pragma("unroll") for (int _i = 0; _i < 2; ++_i) \
;         __builtin_amdgcn_global_load_lds((const unsigned*)((const char*)(gbase) + (voff)[_i]), (PG8_LAS unsigned*)(lds + (bufoff) + ldsw + _i * 8192), 16, 0, 0); } while (0)
; #define PG8_LDA(dst, b, h) do { _Pragma("unroll") for (int m = 0; m < 4; ++m) _Pragma("unroll") for (int k = 0; k < 2; ++k) dst[m][k] = *(const PG8_LAS bf16x8*)(lds + PG8_SA(b, h) + aoff + m * 2048 + k * 1024); } while (0)
; #define PG8_LDB(dst, b, h) do { _Pragma("unroll") for (int n = 0; n < 2; ++n) _Pragma("unroll") for (int k = 0; k < 2; ++k) dst[n][k] = *(const PG8_LAS bf16x8*)(lds + PG8_SB(b, h) + boff + n * 2048 + k * 1024); } while (0)
; #define PG8_MMA(ai, bj, At, Bt) do { __builtin_amdgcn_s_setprio(1); _Pragma("unroll") for (int m = 0; m < 4; ++m) _Pragma("unroll") for (int n = 0; n < 2; ++n) _Pragma("unroll") for (int k = 0; k < 2; ++k) \
;         acc[ai][bj][m][n] = __builtin_amdgcn_mfma_f32_16x16x32_bf16(Bt[n][k], At[m][k], acc[ai][bj][m][n], 0, 0, 0); __builtin_amdgcn_s_setprio(0); } while (0)
; #define PG8_WAIT_V(n) asm volatile("s_waitcnt vmcnt(" #n ")" ::: "memory")
; #define PG8_WAIT_L(n) asm volatile("s_waitcnt lgkmcnt(" #n ")" ::: "memory")
; #define PG8_BAR __builtin_amdgcn_s_barrier()
; #define PG8_SCHED __builtin_amdgcn_sched_barrier(0)
; template <class Epi, class Sched, bool ALIGN_EPI = false, bool SP2 = false>
; __device__ __forceinline__ void gemm_phase(PG8_LAS unsigned char* lds, const Gemm g, const Sched& S, const Epi& E, const int wave_in) {
;     ...
;             PG8_LDB(B0, 1, 0); PG8_LDB(B1, 1, 1); PG8_SCHED; PG8_LDA(At, 1, 0); PG8_STAGE(PG8_SA(0, 1), a2 + hstepA, voffA);
;             PG8_WAIT_V(8); PG8_WAIT_L(0); PG8_BAR; PG8_MMA(0, 0, At, B0); PG8_MMA(0, 1, At, B1); PG8_BAR; PG8_SCHED;
	s_add_i32 s62, 0, 0x18000
	s_add_i32 s63, 0, 0x1c000
	v_add_u32_e32 v140, s62, v212
	v_add_u32_e32 v174, s63, v212
	ds_read_b128 v[128:131], v140
	ds_read_b128 v[132:135], v140 offset:1024
	ds_read_b128 v[136:139], v140 offset:2048
	ds_read_b128 v[140:143], v140 offset:3072
	ds_read_b128 v[162:165], v174
	ds_read_b128 v[166:169], v174 offset:1024
	ds_read_b128 v[170:173], v174 offset:2048
	ds_read_b128 v[174:177], v174 offset:3072
	s_add_u32 s30, s30, 0x80000
	s_addc_u32 s31, s31, 0
	s_mov_b32 m0, s43
	v_lshl_add_u64 v[224:225], s[30:31], 0, v[150:151]
	ds_read_b128 v[178:181], v216 offset:32768
	ds_read_b128 v[182:185], v216 offset:33792
	ds_read_b128 v[186:189], v216 offset:34816
	ds_read_b128 v[190:193], v216 offset:35840
	ds_read_b128 v[194:197], v216 offset:36864
	ds_read_b128 v[198:201], v216 offset:37888
	ds_read_b128 v[202:205], v216 offset:38912
	ds_read_b128 v[206:209], v216 offset:39936
	global_load_lds_dwordx4 v[224:225], off
	v_lshl_add_u64 v[224:225], s[30:31], 0, v[146:147]
	s_mov_b32 m0, s44
	s_nop 0
	global_load_lds_dwordx4 v[224:225], off
	s_waitcnt vmcnt(8)
	s_waitcnt lgkmcnt(0)
	s_setprio 1
	s_barrier
	v_mfma_f32_16x16x32_bf16 v[124:127], v[128:131], v[178:181], v[124:127]
	v_mfma_f32_16x16x32_bf16 v[120:123], v[136:139], v[178:181], v[120:123]
	v_mfma_f32_16x16x32_bf16 v[112:115], v[128:131], v[186:189], v[112:115]
	v_mfma_f32_16x16x32_bf16 v[104:107], v[136:139], v[186:189], v[104:107]
	v_mfma_f32_16x16x32_bf16 v[100:103], v[128:131], v[194:197], v[100:103]
	v_mfma_f32_16x16x32_bf16 v[96:99], v[136:139], v[194:197], v[96:99]
	v_mfma_f32_16x16x32_bf16 v[76:79], v[128:131], v[202:205], v[76:79]
	v_mfma_f32_16x16x32_bf16 v[72:75], v[136:139], v[202:205], v[72:75]
	v_mfma_f32_16x16x32_bf16 v[124:127], v[132:135], v[182:185], v[124:127]
	v_mfma_f32_16x16x32_bf16 v[120:123], v[140:143], v[182:185], v[120:123]
	v_mfma_f32_16x16x32_bf16 v[112:115], v[132:135], v[190:193], v[112:115]
	v_mfma_f32_16x16x32_bf16 v[104:107], v[140:143], v[190:193], v[104:107]
	v_mfma_f32_16x16x32_bf16 v[100:103], v[132:135], v[198:201], v[100:103]
	v_mfma_f32_16x16x32_bf16 v[96:99], v[140:143], v[198:201], v[96:99]
	v_mfma_f32_16x16x32_bf16 v[76:79], v[132:135], v[206:209], v[76:79]
	v_mfma_f32_16x16x32_bf16 v[72:75], v[140:143], v[206:209], v[72:75]
	v_mfma_f32_16x16x32_bf16 v[116:119], v[162:165], v[178:181], v[116:119]
	v_mfma_f32_16x16x32_bf16 v[108:111], v[170:173], v[178:181], v[108:111]
	v_mfma_f32_16x16x32_bf16 v[92:95], v[162:165], v[186:189], v[92:95]
	v_mfma_f32_16x16x32_bf16 v[88:91], v[170:173], v[186:189], v[88:91]
	v_mfma_f32_16x16x32_bf16 v[84:87], v[162:165], v[194:197], v[84:87]
	v_mfma_f32_16x16x32_bf16 v[80:83], v[170:173], v[194:197], v[80:83]
	v_mfma_f32_16x16x32_bf16 v[68:71], v[162:165], v[202:205], v[68:71]
	v_mfma_f32_16x16x32_bf16 v[64:67], v[170:173], v[202:205], v[64:67]
	v_mfma_f32_16x16x32_bf16 v[116:119], v[166:169], v[182:185], v[116:119]
	v_mfma_f32_16x16x32_bf16 v[108:111], v[174:177], v[182:185], v[108:111]
	v_mfma_f32_16x16x32_bf16 v[92:95], v[166:169], v[190:193], v[92:95]
	v_mfma_f32_16x16x32_bf16 v[88:91], v[174:177], v[190:193], v[88:91]
	v_mfma_f32_16x16x32_bf16 v[84:87], v[166:169], v[198:201], v[84:87]
	v_mfma_f32_16x16x32_bf16 v[80:83], v[174:177], v[198:201], v[80:83]
	v_mfma_f32_16x16x32_bf16 v[68:71], v[166:169], v[206:209], v[68:71]
	v_mfma_f32_16x16x32_bf16 v[64:67], v[174:177], v[206:209], v[64:67]
	s_setprio 0
	s_barrier
; #define PG8_STAGE(bufoff, gbase, voff) do { _Pragma("unroll") for (int _i = 0; _i < 2; ++_i) \
;         __builtin_amdgcn_global_load_lds((const unsigned*)((const char*)(gbase) + (voff)[_i]), (PG8_LAS unsigned*)(lds + (bufoff) + ldsw + _i * 8192), 16, 0, 0); } while (0)
; #define PG8_LDA(dst, b, h) do { _Pragma("unroll") for (int m = 0; m < 4; ++m) _Pragma("unroll") for (int k = 0; k < 2; ++k) dst[m][k] = *(const PG8_LAS bf16x8*)(lds + PG8_SA(b, h) + aoff + m * 2048 + k * 1024); } while (0)
; #define PG8_MMA(ai, bj, At, Bt) do { __builtin_amdgcn_s_setprio(1); _Pragma("unroll") for (int m = 0; m < 4; ++m) _Pragma("unroll") for (int n = 0; n < 2; ++n) _Pragma("unroll") for (int k = 0; k < 2; ++k) \
;         acc[ai][bj][m][n] = __builtin_amdgcn_mfma_f32_16x16x32_bf16(Bt[n][k], At[m][k], acc[ai][bj][m][n], 0, 0, 0); __builtin_amdgcn_s_setprio(0); } while (0)
; #define PG8_WAIT_V(n) asm volatile("s_waitcnt vmcnt(" #n ")" ::: "memory")
; #define PG8_WAIT_L(n) asm volatile("s_waitcnt lgkmcnt(" #n ")" ::: "memory")
; #define PG8_BAR __builtin_amdgcn_s_barrier()
; #define PG8_SCHED __builtin_amdgcn_sched_barrier(0)
; template <class Epi, class Sched, bool ALIGN_EPI = false, bool SP2 = false>
; __device__ __forceinline__ void gemm_phase(PG8_LAS unsigned char* lds, const Gemm g, const Sched& S, const Epi& E, const int wave_in) {
;     ...
;         for (int t = 0; t < nt; t += 2) {
;     ...
;             PG8_LDA(At, 1, 1); PG8_STAGE(PG8_SB(1, 0), b3, voffB); PG8_STAGE(PG8_SB(1, 1), b3 + hstepB, voffB); PG8_STAGE(PG8_SA(1, 0), a3, voffA);
;             PG8_WAIT_V(8); PG8_WAIT_L(0); PG8_BAR; PG8_MMA(1, 0, At, B0); PG8_MMA(1, 1, At, B1); PG8_BAR; PG8_SCHED;
	s_add_i32 s30, s62, s38
	v_lshl_add_u64 v[210:211], v[210:211], 0, s[6:7]
	s_mov_b32 m0, s30
	ds_read_b128 v[178:181], v216 offset:49152
	ds_read_b128 v[182:185], v216 offset:50176
	ds_read_b128 v[186:189], v216 offset:51200
	ds_read_b128 v[190:193], v216 offset:52224
	ds_read_b128 v[194:197], v216 offset:53248
	ds_read_b128 v[198:201], v216 offset:54272
	ds_read_b128 v[202:205], v216 offset:55296
	ds_read_b128 v[206:209], v216 offset:56320
	global_load_lds_dwordx4 v[210:211], off
	s_add_i32 m0, s30, 0x2000
	s_add_u32 s28, s28, 0x80080
	v_lshl_add_u64 v[210:211], v[218:219], 0, s[6:7]
	s_addc_u32 s29, s29, 0
	s_add_i32 s30, s63, s38
	global_load_lds_dwordx4 v[210:211], off
	v_lshl_add_u64 v[210:211], s[28:29], 0, v[148:149]
	s_mov_b32 m0, s30
	s_nop 0
	global_load_lds_dwordx4 v[210:211], off
	v_lshl_add_u64 v[210:211], s[28:29], 0, v[144:145]
	s_add_i32 m0, s30, 0x2000
	s_nop 0
	global_load_lds_dwordx4 v[210:211], off
	v_lshl_add_u64 v[210:211], v[220:221], 0, s[6:7]
	s_mov_b32 m0, s48
	s_nop 0
	global_load_lds_dwordx4 v[210:211], off
	v_lshl_add_u64 v[210:211], v[222:223], 0, s[6:7]
	s_mov_b32 m0, s49
	s_nop 0
	global_load_lds_dwordx4 v[210:211], off
	s_waitcnt vmcnt(8)
	s_waitcnt lgkmcnt(0)
	s_setprio 1
	s_barrier
	v_mfma_f32_16x16x32_bf16 v[60:63], v[128:131], v[178:181], v[60:63]
	v_mfma_f32_16x16x32_bf16 v[56:59], v[136:139], v[178:181], v[56:59]
	v_mfma_f32_16x16x32_bf16 v[48:51], v[128:131], v[186:189], v[48:51]
	v_mfma_f32_16x16x32_bf16 v[40:43], v[136:139], v[186:189], v[40:43]
	v_mfma_f32_16x16x32_bf16 v[32:35], v[128:131], v[194:197], v[32:35]
	v_mfma_f32_16x16x32_bf16 v[24:27], v[136:139], v[194:197], v[24:27]
	v_mfma_f32_16x16x32_bf16 v[16:19], v[128:131], v[202:205], v[16:19]
	v_mfma_f32_16x16x32_bf16 v[8:11], v[136:139], v[202:205], v[8:11]
	v_mfma_f32_16x16x32_bf16 v[60:63], v[132:135], v[182:185], v[60:63]
	v_mfma_f32_16x16x32_bf16 v[56:59], v[140:143], v[182:185], v[56:59]
	v_mfma_f32_16x16x32_bf16 v[48:51], v[132:135], v[190:193], v[48:51]
	v_mfma_f32_16x16x32_bf16 v[40:43], v[140:143], v[190:193], v[40:43]
	v_mfma_f32_16x16x32_bf16 v[32:35], v[132:135], v[198:201], v[32:35]
	v_mfma_f32_16x16x32_bf16 v[24:27], v[140:143], v[198:201], v[24:27]
	v_mfma_f32_16x16x32_bf16 v[16:19], v[132:135], v[206:209], v[16:19]
	v_mfma_f32_16x16x32_bf16 v[8:11], v[140:143], v[206:209], v[8:11]
	v_mfma_f32_16x16x32_bf16 v[52:55], v[162:165], v[178:181], v[52:55]
	v_mfma_f32_16x16x32_bf16 v[44:47], v[170:173], v[178:181], v[44:47]
	v_mfma_f32_16x16x32_bf16 v[36:39], v[162:165], v[186:189], v[36:39]
	v_mfma_f32_16x16x32_bf16 v[28:31], v[170:173], v[186:189], v[28:31]
	v_mfma_f32_16x16x32_bf16 v[20:23], v[162:165], v[194:197], v[20:23]
	v_mfma_f32_16x16x32_bf16 v[12:15], v[170:173], v[194:197], v[12:15]
	v_mfma_f32_16x16x32_bf16 v[4:7], v[162:165], v[202:205], v[4:7]
	v_mfma_f32_16x16x32_bf16 v[0:3], v[170:173], v[202:205], v[0:3]
	v_mfma_f32_16x16x32_bf16 v[52:55], v[166:169], v[182:185], v[52:55]
	v_mfma_f32_16x16x32_bf16 v[44:47], v[174:177], v[182:185], v[44:47]
	v_mfma_f32_16x16x32_bf16 v[36:39], v[166:169], v[190:193], v[36:39]
	v_mfma_f32_16x16x32_bf16 v[28:31], v[174:177], v[190:193], v[28:31]
	v_mfma_f32_16x16x32_bf16 v[20:23], v[166:169], v[198:201], v[20:23]
	v_mfma_f32_16x16x32_bf16 v[12:15], v[174:177], v[198:201], v[12:15]
	v_mfma_f32_16x16x32_bf16 v[4:7], v[166:169], v[206:209], v[4:7]
	v_mfma_f32_16x16x32_bf16 v[0:3], v[174:177], v[206:209], v[0:3]
	s_setprio 0
	s_barrier
	s_add_i32 s61, s61, 2
	s_add_u32 s26, s26, 0x100
	s_addc_u32 s27, s27, 0
	s_add_u32 s59, s59, 0x100
	s_addc_u32 s60, s60, 0
	s_cmp_gt_u32 s61, 29
	s_cbranch_scc0 .LBB0_1825

;     __host__ __device__ bool next(int i, Unit& u) const { const bool ok = StaticOrder::next(i, u); u.pm = 0; u.pn = 0; return ok; }
; #define PG8_STAGE(bufoff, gbase, voff) do { _Pragma("unroll") for (int _i = 0; _i < 2; ++_i) \
;         __builtin_amdgcn_global_load_lds((const unsigned*)((const char*)(gbase) + (voff)[_i]), (PG8_LAS unsigned*)(lds + (bufoff) + ldsw + _i * 8192), 16, 0, 0); } while (0)
; #define PG8_LDA(dst, b, h) do { _Pragma("unroll") for (int m = 0; m < 4; ++m) _Pragma("unroll") for (int k = 0; k < 2; ++k) dst[m][k] = *(const PG8_LAS bf16x8*)(lds + PG8_SA(b, h) + aoff + m * 2048 + k * 1024); } while (0)
; #define PG8_LDB(dst, b, h) do { _Pragma("unroll") for (int n = 0; n < 2; ++n) _Pragma("unroll") for (int k = 0; k < 2; ++k) dst[n][k] = *(const PG8_LAS bf16x8*)(lds + PG8_SB(b, h) + boff + n * 2048 + k * 1024); } while (0)
; #define PG8_WAIT_V(n) asm volatile("s_waitcnt vmcnt(" #n ")" ::: "memory")
; #define PG8_WAIT_L(n) asm volatile("s_waitcnt lgkmcnt(" #n ")" ::: "memory")
; #define PG8_BAR __builtin_amdgcn_s_barrier()
; #define PG8_SCHED __builtin_amdgcn_sched_barrier(0)
; template <class Epi, class Sched, bool ALIGN_EPI = false, bool SP2 = false>
; __device__ __forceinline__ void gemm_phase(PG8_LAS unsigned char* lds, const Gemm g, const Sched& S, const Epi& E, const int wave_in) {
;     ...
;         const bool has_next = S.next(ui + 1, nxt);
;         const char* nA = has_next ? (const char*)g.A + (size_t)nxt.pm * tstepA : cA; const char* nB = has_next ? (const char*)g.Bt + (size_t)nxt.pn * tstepB : cB;
;         for (int t = 0; t < nt; t += 2) {
;             const bool last = (t == nt - 2);
;             const char* a1 = cA + (size_t)(t + 1) * kstep;
;             const char* a2 = last ? nA : cA + (size_t)(t + 2) * kstep; const char* b2 = last ? nB : cB + (size_t)(t + 2) * kstep;
;             const char* a3 = a2 + kstep; const char* b3 = b2 + kstep;
;             if (last && has_next) S.a_ready(nxt);
;             if constexpr (SP2) {
;             PG8_LDB(B0, 0, 0); PG8_LDB(B1, 0, 1); PG8_SCHED; PG8_LDA(At, 0, 0); PG8_STAGE(PG8_SA(1, 1), a1 + hstepA, voffA);
;             PG8_WAIT_V(8); PG8_WAIT_L(0); PG8_BAR; PG8_MMA(0, 0, At, B0); PG8_MMA(0, 1, At, B1); PG8_BAR; PG8_SCHED;
;             PG8_LDA(At, 0, 1); PG8_STAGE(PG8_SB(0, 0), b2, voffB); PG8_STAGE(PG8_SB(0, 1), b2 + hstepB, voffB); PG8_STAGE(PG8_SA(0, 0), a2, voffA);
.LBB0_1950:
	s_ashr_i32 s41, s40, 31
	s_lshl_b64 s[42:43], s[40:41], 20
	s_add_u32 s42, s52, s42
	s_addc_u32 s43, s53, s43
	s_and_b64 s[44:45], s[10:11], exec
	s_cselect_b32 s1, s43, s47
	s_cselect_b32 s13, s42, s46
	s_ashr_i32 s39, s38, 31
	s_lshl_b64 s[44:45], s[38:39], 20
	s_add_u32 s44, s54, s44
	s_addc_u32 s45, s55, s45
	s_and_b64 s[50:51], s[10:11], exec
	s_cselect_b32 s39, s45, s49
	s_cselect_b32 s41, s44, s48
	s_add_u32 s46, s46, 0x80080
	s_addc_u32 s47, s47, 0
	s_add_u32 s72, s48, 0x100
	v_mov_b32_e32 v0, 0
	s_addc_u32 s73, s49, 0
	s_mov_b32 s74, -2
	s_waitcnt vmcnt(0)
	ds_read_b128 v[44:47], v189
	ds_read_b128 v[48:51], v189 offset:1024
	ds_read_b128 v[52:55], v189 offset:2048
	ds_read_b128 v[56:59], v189 offset:3072
	ds_read_b128 v[60:63], v197
	ds_read_b128 v[64:67], v197 offset:1024
	ds_read_b128 v[80:83], v197 offset:2048
	ds_read_b128 v[84:87], v197 offset:3072
	s_add_u32 s48, s46, 0xfff80080
	s_addc_u32 s49, s47, -1
	s_cmp_eq_u32 s74, 28
	s_cselect_b32 s51, s1, s49
	s_cselect_b32 s50, s13, s48
	s_cselect_b32 s49, s39, s73
	s_cselect_b32 s48, s41, s72
	v_lshl_add_u64 v[224:225], s[46:47], 0, v[206:207]
	s_add_i32 m0, s57, 0xc000
	ds_read_b128 v[88:91], v199
	ds_read_b128 v[92:95], v199 offset:1024
	ds_read_b128 v[96:99], v199 offset:2048
	ds_read_b128 v[100:103], v199 offset:3072
	ds_read_b128 v[176:179], v199 offset:4096
	ds_read_b128 v[212:215], v199 offset:5120
	ds_read_b128 v[216:219], v199 offset:6144
	ds_read_b128 v[220:223], v199 offset:7168
	global_load_lds_dwordx4 v[224:225], off
	v_lshl_add_u64 v[224:225], s[46:47], 0, v[208:209]
	s_add_i32 m0, s57, 0xe000
	s_nop 0
	global_load_lds_dwordx4 v[224:225], off
	s_waitcnt vmcnt(8)
	s_waitcnt lgkmcnt(0)
	s_setprio 1
	s_barrier
	v_mfma_f32_16x16x32_bf16 v[172:175], v[44:47], v[88:91], 0
	v_mfma_f32_16x16x32_bf16 v[164:167], v[52:55], v[88:91], 0
	v_mfma_f32_16x16x32_bf16 v[156:159], v[44:47], v[96:99], 0
	v_mfma_f32_16x16x32_bf16 v[148:151], v[52:55], v[96:99], 0
	v_mfma_f32_16x16x32_bf16 v[140:143], v[44:47], v[176:179], 0
	v_mfma_f32_16x16x32_bf16 v[132:135], v[52:55], v[176:179], 0
	v_mfma_f32_16x16x32_bf16 v[124:127], v[44:47], v[216:219], 0
	v_mfma_f32_16x16x32_bf16 v[120:123], v[52:55], v[216:219], 0
	v_mfma_f32_16x16x32_bf16 v[172:175], v[48:51], v[92:95], v[172:175]
	v_mfma_f32_16x16x32_bf16 v[164:167], v[56:59], v[92:95], v[164:167]
	v_mfma_f32_16x16x32_bf16 v[156:159], v[48:51], v[100:103], v[156:159]
	v_mfma_f32_16x16x32_bf16 v[148:151], v[56:59], v[100:103], v[148:151]
	v_mfma_f32_16x16x32_bf16 v[140:143], v[48:51], v[212:215], v[140:143]
	v_mfma_f32_16x16x32_bf16 v[132:135], v[56:59], v[212:215], v[132:135]
	v_mfma_f32_16x16x32_bf16 v[124:127], v[48:51], v[220:223], v[124:127]
	v_mfma_f32_16x16x32_bf16 v[120:123], v[56:59], v[220:223], v[120:123]
	v_mfma_f32_16x16x32_bf16 v[168:171], v[60:63], v[88:91], 0
	v_mfma_f32_16x16x32_bf16 v[88:91], v[80:83], v[88:91], 0
	v_mfma_f32_16x16x32_bf16 v[168:171], v[64:67], v[92:95], v[168:171]
	v_mfma_f32_16x16x32_bf16 v[88:91], v[84:87], v[92:95], v[88:91]
	v_mfma_f32_16x16x32_bf16 v[92:95], v[60:63], v[96:99], 0
	v_mfma_f32_16x16x32_bf16 v[96:99], v[80:83], v[96:99], 0
	v_mfma_f32_16x16x32_bf16 v[128:131], v[80:83], v[176:179], 0
	v_mfma_f32_16x16x32_bf16 v[116:119], v[60:63], v[216:219], 0
	v_mfma_f32_16x16x32_bf16 v[112:115], v[80:83], v[216:219], 0
	v_mfma_f32_16x16x32_bf16 v[92:95], v[64:67], v[100:103], v[92:95]
	v_mfma_f32_16x16x32_bf16 v[96:99], v[84:87], v[100:103], v[96:99]
	v_mfma_f32_16x16x32_bf16 v[100:103], v[60:63], v[176:179], 0
	v_mfma_f32_16x16x32_bf16 v[128:131], v[84:87], v[212:215], v[128:131]
	v_mfma_f32_16x16x32_bf16 v[116:119], v[64:67], v[220:223], v[116:119]
	v_mfma_f32_16x16x32_bf16 v[112:115], v[84:87], v[220:223], v[112:115]
	v_mfma_f32_16x16x32_bf16 v[100:103], v[64:67], v[212:215], v[100:103]
	s_setprio 0
	s_barrier
	s_add_i32 s75, s68, s56
	v_lshl_add_u64 v[232:233], s[48:49], 0, v[182:183]
	s_mov_b32 m0, s75
	ds_read_b128 v[136:139], v199 offset:16384
	ds_read_b128 v[144:147], v199 offset:17408
	ds_read_b128 v[152:155], v199 offset:18432
	ds_read_b128 v[160:163], v199 offset:19456
	ds_read_b128 v[176:179], v199 offset:20480
	ds_read_b128 v[212:215], v199 offset:21504
	ds_read_b128 v[216:219], v199 offset:22528
	ds_read_b128 v[220:223], v199 offset:23552
	global_load_lds_dwordx4 v[232:233], off
	s_add_i32 m0, s75, 0x2000
	s_add_u32 s76, s48, 0x80000
	v_lshl_add_u64 v[234:235], s[48:49], 0, v[186:187]
	s_addc_u32 s77, s49, 0
	s_add_i32 s75, s69, s56
	global_load_lds_dwordx4 v[234:235], off
	v_lshl_add_u64 v[224:225], s[76:77], 0, v[182:183]
	s_mov_b32 m0, s75
	v_lshl_add_u64 v[236:237], s[50:51], 0, v[180:181]
	global_load_lds_dwordx4 v[224:225], off
	v_lshl_add_u64 v[224:225], s[76:77], 0, v[186:187]
	s_add_i32 m0, s75, 0x2000
	v_lshl_add_u64 v[238:239], s[50:51], 0, v[184:185]
	global_load_lds_dwordx4 v[224:225], off
	s_mov_b32 m0, s57
	s_nop 0
	global_load_lds_dwordx4 v[236:237], off
	s_mov_b32 m0, s58
	s_nop 0
	global_load_lds_dwordx4 v[238:239], off
	s_waitcnt vmcnt(8)
	s_waitcnt lgkmcnt(0)
	s_setprio 1
	s_barrier
; #define PG8_STAGE(bufoff, gbase, voff) do { _Pragma("unroll") for (int _i = 0; _i < 2; ++_i) \
;         __builtin_amdgcn_global_load_lds((const unsigned*)((const char*)(gbase) + (voff)[_i]), (PG8_LAS unsigned*)(lds + (bufoff) + ldsw + _i * 8192), 16, 0, 0); } while (0)
; #define PG8_LDA(dst, b, h) do { _Pragma("unroll") for (int m = 0; m < 4; ++m) _Pragma("unroll") for (int k = 0; k < 2; ++k) dst[m][k] = *(const PG8_LAS bf16x8*)(lds + PG8_SA(b, h) + aoff + m * 2048 + k * 1024); } while (0)
; #define PG8_LDB(dst, b, h) do { _Pragma("unroll") for (int n = 0; n < 2; ++n) _Pragma("unroll") for (int k = 0; k < 2; ++k) dst[n][k] = *(const PG8_LAS bf16x8*)(lds + PG8_SB(b, h) + boff + n * 2048 + k * 1024); } while (0)
; #define PG8_MMA(ai, bj, At, Bt) do { __builtin_amdgcn_s_setprio(1); _Pragma("unroll") for (int m = 0; m < 4; ++m) _Pragma("unroll") for (int n = 0; n < 2; ++n) _Pragma("unroll") for (int k = 0; k < 2; ++k) \
;         acc[ai][bj][m][n] = __builtin_amdgcn_mfma_f32_16x16x32_bf16(Bt[n][k], At[m][k], acc[ai][bj][m][n], 0, 0, 0); __builtin_amdgcn_s_setprio(0); } while (0)
; #define PG8_WAIT_V(n) asm volatile("s_waitcnt vmcnt(" #n ")" ::: "memory")
; #define PG8_WAIT_L(n) asm volatile("s_waitcnt lgkmcnt(" #n ")" ::: "memory")
; #define PG8_BAR __builtin_amdgcn_s_barrier()
; #define PG8_SCHED __builtin_amdgcn_sched_barrier(0)
; template <class Epi, class Sched, bool ALIGN_EPI = false, bool SP2 = false>
; __device__ __forceinline__ void gemm_phase(PG8_LAS unsigned char* lds, const Gemm g, const Sched& S, const Epi& E, const int wave_in) {
;     ...
;             PG8_WAIT_V(8); PG8_WAIT_L(0); PG8_BAR; PG8_MMA(1, 0, At, B0); PG8_MMA(1, 1, At, B1); PG8_BAR; PG8_SCHED;
;             PG8_LDB(B0, 1, 0); PG8_LDB(B1, 1, 1); PG8_SCHED; PG8_LDA(At, 1, 0); PG8_STAGE(PG8_SA(0, 1), a2 + hstepA, voffA);
;             PG8_WAIT_V(8); PG8_WAIT_L(0); PG8_BAR; PG8_MMA(0, 0, At, B0); PG8_MMA(0, 1, At, B1); PG8_BAR; PG8_SCHED;
	v_mfma_f32_16x16x32_bf16 v[108:111], v[44:47], v[136:139], 0
	v_mfma_f32_16x16x32_bf16 v[76:79], v[52:55], v[136:139], 0
	v_mfma_f32_16x16x32_bf16 v[68:71], v[44:47], v[152:155], 0
	v_mfma_f32_16x16x32_bf16 v[36:39], v[52:55], v[152:155], 0
	v_mfma_f32_16x16x32_bf16 v[28:31], v[44:47], v[176:179], 0
	v_mfma_f32_16x16x32_bf16 v[20:23], v[52:55], v[176:179], 0
	v_mfma_f32_16x16x32_bf16 v[12:15], v[44:47], v[216:219], 0
	v_mfma_f32_16x16x32_bf16 v[8:11], v[52:55], v[216:219], 0
	v_mfma_f32_16x16x32_bf16 v[108:111], v[48:51], v[144:147], v[108:111]
	v_mfma_f32_16x16x32_bf16 v[76:79], v[56:59], v[144:147], v[76:79]
	v_mfma_f32_16x16x32_bf16 v[68:71], v[48:51], v[160:163], v[68:71]
	v_mfma_f32_16x16x32_bf16 v[36:39], v[56:59], v[160:163], v[36:39]
	v_mfma_f32_16x16x32_bf16 v[28:31], v[48:51], v[212:215], v[28:31]
	v_mfma_f32_16x16x32_bf16 v[20:23], v[56:59], v[212:215], v[20:23]
	v_mfma_f32_16x16x32_bf16 v[12:15], v[48:51], v[220:223], v[12:15]
	v_mfma_f32_16x16x32_bf16 v[8:11], v[56:59], v[220:223], v[8:11]
	v_mfma_f32_16x16x32_bf16 v[40:43], v[60:63], v[152:155], 0
	v_mfma_f32_16x16x32_bf16 v[32:35], v[80:83], v[152:155], 0
	v_mfma_f32_16x16x32_bf16 v[24:27], v[60:63], v[176:179], 0
	v_mfma_f32_16x16x32_bf16 v[16:19], v[80:83], v[176:179], 0
	v_mfma_f32_16x16x32_bf16 v[4:7], v[60:63], v[216:219], 0
	v_mfma_f32_16x16x32_bf16 v[0:3], v[80:83], v[216:219], 0
	v_mfma_f32_16x16x32_bf16 v[44:47], v[60:63], v[136:139], 0
	v_mfma_f32_16x16x32_bf16 v[48:51], v[80:83], v[136:139], 0
	v_mfma_f32_16x16x32_bf16 v[40:43], v[64:67], v[160:163], v[40:43]
	v_mfma_f32_16x16x32_bf16 v[32:35], v[84:87], v[160:163], v[32:35]
	v_mfma_f32_16x16x32_bf16 v[24:27], v[64:67], v[212:215], v[24:27]
	v_mfma_f32_16x16x32_bf16 v[16:19], v[84:87], v[212:215], v[16:19]
	v_mfma_f32_16x16x32_bf16 v[4:7], v[64:67], v[220:223], v[4:7]
	v_mfma_f32_16x16x32_bf16 v[0:3], v[84:87], v[220:223], v[0:3]
	v_mfma_f32_16x16x32_bf16 v[44:47], v[64:67], v[144:147], v[44:47]
	v_mfma_f32_16x16x32_bf16 v[48:51], v[84:87], v[144:147], v[48:51]
	s_setprio 0
	s_barrier
	s_add_i32 s75, 0, 0x18000
	s_add_i32 s76, 0, 0x1c000
	v_add_u32_e32 v64, s75, v195
	v_add_u32_e32 v72, s76, v195
	ds_read_b128 v[52:55], v64
	ds_read_b128 v[56:59], v64 offset:1024
	ds_read_b128 v[60:63], v64 offset:2048
	ds_read_b128 v[64:67], v64 offset:3072
	ds_read_b128 v[80:83], v72
	ds_read_b128 v[84:87], v72 offset:1024
	ds_read_b128 v[176:179], v72 offset:2048
	ds_read_b128 v[212:215], v72 offset:3072
	s_add_u32 s50, s50, 0x80000
	s_addc_u32 s51, s51, 0
	s_mov_b32 m0, s59
	v_lshl_add_u64 v[152:153], s[50:51], 0, v[180:181]
	ds_read_b128 v[72:75], v199 offset:32768
	ds_read_b128 v[104:107], v199 offset:33792
	ds_read_b128 v[136:139], v199 offset:34816
	ds_read_b128 v[144:147], v199 offset:35840
	ds_read_b128 v[216:219], v199 offset:36864
	ds_read_b128 v[220:223], v199 offset:37888
	ds_read_b128 v[224:227], v199 offset:38912
	ds_read_b128 v[228:231], v199 offset:39936
	global_load_lds_dwordx4 v[152:153], off
	v_lshl_add_u64 v[152:153], s[50:51], 0, v[184:185]
	s_mov_b32 m0, s60
	s_nop 0
	global_load_lds_dwordx4 v[152:153], off
	s_waitcnt vmcnt(8)
	s_waitcnt lgkmcnt(0)
	s_setprio 1
	s_barrier
	v_mfma_f32_16x16x32_bf16 v[152:155], v[52:55], v[72:75], v[172:175]
	v_mfma_f32_16x16x32_bf16 v[172:175], v[56:59], v[104:107], v[152:155]
	v_mfma_f32_16x16x32_bf16 v[152:155], v[60:63], v[72:75], v[164:167]
	v_mfma_f32_16x16x32_bf16 v[164:167], v[64:67], v[104:107], v[152:155]
	v_mfma_f32_16x16x32_bf16 v[152:155], v[52:55], v[136:139], v[156:159]
	v_mfma_f32_16x16x32_bf16 v[148:151], v[60:63], v[136:139], v[148:151]
	v_mfma_f32_16x16x32_bf16 v[140:143], v[52:55], v[216:219], v[140:143]
	v_mfma_f32_16x16x32_bf16 v[132:135], v[60:63], v[216:219], v[132:135]
	v_mfma_f32_16x16x32_bf16 v[124:127], v[52:55], v[224:227], v[124:127]
	v_mfma_f32_16x16x32_bf16 v[120:123], v[60:63], v[224:227], v[120:123]
	v_mfma_f32_16x16x32_bf16 v[156:159], v[56:59], v[144:147], v[152:155]
	v_mfma_f32_16x16x32_bf16 v[148:151], v[64:67], v[144:147], v[148:151]
	v_mfma_f32_16x16x32_bf16 v[140:143], v[56:59], v[220:223], v[140:143]
	v_mfma_f32_16x16x32_bf16 v[132:135], v[64:67], v[220:223], v[132:135]
	v_mfma_f32_16x16x32_bf16 v[124:127], v[56:59], v[228:231], v[124:127]
	v_mfma_f32_16x16x32_bf16 v[120:123], v[64:67], v[228:231], v[120:123]
	v_mfma_f32_16x16x32_bf16 v[152:155], v[80:83], v[72:75], v[168:171]
	v_mfma_f32_16x16x32_bf16 v[72:75], v[176:179], v[72:75], v[88:91]
	v_mfma_f32_16x16x32_bf16 v[160:163], v[212:215], v[104:107], v[72:75]
	v_mfma_f32_16x16x32_bf16 v[72:75], v[80:83], v[136:139], v[92:95]
	v_mfma_f32_16x16x32_bf16 v[168:171], v[84:87], v[104:107], v[152:155]
	v_mfma_f32_16x16x32_bf16 v[152:155], v[84:87], v[144:147], v[72:75]
	v_mfma_f32_16x16x32_bf16 v[72:75], v[176:179], v[136:139], v[96:99]
	v_mfma_f32_16x16x32_bf16 v[144:147], v[212:215], v[144:147], v[72:75]
	v_mfma_f32_16x16x32_bf16 v[72:75], v[80:83], v[216:219], v[100:103]
	v_mfma_f32_16x16x32_bf16 v[136:139], v[84:87], v[220:223], v[72:75]
	v_mfma_f32_16x16x32_bf16 v[72:75], v[176:179], v[216:219], v[128:131]
	v_mfma_f32_16x16x32_bf16 v[128:131], v[212:215], v[220:223], v[72:75]
	v_mfma_f32_16x16x32_bf16 v[72:75], v[80:83], v[224:227], v[116:119]
	v_mfma_f32_16x16x32_bf16 v[116:119], v[84:87], v[228:231], v[72:75]
	v_mfma_f32_16x16x32_bf16 v[72:75], v[176:179], v[224:227], v[112:115]
	v_mfma_f32_16x16x32_bf16 v[112:115], v[212:215], v[228:231], v[72:75]
	s_setprio 0
	s_barrier
; #define PG8_STAGE(bufoff, gbase, voff) do { _Pragma("unroll") for (int _i = 0; _i < 2; ++_i) \
;         __builtin_amdgcn_global_load_lds((const unsigned*)((const char*)(gbase) + (voff)[_i]), (PG8_LAS unsigned*)(lds + (bufoff) + ldsw + _i * 8192), 16, 0, 0); } while (0)
; #define PG8_LDA(dst, b, h) do { _Pragma("unroll") for (int m = 0; m < 4; ++m) _Pragma("unroll") for (int k = 0; k < 2; ++k) dst[m][k] = *(const PG8_LAS bf16x8*)(lds + PG8_SA(b, h) + aoff + m * 2048 + k * 1024); } while (0)
; #define PG8_MMA(ai, bj, At, Bt) do { __builtin_amdgcn_s_setprio(1); _Pragma("unroll") for (int m = 0; m < 4; ++m) _Pragma("unroll") for (int n = 0; n < 2; ++n) _Pragma("unroll") for (int k = 0; k < 2; ++k) \
;         acc[ai][bj][m][n] = __builtin_amdgcn_mfma_f32_16x16x32_bf16(Bt[n][k], At[m][k], acc[ai][bj][m][n], 0, 0, 0); __builtin_amdgcn_s_setprio(0); } while (0)
; #define PG8_WAIT_V(n) asm volatile("s_waitcnt vmcnt(" #n ")" ::: "memory")
; #define PG8_WAIT_L(n) asm volatile("s_waitcnt lgkmcnt(" #n ")" ::: "memory")
; #define PG8_BAR __builtin_amdgcn_s_barrier()
; #define PG8_SCHED __builtin_amdgcn_sched_barrier(0)
; template <class Epi, class Sched, bool ALIGN_EPI = false, bool SP2 = false>
; __device__ __forceinline__ void gemm_phase(PG8_LAS unsigned char* lds, const Gemm g, const Sched& S, const Epi& E, const int wave_in) {
;     ...
;         for (int t = 0; t < nt; t += 2) {
;     ...
;             PG8_LDA(At, 1, 1); PG8_STAGE(PG8_SB(1, 0), b3, voffB); PG8_STAGE(PG8_SB(1, 1), b3 + hstepB, voffB); PG8_STAGE(PG8_SA(1, 0), a3, voffA);
;             PG8_WAIT_V(8); PG8_WAIT_L(0); PG8_BAR; PG8_MMA(1, 0, At, B0); PG8_MMA(1, 1, At, B1); PG8_BAR; PG8_SCHED;
	s_add_i32 s50, s75, s56
	v_lshl_add_u64 v[104:105], v[232:233], 0, s[22:23]
	s_mov_b32 m0, s50
	s_nop 1
	ds_read_b128 v[72:75], v199 offset:49152
	ds_read_b128 v[88:91], v199 offset:50176
	ds_read_b128 v[92:95], v199 offset:51200
	ds_read_b128 v[96:99], v199 offset:52224
	ds_read_b128 v[100:103], v199 offset:53248
	ds_read_b128 v[216:219], v199 offset:54272
	ds_read_b128 v[220:223], v199 offset:55296
	ds_read_b128 v[224:227], v199 offset:56320
	global_load_lds_dwordx4 v[104:105], off
	s_add_i32 m0, s50, 0x2000
	s_add_u32 s48, s48, 0x80080
	v_lshl_add_u64 v[104:105], v[234:235], 0, s[22:23]
	s_addc_u32 s49, s49, 0
	s_add_i32 s50, s76, s56
	global_load_lds_dwordx4 v[104:105], off
	v_lshl_add_u64 v[104:105], s[48:49], 0, v[182:183]
	s_mov_b32 m0, s50
	s_nop 0
	global_load_lds_dwordx4 v[104:105], off
	v_lshl_add_u64 v[104:105], s[48:49], 0, v[186:187]
	s_add_i32 m0, s50, 0x2000
	s_nop 0
	global_load_lds_dwordx4 v[104:105], off
	v_lshl_add_u64 v[104:105], v[236:237], 0, s[22:23]
	s_mov_b32 m0, s63
	s_nop 0
	global_load_lds_dwordx4 v[104:105], off
	v_lshl_add_u64 v[104:105], v[238:239], 0, s[22:23]
	s_mov_b32 m0, s64
	s_nop 0
	global_load_lds_dwordx4 v[104:105], off
	s_waitcnt vmcnt(8)
	s_waitcnt lgkmcnt(0)
	s_setprio 1
	s_barrier
	v_mfma_f32_16x16x32_bf16 v[104:107], v[52:55], v[72:75], v[108:111]
	v_mfma_f32_16x16x32_bf16 v[76:79], v[60:63], v[72:75], v[76:79]
	v_mfma_f32_16x16x32_bf16 v[68:71], v[52:55], v[92:95], v[68:71]
	v_mfma_f32_16x16x32_bf16 v[36:39], v[60:63], v[92:95], v[36:39]
	v_mfma_f32_16x16x32_bf16 v[28:31], v[52:55], v[100:103], v[28:31]
	v_mfma_f32_16x16x32_bf16 v[20:23], v[60:63], v[100:103], v[20:23]
	v_mfma_f32_16x16x32_bf16 v[12:15], v[52:55], v[220:223], v[12:15]
	v_mfma_f32_16x16x32_bf16 v[8:11], v[60:63], v[220:223], v[8:11]
	v_mfma_f32_16x16x32_bf16 v[108:111], v[56:59], v[88:91], v[104:107]
	v_mfma_f32_16x16x32_bf16 v[76:79], v[64:67], v[88:91], v[76:79]
	v_mfma_f32_16x16x32_bf16 v[68:71], v[56:59], v[96:99], v[68:71]
	v_mfma_f32_16x16x32_bf16 v[36:39], v[64:67], v[96:99], v[36:39]
	v_mfma_f32_16x16x32_bf16 v[28:31], v[56:59], v[216:219], v[28:31]
	v_mfma_f32_16x16x32_bf16 v[20:23], v[64:67], v[216:219], v[20:23]
	v_mfma_f32_16x16x32_bf16 v[12:15], v[56:59], v[224:227], v[12:15]
	v_mfma_f32_16x16x32_bf16 v[8:11], v[64:67], v[224:227], v[8:11]
	v_mfma_f32_16x16x32_bf16 v[44:47], v[80:83], v[72:75], v[44:47]
	v_mfma_f32_16x16x32_bf16 v[104:107], v[84:87], v[88:91], v[44:47]
	v_mfma_f32_16x16x32_bf16 v[44:47], v[176:179], v[72:75], v[48:51]
	v_mfma_f32_16x16x32_bf16 v[40:43], v[80:83], v[92:95], v[40:43]
	v_mfma_f32_16x16x32_bf16 v[32:35], v[176:179], v[92:95], v[32:35]
	v_mfma_f32_16x16x32_bf16 v[24:27], v[80:83], v[100:103], v[24:27]
	v_mfma_f32_16x16x32_bf16 v[16:19], v[176:179], v[100:103], v[16:19]
	v_mfma_f32_16x16x32_bf16 v[4:7], v[80:83], v[220:223], v[4:7]
	v_mfma_f32_16x16x32_bf16 v[0:3], v[176:179], v[220:223], v[0:3]
	v_mfma_f32_16x16x32_bf16 v[72:75], v[212:215], v[88:91], v[44:47]
	v_mfma_f32_16x16x32_bf16 v[40:43], v[84:87], v[96:99], v[40:43]
	v_mfma_f32_16x16x32_bf16 v[32:35], v[212:215], v[96:99], v[32:35]
	v_mfma_f32_16x16x32_bf16 v[24:27], v[84:87], v[216:219], v[24:27]
	v_mfma_f32_16x16x32_bf16 v[16:19], v[212:215], v[216:219], v[16:19]
	v_mfma_f32_16x16x32_bf16 v[4:7], v[84:87], v[224:227], v[4:7]
	v_mfma_f32_16x16x32_bf16 v[0:3], v[212:215], v[224:227], v[0:3]
	s_setprio 0
	s_barrier
	s_add_i32 s74, s74, 2
	s_add_u32 s46, s46, 0x100
	s_addc_u32 s47, s47, 0
	s_add_u32 s72, s72, 0x100
	s_addc_u32 s73, s73, 0
	s_cmp_gt_u32 s74, 29
	s_cbranch_scc0 .LBB0_1951
	s_branch .Lkx_22

;     __host__ __device__ bool next(int i, Unit& u) const { const bool ok = StaticOrder::next(i, u); u.pm = 0; u.pn = 0; return ok; }
; #define PG8_STAGE(bufoff, gbase, voff) do { _Pragma("unroll") for (int _i = 0; _i < 2; ++_i) \
;         __builtin_amdgcn_global_load_lds((const unsigned*)((const char*)(gbase) + (voff)[_i]), (PG8_LAS unsigned*)(lds + (bufoff) + ldsw + _i * 8192), 16, 0, 0); } while (0)
; #define PG8_LDA(dst, b, h) do { _Pragma("unroll") for (int m = 0; m < 4; ++m) _Pragma("unroll") for (int k = 0; k < 2; ++k) dst[m][k] = *(const PG8_LAS bf16x8*)(lds + PG8_SA(b, h) + aoff + m * 2048 + k * 1024); } while (0)
; #define PG8_LDB(dst, b, h) do { _Pragma("unroll") for (int n = 0; n < 2; ++n) _Pragma("unroll") for (int k = 0; k < 2; ++k) dst[n][k] = *(const PG8_LAS bf16x8*)(lds + PG8_SB(b, h) + boff + n * 2048 + k * 1024); } while (0)
; #define PG8_WAIT_V(n) asm volatile("s_waitcnt vmcnt(" #n ")" ::: "memory")
; #define PG8_WAIT_L(n) asm volatile("s_waitcnt lgkmcnt(" #n ")" ::: "memory")
; #define PG8_BAR __builtin_amdgcn_s_barrier()
; #define PG8_SCHED __builtin_amdgcn_sched_barrier(0)
; template <class Epi, class Sched, bool ALIGN_EPI = false, bool SP2 = false>
; __device__ __forceinline__ void gemm_phase(PG8_LAS unsigned char* lds, const Gemm g, const Sched& S, const Epi& E, const int wave_in) {
;     ...
;         const bool has_next = S.next(ui + 1, nxt);
;         const char* nA = has_next ? (const char*)g.A + (size_t)nxt.pm * tstepA : cA; const char* nB = has_next ? (const char*)g.Bt + (size_t)nxt.pn * tstepB : cB;
;         for (int t = 0; t < nt; t += 2) {
;             const bool last = (t == nt - 2);
;             const char* a1 = cA + (size_t)(t + 1) * kstep;
;             const char* a2 = last ? nA : cA + (size_t)(t + 2) * kstep; const char* b2 = last ? nB : cB + (size_t)(t + 2) * kstep;
;             const char* a3 = a2 + kstep; const char* b3 = b2 + kstep;
;             if (last && has_next) S.a_ready(nxt);
;             if constexpr (SP2) {
;             PG8_LDB(B0, 0, 0); PG8_LDB(B1, 0, 1); PG8_SCHED; PG8_LDA(At, 0, 0); PG8_STAGE(PG8_SA(1, 1), a1 + hstepA, voffA);
;             PG8_WAIT_V(8); PG8_WAIT_L(0); PG8_BAR; PG8_MMA(0, 0, At, B0); PG8_MMA(0, 1, At, B1); PG8_BAR; PG8_SCHED;
;             PG8_LDA(At, 0, 1); PG8_STAGE(PG8_SB(0, 0), b2, voffB); PG8_STAGE(PG8_SB(0, 1), b2 + hstepB, voffB); PG8_STAGE(PG8_SA(0, 0), a2, voffA);
.LBB0_2106:
	s_add_u32 s21, s24, 0x100
	v_mov_b32_e32 v0, 0
	s_addc_u32 s58, s25, 0
	s_mov_b32 s59, -2
	s_waitcnt vmcnt(0)
	ds_read_b128 v[128:131], v214
	ds_read_b128 v[132:135], v214 offset:1024
	ds_read_b128 v[136:139], v214 offset:2048
	ds_read_b128 v[140:143], v214 offset:3072
	ds_read_b128 v[162:165], v215
	ds_read_b128 v[166:169], v215 offset:1024
	ds_read_b128 v[170:173], v215 offset:2048
	ds_read_b128 v[174:177], v215 offset:3072
	s_add_u32 s24, s22, 0x100
	s_addc_u32 s25, s23, 0
	s_cmpk_eq_i32 s59, 0x52
	s_cselect_b32 s29, s5, s25
	s_cselect_b32 s28, s4, s24
	s_cselect_b32 s27, s19, s58
	s_cselect_b32 s26, s18, s21
	v_lshl_add_u64 v[210:211], s[22:23], 0, v[154:155]
	s_add_i32 m0, s39, 0xc000
	ds_read_b128 v[178:181], v216
	ds_read_b128 v[182:185], v216 offset:1024
	ds_read_b128 v[186:189], v216 offset:2048
	ds_read_b128 v[190:193], v216 offset:3072
	ds_read_b128 v[194:197], v216 offset:4096
	ds_read_b128 v[198:201], v216 offset:5120
	ds_read_b128 v[202:205], v216 offset:6144
	ds_read_b128 v[206:209], v216 offset:7168
	global_load_lds_dwordx4 v[210:211], off
	v_lshl_add_u64 v[210:211], s[22:23], 0, v[156:157]
	s_add_i32 m0, s39, 0xe000
	s_nop 0
	global_load_lds_dwordx4 v[210:211], off
	s_waitcnt vmcnt(8)
	s_waitcnt lgkmcnt(0)
	s_setprio 1
	s_barrier
	v_mfma_f32_16x16x32_bf16 v[124:127], v[128:131], v[178:181], 0
	v_mfma_f32_16x16x32_bf16 v[120:123], v[136:139], v[178:181], 0
	v_mfma_f32_16x16x32_bf16 v[112:115], v[128:131], v[186:189], 0
	v_mfma_f32_16x16x32_bf16 v[104:107], v[136:139], v[186:189], 0
	v_mfma_f32_16x16x32_bf16 v[100:103], v[128:131], v[194:197], 0
	v_mfma_f32_16x16x32_bf16 v[96:99], v[136:139], v[194:197], 0
	v_mfma_f32_16x16x32_bf16 v[76:79], v[128:131], v[202:205], 0
	v_mfma_f32_16x16x32_bf16 v[72:75], v[136:139], v[202:205], 0
	v_mfma_f32_16x16x32_bf16 v[124:127], v[132:135], v[182:185], v[124:127]
	v_mfma_f32_16x16x32_bf16 v[120:123], v[140:143], v[182:185], v[120:123]
	v_mfma_f32_16x16x32_bf16 v[112:115], v[132:135], v[190:193], v[112:115]
	v_mfma_f32_16x16x32_bf16 v[104:107], v[140:143], v[190:193], v[104:107]
	v_mfma_f32_16x16x32_bf16 v[100:103], v[132:135], v[198:201], v[100:103]
	v_mfma_f32_16x16x32_bf16 v[96:99], v[140:143], v[198:201], v[96:99]
	v_mfma_f32_16x16x32_bf16 v[76:79], v[132:135], v[206:209], v[76:79]
	v_mfma_f32_16x16x32_bf16 v[72:75], v[140:143], v[206:209], v[72:75]
	v_mfma_f32_16x16x32_bf16 v[116:119], v[162:165], v[178:181], 0
	v_mfma_f32_16x16x32_bf16 v[108:111], v[170:173], v[178:181], 0
	v_mfma_f32_16x16x32_bf16 v[92:95], v[162:165], v[186:189], 0
	v_mfma_f32_16x16x32_bf16 v[88:91], v[170:173], v[186:189], 0
	v_mfma_f32_16x16x32_bf16 v[84:87], v[162:165], v[194:197], 0
	v_mfma_f32_16x16x32_bf16 v[80:83], v[170:173], v[194:197], 0
	v_mfma_f32_16x16x32_bf16 v[68:71], v[162:165], v[202:205], 0
	v_mfma_f32_16x16x32_bf16 v[64:67], v[170:173], v[202:205], 0
	v_mfma_f32_16x16x32_bf16 v[116:119], v[166:169], v[182:185], v[116:119]
	v_mfma_f32_16x16x32_bf16 v[108:111], v[174:177], v[182:185], v[108:111]
	v_mfma_f32_16x16x32_bf16 v[92:95], v[166:169], v[190:193], v[92:95]
	v_mfma_f32_16x16x32_bf16 v[88:91], v[174:177], v[190:193], v[88:91]
	v_mfma_f32_16x16x32_bf16 v[84:87], v[166:169], v[198:201], v[84:87]
	v_mfma_f32_16x16x32_bf16 v[80:83], v[174:177], v[198:201], v[80:83]
	v_mfma_f32_16x16x32_bf16 v[68:71], v[166:169], v[206:209], v[68:71]
	v_mfma_f32_16x16x32_bf16 v[64:67], v[174:177], v[206:209], v[64:67]
	s_setprio 0
	s_barrier
	s_add_i32 s22, s49, s36
	v_lshl_add_u64 v[210:211], s[26:27], 0, v[148:149]
	s_mov_b32 m0, s22
	ds_read_b128 v[178:181], v216 offset:16384
	ds_read_b128 v[182:185], v216 offset:17408
	ds_read_b128 v[186:189], v216 offset:18432
	ds_read_b128 v[190:193], v216 offset:19456
	ds_read_b128 v[194:197], v216 offset:20480
	ds_read_b128 v[198:201], v216 offset:21504
	ds_read_b128 v[202:205], v216 offset:22528
	ds_read_b128 v[206:209], v216 offset:23552
	global_load_lds_dwordx4 v[210:211], off
	s_add_i32 m0, s22, 0x2000
	s_add_u32 s22, s26, 0x158000
	v_lshl_add_u64 v[218:219], s[26:27], 0, v[144:145]
	s_addc_u32 s23, s27, 0
	s_add_i32 s60, s50, s36
	global_load_lds_dwordx4 v[218:219], off
	v_lshl_add_u64 v[220:221], s[22:23], 0, v[148:149]
	s_mov_b32 m0, s60
	v_lshl_add_u64 v[222:223], s[28:29], 0, v[146:147]
	global_load_lds_dwordx4 v[220:221], off
	v_lshl_add_u64 v[220:221], s[22:23], 0, v[144:145]
	s_add_i32 m0, s60, 0x2000
	s_nop 0
	global_load_lds_dwordx4 v[220:221], off
	v_lshl_add_u64 v[220:221], s[28:29], 0, v[150:151]
	s_mov_b32 m0, s39
	s_nop 0
	global_load_lds_dwordx4 v[220:221], off
	s_mov_b32 m0, s40
	s_nop 0
	global_load_lds_dwordx4 v[222:223], off
	s_waitcnt vmcnt(8)
	s_waitcnt lgkmcnt(0)
	s_setprio 1
	s_barrier
; #define PG8_STAGE(bufoff, gbase, voff) do { _Pragma("unroll") for (int _i = 0; _i < 2; ++_i) \
;         __builtin_amdgcn_global_load_lds((const unsigned*)((const char*)(gbase) + (voff)[_i]), (PG8_LAS unsigned*)(lds + (bufoff) + ldsw + _i * 8192), 16, 0, 0); } while (0)
; #define PG8_LDA(dst, b, h) do { _Pragma("unroll") for (int m = 0; m < 4; ++m) _Pragma("unroll") for (int k = 0; k < 2; ++k) dst[m][k] = *(const PG8_LAS bf16x8*)(lds + PG8_SA(b, h) + aoff + m * 2048 + k * 1024); } while (0)
; #define PG8_LDB(dst, b, h) do { _Pragma("unroll") for (int n = 0; n < 2; ++n) _Pragma("unroll") for (int k = 0; k < 2; ++k) dst[n][k] = *(const PG8_LAS bf16x8*)(lds + PG8_SB(b, h) + boff + n * 2048 + k * 1024); } while (0)
; #define PG8_MMA(ai, bj, At, Bt) do { __builtin_amdgcn_s_setprio(1); _Pragma("unroll") for (int m = 0; m < 4; ++m) _Pragma("unroll") for (int n = 0; n < 2; ++n) _Pragma("unroll") for (int k = 0; k < 2; ++k) \
;         acc[ai][bj][m][n] = __builtin_amdgcn_mfma_f32_16x16x32_bf16(Bt[n][k], At[m][k], acc[ai][bj][m][n], 0, 0, 0); __builtin_amdgcn_s_setprio(0); } while (0)
; #define PG8_WAIT_V(n) asm volatile("s_waitcnt vmcnt(" #n ")" ::: "memory")
; #define PG8_WAIT_L(n) asm volatile("s_waitcnt lgkmcnt(" #n ")" ::: "memory")
; #define PG8_BAR __builtin_amdgcn_s_barrier()
; #define PG8_SCHED __builtin_amdgcn_sched_barrier(0)
; template <class Epi, class Sched, bool ALIGN_EPI = false, bool SP2 = false>
; __device__ __forceinline__ void gemm_phase(PG8_LAS unsigned char* lds, const Gemm g, const Sched& S, const Epi& E, const int wave_in) {
;     ...
;             PG8_WAIT_V(8); PG8_WAIT_L(0); PG8_BAR; PG8_MMA(1, 0, At, B0); PG8_MMA(1, 1, At, B1); PG8_BAR; PG8_SCHED;
;             PG8_LDB(B0, 1, 0); PG8_LDB(B1, 1, 1); PG8_SCHED; PG8_LDA(At, 1, 0); PG8_STAGE(PG8_SA(0, 1), a2 + hstepA, voffA);
;             PG8_WAIT_V(8); PG8_WAIT_L(0); PG8_BAR; PG8_MMA(0, 0, At, B0); PG8_MMA(0, 1, At, B1); PG8_BAR; PG8_SCHED;
	v_mfma_f32_16x16x32_bf16 v[60:63], v[128:131], v[178:181], 0
	v_mfma_f32_16x16x32_bf16 v[56:59], v[136:139], v[178:181], 0
	v_mfma_f32_16x16x32_bf16 v[48:51], v[128:131], v[186:189], 0
	v_mfma_f32_16x16x32_bf16 v[40:43], v[136:139], v[186:189], 0
	v_mfma_f32_16x16x32_bf16 v[32:35], v[128:131], v[194:197], 0
	v_mfma_f32_16x16x32_bf16 v[24:27], v[136:139], v[194:197], 0
	v_mfma_f32_16x16x32_bf16 v[16:19], v[128:131], v[202:205], 0
	v_mfma_f32_16x16x32_bf16 v[8:11], v[136:139], v[202:205], 0
	v_mfma_f32_16x16x32_bf16 v[60:63], v[132:135], v[182:185], v[60:63]
	v_mfma_f32_16x16x32_bf16 v[56:59], v[140:143], v[182:185], v[56:59]
	v_mfma_f32_16x16x32_bf16 v[48:51], v[132:135], v[190:193], v[48:51]
	v_mfma_f32_16x16x32_bf16 v[40:43], v[140:143], v[190:193], v[40:43]
	v_mfma_f32_16x16x32_bf16 v[32:35], v[132:135], v[198:201], v[32:35]
	v_mfma_f32_16x16x32_bf16 v[24:27], v[140:143], v[198:201], v[24:27]
	v_mfma_f32_16x16x32_bf16 v[16:19], v[132:135], v[206:209], v[16:19]
	v_mfma_f32_16x16x32_bf16 v[8:11], v[140:143], v[206:209], v[8:11]
	v_mfma_f32_16x16x32_bf16 v[52:55], v[162:165], v[178:181], 0
	v_mfma_f32_16x16x32_bf16 v[44:47], v[170:173], v[178:181], 0
	v_mfma_f32_16x16x32_bf16 v[36:39], v[162:165], v[186:189], 0
	v_mfma_f32_16x16x32_bf16 v[28:31], v[170:173], v[186:189], 0
	v_mfma_f32_16x16x32_bf16 v[20:23], v[162:165], v[194:197], 0
	v_mfma_f32_16x16x32_bf16 v[12:15], v[170:173], v[194:197], 0
	v_mfma_f32_16x16x32_bf16 v[4:7], v[162:165], v[202:205], 0
	v_mfma_f32_16x16x32_bf16 v[0:3], v[170:173], v[202:205], 0
	v_mfma_f32_16x16x32_bf16 v[52:55], v[166:169], v[182:185], v[52:55]
	v_mfma_f32_16x16x32_bf16 v[44:47], v[174:177], v[182:185], v[44:47]
	v_mfma_f32_16x16x32_bf16 v[36:39], v[166:169], v[190:193], v[36:39]
	v_mfma_f32_16x16x32_bf16 v[28:31], v[174:177], v[190:193], v[28:31]
	v_mfma_f32_16x16x32_bf16 v[20:23], v[166:169], v[198:201], v[20:23]
	v_mfma_f32_16x16x32_bf16 v[12:15], v[174:177], v[198:201], v[12:15]
	v_mfma_f32_16x16x32_bf16 v[4:7], v[166:169], v[206:209], v[4:7]
	v_mfma_f32_16x16x32_bf16 v[0:3], v[174:177], v[206:209], v[0:3]
	s_setprio 0
	s_barrier
	s_add_i32 s60, 0, 0x18000
	s_add_i32 s61, 0, 0x1c000
	v_add_u32_e32 v140, s60, v212
	v_add_u32_e32 v174, s61, v212
	ds_read_b128 v[128:131], v140
	ds_read_b128 v[132:135], v140 offset:1024
	ds_read_b128 v[136:139], v140 offset:2048
	ds_read_b128 v[140:143], v140 offset:3072
	ds_read_b128 v[162:165], v174
	ds_read_b128 v[166:169], v174 offset:1024
	ds_read_b128 v[170:173], v174 offset:2048
	ds_read_b128 v[174:177], v174 offset:3072
	s_add_u32 s22, s28, 0x158000
	s_addc_u32 s23, s29, 0
	s_mov_b32 m0, s41
	v_lshl_add_u64 v[224:225], s[22:23], 0, v[150:151]
	ds_read_b128 v[178:181], v216 offset:32768
	ds_read_b128 v[182:185], v216 offset:33792
	ds_read_b128 v[186:189], v216 offset:34816
	ds_read_b128 v[190:193], v216 offset:35840
	ds_read_b128 v[194:197], v216 offset:36864
	ds_read_b128 v[198:201], v216 offset:37888
	ds_read_b128 v[202:205], v216 offset:38912
	ds_read_b128 v[206:209], v216 offset:39936
	global_load_lds_dwordx4 v[224:225], off
	v_lshl_add_u64 v[224:225], s[22:23], 0, v[146:147]
	s_mov_b32 m0, s42
	s_nop 0
	global_load_lds_dwordx4 v[224:225], off
	s_waitcnt vmcnt(8)
	s_waitcnt lgkmcnt(0)
	s_setprio 1
	s_barrier
	v_mfma_f32_16x16x32_bf16 v[124:127], v[128:131], v[178:181], v[124:127]
	v_mfma_f32_16x16x32_bf16 v[120:123], v[136:139], v[178:181], v[120:123]
	v_mfma_f32_16x16x32_bf16 v[112:115], v[128:131], v[186:189], v[112:115]
	v_mfma_f32_16x16x32_bf16 v[104:107], v[136:139], v[186:189], v[104:107]
	v_mfma_f32_16x16x32_bf16 v[100:103], v[128:131], v[194:197], v[100:103]
	v_mfma_f32_16x16x32_bf16 v[96:99], v[136:139], v[194:197], v[96:99]
	v_mfma_f32_16x16x32_bf16 v[76:79], v[128:131], v[202:205], v[76:79]
	v_mfma_f32_16x16x32_bf16 v[72:75], v[136:139], v[202:205], v[72:75]
	v_mfma_f32_16x16x32_bf16 v[124:127], v[132:135], v[182:185], v[124:127]
	v_mfma_f32_16x16x32_bf16 v[120:123], v[140:143], v[182:185], v[120:123]
	v_mfma_f32_16x16x32_bf16 v[112:115], v[132:135], v[190:193], v[112:115]
	v_mfma_f32_16x16x32_bf16 v[104:107], v[140:143], v[190:193], v[104:107]
	v_mfma_f32_16x16x32_bf16 v[100:103], v[132:135], v[198:201], v[100:103]
	v_mfma_f32_16x16x32_bf16 v[96:99], v[140:143], v[198:201], v[96:99]
	v_mfma_f32_16x16x32_bf16 v[76:79], v[132:135], v[206:209], v[76:79]
	v_mfma_f32_16x16x32_bf16 v[72:75], v[140:143], v[206:209], v[72:75]
	v_mfma_f32_16x16x32_bf16 v[116:119], v[162:165], v[178:181], v[116:119]
	v_mfma_f32_16x16x32_bf16 v[108:111], v[170:173], v[178:181], v[108:111]
	v_mfma_f32_16x16x32_bf16 v[92:95], v[162:165], v[186:189], v[92:95]
	v_mfma_f32_16x16x32_bf16 v[88:91], v[170:173], v[186:189], v[88:91]
	v_mfma_f32_16x16x32_bf16 v[84:87], v[162:165], v[194:197], v[84:87]
	v_mfma_f32_16x16x32_bf16 v[80:83], v[170:173], v[194:197], v[80:83]
	v_mfma_f32_16x16x32_bf16 v[68:71], v[162:165], v[202:205], v[68:71]
	v_mfma_f32_16x16x32_bf16 v[64:67], v[170:173], v[202:205], v[64:67]
	v_mfma_f32_16x16x32_bf16 v[116:119], v[166:169], v[182:185], v[116:119]
	v_mfma_f32_16x16x32_bf16 v[108:111], v[174:177], v[182:185], v[108:111]
	v_mfma_f32_16x16x32_bf16 v[92:95], v[166:169], v[190:193], v[92:95]
	v_mfma_f32_16x16x32_bf16 v[88:91], v[174:177], v[190:193], v[88:91]
	v_mfma_f32_16x16x32_bf16 v[84:87], v[166:169], v[198:201], v[84:87]
	v_mfma_f32_16x16x32_bf16 v[80:83], v[174:177], v[198:201], v[80:83]
	v_mfma_f32_16x16x32_bf16 v[68:71], v[166:169], v[206:209], v[68:71]
	v_mfma_f32_16x16x32_bf16 v[64:67], v[174:177], v[206:209], v[64:67]
	s_setprio 0
	s_barrier
; #define PG8_STAGE(bufoff, gbase, voff) do { _Pragma("unroll") for (int _i = 0; _i < 2; ++_i) \
;         __builtin_amdgcn_global_load_lds((const unsigned*)((const char*)(gbase) + (voff)[_i]), (PG8_LAS unsigned*)(lds + (bufoff) + ldsw + _i * 8192), 16, 0, 0); } while (0)
; #define PG8_LDA(dst, b, h) do { _Pragma("unroll") for (int m = 0; m < 4; ++m) _Pragma("unroll") for (int k = 0; k < 2; ++k) dst[m][k] = *(const PG8_LAS bf16x8*)(lds + PG8_SA(b, h) + aoff + m * 2048 + k * 1024); } while (0)
; #define PG8_LDB(dst, b, h) do { _Pragma("unroll") for (int n = 0; n < 2; ++n) _Pragma("unroll") for (int k = 0; k < 2; ++k) dst[n][k] = *(const PG8_LAS bf16x8*)(lds + PG8_SB(b, h) + boff + n * 2048 + k * 1024); } while (0)
; #define PG8_MMA(ai, bj, At, Bt) do { __builtin_amdgcn_s_setprio(1); _Pragma("unroll") for (int m = 0; m < 4; ++m) _Pragma("unroll") for (int n = 0; n < 2; ++n) _Pragma("unroll") for (int k = 0; k < 2; ++k) \
;         acc[ai][bj][m][n] = __builtin_amdgcn_mfma_f32_16x16x32_bf16(Bt[n][k], At[m][k], acc[ai][bj][m][n], 0, 0, 0); __builtin_amdgcn_s_setprio(0); } while (0)
; #define PG8_WAIT_V(n) asm volatile("s_waitcnt vmcnt(" #n ")" ::: "memory")
; #define PG8_WAIT_L(n) asm volatile("s_waitcnt lgkmcnt(" #n ")" ::: "memory")
; #define PG8_BAR __builtin_amdgcn_s_barrier()
; #define PG8_SCHED __builtin_amdgcn_sched_barrier(0)
; template <class Epi, class Sched, bool ALIGN_EPI = false, bool SP2 = false>
; __device__ __forceinline__ void gemm_phase(PG8_LAS unsigned char* lds, const Gemm g, const Sched& S, const Epi& E, const int wave_in) {
;     ...
;             PG8_LDB(B0, 0, 0); PG8_LDB(B1, 0, 1); PG8_SCHED; PG8_LDA(At, 0, 0); PG8_STAGE(PG8_SA(1, 1), a1 + hstepA, voffA);
;     ...
;             PG8_LDA(At, 1, 1); PG8_STAGE(PG8_SB(1, 0), b3, voffB); PG8_STAGE(PG8_SB(1, 1), b3 + hstepB, voffB); PG8_STAGE(PG8_SA(1, 0), a3, voffA);
;             PG8_WAIT_V(8); PG8_WAIT_L(0); PG8_BAR; PG8_MMA(1, 0, At, B0); PG8_MMA(1, 1, At, B1); PG8_BAR; PG8_SCHED;
	s_add_i32 s22, s60, s36
	v_lshl_add_u64 v[210:211], v[210:211], 0, s[6:7]
	s_mov_b32 m0, s22
	ds_read_b128 v[178:181], v216 offset:49152
	ds_read_b128 v[182:185], v216 offset:50176
	ds_read_b128 v[186:189], v216 offset:51200
	ds_read_b128 v[190:193], v216 offset:52224
	ds_read_b128 v[194:197], v216 offset:53248
	ds_read_b128 v[198:201], v216 offset:54272
	ds_read_b128 v[202:205], v216 offset:55296
	ds_read_b128 v[206:209], v216 offset:56320
	global_load_lds_dwordx4 v[210:211], off
	s_add_i32 m0, s22, 0x2000
	s_add_u32 s22, s26, 0x158080
	v_lshl_add_u64 v[210:211], v[218:219], 0, s[6:7]
	s_addc_u32 s23, s27, 0
	s_add_i32 s26, s61, s36
	global_load_lds_dwordx4 v[210:211], off
	v_lshl_add_u64 v[210:211], s[22:23], 0, v[148:149]
	s_mov_b32 m0, s26
	s_nop 0
	global_load_lds_dwordx4 v[210:211], off
	v_lshl_add_u64 v[210:211], s[22:23], 0, v[144:145]
	s_add_i32 m0, s26, 0x2000
	s_nop 0
	global_load_lds_dwordx4 v[210:211], off
	v_lshl_add_u64 v[210:211], v[220:221], 0, s[6:7]
	s_mov_b32 m0, s46
	s_nop 0
	global_load_lds_dwordx4 v[210:211], off
	v_lshl_add_u64 v[210:211], v[222:223], 0, s[6:7]
	s_mov_b32 m0, s47
	s_nop 0
	global_load_lds_dwordx4 v[210:211], off
	s_waitcnt vmcnt(8)
	s_waitcnt lgkmcnt(0)
	s_setprio 1
	s_barrier
	v_mfma_f32_16x16x32_bf16 v[60:63], v[128:131], v[178:181], v[60:63]
	v_mfma_f32_16x16x32_bf16 v[56:59], v[136:139], v[178:181], v[56:59]
	v_mfma_f32_16x16x32_bf16 v[48:51], v[128:131], v[186:189], v[48:51]
	v_mfma_f32_16x16x32_bf16 v[40:43], v[136:139], v[186:189], v[40:43]
	v_mfma_f32_16x16x32_bf16 v[32:35], v[128:131], v[194:197], v[32:35]
	v_mfma_f32_16x16x32_bf16 v[24:27], v[136:139], v[194:197], v[24:27]
	v_mfma_f32_16x16x32_bf16 v[16:19], v[128:131], v[202:205], v[16:19]
	v_mfma_f32_16x16x32_bf16 v[8:11], v[136:139], v[202:205], v[8:11]
	v_mfma_f32_16x16x32_bf16 v[60:63], v[132:135], v[182:185], v[60:63]
	v_mfma_f32_16x16x32_bf16 v[56:59], v[140:143], v[182:185], v[56:59]
	v_mfma_f32_16x16x32_bf16 v[48:51], v[132:135], v[190:193], v[48:51]
	v_mfma_f32_16x16x32_bf16 v[40:43], v[140:143], v[190:193], v[40:43]
	v_mfma_f32_16x16x32_bf16 v[32:35], v[132:135], v[198:201], v[32:35]
	v_mfma_f32_16x16x32_bf16 v[24:27], v[140:143], v[198:201], v[24:27]
	v_mfma_f32_16x16x32_bf16 v[16:19], v[132:135], v[206:209], v[16:19]
	v_mfma_f32_16x16x32_bf16 v[8:11], v[140:143], v[206:209], v[8:11]
	v_mfma_f32_16x16x32_bf16 v[52:55], v[162:165], v[178:181], v[52:55]
	v_mfma_f32_16x16x32_bf16 v[44:47], v[170:173], v[178:181], v[44:47]
	v_mfma_f32_16x16x32_bf16 v[36:39], v[162:165], v[186:189], v[36:39]
	v_mfma_f32_16x16x32_bf16 v[28:31], v[170:173], v[186:189], v[28:31]
	v_mfma_f32_16x16x32_bf16 v[20:23], v[162:165], v[194:197], v[20:23]
	v_mfma_f32_16x16x32_bf16 v[12:15], v[170:173], v[194:197], v[12:15]
	v_mfma_f32_16x16x32_bf16 v[4:7], v[162:165], v[202:205], v[4:7]
	v_mfma_f32_16x16x32_bf16 v[0:3], v[170:173], v[202:205], v[0:3]
	v_mfma_f32_16x16x32_bf16 v[52:55], v[166:169], v[182:185], v[52:55]
	v_mfma_f32_16x16x32_bf16 v[44:47], v[174:177], v[182:185], v[44:47]
	v_mfma_f32_16x16x32_bf16 v[36:39], v[166:169], v[190:193], v[36:39]
	v_mfma_f32_16x16x32_bf16 v[28:31], v[174:177], v[190:193], v[28:31]
	v_mfma_f32_16x16x32_bf16 v[20:23], v[166:169], v[198:201], v[20:23]
	v_mfma_f32_16x16x32_bf16 v[12:15], v[174:177], v[198:201], v[12:15]
	v_mfma_f32_16x16x32_bf16 v[4:7], v[166:169], v[206:209], v[4:7]
	v_mfma_f32_16x16x32_bf16 v[0:3], v[174:177], v[206:209], v[0:3]
	s_setprio 0
	s_barrier
	s_add_i32 s59, s59, 2
	s_add_u32 s21, s21, 0x100
	s_addc_u32 s58, s58, 0
	s_cmpk_gt_u32 s59, 0x53
	s_mov_b64 s[22:23], s[24:25]
	s_cbranch_scc0 .LBB0_2107
	s_branch .Lkx_24
.LBB0_2107:
	ds_read_b128 v[128:131], v214
	ds_read_b128 v[132:135], v214 offset:1024
	ds_read_b128 v[136:139], v214 offset:2048
	ds_read_b128 v[140:143], v214 offset:3072
	ds_read_b128 v[162:165], v215
	ds_read_b128 v[166:169], v215 offset:1024
	ds_read_b128 v[170:173], v215 offset:2048
	ds_read_b128 v[174:177], v215 offset:3072
	s_add_u32 s24, s22, 0x100
	s_addc_u32 s25, s23, 0
	s_cmpk_eq_i32 s59, 0x52
	s_cselect_b32 s29, s5, s25
	s_cselect_b32 s28, s4, s24
	s_cselect_b32 s27, s19, s58
	s_cselect_b32 s26, s18, s21
	v_lshl_add_u64 v[210:211], s[22:23], 0, v[154:155]
	s_add_i32 m0, s39, 0xc000
	ds_read_b128 v[178:181], v216
	ds_read_b128 v[182:185], v216 offset:1024
	ds_read_b128 v[186:189], v216 offset:2048
	ds_read_b128 v[190:193], v216 offset:3072
	ds_read_b128 v[194:197], v216 offset:4096
	ds_read_b128 v[198:201], v216 offset:5120
	ds_read_b128 v[202:205], v216 offset:6144
	ds_read_b128 v[206:209], v216 offset:7168
	global_load_lds_dwordx4 v[210:211], off
	v_lshl_add_u64 v[210:211], s[22:23], 0, v[156:157]
	s_add_i32 m0, s39, 0xe000
	s_nop 0
	global_load_lds_dwordx4 v[210:211], off
	s_waitcnt vmcnt(8)
	s_waitcnt lgkmcnt(0)
	s_setprio 1
	s_barrier
; #define PG8_STAGE(bufoff, gbase, voff) do { _Pragma("unroll") for (int _i = 0; _i < 2; ++_i) \
;         __builtin_amdgcn_global_load_lds((const unsigned*)((const char*)(gbase) + (voff)[_i]), (PG8_LAS unsigned*)(lds + (bufoff) + ldsw + _i * 8192), 16, 0, 0); } while (0)
; #define PG8_LDA(dst, b, h) do { _Pragma("unroll") for (int m = 0; m < 4; ++m) _Pragma("unroll") for (int k = 0; k < 2; ++k) dst[m][k] = *(const PG8_LAS bf16x8*)(lds + PG8_SA(b, h) + aoff + m * 2048 + k * 1024); } while (0)
; #define PG8_LDB(dst, b, h) do { _Pragma("unroll") for (int n = 0; n < 2; ++n) _Pragma("unroll") for (int k = 0; k < 2; ++k) dst[n][k] = *(const PG8_LAS bf16x8*)(lds + PG8_SB(b, h) + boff + n * 2048 + k * 1024); } while (0)
; #define PG8_MMA(ai, bj, At, Bt) do { __builtin_amdgcn_s_setprio(1); _Pragma("unroll") for (int m = 0; m < 4; ++m) _Pragma("unroll") for (int n = 0; n < 2; ++n) _Pragma("unroll") for (int k = 0; k < 2; ++k) \
;         acc[ai][bj][m][n] = __builtin_amdgcn_mfma_f32_16x16x32_bf16(Bt[n][k], At[m][k], acc[ai][bj][m][n], 0, 0, 0); __builtin_amdgcn_s_setprio(0); } while (0)
; #define PG8_WAIT_V(n) asm volatile("s_waitcnt vmcnt(" #n ")" ::: "memory")
; #define PG8_WAIT_L(n) asm volatile("s_waitcnt lgkmcnt(" #n ")" ::: "memory")
; #define PG8_BAR __builtin_amdgcn_s_barrier()
; #define PG8_SCHED __builtin_amdgcn_sched_barrier(0)
; template <class Epi, class Sched, bool ALIGN_EPI = false, bool SP2 = false>
; __device__ __forceinline__ void gemm_phase(PG8_LAS unsigned char* lds, const Gemm g, const Sched& S, const Epi& E, const int wave_in) {
;     ...
;             PG8_LDB(B0, 0, 0); PG8_LDB(B1, 0, 1); PG8_SCHED; PG8_LDA(At, 0, 0); PG8_STAGE(PG8_SA(1, 1), a1 + hstepA, voffA);
;             PG8_WAIT_V(8); PG8_WAIT_L(0); PG8_BAR; PG8_MMA(0, 0, At, B0); PG8_MMA(0, 1, At, B1); PG8_BAR; PG8_SCHED;
;             PG8_LDA(At, 0, 1); PG8_STAGE(PG8_SB(0, 0), b2, voffB); PG8_STAGE(PG8_SB(0, 1), b2 + hstepB, voffB); PG8_STAGE(PG8_SA(0, 0), a2, voffA);
;             PG8_WAIT_V(8); PG8_WAIT_L(0); PG8_BAR; PG8_MMA(1, 0, At, B0); PG8_MMA(1, 1, At, B1); PG8_BAR; PG8_SCHED;
	v_mfma_f32_16x16x32_bf16 v[124:127], v[128:131], v[178:181], v[124:127]
	v_mfma_f32_16x16x32_bf16 v[120:123], v[136:139], v[178:181], v[120:123]
	v_mfma_f32_16x16x32_bf16 v[112:115], v[128:131], v[186:189], v[112:115]
	v_mfma_f32_16x16x32_bf16 v[104:107], v[136:139], v[186:189], v[104:107]
	v_mfma_f32_16x16x32_bf16 v[100:103], v[128:131], v[194:197], v[100:103]
	v_mfma_f32_16x16x32_bf16 v[96:99], v[136:139], v[194:197], v[96:99]
	v_mfma_f32_16x16x32_bf16 v[76:79], v[128:131], v[202:205], v[76:79]
	v_mfma_f32_16x16x32_bf16 v[72:75], v[136:139], v[202:205], v[72:75]
	v_mfma_f32_16x16x32_bf16 v[124:127], v[132:135], v[182:185], v[124:127]
	v_mfma_f32_16x16x32_bf16 v[120:123], v[140:143], v[182:185], v[120:123]
	v_mfma_f32_16x16x32_bf16 v[112:115], v[132:135], v[190:193], v[112:115]
	v_mfma_f32_16x16x32_bf16 v[104:107], v[140:143], v[190:193], v[104:107]
	v_mfma_f32_16x16x32_bf16 v[100:103], v[132:135], v[198:201], v[100:103]
	v_mfma_f32_16x16x32_bf16 v[96:99], v[140:143], v[198:201], v[96:99]
	v_mfma_f32_16x16x32_bf16 v[76:79], v[132:135], v[206:209], v[76:79]
	v_mfma_f32_16x16x32_bf16 v[72:75], v[140:143], v[206:209], v[72:75]
	v_mfma_f32_16x16x32_bf16 v[116:119], v[162:165], v[178:181], v[116:119]
	v_mfma_f32_16x16x32_bf16 v[108:111], v[170:173], v[178:181], v[108:111]
	v_mfma_f32_16x16x32_bf16 v[92:95], v[162:165], v[186:189], v[92:95]
	v_mfma_f32_16x16x32_bf16 v[88:91], v[170:173], v[186:189], v[88:91]
	v_mfma_f32_16x16x32_bf16 v[84:87], v[162:165], v[194:197], v[84:87]
	v_mfma_f32_16x16x32_bf16 v[80:83], v[170:173], v[194:197], v[80:83]
	v_mfma_f32_16x16x32_bf16 v[68:71], v[162:165], v[202:205], v[68:71]
	v_mfma_f32_16x16x32_bf16 v[64:67], v[170:173], v[202:205], v[64:67]
	v_mfma_f32_16x16x32_bf16 v[116:119], v[166:169], v[182:185], v[116:119]
	v_mfma_f32_16x16x32_bf16 v[108:111], v[174:177], v[182:185], v[108:111]
	v_mfma_f32_16x16x32_bf16 v[92:95], v[166:169], v[190:193], v[92:95]
	v_mfma_f32_16x16x32_bf16 v[88:91], v[174:177], v[190:193], v[88:91]
	v_mfma_f32_16x16x32_bf16 v[84:87], v[166:169], v[198:201], v[84:87]
	v_mfma_f32_16x16x32_bf16 v[80:83], v[174:177], v[198:201], v[80:83]
	v_mfma_f32_16x16x32_bf16 v[68:71], v[166:169], v[206:209], v[68:71]
	v_mfma_f32_16x16x32_bf16 v[64:67], v[174:177], v[206:209], v[64:67]
	s_setprio 0
	s_barrier
	s_add_i32 s22, s49, s36
	v_lshl_add_u64 v[210:211], s[26:27], 0, v[148:149]
	s_mov_b32 m0, s22
	ds_read_b128 v[178:181], v216 offset:16384
	ds_read_b128 v[182:185], v216 offset:17408
	ds_read_b128 v[186:189], v216 offset:18432
	ds_read_b128 v[190:193], v216 offset:19456
	ds_read_b128 v[194:197], v216 offset:20480
	ds_read_b128 v[198:201], v216 offset:21504
	ds_read_b128 v[202:205], v216 offset:22528
	ds_read_b128 v[206:209], v216 offset:23552
	global_load_lds_dwordx4 v[210:211], off
	s_add_i32 m0, s22, 0x2000
	s_add_u32 s22, s26, 0x158000
	v_lshl_add_u64 v[218:219], s[26:27], 0, v[144:145]
	s_addc_u32 s23, s27, 0
	s_add_i32 s60, s50, s36
	global_load_lds_dwordx4 v[218:219], off
	v_lshl_add_u64 v[220:221], s[22:23], 0, v[148:149]
	s_mov_b32 m0, s60
	v_lshl_add_u64 v[222:223], s[28:29], 0, v[146:147]
	global_load_lds_dwordx4 v[220:221], off
	v_lshl_add_u64 v[220:221], s[22:23], 0, v[144:145]
	s_add_i32 m0, s60, 0x2000
	s_nop 0
	global_load_lds_dwordx4 v[220:221], off
	v_lshl_add_u64 v[220:221], s[28:29], 0, v[150:151]
	s_mov_b32 m0, s39
	s_nop 0
	global_load_lds_dwordx4 v[220:221], off
	s_mov_b32 m0, s40
	s_nop 0
	global_load_lds_dwordx4 v[222:223], off
	s_waitcnt vmcnt(8)
	s_waitcnt lgkmcnt(0)
	s_setprio 1
	s_barrier
	v_mfma_f32_16x16x32_bf16 v[60:63], v[128:131], v[178:181], v[60:63]
	v_mfma_f32_16x16x32_bf16 v[56:59], v[136:139], v[178:181], v[56:59]
	v_mfma_f32_16x16x32_bf16 v[48:51], v[128:131], v[186:189], v[48:51]
	v_mfma_f32_16x16x32_bf16 v[40:43], v[136:139], v[186:189], v[40:43]
	v_mfma_f32_16x16x32_bf16 v[32:35], v[128:131], v[194:197], v[32:35]
	v_mfma_f32_16x16x32_bf16 v[24:27], v[136:139], v[194:197], v[24:27]
	v_mfma_f32_16x16x32_bf16 v[16:19], v[128:131], v[202:205], v[16:19]
	v_mfma_f32_16x16x32_bf16 v[8:11], v[136:139], v[202:205], v[8:11]
	v_mfma_f32_16x16x32_bf16 v[60:63], v[132:135], v[182:185], v[60:63]
	v_mfma_f32_16x16x32_bf16 v[56:59], v[140:143], v[182:185], v[56:59]
	v_mfma_f32_16x16x32_bf16 v[48:51], v[132:135], v[190:193], v[48:51]
	v_mfma_f32_16x16x32_bf16 v[40:43], v[140:143], v[190:193], v[40:43]
	v_mfma_f32_16x16x32_bf16 v[32:35], v[132:135], v[198:201], v[32:35]
	v_mfma_f32_16x16x32_bf16 v[24:27], v[140:143], v[198:201], v[24:27]
	v_mfma_f32_16x16x32_bf16 v[16:19], v[132:135], v[206:209], v[16:19]
	v_mfma_f32_16x16x32_bf16 v[8:11], v[140:143], v[206:209], v[8:11]
	v_mfma_f32_16x16x32_bf16 v[52:55], v[162:165], v[178:181], v[52:55]
	v_mfma_f32_16x16x32_bf16 v[44:47], v[170:173], v[178:181], v[44:47]
	v_mfma_f32_16x16x32_bf16 v[36:39], v[162:165], v[186:189], v[36:39]
	v_mfma_f32_16x16x32_bf16 v[28:31], v[170:173], v[186:189], v[28:31]
	v_mfma_f32_16x16x32_bf16 v[20:23], v[162:165], v[194:197], v[20:23]
	v_mfma_f32_16x16x32_bf16 v[12:15], v[170:173], v[194:197], v[12:15]
	v_mfma_f32_16x16x32_bf16 v[4:7], v[162:165], v[202:205], v[4:7]
	v_mfma_f32_16x16x32_bf16 v[0:3], v[170:173], v[202:205], v[0:3]
	v_mfma_f32_16x16x32_bf16 v[52:55], v[166:169], v[182:185], v[52:55]
	v_mfma_f32_16x16x32_bf16 v[44:47], v[174:177], v[182:185], v[44:47]
	v_mfma_f32_16x16x32_bf16 v[36:39], v[166:169], v[190:193], v[36:39]
	v_mfma_f32_16x16x32_bf16 v[28:31], v[174:177], v[190:193], v[28:31]
	v_mfma_f32_16x16x32_bf16 v[20:23], v[166:169], v[198:201], v[20:23]
	v_mfma_f32_16x16x32_bf16 v[12:15], v[174:177], v[198:201], v[12:15]
	v_mfma_f32_16x16x32_bf16 v[4:7], v[166:169], v[206:209], v[4:7]
	v_mfma_f32_16x16x32_bf16 v[0:3], v[174:177], v[206:209], v[0:3]
	s_setprio 0
	s_barrier
; #define PG8_STAGE(bufoff, gbase, voff) do { _Pragma("unroll") for (int _i = 0; _i < 2; ++_i) \
;         __builtin_amdgcn_global_load_lds((const unsigned*)((const char*)(gbase) + (voff)[_i]), (PG8_LAS unsigned*)(lds + (bufoff) + ldsw + _i * 8192), 16, 0, 0); } while (0)
; #define PG8_LDA(dst, b, h) do { _Pragma("unroll") for (int m = 0; m < 4; ++m) _Pragma("unroll") for (int k = 0; k < 2; ++k) dst[m][k] = *(const PG8_LAS bf16x8*)(lds + PG8_SA(b, h) + aoff + m * 2048 + k * 1024); } while (0)
; #define PG8_LDB(dst, b, h) do { _Pragma("unroll") for (int n = 0; n < 2; ++n) _Pragma("unroll") for (int k = 0; k < 2; ++k) dst[n][k] = *(const PG8_LAS bf16x8*)(lds + PG8_SB(b, h) + boff + n * 2048 + k * 1024); } while (0)
; #define PG8_MMA(ai, bj, At, Bt) do { __builtin_amdgcn_s_setprio(1); _Pragma("unroll") for (int m = 0; m < 4; ++m) _Pragma("unroll") for (int n = 0; n < 2; ++n) _Pragma("unroll") for (int k = 0; k < 2; ++k) \
;         acc[ai][bj][m][n] = __builtin_amdgcn_mfma_f32_16x16x32_bf16(Bt[n][k], At[m][k], acc[ai][bj][m][n], 0, 0, 0); __builtin_amdgcn_s_setprio(0); } while (0)
; #define PG8_WAIT_V(n) asm volatile("s_waitcnt vmcnt(" #n ")" ::: "memory")
; #define PG8_WAIT_L(n) asm volatile("s_waitcnt lgkmcnt(" #n ")" ::: "memory")
; #define PG8_BAR __builtin_amdgcn_s_barrier()
; #define PG8_SCHED __builtin_amdgcn_sched_barrier(0)
; template <class Epi, class Sched, bool ALIGN_EPI = false, bool SP2 = false>
; __device__ __forceinline__ void gemm_phase(PG8_LAS unsigned char* lds, const Gemm g, const Sched& S, const Epi& E, const int wave_in) {
;     ...
;         for (int t = 0; t < nt; t += 2) {
;     ...
;             PG8_LDB(B0, 1, 0); PG8_LDB(B1, 1, 1); PG8_SCHED; PG8_LDA(At, 1, 0); PG8_STAGE(PG8_SA(0, 1), a2 + hstepA, voffA);
;             PG8_WAIT_V(8); PG8_WAIT_L(0); PG8_BAR; PG8_MMA(0, 0, At, B0); PG8_MMA(0, 1, At, B1); PG8_BAR; PG8_SCHED;
;             PG8_LDA(At, 1, 1); PG8_STAGE(PG8_SB(1, 0), b3, voffB); PG8_STAGE(PG8_SB(1, 1), b3 + hstepB, voffB); PG8_STAGE(PG8_SA(1, 0), a3, voffA);
;             PG8_WAIT_V(8); PG8_WAIT_L(0); PG8_BAR; PG8_MMA(1, 0, At, B0); PG8_MMA(1, 1, At, B1); PG8_BAR; PG8_SCHED;
	s_add_i32 s60, 0, 0x18000
	s_add_i32 s61, 0, 0x1c000
	v_add_u32_e32 v140, s60, v212
	v_add_u32_e32 v174, s61, v212
	ds_read_b128 v[128:131], v140
	ds_read_b128 v[132:135], v140 offset:1024
	ds_read_b128 v[136:139], v140 offset:2048
	ds_read_b128 v[140:143], v140 offset:3072
	ds_read_b128 v[162:165], v174
	ds_read_b128 v[166:169], v174 offset:1024
	ds_read_b128 v[170:173], v174 offset:2048
	ds_read_b128 v[174:177], v174 offset:3072
	s_add_u32 s22, s28, 0x158000
	s_addc_u32 s23, s29, 0
	s_mov_b32 m0, s41
	v_lshl_add_u64 v[224:225], s[22:23], 0, v[150:151]
	ds_read_b128 v[178:181], v216 offset:32768
	ds_read_b128 v[182:185], v216 offset:33792
	ds_read_b128 v[186:189], v216 offset:34816
	ds_read_b128 v[190:193], v216 offset:35840
	ds_read_b128 v[194:197], v216 offset:36864
	ds_read_b128 v[198:201], v216 offset:37888
	ds_read_b128 v[202:205], v216 offset:38912
	ds_read_b128 v[206:209], v216 offset:39936
	global_load_lds_dwordx4 v[224:225], off
	v_lshl_add_u64 v[224:225], s[22:23], 0, v[146:147]
	s_mov_b32 m0, s42
	s_nop 0
	global_load_lds_dwordx4 v[224:225], off
	s_waitcnt vmcnt(8)
	s_waitcnt lgkmcnt(0)
	s_setprio 1
	s_barrier
	v_mfma_f32_16x16x32_bf16 v[124:127], v[128:131], v[178:181], v[124:127]
	v_mfma_f32_16x16x32_bf16 v[120:123], v[136:139], v[178:181], v[120:123]
	v_mfma_f32_16x16x32_bf16 v[112:115], v[128:131], v[186:189], v[112:115]
	v_mfma_f32_16x16x32_bf16 v[104:107], v[136:139], v[186:189], v[104:107]
	v_mfma_f32_16x16x32_bf16 v[100:103], v[128:131], v[194:197], v[100:103]
	v_mfma_f32_16x16x32_bf16 v[96:99], v[136:139], v[194:197], v[96:99]
	v_mfma_f32_16x16x32_bf16 v[76:79], v[128:131], v[202:205], v[76:79]
	v_mfma_f32_16x16x32_bf16 v[72:75], v[136:139], v[202:205], v[72:75]
	v_mfma_f32_16x16x32_bf16 v[124:127], v[132:135], v[182:185], v[124:127]
	v_mfma_f32_16x16x32_bf16 v[120:123], v[140:143], v[182:185], v[120:123]
	v_mfma_f32_16x16x32_bf16 v[112:115], v[132:135], v[190:193], v[112:115]
	v_mfma_f32_16x16x32_bf16 v[104:107], v[140:143], v[190:193], v[104:107]
	v_mfma_f32_16x16x32_bf16 v[100:103], v[132:135], v[198:201], v[100:103]
	v_mfma_f32_16x16x32_bf16 v[96:99], v[140:143], v[198:201], v[96:99]
	v_mfma_f32_16x16x32_bf16 v[76:79], v[132:135], v[206:209], v[76:79]
	v_mfma_f32_16x16x32_bf16 v[72:75], v[140:143], v[206:209], v[72:75]
	v_mfma_f32_16x16x32_bf16 v[116:119], v[162:165], v[178:181], v[116:119]
	v_mfma_f32_16x16x32_bf16 v[108:111], v[170:173], v[178:181], v[108:111]
	v_mfma_f32_16x16x32_bf16 v[92:95], v[162:165], v[186:189], v[92:95]
	v_mfma_f32_16x16x32_bf16 v[88:91], v[170:173], v[186:189], v[88:91]
	v_mfma_f32_16x16x32_bf16 v[84:87], v[162:165], v[194:197], v[84:87]
	v_mfma_f32_16x16x32_bf16 v[80:83], v[170:173], v[194:197], v[80:83]
	v_mfma_f32_16x16x32_bf16 v[68:71], v[162:165], v[202:205], v[68:71]
	v_mfma_f32_16x16x32_bf16 v[64:67], v[170:173], v[202:205], v[64:67]
	v_mfma_f32_16x16x32_bf16 v[116:119], v[166:169], v[182:185], v[116:119]
	v_mfma_f32_16x16x32_bf16 v[108:111], v[174:177], v[182:185], v[108:111]
	v_mfma_f32_16x16x32_bf16 v[92:95], v[166:169], v[190:193], v[92:95]
	v_mfma_f32_16x16x32_bf16 v[88:91], v[174:177], v[190:193], v[88:91]
	v_mfma_f32_16x16x32_bf16 v[84:87], v[166:169], v[198:201], v[84:87]
	v_mfma_f32_16x16x32_bf16 v[80:83], v[174:177], v[198:201], v[80:83]
	v_mfma_f32_16x16x32_bf16 v[68:71], v[166:169], v[206:209], v[68:71]
	v_mfma_f32_16x16x32_bf16 v[64:67], v[174:177], v[206:209], v[64:67]
	s_setprio 0
	s_barrier
	s_add_i32 s22, s60, s36
	v_lshl_add_u64 v[210:211], v[210:211], 0, s[6:7]
	s_mov_b32 m0, s22
	ds_read_b128 v[178:181], v216 offset:49152
	ds_read_b128 v[182:185], v216 offset:50176
	ds_read_b128 v[186:189], v216 offset:51200
	ds_read_b128 v[190:193], v216 offset:52224
	ds_read_b128 v[194:197], v216 offset:53248
	ds_read_b128 v[198:201], v216 offset:54272
	ds_read_b128 v[202:205], v216 offset:55296
	ds_read_b128 v[206:209], v216 offset:56320
	global_load_lds_dwordx4 v[210:211], off
	s_add_i32 m0, s22, 0x2000
	s_add_u32 s22, s26, 0x158080
	v_lshl_add_u64 v[210:211], v[218:219], 0, s[6:7]
	s_addc_u32 s23, s27, 0
	s_add_i32 s26, s61, s36
	global_load_lds_dwordx4 v[210:211], off
	v_lshl_add_u64 v[210:211], s[22:23], 0, v[148:149]
	s_mov_b32 m0, s26
	s_nop 0
	global_load_lds_dwordx4 v[210:211], off
	v_lshl_add_u64 v[210:211], s[22:23], 0, v[144:145]
	s_add_i32 m0, s26, 0x2000
	s_nop 0
	global_load_lds_dwordx4 v[210:211], off
	v_lshl_add_u64 v[210:211], v[220:221], 0, s[6:7]
	s_mov_b32 m0, s46
	s_nop 0
	global_load_lds_dwordx4 v[210:211], off
	v_lshl_add_u64 v[210:211], v[222:223], 0, s[6:7]
	s_mov_b32 m0, s47
	s_nop 0
	global_load_lds_dwordx4 v[210:211], off
	s_waitcnt vmcnt(8)
	s_waitcnt lgkmcnt(0)
	s_setprio 1
	s_barrier
	v_mfma_f32_16x16x32_bf16 v[60:63], v[128:131], v[178:181], v[60:63]
	v_mfma_f32_16x16x32_bf16 v[56:59], v[136:139], v[178:181], v[56:59]
	v_mfma_f32_16x16x32_bf16 v[48:51], v[128:131], v[186:189], v[48:51]
	v_mfma_f32_16x16x32_bf16 v[40:43], v[136:139], v[186:189], v[40:43]
	v_mfma_f32_16x16x32_bf16 v[32:35], v[128:131], v[194:197], v[32:35]
	v_mfma_f32_16x16x32_bf16 v[24:27], v[136:139], v[194:197], v[24:27]
	v_mfma_f32_16x16x32_bf16 v[16:19], v[128:131], v[202:205], v[16:19]
	v_mfma_f32_16x16x32_bf16 v[8:11], v[136:139], v[202:205], v[8:11]
	v_mfma_f32_16x16x32_bf16 v[60:63], v[132:135], v[182:185], v[60:63]
	v_mfma_f32_16x16x32_bf16 v[56:59], v[140:143], v[182:185], v[56:59]
	v_mfma_f32_16x16x32_bf16 v[48:51], v[132:135], v[190:193], v[48:51]
	v_mfma_f32_16x16x32_bf16 v[40:43], v[140:143], v[190:193], v[40:43]
	v_mfma_f32_16x16x32_bf16 v[32:35], v[132:135], v[198:201], v[32:35]
	v_mfma_f32_16x16x32_bf16 v[24:27], v[140:143], v[198:201], v[24:27]
	v_mfma_f32_16x16x32_bf16 v[16:19], v[132:135], v[206:209], v[16:19]
	v_mfma_f32_16x16x32_bf16 v[8:11], v[140:143], v[206:209], v[8:11]
	v_mfma_f32_16x16x32_bf16 v[52:55], v[162:165], v[178:181], v[52:55]
	v_mfma_f32_16x16x32_bf16 v[44:47], v[170:173], v[178:181], v[44:47]
	v_mfma_f32_16x16x32_bf16 v[36:39], v[162:165], v[186:189], v[36:39]
	v_mfma_f32_16x16x32_bf16 v[28:31], v[170:173], v[186:189], v[28:31]
	v_mfma_f32_16x16x32_bf16 v[20:23], v[162:165], v[194:197], v[20:23]
	v_mfma_f32_16x16x32_bf16 v[12:15], v[170:173], v[194:197], v[12:15]
	v_mfma_f32_16x16x32_bf16 v[4:7], v[162:165], v[202:205], v[4:7]
	v_mfma_f32_16x16x32_bf16 v[0:3], v[170:173], v[202:205], v[0:3]
	v_mfma_f32_16x16x32_bf16 v[52:55], v[166:169], v[182:185], v[52:55]
	v_mfma_f32_16x16x32_bf16 v[44:47], v[174:177], v[182:185], v[44:47]
	v_mfma_f32_16x16x32_bf16 v[36:39], v[166:169], v[190:193], v[36:39]
	v_mfma_f32_16x16x32_bf16 v[28:31], v[174:177], v[190:193], v[28:31]
	v_mfma_f32_16x16x32_bf16 v[20:23], v[166:169], v[198:201], v[20:23]
	v_mfma_f32_16x16x32_bf16 v[12:15], v[174:177], v[198:201], v[12:15]
	v_mfma_f32_16x16x32_bf16 v[4:7], v[166:169], v[206:209], v[4:7]
	v_mfma_f32_16x16x32_bf16 v[0:3], v[174:177], v[206:209], v[0:3]
	s_setprio 0
	s_barrier
	s_add_i32 s59, s59, 2
	s_add_u32 s21, s21, 0x100
	s_addc_u32 s58, s58, 0
	s_cmpk_gt_u32 s59, 0x53
	s_mov_b64 s[22:23], s[24:25]
	s_cbranch_scc0 .LBB0_2107

;     __host__ __device__ bool next(int i, Unit& u) const { const bool ok = StaticOrder::next(i, u); u.pm = 0; u.pn = 0; return ok; }
; #define PG8_STAGE(bufoff, gbase, voff) do { _Pragma("unroll") for (int _i = 0; _i < 2; ++_i) \
;         __builtin_amdgcn_global_load_lds((const unsigned*)((const char*)(gbase) + (voff)[_i]), (PG8_LAS unsigned*)(lds + (bufoff) + ldsw + _i * 8192), 16, 0, 0); } while (0)
; #define PG8_LDA(dst, b, h) do { _Pragma("unroll") for (int m = 0; m < 4; ++m) _Pragma("unroll") for (int k = 0; k < 2; ++k) dst[m][k] = *(const PG8_LAS bf16x8*)(lds + PG8_SA(b, h) + aoff + m * 2048 + k * 1024); } while (0)
; #define PG8_LDB(dst, b, h) do { _Pragma("unroll") for (int n = 0; n < 2; ++n) _Pragma("unroll") for (int k = 0; k < 2; ++k) dst[n][k] = *(const PG8_LAS bf16x8*)(lds + PG8_SB(b, h) + boff + n * 2048 + k * 1024); } while (0)
; #define PG8_WAIT_V(n) asm volatile("s_waitcnt vmcnt(" #n ")" ::: "memory")
; #define PG8_WAIT_L(n) asm volatile("s_waitcnt lgkmcnt(" #n ")" ::: "memory")
; #define PG8_BAR __builtin_amdgcn_s_barrier()
; #define PG8_SCHED __builtin_amdgcn_sched_barrier(0)
; template <class Epi, class Sched, bool ALIGN_EPI = false, bool SP2 = false>
; __device__ __forceinline__ void gemm_phase(PG8_LAS unsigned char* lds, const Gemm g, const Sched& S, const Epi& E, const int wave_in) {
;     ...
;         const bool has_next = S.next(ui + 1, nxt);
;         const char* nA = has_next ? (const char*)g.A + (size_t)nxt.pm * tstepA : cA; const char* nB = has_next ? (const char*)g.Bt + (size_t)nxt.pn * tstepB : cB;
;         for (int t = 0; t < nt; t += 2) {
;             const bool last = (t == nt - 2);
;             const char* a1 = cA + (size_t)(t + 1) * kstep;
;             const char* a2 = last ? nA : cA + (size_t)(t + 2) * kstep; const char* b2 = last ? nB : cB + (size_t)(t + 2) * kstep;
;             const char* a3 = a2 + kstep; const char* b3 = b2 + kstep;
;             if (last && has_next) S.a_ready(nxt);
;             if constexpr (SP2) {
;             PG8_LDB(B0, 0, 0); PG8_LDB(B1, 0, 1); PG8_SCHED; PG8_LDA(At, 0, 0); PG8_STAGE(PG8_SA(1, 1), a1 + hstepA, voffA);
;             PG8_WAIT_V(8); PG8_WAIT_L(0); PG8_BAR; PG8_MMA(0, 0, At, B0); PG8_MMA(0, 1, At, B1); PG8_BAR; PG8_SCHED;
;             PG8_LDA(At, 0, 1); PG8_STAGE(PG8_SB(0, 0), b2, voffB); PG8_STAGE(PG8_SB(0, 1), b2 + hstepB, voffB); PG8_STAGE(PG8_SA(0, 0), a2, voffA);
.LBB0_2247:
	s_ashr_i32 s15, s14, 31
	s_lshl_b64 s[16:17], s[14:15], 20
	s_add_u32 s16, s28, s16
	s_addc_u32 s17, s29, s17
	s_and_b64 s[18:19], s[2:3], exec
	s_cselect_b32 s5, s17, s23
	s_cselect_b32 s15, s16, s22
	s_ashr_i32 s13, s12, 31
	s_lshl_b64 s[18:19], s[12:13], 20
	s_add_u32 s18, s30, s18
	s_addc_u32 s19, s31, s19
	s_and_b64 s[26:27], s[2:3], exec
	s_cselect_b32 s13, s19, s25
	s_cselect_b32 s47, s18, s24
	s_add_u32 s22, s22, 0x80080
	s_addc_u32 s23, s23, 0
	s_add_u32 s48, s24, 0x100
	v_mov_b32_e32 v0, 0
	s_addc_u32 s49, s25, 0
	s_mov_b32 s50, -2
	ds_read_b128 v[144:147], v151
	ds_read_b128 v[154:157], v151 offset:1024
	ds_read_b128 v[158:161], v151 offset:2048
	ds_read_b128 v[162:165], v151 offset:3072
	ds_read_b128 v[166:169], v152
	ds_read_b128 v[170:173], v152 offset:1024
	ds_read_b128 v[174:177], v152 offset:2048
	ds_read_b128 v[178:181], v152 offset:3072
	s_add_u32 s24, s22, 0xfff80080
	s_addc_u32 s25, s23, -1
	s_cmp_eq_u32 s50, 28
	s_cselect_b32 s27, s5, s25
	s_cselect_b32 s26, s15, s24
	s_cselect_b32 s25, s13, s49
	s_cselect_b32 s24, s47, s48
	v_lshl_add_u64 v[214:215], s[22:23], 0, v[136:137]
	s_add_i32 m0, s21, 0xc000
	ds_read_b128 v[182:185], v153
	ds_read_b128 v[186:189], v153 offset:1024
	ds_read_b128 v[190:193], v153 offset:2048
	ds_read_b128 v[194:197], v153 offset:3072
	ds_read_b128 v[198:201], v153 offset:4096
	ds_read_b128 v[202:205], v153 offset:5120
	ds_read_b128 v[206:209], v153 offset:6144
	ds_read_b128 v[210:213], v153 offset:7168
	global_load_lds_dwordx4 v[214:215], off
	v_lshl_add_u64 v[214:215], s[22:23], 0, v[138:139]
	s_add_i32 m0, s21, 0xe000
	s_nop 0
	global_load_lds_dwordx4 v[214:215], off
	s_waitcnt vmcnt(8)
	s_waitcnt lgkmcnt(0)
	s_setprio 1
	s_barrier
	v_mfma_f32_16x16x32_bf16 v[124:127], v[144:147], v[182:185], 0
	v_mfma_f32_16x16x32_bf16 v[120:123], v[158:161], v[182:185], 0
	v_mfma_f32_16x16x32_bf16 v[108:111], v[144:147], v[190:193], 0
	v_mfma_f32_16x16x32_bf16 v[104:107], v[158:161], v[190:193], 0
	v_mfma_f32_16x16x32_bf16 v[92:95], v[144:147], v[198:201], 0
	v_mfma_f32_16x16x32_bf16 v[88:91], v[158:161], v[198:201], 0
	v_mfma_f32_16x16x32_bf16 v[76:79], v[144:147], v[206:209], 0
	v_mfma_f32_16x16x32_bf16 v[72:75], v[158:161], v[206:209], 0
	v_mfma_f32_16x16x32_bf16 v[124:127], v[154:157], v[186:189], v[124:127]
	v_mfma_f32_16x16x32_bf16 v[120:123], v[162:165], v[186:189], v[120:123]
	v_mfma_f32_16x16x32_bf16 v[108:111], v[154:157], v[194:197], v[108:111]
	v_mfma_f32_16x16x32_bf16 v[104:107], v[162:165], v[194:197], v[104:107]
	v_mfma_f32_16x16x32_bf16 v[92:95], v[154:157], v[202:205], v[92:95]
	v_mfma_f32_16x16x32_bf16 v[88:91], v[162:165], v[202:205], v[88:91]
	v_mfma_f32_16x16x32_bf16 v[76:79], v[154:157], v[210:213], v[76:79]
	v_mfma_f32_16x16x32_bf16 v[72:75], v[162:165], v[210:213], v[72:75]
	v_mfma_f32_16x16x32_bf16 v[116:119], v[166:169], v[182:185], 0
	v_mfma_f32_16x16x32_bf16 v[112:115], v[174:177], v[182:185], 0
	v_mfma_f32_16x16x32_bf16 v[100:103], v[166:169], v[190:193], 0
	v_mfma_f32_16x16x32_bf16 v[96:99], v[174:177], v[190:193], 0
	v_mfma_f32_16x16x32_bf16 v[84:87], v[166:169], v[198:201], 0
	v_mfma_f32_16x16x32_bf16 v[80:83], v[174:177], v[198:201], 0
	v_mfma_f32_16x16x32_bf16 v[68:71], v[166:169], v[206:209], 0
	v_mfma_f32_16x16x32_bf16 v[64:67], v[174:177], v[206:209], 0
	v_mfma_f32_16x16x32_bf16 v[116:119], v[170:173], v[186:189], v[116:119]
	v_mfma_f32_16x16x32_bf16 v[112:115], v[178:181], v[186:189], v[112:115]
	v_mfma_f32_16x16x32_bf16 v[100:103], v[170:173], v[194:197], v[100:103]
	v_mfma_f32_16x16x32_bf16 v[96:99], v[178:181], v[194:197], v[96:99]
	v_mfma_f32_16x16x32_bf16 v[84:87], v[170:173], v[202:205], v[84:87]
	v_mfma_f32_16x16x32_bf16 v[80:83], v[178:181], v[202:205], v[80:83]
	v_mfma_f32_16x16x32_bf16 v[68:71], v[170:173], v[210:213], v[68:71]
	v_mfma_f32_16x16x32_bf16 v[64:67], v[178:181], v[210:213], v[64:67]
	s_setprio 0
	s_barrier
	s_add_i32 s51, s44, s34
	v_lshl_add_u64 v[214:215], s[24:25], 0, v[130:131]
	s_mov_b32 m0, s51
	ds_read_b128 v[182:185], v153 offset:16384
	ds_read_b128 v[186:189], v153 offset:17408
	ds_read_b128 v[190:193], v153 offset:18432
	ds_read_b128 v[194:197], v153 offset:19456
	ds_read_b128 v[198:201], v153 offset:20480
	ds_read_b128 v[202:205], v153 offset:21504
	ds_read_b128 v[206:209], v153 offset:22528
	ds_read_b128 v[210:213], v153 offset:23552
	global_load_lds_dwordx4 v[214:215], off
	s_add_i32 m0, s51, 0x2000
	s_add_u32 s52, s24, 0x80000
	v_lshl_add_u64 v[216:217], s[24:25], 0, v[134:135]
	s_addc_u32 s53, s25, 0
	s_add_i32 s51, s45, s34
	global_load_lds_dwordx4 v[216:217], off
	v_lshl_add_u64 v[218:219], s[52:53], 0, v[130:131]
	s_mov_b32 m0, s51
	v_lshl_add_u64 v[220:221], s[26:27], 0, v[132:133]
	global_load_lds_dwordx4 v[218:219], off
	v_lshl_add_u64 v[218:219], s[52:53], 0, v[134:135]
	s_add_i32 m0, s51, 0x2000
	s_nop 0
	global_load_lds_dwordx4 v[218:219], off
	v_lshl_add_u64 v[218:219], s[26:27], 0, v[128:129]
	s_mov_b32 m0, s21
	s_nop 0
	global_load_lds_dwordx4 v[218:219], off
	s_mov_b32 m0, s35
	s_nop 0
	global_load_lds_dwordx4 v[220:221], off
	s_waitcnt vmcnt(8)
	s_waitcnt lgkmcnt(0)
	s_setprio 1
	s_barrier
; #define PG8_STAGE(bufoff, gbase, voff) do { _Pragma("unroll") for (int _i = 0; _i < 2; ++_i) \
;         __builtin_amdgcn_global_load_lds((const unsigned*)((const char*)(gbase) + (voff)[_i]), (PG8_LAS unsigned*)(lds + (bufoff) + ldsw + _i * 8192), 16, 0, 0); } while (0)
; #define PG8_LDA(dst, b, h) do { _Pragma("unroll") for (int m = 0; m < 4; ++m) _Pragma("unroll") for (int k = 0; k < 2; ++k) dst[m][k] = *(const PG8_LAS bf16x8*)(lds + PG8_SA(b, h) + aoff + m * 2048 + k * 1024); } while (0)
; #define PG8_LDB(dst, b, h) do { _Pragma("unroll") for (int n = 0; n < 2; ++n) _Pragma("unroll") for (int k = 0; k < 2; ++k) dst[n][k] = *(const PG8_LAS bf16x8*)(lds + PG8_SB(b, h) + boff + n * 2048 + k * 1024); } while (0)
; #define PG8_MMA(ai, bj, At, Bt) do { __builtin_amdgcn_s_setprio(1); _Pragma("unroll") for (int m = 0; m < 4; ++m) _Pragma("unroll") for (int n = 0; n < 2; ++n) _Pragma("unroll") for (int k = 0; k < 2; ++k) \
;         acc[ai][bj][m][n] = __builtin_amdgcn_mfma_f32_16x16x32_bf16(Bt[n][k], At[m][k], acc[ai][bj][m][n], 0, 0, 0); __builtin_amdgcn_s_setprio(0); } while (0)
; #define PG8_WAIT_V(n) asm volatile("s_waitcnt vmcnt(" #n ")" ::: "memory")
; #define PG8_WAIT_L(n) asm volatile("s_waitcnt lgkmcnt(" #n ")" ::: "memory")
; #define PG8_BAR __builtin_amdgcn_s_barrier()
; #define PG8_SCHED __builtin_amdgcn_sched_barrier(0)
; template <class Epi, class Sched, bool ALIGN_EPI = false, bool SP2 = false>
; __device__ __forceinline__ void gemm_phase(PG8_LAS unsigned char* lds, const Gemm g, const Sched& S, const Epi& E, const int wave_in) {
;     ...
;             PG8_WAIT_V(8); PG8_WAIT_L(0); PG8_BAR; PG8_MMA(1, 0, At, B0); PG8_MMA(1, 1, At, B1); PG8_BAR; PG8_SCHED;
;             PG8_LDB(B0, 1, 0); PG8_LDB(B1, 1, 1); PG8_SCHED; PG8_LDA(At, 1, 0); PG8_STAGE(PG8_SA(0, 1), a2 + hstepA, voffA);
;             PG8_WAIT_V(8); PG8_WAIT_L(0); PG8_BAR; PG8_MMA(0, 0, At, B0); PG8_MMA(0, 1, At, B1); PG8_BAR; PG8_SCHED;
	v_mfma_f32_16x16x32_bf16 v[60:63], v[144:147], v[182:185], 0
	v_mfma_f32_16x16x32_bf16 v[56:59], v[158:161], v[182:185], 0
	v_mfma_f32_16x16x32_bf16 v[44:47], v[144:147], v[190:193], 0
	v_mfma_f32_16x16x32_bf16 v[40:43], v[158:161], v[190:193], 0
	v_mfma_f32_16x16x32_bf16 v[28:31], v[144:147], v[198:201], 0
	v_mfma_f32_16x16x32_bf16 v[24:27], v[158:161], v[198:201], 0
	v_mfma_f32_16x16x32_bf16 v[12:15], v[144:147], v[206:209], 0
	v_mfma_f32_16x16x32_bf16 v[8:11], v[158:161], v[206:209], 0
	v_mfma_f32_16x16x32_bf16 v[60:63], v[154:157], v[186:189], v[60:63]
	v_mfma_f32_16x16x32_bf16 v[56:59], v[162:165], v[186:189], v[56:59]
	v_mfma_f32_16x16x32_bf16 v[44:47], v[154:157], v[194:197], v[44:47]
	v_mfma_f32_16x16x32_bf16 v[40:43], v[162:165], v[194:197], v[40:43]
	v_mfma_f32_16x16x32_bf16 v[28:31], v[154:157], v[202:205], v[28:31]
	v_mfma_f32_16x16x32_bf16 v[24:27], v[162:165], v[202:205], v[24:27]
	v_mfma_f32_16x16x32_bf16 v[12:15], v[154:157], v[210:213], v[12:15]
	v_mfma_f32_16x16x32_bf16 v[8:11], v[162:165], v[210:213], v[8:11]
	v_mfma_f32_16x16x32_bf16 v[52:55], v[166:169], v[182:185], 0
	v_mfma_f32_16x16x32_bf16 v[48:51], v[174:177], v[182:185], 0
	v_mfma_f32_16x16x32_bf16 v[36:39], v[166:169], v[190:193], 0
	v_mfma_f32_16x16x32_bf16 v[32:35], v[174:177], v[190:193], 0
	v_mfma_f32_16x16x32_bf16 v[20:23], v[166:169], v[198:201], 0
	v_mfma_f32_16x16x32_bf16 v[16:19], v[174:177], v[198:201], 0
	v_mfma_f32_16x16x32_bf16 v[4:7], v[166:169], v[206:209], 0
	v_mfma_f32_16x16x32_bf16 v[0:3], v[174:177], v[206:209], 0
	v_mfma_f32_16x16x32_bf16 v[52:55], v[170:173], v[186:189], v[52:55]
	v_mfma_f32_16x16x32_bf16 v[48:51], v[178:181], v[186:189], v[48:51]
	v_mfma_f32_16x16x32_bf16 v[36:39], v[170:173], v[194:197], v[36:39]
	v_mfma_f32_16x16x32_bf16 v[32:35], v[178:181], v[194:197], v[32:35]
	v_mfma_f32_16x16x32_bf16 v[20:23], v[170:173], v[202:205], v[20:23]
	v_mfma_f32_16x16x32_bf16 v[16:19], v[178:181], v[202:205], v[16:19]
	v_mfma_f32_16x16x32_bf16 v[4:7], v[170:173], v[210:213], v[4:7]
	v_mfma_f32_16x16x32_bf16 v[0:3], v[178:181], v[210:213], v[0:3]
	s_setprio 0
	s_barrier
	s_add_i32 s51, 0, 0x18000
	s_add_i32 s52, 0, 0x1c000
	v_add_u32_e32 v162, s51, v149
	v_add_u32_e32 v178, s52, v149
	ds_read_b128 v[144:147], v162
	ds_read_b128 v[154:157], v162 offset:1024
	ds_read_b128 v[158:161], v162 offset:2048
	ds_read_b128 v[162:165], v162 offset:3072
	ds_read_b128 v[166:169], v178
	ds_read_b128 v[170:173], v178 offset:1024
	ds_read_b128 v[174:177], v178 offset:2048
	ds_read_b128 v[178:181], v178 offset:3072
	s_add_u32 s26, s26, 0x80000
	s_addc_u32 s27, s27, 0
	s_mov_b32 m0, s36
	v_lshl_add_u64 v[222:223], s[26:27], 0, v[128:129]
	ds_read_b128 v[182:185], v153 offset:32768
	ds_read_b128 v[186:189], v153 offset:33792
	ds_read_b128 v[190:193], v153 offset:34816
	ds_read_b128 v[194:197], v153 offset:35840
	ds_read_b128 v[198:201], v153 offset:36864
	ds_read_b128 v[202:205], v153 offset:37888
	ds_read_b128 v[206:209], v153 offset:38912
	ds_read_b128 v[210:213], v153 offset:39936
	global_load_lds_dwordx4 v[222:223], off
	v_lshl_add_u64 v[222:223], s[26:27], 0, v[132:133]
	s_mov_b32 m0, s37
	s_nop 0
	global_load_lds_dwordx4 v[222:223], off
	s_waitcnt vmcnt(8)
	s_waitcnt lgkmcnt(0)
	s_setprio 1
	s_barrier
	v_mfma_f32_16x16x32_bf16 v[124:127], v[144:147], v[182:185], v[124:127]
	v_mfma_f32_16x16x32_bf16 v[120:123], v[158:161], v[182:185], v[120:123]
	v_mfma_f32_16x16x32_bf16 v[108:111], v[144:147], v[190:193], v[108:111]
	v_mfma_f32_16x16x32_bf16 v[104:107], v[158:161], v[190:193], v[104:107]
	v_mfma_f32_16x16x32_bf16 v[92:95], v[144:147], v[198:201], v[92:95]
	v_mfma_f32_16x16x32_bf16 v[88:91], v[158:161], v[198:201], v[88:91]
	v_mfma_f32_16x16x32_bf16 v[76:79], v[144:147], v[206:209], v[76:79]
	v_mfma_f32_16x16x32_bf16 v[72:75], v[158:161], v[206:209], v[72:75]
	v_mfma_f32_16x16x32_bf16 v[124:127], v[154:157], v[186:189], v[124:127]
	v_mfma_f32_16x16x32_bf16 v[120:123], v[162:165], v[186:189], v[120:123]
	v_mfma_f32_16x16x32_bf16 v[108:111], v[154:157], v[194:197], v[108:111]
	v_mfma_f32_16x16x32_bf16 v[104:107], v[162:165], v[194:197], v[104:107]
	v_mfma_f32_16x16x32_bf16 v[92:95], v[154:157], v[202:205], v[92:95]
	v_mfma_f32_16x16x32_bf16 v[88:91], v[162:165], v[202:205], v[88:91]
	v_mfma_f32_16x16x32_bf16 v[76:79], v[154:157], v[210:213], v[76:79]
	v_mfma_f32_16x16x32_bf16 v[72:75], v[162:165], v[210:213], v[72:75]
	v_mfma_f32_16x16x32_bf16 v[116:119], v[166:169], v[182:185], v[116:119]
	v_mfma_f32_16x16x32_bf16 v[112:115], v[174:177], v[182:185], v[112:115]
	v_mfma_f32_16x16x32_bf16 v[100:103], v[166:169], v[190:193], v[100:103]
	v_mfma_f32_16x16x32_bf16 v[96:99], v[174:177], v[190:193], v[96:99]
	v_mfma_f32_16x16x32_bf16 v[84:87], v[166:169], v[198:201], v[84:87]
	v_mfma_f32_16x16x32_bf16 v[80:83], v[174:177], v[198:201], v[80:83]
	v_mfma_f32_16x16x32_bf16 v[68:71], v[166:169], v[206:209], v[68:71]
	v_mfma_f32_16x16x32_bf16 v[64:67], v[174:177], v[206:209], v[64:67]
	v_mfma_f32_16x16x32_bf16 v[116:119], v[170:173], v[186:189], v[116:119]
	v_mfma_f32_16x16x32_bf16 v[112:115], v[178:181], v[186:189], v[112:115]
	v_mfma_f32_16x16x32_bf16 v[100:103], v[170:173], v[194:197], v[100:103]
	v_mfma_f32_16x16x32_bf16 v[96:99], v[178:181], v[194:197], v[96:99]
	v_mfma_f32_16x16x32_bf16 v[84:87], v[170:173], v[202:205], v[84:87]
	v_mfma_f32_16x16x32_bf16 v[80:83], v[178:181], v[202:205], v[80:83]
	v_mfma_f32_16x16x32_bf16 v[68:71], v[170:173], v[210:213], v[68:71]
	v_mfma_f32_16x16x32_bf16 v[64:67], v[178:181], v[210:213], v[64:67]
	s_setprio 0
	s_barrier
; #define PG8_STAGE(bufoff, gbase, voff) do { _Pragma("unroll") for (int _i = 0; _i < 2; ++_i) \
;         __builtin_amdgcn_global_load_lds((const unsigned*)((const char*)(gbase) + (voff)[_i]), (PG8_LAS unsigned*)(lds + (bufoff) + ldsw + _i * 8192), 16, 0, 0); } while (0)
; #define PG8_LDA(dst, b, h) do { _Pragma("unroll") for (int m = 0; m < 4; ++m) _Pragma("unroll") for (int k = 0; k < 2; ++k) dst[m][k] = *(const PG8_LAS bf16x8*)(lds + PG8_SA(b, h) + aoff + m * 2048 + k * 1024); } while (0)
; #define PG8_LDB(dst, b, h) do { _Pragma("unroll") for (int n = 0; n < 2; ++n) _Pragma("unroll") for (int k = 0; k < 2; ++k) dst[n][k] = *(const PG8_LAS bf16x8*)(lds + PG8_SB(b, h) + boff + n * 2048 + k * 1024); } while (0)
; #define PG8_MMA(ai, bj, At, Bt) do { __builtin_amdgcn_s_setprio(1); _Pragma("unroll") for (int m = 0; m < 4; ++m) _Pragma("unroll") for (int n = 0; n < 2; ++n) _Pragma("unroll") for (int k = 0; k < 2; ++k) \
;         acc[ai][bj][m][n] = __builtin_amdgcn_mfma_f32_16x16x32_bf16(Bt[n][k], At[m][k], acc[ai][bj][m][n], 0, 0, 0); __builtin_amdgcn_s_setprio(0); } while (0)
; #define PG8_WAIT_V(n) asm volatile("s_waitcnt vmcnt(" #n ")" ::: "memory")
; #define PG8_WAIT_L(n) asm volatile("s_waitcnt lgkmcnt(" #n ")" ::: "memory")
; #define PG8_BAR __builtin_amdgcn_s_barrier()
; #define PG8_SCHED __builtin_amdgcn_sched_barrier(0)
; template <class Epi, class Sched, bool ALIGN_EPI = false, bool SP2 = false>
; __device__ __forceinline__ void gemm_phase(PG8_LAS unsigned char* lds, const Gemm g, const Sched& S, const Epi& E, const int wave_in) {
;     ...
;             PG8_LDB(B0, 0, 0); PG8_LDB(B1, 0, 1); PG8_SCHED; PG8_LDA(At, 0, 0); PG8_STAGE(PG8_SA(1, 1), a1 + hstepA, voffA);
;     ...
;             PG8_LDA(At, 1, 1); PG8_STAGE(PG8_SB(1, 0), b3, voffB); PG8_STAGE(PG8_SB(1, 1), b3 + hstepB, voffB); PG8_STAGE(PG8_SA(1, 0), a3, voffA);
;             PG8_WAIT_V(8); PG8_WAIT_L(0); PG8_BAR; PG8_MMA(1, 0, At, B0); PG8_MMA(1, 1, At, B1); PG8_BAR; PG8_SCHED;
	s_add_i32 s26, s51, s34
	v_lshl_add_u64 v[214:215], v[214:215], 0, s[8:9]
	s_mov_b32 m0, s26
	ds_read_b128 v[182:185], v153 offset:49152
	ds_read_b128 v[186:189], v153 offset:50176
	ds_read_b128 v[190:193], v153 offset:51200
	ds_read_b128 v[194:197], v153 offset:52224
	ds_read_b128 v[198:201], v153 offset:53248
	ds_read_b128 v[202:205], v153 offset:54272
	ds_read_b128 v[206:209], v153 offset:55296
	ds_read_b128 v[210:213], v153 offset:56320
	global_load_lds_dwordx4 v[214:215], off
	s_add_i32 m0, s26, 0x2000
	s_add_u32 s24, s24, 0x80080
	v_lshl_add_u64 v[214:215], v[216:217], 0, s[8:9]
	s_addc_u32 s25, s25, 0
	s_add_i32 s26, s52, s34
	global_load_lds_dwordx4 v[214:215], off
	v_lshl_add_u64 v[214:215], s[24:25], 0, v[130:131]
	s_mov_b32 m0, s26
	s_nop 0
	global_load_lds_dwordx4 v[214:215], off
	v_lshl_add_u64 v[214:215], s[24:25], 0, v[134:135]
	s_add_i32 m0, s26, 0x2000
	s_nop 0
	global_load_lds_dwordx4 v[214:215], off
	v_lshl_add_u64 v[214:215], v[218:219], 0, s[8:9]
	s_mov_b32 m0, s39
	s_nop 0
	global_load_lds_dwordx4 v[214:215], off
	v_lshl_add_u64 v[214:215], v[220:221], 0, s[8:9]
	s_mov_b32 m0, s40
	s_nop 0
	global_load_lds_dwordx4 v[214:215], off
	s_waitcnt vmcnt(8)
	s_waitcnt lgkmcnt(0)
	s_setprio 1
	s_barrier
	v_mfma_f32_16x16x32_bf16 v[60:63], v[144:147], v[182:185], v[60:63]
	v_mfma_f32_16x16x32_bf16 v[56:59], v[158:161], v[182:185], v[56:59]
	v_mfma_f32_16x16x32_bf16 v[44:47], v[144:147], v[190:193], v[44:47]
	v_mfma_f32_16x16x32_bf16 v[40:43], v[158:161], v[190:193], v[40:43]
	v_mfma_f32_16x16x32_bf16 v[28:31], v[144:147], v[198:201], v[28:31]
	v_mfma_f32_16x16x32_bf16 v[24:27], v[158:161], v[198:201], v[24:27]
	v_mfma_f32_16x16x32_bf16 v[12:15], v[144:147], v[206:209], v[12:15]
	v_mfma_f32_16x16x32_bf16 v[8:11], v[158:161], v[206:209], v[8:11]
	v_mfma_f32_16x16x32_bf16 v[60:63], v[154:157], v[186:189], v[60:63]
	v_mfma_f32_16x16x32_bf16 v[56:59], v[162:165], v[186:189], v[56:59]
	v_mfma_f32_16x16x32_bf16 v[44:47], v[154:157], v[194:197], v[44:47]
	v_mfma_f32_16x16x32_bf16 v[40:43], v[162:165], v[194:197], v[40:43]
	v_mfma_f32_16x16x32_bf16 v[28:31], v[154:157], v[202:205], v[28:31]
	v_mfma_f32_16x16x32_bf16 v[24:27], v[162:165], v[202:205], v[24:27]
	v_mfma_f32_16x16x32_bf16 v[12:15], v[154:157], v[210:213], v[12:15]
	v_mfma_f32_16x16x32_bf16 v[8:11], v[162:165], v[210:213], v[8:11]
	v_mfma_f32_16x16x32_bf16 v[52:55], v[166:169], v[182:185], v[52:55]
	v_mfma_f32_16x16x32_bf16 v[48:51], v[174:177], v[182:185], v[48:51]
	v_mfma_f32_16x16x32_bf16 v[36:39], v[166:169], v[190:193], v[36:39]
	v_mfma_f32_16x16x32_bf16 v[32:35], v[174:177], v[190:193], v[32:35]
	v_mfma_f32_16x16x32_bf16 v[20:23], v[166:169], v[198:201], v[20:23]
	v_mfma_f32_16x16x32_bf16 v[16:19], v[174:177], v[198:201], v[16:19]
	v_mfma_f32_16x16x32_bf16 v[4:7], v[166:169], v[206:209], v[4:7]
	v_mfma_f32_16x16x32_bf16 v[0:3], v[174:177], v[206:209], v[0:3]
	v_mfma_f32_16x16x32_bf16 v[52:55], v[170:173], v[186:189], v[52:55]
	v_mfma_f32_16x16x32_bf16 v[48:51], v[178:181], v[186:189], v[48:51]
	v_mfma_f32_16x16x32_bf16 v[36:39], v[170:173], v[194:197], v[36:39]
	v_mfma_f32_16x16x32_bf16 v[32:35], v[178:181], v[194:197], v[32:35]
	v_mfma_f32_16x16x32_bf16 v[20:23], v[170:173], v[202:205], v[20:23]
	v_mfma_f32_16x16x32_bf16 v[16:19], v[178:181], v[202:205], v[16:19]
	v_mfma_f32_16x16x32_bf16 v[4:7], v[170:173], v[210:213], v[4:7]
	v_mfma_f32_16x16x32_bf16 v[0:3], v[178:181], v[210:213], v[0:3]
	s_setprio 0
	s_barrier
	s_add_i32 s50, s50, 2
	s_add_u32 s22, s22, 0x100
	s_addc_u32 s23, s23, 0
	s_add_u32 s48, s48, 0x100
	s_addc_u32 s49, s49, 0
	s_cmp_gt_u32 s50, 29
	s_cbranch_scc0 .LBB0_2248
	s_branch .Lkx_26
.LBB0_2248:
	ds_read_b128 v[144:147], v151
	ds_read_b128 v[154:157], v151 offset:1024
	ds_read_b128 v[158:161], v151 offset:2048
	ds_read_b128 v[162:165], v151 offset:3072
	ds_read_b128 v[166:169], v152
	ds_read_b128 v[170:173], v152 offset:1024
	ds_read_b128 v[174:177], v152 offset:2048
	ds_read_b128 v[178:181], v152 offset:3072
	s_add_u32 s24, s22, 0xfff80080
	s_addc_u32 s25, s23, -1
	s_cmp_eq_u32 s50, 28
	s_cselect_b32 s27, s5, s25
	s_cselect_b32 s26, s15, s24
	s_cselect_b32 s25, s13, s49
	s_cselect_b32 s24, s47, s48
	v_lshl_add_u64 v[214:215], s[22:23], 0, v[136:137]
	s_add_i32 m0, s21, 0xc000
	ds_read_b128 v[182:185], v153
	ds_read_b128 v[186:189], v153 offset:1024
	ds_read_b128 v[190:193], v153 offset:2048
	ds_read_b128 v[194:197], v153 offset:3072
	ds_read_b128 v[198:201], v153 offset:4096
	ds_read_b128 v[202:205], v153 offset:5120
	ds_read_b128 v[206:209], v153 offset:6144
	ds_read_b128 v[210:213], v153 offset:7168
	global_load_lds_dwordx4 v[214:215], off
	v_lshl_add_u64 v[214:215], s[22:23], 0, v[138:139]
	s_add_i32 m0, s21, 0xe000
	s_nop 0
	global_load_lds_dwordx4 v[214:215], off
	s_waitcnt vmcnt(8)
	s_waitcnt lgkmcnt(0)
	s_setprio 1
	s_barrier
; #define PG8_STAGE(bufoff, gbase, voff) do { _Pragma("unroll") for (int _i = 0; _i < 2; ++_i) \
;         __builtin_amdgcn_global_load_lds((const unsigned*)((const char*)(gbase) + (voff)[_i]), (PG8_LAS unsigned*)(lds + (bufoff) + ldsw + _i * 8192), 16, 0, 0); } while (0)
; #define PG8_LDA(dst, b, h) do { _Pragma("unroll") for (int m = 0; m < 4; ++m) _Pragma("unroll") for (int k = 0; k < 2; ++k) dst[m][k] = *(const PG8_LAS bf16x8*)(lds + PG8_SA(b, h) + aoff + m * 2048 + k * 1024); } while (0)
; #define PG8_LDB(dst, b, h) do { _Pragma("unroll") for (int n = 0; n < 2; ++n) _Pragma("unroll") for (int k = 0; k < 2; ++k) dst[n][k] = *(const PG8_LAS bf16x8*)(lds + PG8_SB(b, h) + boff + n * 2048 + k * 1024); } while (0)
; #define PG8_MMA(ai, bj, At, Bt) do { __builtin_amdgcn_s_setprio(1); _Pragma("unroll") for (int m = 0; m < 4; ++m) _Pragma("unroll") for (int n = 0; n < 2; ++n) _Pragma("unroll") for (int k = 0; k < 2; ++k) \
;         acc[ai][bj][m][n] = __builtin_amdgcn_mfma_f32_16x16x32_bf16(Bt[n][k], At[m][k], acc[ai][bj][m][n], 0, 0, 0); __builtin_amdgcn_s_setprio(0); } while (0)
; #define PG8_WAIT_V(n) asm volatile("s_waitcnt vmcnt(" #n ")" ::: "memory")
; #define PG8_WAIT_L(n) asm volatile("s_waitcnt lgkmcnt(" #n ")" ::: "memory")
; #define PG8_BAR __builtin_amdgcn_s_barrier()
; #define PG8_SCHED __builtin_amdgcn_sched_barrier(0)
; template <class Epi, class Sched, bool ALIGN_EPI = false, bool SP2 = false>
; __device__ __forceinline__ void gemm_phase(PG8_LAS unsigned char* lds, const Gemm g, const Sched& S, const Epi& E, const int wave_in) {
;     ...
;             PG8_LDB(B0, 0, 0); PG8_LDB(B1, 0, 1); PG8_SCHED; PG8_LDA(At, 0, 0); PG8_STAGE(PG8_SA(1, 1), a1 + hstepA, voffA);
;             PG8_WAIT_V(8); PG8_WAIT_L(0); PG8_BAR; PG8_MMA(0, 0, At, B0); PG8_MMA(0, 1, At, B1); PG8_BAR; PG8_SCHED;
;             PG8_LDA(At, 0, 1); PG8_STAGE(PG8_SB(0, 0), b2, voffB); PG8_STAGE(PG8_SB(0, 1), b2 + hstepB, voffB); PG8_STAGE(PG8_SA(0, 0), a2, voffA);
;             PG8_WAIT_V(8); PG8_WAIT_L(0); PG8_BAR; PG8_MMA(1, 0, At, B0); PG8_MMA(1, 1, At, B1); PG8_BAR; PG8_SCHED;
	v_mfma_f32_16x16x32_bf16 v[124:127], v[144:147], v[182:185], v[124:127]
	v_mfma_f32_16x16x32_bf16 v[120:123], v[158:161], v[182:185], v[120:123]
	v_mfma_f32_16x16x32_bf16 v[108:111], v[144:147], v[190:193], v[108:111]
	v_mfma_f32_16x16x32_bf16 v[104:107], v[158:161], v[190:193], v[104:107]
	v_mfma_f32_16x16x32_bf16 v[92:95], v[144:147], v[198:201], v[92:95]
	v_mfma_f32_16x16x32_bf16 v[88:91], v[158:161], v[198:201], v[88:91]
	v_mfma_f32_16x16x32_bf16 v[76:79], v[144:147], v[206:209], v[76:79]
	v_mfma_f32_16x16x32_bf16 v[72:75], v[158:161], v[206:209], v[72:75]
	v_mfma_f32_16x16x32_bf16 v[124:127], v[154:157], v[186:189], v[124:127]
	v_mfma_f32_16x16x32_bf16 v[120:123], v[162:165], v[186:189], v[120:123]
	v_mfma_f32_16x16x32_bf16 v[108:111], v[154:157], v[194:197], v[108:111]
	v_mfma_f32_16x16x32_bf16 v[104:107], v[162:165], v[194:197], v[104:107]
	v_mfma_f32_16x16x32_bf16 v[92:95], v[154:157], v[202:205], v[92:95]
	v_mfma_f32_16x16x32_bf16 v[88:91], v[162:165], v[202:205], v[88:91]
	v_mfma_f32_16x16x32_bf16 v[76:79], v[154:157], v[210:213], v[76:79]
	v_mfma_f32_16x16x32_bf16 v[72:75], v[162:165], v[210:213], v[72:75]
	v_mfma_f32_16x16x32_bf16 v[116:119], v[166:169], v[182:185], v[116:119]
	v_mfma_f32_16x16x32_bf16 v[112:115], v[174:177], v[182:185], v[112:115]
	v_mfma_f32_16x16x32_bf16 v[100:103], v[166:169], v[190:193], v[100:103]
	v_mfma_f32_16x16x32_bf16 v[96:99], v[174:177], v[190:193], v[96:99]
	v_mfma_f32_16x16x32_bf16 v[84:87], v[166:169], v[198:201], v[84:87]
	v_mfma_f32_16x16x32_bf16 v[80:83], v[174:177], v[198:201], v[80:83]
	v_mfma_f32_16x16x32_bf16 v[68:71], v[166:169], v[206:209], v[68:71]
	v_mfma_f32_16x16x32_bf16 v[64:67], v[174:177], v[206:209], v[64:67]
	v_mfma_f32_16x16x32_bf16 v[116:119], v[170:173], v[186:189], v[116:119]
	v_mfma_f32_16x16x32_bf16 v[112:115], v[178:181], v[186:189], v[112:115]
	v_mfma_f32_16x16x32_bf16 v[100:103], v[170:173], v[194:197], v[100:103]
	v_mfma_f32_16x16x32_bf16 v[96:99], v[178:181], v[194:197], v[96:99]
	v_mfma_f32_16x16x32_bf16 v[84:87], v[170:173], v[202:205], v[84:87]
	v_mfma_f32_16x16x32_bf16 v[80:83], v[178:181], v[202:205], v[80:83]
	v_mfma_f32_16x16x32_bf16 v[68:71], v[170:173], v[210:213], v[68:71]
	v_mfma_f32_16x16x32_bf16 v[64:67], v[178:181], v[210:213], v[64:67]
	s_setprio 0
	s_barrier
	s_add_i32 s51, s44, s34
	v_lshl_add_u64 v[214:215], s[24:25], 0, v[130:131]
	s_mov_b32 m0, s51
	ds_read_b128 v[182:185], v153 offset:16384
	ds_read_b128 v[186:189], v153 offset:17408
	ds_read_b128 v[190:193], v153 offset:18432
	ds_read_b128 v[194:197], v153 offset:19456
	ds_read_b128 v[198:201], v153 offset:20480
	ds_read_b128 v[202:205], v153 offset:21504
	ds_read_b128 v[206:209], v153 offset:22528
	ds_read_b128 v[210:213], v153 offset:23552
	global_load_lds_dwordx4 v[214:215], off
	s_add_i32 m0, s51, 0x2000
	s_add_u32 s52, s24, 0x80000
	v_lshl_add_u64 v[216:217], s[24:25], 0, v[134:135]
	s_addc_u32 s53, s25, 0
	s_add_i32 s51, s45, s34
	global_load_lds_dwordx4 v[216:217], off
	v_lshl_add_u64 v[218:219], s[52:53], 0, v[130:131]
	s_mov_b32 m0, s51
	v_lshl_add_u64 v[220:221], s[26:27], 0, v[132:133]
	global_load_lds_dwordx4 v[218:219], off
	v_lshl_add_u64 v[218:219], s[52:53], 0, v[134:135]
	s_add_i32 m0, s51, 0x2000
	s_nop 0
	global_load_lds_dwordx4 v[218:219], off
	v_lshl_add_u64 v[218:219], s[26:27], 0, v[128:129]
	s_mov_b32 m0, s21
	s_nop 0
	global_load_lds_dwordx4 v[218:219], off
	s_mov_b32 m0, s35
	s_nop 0
	global_load_lds_dwordx4 v[220:221], off
	s_waitcnt vmcnt(8)
	s_waitcnt lgkmcnt(0)
	s_setprio 1
	s_barrier
	v_mfma_f32_16x16x32_bf16 v[60:63], v[144:147], v[182:185], v[60:63]
	v_mfma_f32_16x16x32_bf16 v[56:59], v[158:161], v[182:185], v[56:59]
	v_mfma_f32_16x16x32_bf16 v[44:47], v[144:147], v[190:193], v[44:47]
	v_mfma_f32_16x16x32_bf16 v[40:43], v[158:161], v[190:193], v[40:43]
	v_mfma_f32_16x16x32_bf16 v[28:31], v[144:147], v[198:201], v[28:31]
	v_mfma_f32_16x16x32_bf16 v[24:27], v[158:161], v[198:201], v[24:27]
	v_mfma_f32_16x16x32_bf16 v[12:15], v[144:147], v[206:209], v[12:15]
	v_mfma_f32_16x16x32_bf16 v[8:11], v[158:161], v[206:209], v[8:11]
	v_mfma_f32_16x16x32_bf16 v[60:63], v[154:157], v[186:189], v[60:63]
	v_mfma_f32_16x16x32_bf16 v[56:59], v[162:165], v[186:189], v[56:59]
	v_mfma_f32_16x16x32_bf16 v[44:47], v[154:157], v[194:197], v[44:47]
	v_mfma_f32_16x16x32_bf16 v[40:43], v[162:165], v[194:197], v[40:43]
	v_mfma_f32_16x16x32_bf16 v[28:31], v[154:157], v[202:205], v[28:31]
	v_mfma_f32_16x16x32_bf16 v[24:27], v[162:165], v[202:205], v[24:27]
	v_mfma_f32_16x16x32_bf16 v[12:15], v[154:157], v[210:213], v[12:15]
	v_mfma_f32_16x16x32_bf16 v[8:11], v[162:165], v[210:213], v[8:11]
	v_mfma_f32_16x16x32_bf16 v[52:55], v[166:169], v[182:185], v[52:55]
	v_mfma_f32_16x16x32_bf16 v[48:51], v[174:177], v[182:185], v[48:51]
	v_mfma_f32_16x16x32_bf16 v[36:39], v[166:169], v[190:193], v[36:39]
	v_mfma_f32_16x16x32_bf16 v[32:35], v[174:177], v[190:193], v[32:35]
	v_mfma_f32_16x16x32_bf16 v[20:23], v[166:169], v[198:201], v[20:23]
	v_mfma_f32_16x16x32_bf16 v[16:19], v[174:177], v[198:201], v[16:19]
	v_mfma_f32_16x16x32_bf16 v[4:7], v[166:169], v[206:209], v[4:7]
	v_mfma_f32_16x16x32_bf16 v[0:3], v[174:177], v[206:209], v[0:3]
	v_mfma_f32_16x16x32_bf16 v[52:55], v[170:173], v[186:189], v[52:55]
	v_mfma_f32_16x16x32_bf16 v[48:51], v[178:181], v[186:189], v[48:51]
	v_mfma_f32_16x16x32_bf16 v[36:39], v[170:173], v[194:197], v[36:39]
	v_mfma_f32_16x16x32_bf16 v[32:35], v[178:181], v[194:197], v[32:35]
	v_mfma_f32_16x16x32_bf16 v[20:23], v[170:173], v[202:205], v[20:23]
	v_mfma_f32_16x16x32_bf16 v[16:19], v[178:181], v[202:205], v[16:19]
	v_mfma_f32_16x16x32_bf16 v[4:7], v[170:173], v[210:213], v[4:7]
	v_mfma_f32_16x16x32_bf16 v[0:3], v[178:181], v[210:213], v[0:3]
	s_setprio 0
	s_barrier
; #define PG8_STAGE(bufoff, gbase, voff) do { _Pragma("unroll") for (int _i = 0; _i < 2; ++_i) \
;         __builtin_amdgcn_global_load_lds((const unsigned*)((const char*)(gbase) + (voff)[_i]), (PG8_LAS unsigned*)(lds + (bufoff) + ldsw + _i * 8192), 16, 0, 0); } while (0)
; #define PG8_LDA(dst, b, h) do { _Pragma("unroll") for (int m = 0; m < 4; ++m) _Pragma("unroll") for (int k = 0; k < 2; ++k) dst[m][k] = *(const PG8_LAS bf16x8*)(lds + PG8_SA(b, h) + aoff + m * 2048 + k * 1024); } while (0)
; #define PG8_LDB(dst, b, h) do { _Pragma("unroll") for (int n = 0; n < 2; ++n) _Pragma("unroll") for (int k = 0; k < 2; ++k) dst[n][k] = *(const PG8_LAS bf16x8*)(lds + PG8_SB(b, h) + boff + n * 2048 + k * 1024); } while (0)
; #define PG8_MMA(ai, bj, At, Bt) do { __builtin_amdgcn_s_setprio(1); _Pragma("unroll") for (int m = 0; m < 4; ++m) _Pragma("unroll") for (int n = 0; n < 2; ++n) _Pragma("unroll") for (int k = 0; k < 2; ++k) \
;         acc[ai][bj][m][n] = __builtin_amdgcn_mfma_f32_16x16x32_bf16(Bt[n][k], At[m][k], acc[ai][bj][m][n], 0, 0, 0); __builtin_amdgcn_s_setprio(0); } while (0)
; #define PG8_WAIT_V(n) asm volatile("s_waitcnt vmcnt(" #n ")" ::: "memory")
; #define PG8_WAIT_L(n) asm volatile("s_waitcnt lgkmcnt(" #n ")" ::: "memory")
; #define PG8_BAR __builtin_amdgcn_s_barrier()
; #define PG8_SCHED __builtin_amdgcn_sched_barrier(0)
; template <class Epi, class Sched, bool ALIGN_EPI = false, bool SP2 = false>
; __device__ __forceinline__ void gemm_phase(PG8_LAS unsigned char* lds, const Gemm g, const Sched& S, const Epi& E, const int wave_in) {
;     ...
;             PG8_LDB(B0, 1, 0); PG8_LDB(B1, 1, 1); PG8_SCHED; PG8_LDA(At, 1, 0); PG8_STAGE(PG8_SA(0, 1), a2 + hstepA, voffA);
;             PG8_WAIT_V(8); PG8_WAIT_L(0); PG8_BAR; PG8_MMA(0, 0, At, B0); PG8_MMA(0, 1, At, B1); PG8_BAR; PG8_SCHED;
	s_add_i32 s51, 0, 0x18000
	s_add_i32 s52, 0, 0x1c000
	v_add_u32_e32 v162, s51, v149
	v_add_u32_e32 v178, s52, v149
	ds_read_b128 v[144:147], v162
	ds_read_b128 v[154:157], v162 offset:1024
	ds_read_b128 v[158:161], v162 offset:2048
	ds_read_b128 v[162:165], v162 offset:3072
	ds_read_b128 v[166:169], v178
	ds_read_b128 v[170:173], v178 offset:1024
	ds_read_b128 v[174:177], v178 offset:2048
	ds_read_b128 v[178:181], v178 offset:3072
	s_add_u32 s26, s26, 0x80000
	s_addc_u32 s27, s27, 0
	s_mov_b32 m0, s36
	v_lshl_add_u64 v[222:223], s[26:27], 0, v[128:129]
	ds_read_b128 v[182:185], v153 offset:32768
	ds_read_b128 v[186:189], v153 offset:33792
	ds_read_b128 v[190:193], v153 offset:34816
	ds_read_b128 v[194:197], v153 offset:35840
	ds_read_b128 v[198:201], v153 offset:36864
	ds_read_b128 v[202:205], v153 offset:37888
	ds_read_b128 v[206:209], v153 offset:38912
	ds_read_b128 v[210:213], v153 offset:39936
	global_load_lds_dwordx4 v[222:223], off
	v_lshl_add_u64 v[222:223], s[26:27], 0, v[132:133]
	s_mov_b32 m0, s37
	s_nop 0
	global_load_lds_dwordx4 v[222:223], off
	s_waitcnt vmcnt(8)
	s_waitcnt lgkmcnt(0)
	s_setprio 1
	s_barrier
	v_mfma_f32_16x16x32_bf16 v[124:127], v[144:147], v[182:185], v[124:127]
	v_mfma_f32_16x16x32_bf16 v[120:123], v[158:161], v[182:185], v[120:123]
	v_mfma_f32_16x16x32_bf16 v[108:111], v[144:147], v[190:193], v[108:111]
	v_mfma_f32_16x16x32_bf16 v[104:107], v[158:161], v[190:193], v[104:107]
	v_mfma_f32_16x16x32_bf16 v[92:95], v[144:147], v[198:201], v[92:95]
	v_mfma_f32_16x16x32_bf16 v[88:91], v[158:161], v[198:201], v[88:91]
	v_mfma_f32_16x16x32_bf16 v[76:79], v[144:147], v[206:209], v[76:79]
	v_mfma_f32_16x16x32_bf16 v[72:75], v[158:161], v[206:209], v[72:75]
	v_mfma_f32_16x16x32_bf16 v[124:127], v[154:157], v[186:189], v[124:127]
	v_mfma_f32_16x16x32_bf16 v[120:123], v[162:165], v[186:189], v[120:123]
	v_mfma_f32_16x16x32_bf16 v[108:111], v[154:157], v[194:197], v[108:111]
	v_mfma_f32_16x16x32_bf16 v[104:107], v[162:165], v[194:197], v[104:107]
	v_mfma_f32_16x16x32_bf16 v[92:95], v[154:157], v[202:205], v[92:95]
	v_mfma_f32_16x16x32_bf16 v[88:91], v[162:165], v[202:205], v[88:91]
	v_mfma_f32_16x16x32_bf16 v[76:79], v[154:157], v[210:213], v[76:79]
	v_mfma_f32_16x16x32_bf16 v[72:75], v[162:165], v[210:213], v[72:75]
	v_mfma_f32_16x16x32_bf16 v[116:119], v[166:169], v[182:185], v[116:119]
	v_mfma_f32_16x16x32_bf16 v[112:115], v[174:177], v[182:185], v[112:115]
	v_mfma_f32_16x16x32_bf16 v[100:103], v[166:169], v[190:193], v[100:103]
	v_mfma_f32_16x16x32_bf16 v[96:99], v[174:177], v[190:193], v[96:99]
	v_mfma_f32_16x16x32_bf16 v[84:87], v[166:169], v[198:201], v[84:87]
	v_mfma_f32_16x16x32_bf16 v[80:83], v[174:177], v[198:201], v[80:83]
	v_mfma_f32_16x16x32_bf16 v[68:71], v[166:169], v[206:209], v[68:71]
	v_mfma_f32_16x16x32_bf16 v[64:67], v[174:177], v[206:209], v[64:67]
	v_mfma_f32_16x16x32_bf16 v[116:119], v[170:173], v[186:189], v[116:119]
	v_mfma_f32_16x16x32_bf16 v[112:115], v[178:181], v[186:189], v[112:115]
	v_mfma_f32_16x16x32_bf16 v[100:103], v[170:173], v[194:197], v[100:103]
	v_mfma_f32_16x16x32_bf16 v[96:99], v[178:181], v[194:197], v[96:99]
	v_mfma_f32_16x16x32_bf16 v[84:87], v[170:173], v[202:205], v[84:87]
	v_mfma_f32_16x16x32_bf16 v[80:83], v[178:181], v[202:205], v[80:83]
	v_mfma_f32_16x16x32_bf16 v[68:71], v[170:173], v[210:213], v[68:71]
	v_mfma_f32_16x16x32_bf16 v[64:67], v[178:181], v[210:213], v[64:67]
	s_setprio 0
	s_barrier
; #define PG8_STAGE(bufoff, gbase, voff) do { _Pragma("unroll") for (int _i = 0; _i < 2; ++_i) \
;         __builtin_amdgcn_global_load_lds((const unsigned*)((const char*)(gbase) + (voff)[_i]), (PG8_LAS unsigned*)(lds + (bufoff) + ldsw + _i * 8192), 16, 0, 0); } while (0)
; #define PG8_LDA(dst, b, h) do { _Pragma("unroll") for (int m = 0; m < 4; ++m) _Pragma("unroll") for (int k = 0; k < 2; ++k) dst[m][k] = *(const PG8_LAS bf16x8*)(lds + PG8_SA(b, h) + aoff + m * 2048 + k * 1024); } while (0)
; #define PG8_MMA(ai, bj, At, Bt) do { __builtin_amdgcn_s_setprio(1); _Pragma("unroll") for (int m = 0; m < 4; ++m) _Pragma("unroll") for (int n = 0; n < 2; ++n) _Pragma("unroll") for (int k = 0; k < 2; ++k) \
;         acc[ai][bj][m][n] = __builtin_amdgcn_mfma_f32_16x16x32_bf16(Bt[n][k], At[m][k], acc[ai][bj][m][n], 0, 0, 0); __builtin_amdgcn_s_setprio(0); } while (0)
; #define PG8_WAIT_V(n) asm volatile("s_waitcnt vmcnt(" #n ")" ::: "memory")
; #define PG8_WAIT_L(n) asm volatile("s_waitcnt lgkmcnt(" #n ")" ::: "memory")
; #define PG8_BAR __builtin_amdgcn_s_barrier()
; #define PG8_SCHED __builtin_amdgcn_sched_barrier(0)
; template <class Epi, class Sched, bool ALIGN_EPI = false, bool SP2 = false>
; __device__ __forceinline__ void gemm_phase(PG8_LAS unsigned char* lds, const Gemm g, const Sched& S, const Epi& E, const int wave_in) {
;     ...
;         for (int t = 0; t < nt; t += 2) {
;     ...
;             PG8_LDA(At, 1, 1); PG8_STAGE(PG8_SB(1, 0), b3, voffB); PG8_STAGE(PG8_SB(1, 1), b3 + hstepB, voffB); PG8_STAGE(PG8_SA(1, 0), a3, voffA);
;             PG8_WAIT_V(8); PG8_WAIT_L(0); PG8_BAR; PG8_MMA(1, 0, At, B0); PG8_MMA(1, 1, At, B1); PG8_BAR; PG8_SCHED;
	s_add_i32 s26, s51, s34
	v_lshl_add_u64 v[214:215], v[214:215], 0, s[8:9]
	s_mov_b32 m0, s26
	ds_read_b128 v[182:185], v153 offset:49152
	ds_read_b128 v[186:189], v153 offset:50176
	ds_read_b128 v[190:193], v153 offset:51200
	ds_read_b128 v[194:197], v153 offset:52224
	ds_read_b128 v[198:201], v153 offset:53248
	ds_read_b128 v[202:205], v153 offset:54272
	ds_read_b128 v[206:209], v153 offset:55296
	ds_read_b128 v[210:213], v153 offset:56320
	global_load_lds_dwordx4 v[214:215], off
	s_add_i32 m0, s26, 0x2000
	s_add_u32 s24, s24, 0x80080
	v_lshl_add_u64 v[214:215], v[216:217], 0, s[8:9]
	s_addc_u32 s25, s25, 0
	s_add_i32 s26, s52, s34
	global_load_lds_dwordx4 v[214:215], off
	v_lshl_add_u64 v[214:215], s[24:25], 0, v[130:131]
	s_mov_b32 m0, s26
	s_nop 0
	global_load_lds_dwordx4 v[214:215], off
	v_lshl_add_u64 v[214:215], s[24:25], 0, v[134:135]
	s_add_i32 m0, s26, 0x2000
	s_nop 0
	global_load_lds_dwordx4 v[214:215], off
	v_lshl_add_u64 v[214:215], v[218:219], 0, s[8:9]
	s_mov_b32 m0, s39
	s_nop 0
	global_load_lds_dwordx4 v[214:215], off
	v_lshl_add_u64 v[214:215], v[220:221], 0, s[8:9]
	s_mov_b32 m0, s40
	s_nop 0
	global_load_lds_dwordx4 v[214:215], off
	s_waitcnt vmcnt(8)
	s_waitcnt lgkmcnt(0)
	s_setprio 1
	s_barrier
	v_mfma_f32_16x16x32_bf16 v[60:63], v[144:147], v[182:185], v[60:63]
	v_mfma_f32_16x16x32_bf16 v[56:59], v[158:161], v[182:185], v[56:59]
	v_mfma_f32_16x16x32_bf16 v[44:47], v[144:147], v[190:193], v[44:47]
	v_mfma_f32_16x16x32_bf16 v[40:43], v[158:161], v[190:193], v[40:43]
	v_mfma_f32_16x16x32_bf16 v[28:31], v[144:147], v[198:201], v[28:31]
	v_mfma_f32_16x16x32_bf16 v[24:27], v[158:161], v[198:201], v[24:27]
	v_mfma_f32_16x16x32_bf16 v[12:15], v[144:147], v[206:209], v[12:15]
	v_mfma_f32_16x16x32_bf16 v[8:11], v[158:161], v[206:209], v[8:11]
	v_mfma_f32_16x16x32_bf16 v[60:63], v[154:157], v[186:189], v[60:63]
	v_mfma_f32_16x16x32_bf16 v[56:59], v[162:165], v[186:189], v[56:59]
	v_mfma_f32_16x16x32_bf16 v[44:47], v[154:157], v[194:197], v[44:47]
	v_mfma_f32_16x16x32_bf16 v[40:43], v[162:165], v[194:197], v[40:43]
	v_mfma_f32_16x16x32_bf16 v[28:31], v[154:157], v[202:205], v[28:31]
	v_mfma_f32_16x16x32_bf16 v[24:27], v[162:165], v[202:205], v[24:27]
	v_mfma_f32_16x16x32_bf16 v[12:15], v[154:157], v[210:213], v[12:15]
	v_mfma_f32_16x16x32_bf16 v[8:11], v[162:165], v[210:213], v[8:11]
	v_mfma_f32_16x16x32_bf16 v[52:55], v[166:169], v[182:185], v[52:55]
	v_mfma_f32_16x16x32_bf16 v[48:51], v[174:177], v[182:185], v[48:51]
	v_mfma_f32_16x16x32_bf16 v[36:39], v[166:169], v[190:193], v[36:39]
	v_mfma_f32_16x16x32_bf16 v[32:35], v[174:177], v[190:193], v[32:35]
	v_mfma_f32_16x16x32_bf16 v[20:23], v[166:169], v[198:201], v[20:23]
	v_mfma_f32_16x16x32_bf16 v[16:19], v[174:177], v[198:201], v[16:19]
	v_mfma_f32_16x16x32_bf16 v[4:7], v[166:169], v[206:209], v[4:7]
	v_mfma_f32_16x16x32_bf16 v[0:3], v[174:177], v[206:209], v[0:3]
	v_mfma_f32_16x16x32_bf16 v[52:55], v[170:173], v[186:189], v[52:55]
	v_mfma_f32_16x16x32_bf16 v[48:51], v[178:181], v[186:189], v[48:51]
	v_mfma_f32_16x16x32_bf16 v[36:39], v[170:173], v[194:197], v[36:39]
	v_mfma_f32_16x16x32_bf16 v[32:35], v[178:181], v[194:197], v[32:35]
	v_mfma_f32_16x16x32_bf16 v[20:23], v[170:173], v[202:205], v[20:23]
	v_mfma_f32_16x16x32_bf16 v[16:19], v[178:181], v[202:205], v[16:19]
	v_mfma_f32_16x16x32_bf16 v[4:7], v[170:173], v[210:213], v[4:7]
	v_mfma_f32_16x16x32_bf16 v[0:3], v[178:181], v[210:213], v[0:3]
	s_setprio 0
	s_barrier
	s_add_i32 s50, s50, 2
	s_add_u32 s22, s22, 0x100
	s_addc_u32 s23, s23, 0
	s_add_u32 s48, s48, 0x100
	s_addc_u32 s49, s49, 0
	s_cmp_gt_u32 s50, 29
	s_cbranch_scc0 .LBB0_2248

;     __host__ __device__ bool next(int i, Unit& u) const { const bool ok = StaticOrder::next(i, u); u.pm = 0; u.pn = 0; return ok; }
; #define PG8_STAGE(bufoff, gbase, voff) do { _Pragma("unroll") for (int _i = 0; _i < 2; ++_i) \
;         __builtin_amdgcn_global_load_lds((const unsigned*)((const char*)(gbase) + (voff)[_i]), (PG8_LAS unsigned*)(lds + (bufoff) + ldsw + _i * 8192), 16, 0, 0); } while (0)
; #define PG8_LDA(dst, b, h) do { _Pragma("unroll") for (int m = 0; m < 4; ++m) _Pragma("unroll") for (int k = 0; k < 2; ++k) dst[m][k] = *(const PG8_LAS bf16x8*)(lds + PG8_SA(b, h) + aoff + m * 2048 + k * 1024); } while (0)
; #define PG8_LDB(dst, b, h) do { _Pragma("unroll") for (int n = 0; n < 2; ++n) _Pragma("unroll") for (int k = 0; k < 2; ++k) dst[n][k] = *(const PG8_LAS bf16x8*)(lds + PG8_SB(b, h) + boff + n * 2048 + k * 1024); } while (0)
; #define PG8_WAIT_V(n) asm volatile("s_waitcnt vmcnt(" #n ")" ::: "memory")
; #define PG8_WAIT_L(n) asm volatile("s_waitcnt lgkmcnt(" #n ")" ::: "memory")
; #define PG8_BAR __builtin_amdgcn_s_barrier()
; #define PG8_SCHED __builtin_amdgcn_sched_barrier(0)
; template <class Epi, class Sched, bool ALIGN_EPI = false, bool SP2 = false>
; __device__ __forceinline__ void gemm_phase(PG8_LAS unsigned char* lds, const Gemm g, const Sched& S, const Epi& E, const int wave_in) {
;     ...
;         const bool has_next = S.next(ui + 1, nxt);
;         const char* nA = has_next ? (const char*)g.A + (size_t)nxt.pm * tstepA : cA; const char* nB = has_next ? (const char*)g.Bt + (size_t)nxt.pn * tstepB : cB;
;         for (int t = 0; t < nt; t += 2) {
;             const bool last = (t == nt - 2);
;             const char* a1 = cA + (size_t)(t + 1) * kstep;
;             const char* a2 = last ? nA : cA + (size_t)(t + 2) * kstep; const char* b2 = last ? nB : cB + (size_t)(t + 2) * kstep;
;             const char* a3 = a2 + kstep; const char* b3 = b2 + kstep;
;             if (last && has_next) S.a_ready(nxt);
;             if constexpr (SP2) {
;             PG8_LDB(B0, 0, 0); PG8_LDB(B1, 0, 1); PG8_SCHED; PG8_LDA(At, 0, 0); PG8_STAGE(PG8_SA(1, 1), a1 + hstepA, voffA);
;             PG8_WAIT_V(8); PG8_WAIT_L(0); PG8_BAR; PG8_MMA(0, 0, At, B0); PG8_MMA(0, 1, At, B1); PG8_BAR; PG8_SCHED;
;             PG8_LDA(At, 0, 1); PG8_STAGE(PG8_SB(0, 0), b2, voffB); PG8_STAGE(PG8_SB(0, 1), b2 + hstepB, voffB); PG8_STAGE(PG8_SA(0, 0), a2, voffA);
.LBB0_2450:
	s_ashr_i32 s19, s18, 31
	s_lshl_b64 s[22:23], s[18:19], 20
	s_add_u32 s22, s37, s22
	s_addc_u32 s23, s38, s23
	s_and_b64 s[4:5], s[4:5], exec
	s_cselect_b32 s19, s23, s29
	s_cselect_b32 s25, s22, s28
	s_add_u32 s58, s28, 0x100
	v_mov_b32_e32 v0, 0
	s_addc_u32 s59, s29, 0
	s_mov_b32 s60, -2
	s_waitcnt vmcnt(0)
	ds_read_b128 v[128:131], v170
	ds_read_b128 v[132:135], v170 offset:1024
	ds_read_b128 v[136:139], v170 offset:2048
	ds_read_b128 v[140:143], v170 offset:3072
	ds_read_b128 v[162:165], v171
	ds_read_b128 v[174:177], v171 offset:1024
	ds_read_b128 v[178:181], v171 offset:2048
	ds_read_b128 v[182:185], v171 offset:3072
	s_add_u32 s4, s26, 0x100
	s_addc_u32 s5, s27, 0
	s_cmp_eq_u32 s60, 28
	s_cselect_b32 s31, s21, s5
	s_cselect_b32 s30, s20, s4
	s_cselect_b32 s29, s19, s59
	s_cselect_b32 s28, s25, s58
	v_lshl_add_u64 v[166:167], s[26:27], 0, v[154:155]
	s_add_i32 m0, s40, 0xc000
	ds_read_b128 v[186:189], v172
	ds_read_b128 v[190:193], v172 offset:1024
	ds_read_b128 v[194:197], v172 offset:2048
	ds_read_b128 v[198:201], v172 offset:3072
	ds_read_b128 v[202:205], v172 offset:4096
	ds_read_b128 v[206:209], v172 offset:5120
	ds_read_b128 v[210:213], v172 offset:6144
	ds_read_b128 v[214:217], v172 offset:7168
	global_load_lds_dwordx4 v[166:167], off
	v_lshl_add_u64 v[166:167], s[26:27], 0, v[156:157]
	s_add_i32 m0, s40, 0xe000
	s_nop 0
	global_load_lds_dwordx4 v[166:167], off
	s_waitcnt vmcnt(8)
	s_waitcnt lgkmcnt(0)
	s_setprio 1
	s_barrier
	v_mfma_f32_16x16x32_bf16 v[124:127], v[128:131], v[186:189], 0
	v_mfma_f32_16x16x32_bf16 v[120:123], v[136:139], v[186:189], 0
	v_mfma_f32_16x16x32_bf16 v[112:115], v[128:131], v[194:197], 0
	v_mfma_f32_16x16x32_bf16 v[104:107], v[136:139], v[194:197], 0
	v_mfma_f32_16x16x32_bf16 v[96:99], v[128:131], v[202:205], 0
	v_mfma_f32_16x16x32_bf16 v[88:91], v[136:139], v[202:205], 0
	v_mfma_f32_16x16x32_bf16 v[80:83], v[128:131], v[210:213], 0
	v_mfma_f32_16x16x32_bf16 v[72:75], v[136:139], v[210:213], 0
	v_mfma_f32_16x16x32_bf16 v[124:127], v[132:135], v[190:193], v[124:127]
	v_mfma_f32_16x16x32_bf16 v[120:123], v[140:143], v[190:193], v[120:123]
	v_mfma_f32_16x16x32_bf16 v[112:115], v[132:135], v[198:201], v[112:115]
	v_mfma_f32_16x16x32_bf16 v[104:107], v[140:143], v[198:201], v[104:107]
	v_mfma_f32_16x16x32_bf16 v[96:99], v[132:135], v[206:209], v[96:99]
	v_mfma_f32_16x16x32_bf16 v[88:91], v[140:143], v[206:209], v[88:91]
	v_mfma_f32_16x16x32_bf16 v[80:83], v[132:135], v[214:217], v[80:83]
	v_mfma_f32_16x16x32_bf16 v[72:75], v[140:143], v[214:217], v[72:75]
	v_mfma_f32_16x16x32_bf16 v[116:119], v[162:165], v[186:189], 0
	v_mfma_f32_16x16x32_bf16 v[108:111], v[178:181], v[186:189], 0
	v_mfma_f32_16x16x32_bf16 v[100:103], v[162:165], v[194:197], 0
	v_mfma_f32_16x16x32_bf16 v[92:95], v[178:181], v[194:197], 0
	v_mfma_f32_16x16x32_bf16 v[84:87], v[162:165], v[202:205], 0
	v_mfma_f32_16x16x32_bf16 v[76:79], v[178:181], v[202:205], 0
	v_mfma_f32_16x16x32_bf16 v[68:71], v[162:165], v[210:213], 0
	v_mfma_f32_16x16x32_bf16 v[64:67], v[178:181], v[210:213], 0
	v_mfma_f32_16x16x32_bf16 v[116:119], v[174:177], v[190:193], v[116:119]
	v_mfma_f32_16x16x32_bf16 v[108:111], v[182:185], v[190:193], v[108:111]
	v_mfma_f32_16x16x32_bf16 v[100:103], v[174:177], v[198:201], v[100:103]
	v_mfma_f32_16x16x32_bf16 v[92:95], v[182:185], v[198:201], v[92:95]
	v_mfma_f32_16x16x32_bf16 v[84:87], v[174:177], v[206:209], v[84:87]
	v_mfma_f32_16x16x32_bf16 v[76:79], v[182:185], v[206:209], v[76:79]
	v_mfma_f32_16x16x32_bf16 v[68:71], v[174:177], v[214:217], v[68:71]
	v_mfma_f32_16x16x32_bf16 v[64:67], v[182:185], v[214:217], v[64:67]
	s_setprio 0
	s_barrier
	s_add_i32 s26, s50, s39
	v_lshl_add_u64 v[166:167], s[28:29], 0, v[146:147]
	s_mov_b32 m0, s26
	ds_read_b128 v[186:189], v172 offset:16384
	ds_read_b128 v[190:193], v172 offset:17408
	ds_read_b128 v[194:197], v172 offset:18432
	ds_read_b128 v[198:201], v172 offset:19456
	ds_read_b128 v[202:205], v172 offset:20480
	ds_read_b128 v[206:209], v172 offset:21504
	ds_read_b128 v[210:213], v172 offset:22528
	ds_read_b128 v[214:217], v172 offset:23552
	global_load_lds_dwordx4 v[166:167], off
	s_add_i32 m0, s26, 0x2000
	s_add_u32 s26, s28, 0x80000
	v_lshl_add_u64 v[218:219], s[28:29], 0, v[150:151]
	s_addc_u32 s27, s29, 0
	s_add_i32 s61, s51, s39
	global_load_lds_dwordx4 v[218:219], off
	v_lshl_add_u64 v[220:221], s[26:27], 0, v[146:147]
	s_mov_b32 m0, s61
	v_lshl_add_u64 v[222:223], s[30:31], 0, v[148:149]
	global_load_lds_dwordx4 v[220:221], off
	v_lshl_add_u64 v[220:221], s[26:27], 0, v[150:151]
	s_add_i32 m0, s61, 0x2000
	s_nop 0
	global_load_lds_dwordx4 v[220:221], off
	v_lshl_add_u64 v[220:221], s[30:31], 0, v[144:145]
	s_mov_b32 m0, s40
	s_nop 0
	global_load_lds_dwordx4 v[220:221], off
	s_mov_b32 m0, s41
	s_nop 0
	global_load_lds_dwordx4 v[222:223], off
	s_waitcnt vmcnt(8)
	s_waitcnt lgkmcnt(0)
	s_setprio 1
	s_barrier
; #define PG8_STAGE(bufoff, gbase, voff) do { _Pragma("unroll") for (int _i = 0; _i < 2; ++_i) \
;         __builtin_amdgcn_global_load_lds((const unsigned*)((const char*)(gbase) + (voff)[_i]), (PG8_LAS unsigned*)(lds + (bufoff) + ldsw + _i * 8192), 16, 0, 0); } while (0)
; #define PG8_LDA(dst, b, h) do { _Pragma("unroll") for (int m = 0; m < 4; ++m) _Pragma("unroll") for (int k = 0; k < 2; ++k) dst[m][k] = *(const PG8_LAS bf16x8*)(lds + PG8_SA(b, h) + aoff + m * 2048 + k * 1024); } while (0)
; #define PG8_LDB(dst, b, h) do { _Pragma("unroll") for (int n = 0; n < 2; ++n) _Pragma("unroll") for (int k = 0; k < 2; ++k) dst[n][k] = *(const PG8_LAS bf16x8*)(lds + PG8_SB(b, h) + boff + n * 2048 + k * 1024); } while (0)
; #define PG8_MMA(ai, bj, At, Bt) do { __builtin_amdgcn_s_setprio(1); _Pragma("unroll") for (int m = 0; m < 4; ++m) _Pragma("unroll") for (int n = 0; n < 2; ++n) _Pragma("unroll") for (int k = 0; k < 2; ++k) \
;         acc[ai][bj][m][n] = __builtin_amdgcn_mfma_f32_16x16x32_bf16(Bt[n][k], At[m][k], acc[ai][bj][m][n], 0, 0, 0); __builtin_amdgcn_s_setprio(0); } while (0)
; #define PG8_WAIT_V(n) asm volatile("s_waitcnt vmcnt(" #n ")" ::: "memory")
; #define PG8_WAIT_L(n) asm volatile("s_waitcnt lgkmcnt(" #n ")" ::: "memory")
; #define PG8_BAR __builtin_amdgcn_s_barrier()
; #define PG8_SCHED __builtin_amdgcn_sched_barrier(0)
; template <class Epi, class Sched, bool ALIGN_EPI = false, bool SP2 = false>
; __device__ __forceinline__ void gemm_phase(PG8_LAS unsigned char* lds, const Gemm g, const Sched& S, const Epi& E, const int wave_in) {
;     ...
;             PG8_WAIT_V(8); PG8_WAIT_L(0); PG8_BAR; PG8_MMA(1, 0, At, B0); PG8_MMA(1, 1, At, B1); PG8_BAR; PG8_SCHED;
;             PG8_LDB(B0, 1, 0); PG8_LDB(B1, 1, 1); PG8_SCHED; PG8_LDA(At, 1, 0); PG8_STAGE(PG8_SA(0, 1), a2 + hstepA, voffA);
;             PG8_WAIT_V(8); PG8_WAIT_L(0); PG8_BAR; PG8_MMA(0, 0, At, B0); PG8_MMA(0, 1, At, B1); PG8_BAR; PG8_SCHED;
	v_mfma_f32_16x16x32_bf16 v[60:63], v[128:131], v[186:189], 0
	v_mfma_f32_16x16x32_bf16 v[56:59], v[136:139], v[186:189], 0
	v_mfma_f32_16x16x32_bf16 v[48:51], v[128:131], v[194:197], 0
	v_mfma_f32_16x16x32_bf16 v[40:43], v[136:139], v[194:197], 0
	v_mfma_f32_16x16x32_bf16 v[32:35], v[128:131], v[202:205], 0
	v_mfma_f32_16x16x32_bf16 v[24:27], v[136:139], v[202:205], 0
	v_mfma_f32_16x16x32_bf16 v[16:19], v[128:131], v[210:213], 0
	v_mfma_f32_16x16x32_bf16 v[8:11], v[136:139], v[210:213], 0
	v_mfma_f32_16x16x32_bf16 v[60:63], v[132:135], v[190:193], v[60:63]
	v_mfma_f32_16x16x32_bf16 v[56:59], v[140:143], v[190:193], v[56:59]
	v_mfma_f32_16x16x32_bf16 v[48:51], v[132:135], v[198:201], v[48:51]
	v_mfma_f32_16x16x32_bf16 v[40:43], v[140:143], v[198:201], v[40:43]
	v_mfma_f32_16x16x32_bf16 v[32:35], v[132:135], v[206:209], v[32:35]
	v_mfma_f32_16x16x32_bf16 v[24:27], v[140:143], v[206:209], v[24:27]
	v_mfma_f32_16x16x32_bf16 v[16:19], v[132:135], v[214:217], v[16:19]
	v_mfma_f32_16x16x32_bf16 v[8:11], v[140:143], v[214:217], v[8:11]
	v_mfma_f32_16x16x32_bf16 v[52:55], v[162:165], v[186:189], 0
	v_mfma_f32_16x16x32_bf16 v[44:47], v[178:181], v[186:189], 0
	v_mfma_f32_16x16x32_bf16 v[36:39], v[162:165], v[194:197], 0
	v_mfma_f32_16x16x32_bf16 v[28:31], v[178:181], v[194:197], 0
	v_mfma_f32_16x16x32_bf16 v[20:23], v[162:165], v[202:205], 0
	v_mfma_f32_16x16x32_bf16 v[12:15], v[178:181], v[202:205], 0
	v_mfma_f32_16x16x32_bf16 v[4:7], v[162:165], v[210:213], 0
	v_mfma_f32_16x16x32_bf16 v[0:3], v[178:181], v[210:213], 0
	v_mfma_f32_16x16x32_bf16 v[52:55], v[174:177], v[190:193], v[52:55]
	v_mfma_f32_16x16x32_bf16 v[44:47], v[182:185], v[190:193], v[44:47]
	v_mfma_f32_16x16x32_bf16 v[36:39], v[174:177], v[198:201], v[36:39]
	v_mfma_f32_16x16x32_bf16 v[28:31], v[182:185], v[198:201], v[28:31]
	v_mfma_f32_16x16x32_bf16 v[20:23], v[174:177], v[206:209], v[20:23]
	v_mfma_f32_16x16x32_bf16 v[12:15], v[182:185], v[206:209], v[12:15]
	v_mfma_f32_16x16x32_bf16 v[4:7], v[174:177], v[214:217], v[4:7]
	v_mfma_f32_16x16x32_bf16 v[0:3], v[182:185], v[214:217], v[0:3]
	s_setprio 0
	s_barrier
	s_add_i32 s61, 0, 0x18000
	s_add_i32 s62, 0, 0x1c000
	v_add_u32_e32 v140, s61, v168
	v_add_u32_e32 v173, s62, v168
	ds_read_b128 v[128:131], v140
	ds_read_b128 v[132:135], v140 offset:1024
	ds_read_b128 v[136:139], v140 offset:2048
	ds_read_b128 v[140:143], v140 offset:3072
	ds_read_b128 v[162:165], v173
	ds_read_b128 v[174:177], v173 offset:1024
	ds_read_b128 v[178:181], v173 offset:2048
	ds_read_b128 v[182:185], v173 offset:3072
	s_add_u32 s26, s30, 0x280000
	s_addc_u32 s27, s31, 0
	s_mov_b32 m0, s42
	v_lshl_add_u64 v[224:225], s[26:27], 0, v[144:145]
	ds_read_b128 v[186:189], v172 offset:32768
	ds_read_b128 v[190:193], v172 offset:33792
	ds_read_b128 v[194:197], v172 offset:34816
	ds_read_b128 v[198:201], v172 offset:35840
	ds_read_b128 v[202:205], v172 offset:36864
	ds_read_b128 v[206:209], v172 offset:37888
	ds_read_b128 v[210:213], v172 offset:38912
	ds_read_b128 v[214:217], v172 offset:39936
	global_load_lds_dwordx4 v[224:225], off
	v_lshl_add_u64 v[224:225], s[26:27], 0, v[148:149]
	s_mov_b32 m0, s43
	s_nop 0
	global_load_lds_dwordx4 v[224:225], off
	s_waitcnt vmcnt(8)
	s_waitcnt lgkmcnt(0)
	s_setprio 1
	s_barrier
	v_mfma_f32_16x16x32_bf16 v[124:127], v[128:131], v[186:189], v[124:127]
	v_mfma_f32_16x16x32_bf16 v[120:123], v[136:139], v[186:189], v[120:123]
	v_mfma_f32_16x16x32_bf16 v[112:115], v[128:131], v[194:197], v[112:115]
	v_mfma_f32_16x16x32_bf16 v[104:107], v[136:139], v[194:197], v[104:107]
	v_mfma_f32_16x16x32_bf16 v[96:99], v[128:131], v[202:205], v[96:99]
	v_mfma_f32_16x16x32_bf16 v[88:91], v[136:139], v[202:205], v[88:91]
	v_mfma_f32_16x16x32_bf16 v[80:83], v[128:131], v[210:213], v[80:83]
	v_mfma_f32_16x16x32_bf16 v[72:75], v[136:139], v[210:213], v[72:75]
	v_mfma_f32_16x16x32_bf16 v[124:127], v[132:135], v[190:193], v[124:127]
	v_mfma_f32_16x16x32_bf16 v[120:123], v[140:143], v[190:193], v[120:123]
	v_mfma_f32_16x16x32_bf16 v[112:115], v[132:135], v[198:201], v[112:115]
	v_mfma_f32_16x16x32_bf16 v[104:107], v[140:143], v[198:201], v[104:107]
	v_mfma_f32_16x16x32_bf16 v[96:99], v[132:135], v[206:209], v[96:99]
	v_mfma_f32_16x16x32_bf16 v[88:91], v[140:143], v[206:209], v[88:91]
	v_mfma_f32_16x16x32_bf16 v[80:83], v[132:135], v[214:217], v[80:83]
	v_mfma_f32_16x16x32_bf16 v[72:75], v[140:143], v[214:217], v[72:75]
	v_mfma_f32_16x16x32_bf16 v[116:119], v[162:165], v[186:189], v[116:119]
	v_mfma_f32_16x16x32_bf16 v[108:111], v[178:181], v[186:189], v[108:111]
	v_mfma_f32_16x16x32_bf16 v[100:103], v[162:165], v[194:197], v[100:103]
	v_mfma_f32_16x16x32_bf16 v[92:95], v[178:181], v[194:197], v[92:95]
	v_mfma_f32_16x16x32_bf16 v[84:87], v[162:165], v[202:205], v[84:87]
	v_mfma_f32_16x16x32_bf16 v[76:79], v[178:181], v[202:205], v[76:79]
	v_mfma_f32_16x16x32_bf16 v[68:71], v[162:165], v[210:213], v[68:71]
	v_mfma_f32_16x16x32_bf16 v[64:67], v[178:181], v[210:213], v[64:67]
	v_mfma_f32_16x16x32_bf16 v[116:119], v[174:177], v[190:193], v[116:119]
	v_mfma_f32_16x16x32_bf16 v[108:111], v[182:185], v[190:193], v[108:111]
	v_mfma_f32_16x16x32_bf16 v[100:103], v[174:177], v[198:201], v[100:103]
	v_mfma_f32_16x16x32_bf16 v[92:95], v[182:185], v[198:201], v[92:95]
	v_mfma_f32_16x16x32_bf16 v[84:87], v[174:177], v[206:209], v[84:87]
	v_mfma_f32_16x16x32_bf16 v[76:79], v[182:185], v[206:209], v[76:79]
	v_mfma_f32_16x16x32_bf16 v[68:71], v[174:177], v[214:217], v[68:71]
	v_mfma_f32_16x16x32_bf16 v[64:67], v[182:185], v[214:217], v[64:67]
	s_setprio 0
	s_barrier
; #define PG8_STAGE(bufoff, gbase, voff) do { _Pragma("unroll") for (int _i = 0; _i < 2; ++_i) \
;         __builtin_amdgcn_global_load_lds((const unsigned*)((const char*)(gbase) + (voff)[_i]), (PG8_LAS unsigned*)(lds + (bufoff) + ldsw + _i * 8192), 16, 0, 0); } while (0)
; #define PG8_LDA(dst, b, h) do { _Pragma("unroll") for (int m = 0; m < 4; ++m) _Pragma("unroll") for (int k = 0; k < 2; ++k) dst[m][k] = *(const PG8_LAS bf16x8*)(lds + PG8_SA(b, h) + aoff + m * 2048 + k * 1024); } while (0)
; #define PG8_LDB(dst, b, h) do { _Pragma("unroll") for (int n = 0; n < 2; ++n) _Pragma("unroll") for (int k = 0; k < 2; ++k) dst[n][k] = *(const PG8_LAS bf16x8*)(lds + PG8_SB(b, h) + boff + n * 2048 + k * 1024); } while (0)
; #define PG8_MMA(ai, bj, At, Bt) do { __builtin_amdgcn_s_setprio(1); _Pragma("unroll") for (int m = 0; m < 4; ++m) _Pragma("unroll") for (int n = 0; n < 2; ++n) _Pragma("unroll") for (int k = 0; k < 2; ++k) \
;         acc[ai][bj][m][n] = __builtin_amdgcn_mfma_f32_16x16x32_bf16(Bt[n][k], At[m][k], acc[ai][bj][m][n], 0, 0, 0); __builtin_amdgcn_s_setprio(0); } while (0)
; #define PG8_WAIT_V(n) asm volatile("s_waitcnt vmcnt(" #n ")" ::: "memory")
; #define PG8_WAIT_L(n) asm volatile("s_waitcnt lgkmcnt(" #n ")" ::: "memory")
; #define PG8_BAR __builtin_amdgcn_s_barrier()
; #define PG8_SCHED __builtin_amdgcn_sched_barrier(0)
; template <class Epi, class Sched, bool ALIGN_EPI = false, bool SP2 = false>
; __device__ __forceinline__ void gemm_phase(PG8_LAS unsigned char* lds, const Gemm g, const Sched& S, const Epi& E, const int wave_in) {
;     ...
;             PG8_LDB(B0, 0, 0); PG8_LDB(B1, 0, 1); PG8_SCHED; PG8_LDA(At, 0, 0); PG8_STAGE(PG8_SA(1, 1), a1 + hstepA, voffA);
;     ...
;             PG8_LDA(At, 1, 1); PG8_STAGE(PG8_SB(1, 0), b3, voffB); PG8_STAGE(PG8_SB(1, 1), b3 + hstepB, voffB); PG8_STAGE(PG8_SA(1, 0), a3, voffA);
;             PG8_WAIT_V(8); PG8_WAIT_L(0); PG8_BAR; PG8_MMA(1, 0, At, B0); PG8_MMA(1, 1, At, B1); PG8_BAR; PG8_SCHED;
	s_add_i32 s26, s61, s39
	v_lshl_add_u64 v[166:167], v[166:167], 0, s[8:9]
	s_mov_b32 m0, s26
	ds_read_b128 v[186:189], v172 offset:49152
	ds_read_b128 v[190:193], v172 offset:50176
	ds_read_b128 v[194:197], v172 offset:51200
	ds_read_b128 v[198:201], v172 offset:52224
	ds_read_b128 v[202:205], v172 offset:53248
	ds_read_b128 v[206:209], v172 offset:54272
	ds_read_b128 v[210:213], v172 offset:55296
	ds_read_b128 v[214:217], v172 offset:56320
	global_load_lds_dwordx4 v[166:167], off
	s_add_i32 m0, s26, 0x2000
	s_add_u32 s26, s28, 0x80080
	v_lshl_add_u64 v[166:167], v[218:219], 0, s[8:9]
	s_addc_u32 s27, s29, 0
	s_add_i32 s28, s62, s39
	global_load_lds_dwordx4 v[166:167], off
	v_lshl_add_u64 v[166:167], s[26:27], 0, v[146:147]
	s_mov_b32 m0, s28
	s_nop 0
	global_load_lds_dwordx4 v[166:167], off
	v_lshl_add_u64 v[166:167], s[26:27], 0, v[150:151]
	s_add_i32 m0, s28, 0x2000
	s_nop 0
	global_load_lds_dwordx4 v[166:167], off
	v_lshl_add_u64 v[166:167], v[220:221], 0, s[8:9]
	s_mov_b32 m0, s47
	s_nop 0
	global_load_lds_dwordx4 v[166:167], off
	v_lshl_add_u64 v[166:167], v[222:223], 0, s[8:9]
	s_mov_b32 m0, s48
	s_nop 0
	global_load_lds_dwordx4 v[166:167], off
	s_waitcnt vmcnt(8)
	s_waitcnt lgkmcnt(0)
	s_setprio 1
	s_barrier
	v_mfma_f32_16x16x32_bf16 v[60:63], v[128:131], v[186:189], v[60:63]
	v_mfma_f32_16x16x32_bf16 v[56:59], v[136:139], v[186:189], v[56:59]
	v_mfma_f32_16x16x32_bf16 v[48:51], v[128:131], v[194:197], v[48:51]
	v_mfma_f32_16x16x32_bf16 v[40:43], v[136:139], v[194:197], v[40:43]
	v_mfma_f32_16x16x32_bf16 v[32:35], v[128:131], v[202:205], v[32:35]
	v_mfma_f32_16x16x32_bf16 v[24:27], v[136:139], v[202:205], v[24:27]
	v_mfma_f32_16x16x32_bf16 v[16:19], v[128:131], v[210:213], v[16:19]
	v_mfma_f32_16x16x32_bf16 v[8:11], v[136:139], v[210:213], v[8:11]
	v_mfma_f32_16x16x32_bf16 v[60:63], v[132:135], v[190:193], v[60:63]
	v_mfma_f32_16x16x32_bf16 v[56:59], v[140:143], v[190:193], v[56:59]
	v_mfma_f32_16x16x32_bf16 v[48:51], v[132:135], v[198:201], v[48:51]
	v_mfma_f32_16x16x32_bf16 v[40:43], v[140:143], v[198:201], v[40:43]
	v_mfma_f32_16x16x32_bf16 v[32:35], v[132:135], v[206:209], v[32:35]
	v_mfma_f32_16x16x32_bf16 v[24:27], v[140:143], v[206:209], v[24:27]
	v_mfma_f32_16x16x32_bf16 v[16:19], v[132:135], v[214:217], v[16:19]
	v_mfma_f32_16x16x32_bf16 v[8:11], v[140:143], v[214:217], v[8:11]
	v_mfma_f32_16x16x32_bf16 v[52:55], v[162:165], v[186:189], v[52:55]
	v_mfma_f32_16x16x32_bf16 v[44:47], v[178:181], v[186:189], v[44:47]
	v_mfma_f32_16x16x32_bf16 v[36:39], v[162:165], v[194:197], v[36:39]
	v_mfma_f32_16x16x32_bf16 v[28:31], v[178:181], v[194:197], v[28:31]
	v_mfma_f32_16x16x32_bf16 v[20:23], v[162:165], v[202:205], v[20:23]
	v_mfma_f32_16x16x32_bf16 v[12:15], v[178:181], v[202:205], v[12:15]
	v_mfma_f32_16x16x32_bf16 v[4:7], v[162:165], v[210:213], v[4:7]
	v_mfma_f32_16x16x32_bf16 v[0:3], v[178:181], v[210:213], v[0:3]
	v_mfma_f32_16x16x32_bf16 v[52:55], v[174:177], v[190:193], v[52:55]
	v_mfma_f32_16x16x32_bf16 v[44:47], v[182:185], v[190:193], v[44:47]
	v_mfma_f32_16x16x32_bf16 v[36:39], v[174:177], v[198:201], v[36:39]
	v_mfma_f32_16x16x32_bf16 v[28:31], v[182:185], v[198:201], v[28:31]
	v_mfma_f32_16x16x32_bf16 v[20:23], v[174:177], v[206:209], v[20:23]
	v_mfma_f32_16x16x32_bf16 v[12:15], v[182:185], v[206:209], v[12:15]
	v_mfma_f32_16x16x32_bf16 v[4:7], v[174:177], v[214:217], v[4:7]
	v_mfma_f32_16x16x32_bf16 v[0:3], v[182:185], v[214:217], v[0:3]
	s_setprio 0
	s_barrier
	s_add_i32 s60, s60, 2
	s_add_u32 s58, s58, 0x100
	s_addc_u32 s59, s59, 0
	s_cmp_gt_u32 s60, 29
	s_mov_b64 s[26:27], s[4:5]
	s_cbranch_scc0 .LBB0_2451
	s_branch .Lkx_28
.LBB0_2451:
	ds_read_b128 v[128:131], v170
	ds_read_b128 v[132:135], v170 offset:1024
	ds_read_b128 v[136:139], v170 offset:2048
	ds_read_b128 v[140:143], v170 offset:3072
	ds_read_b128 v[162:165], v171
	ds_read_b128 v[174:177], v171 offset:1024
	ds_read_b128 v[178:181], v171 offset:2048
	ds_read_b128 v[182:185], v171 offset:3072
	s_add_u32 s4, s26, 0x100
	s_addc_u32 s5, s27, 0
	s_cmp_eq_u32 s60, 28
	s_cselect_b32 s31, s21, s5
	s_cselect_b32 s30, s20, s4
	s_cselect_b32 s29, s19, s59
	s_cselect_b32 s28, s25, s58
	v_lshl_add_u64 v[166:167], s[26:27], 0, v[154:155]
	s_add_i32 m0, s40, 0xc000
	ds_read_b128 v[186:189], v172
	ds_read_b128 v[190:193], v172 offset:1024
	ds_read_b128 v[194:197], v172 offset:2048
	ds_read_b128 v[198:201], v172 offset:3072
	ds_read_b128 v[202:205], v172 offset:4096
	ds_read_b128 v[206:209], v172 offset:5120
	ds_read_b128 v[210:213], v172 offset:6144
	ds_read_b128 v[214:217], v172 offset:7168
	global_load_lds_dwordx4 v[166:167], off
	v_lshl_add_u64 v[166:167], s[26:27], 0, v[156:157]
	s_add_i32 m0, s40, 0xe000
	s_nop 0
	global_load_lds_dwordx4 v[166:167], off
	s_waitcnt vmcnt(8)
	s_waitcnt lgkmcnt(0)
	s_setprio 1
	s_barrier
; #define PG8_STAGE(bufoff, gbase, voff) do { _Pragma("unroll") for (int _i = 0; _i < 2; ++_i) \
;         __builtin_amdgcn_global_load_lds((const unsigned*)((const char*)(gbase) + (voff)[_i]), (PG8_LAS unsigned*)(lds + (bufoff) + ldsw + _i * 8192), 16, 0, 0); } while (0)
; #define PG8_LDA(dst, b, h) do { _Pragma("unroll") for (int m = 0; m < 4; ++m) _Pragma("unroll") for (int k = 0; k < 2; ++k) dst[m][k] = *(const PG8_LAS bf16x8*)(lds + PG8_SA(b, h) + aoff + m * 2048 + k * 1024); } while (0)
; #define PG8_LDB(dst, b, h) do { _Pragma("unroll") for (int n = 0; n < 2; ++n) _Pragma("unroll") for (int k = 0; k < 2; ++k) dst[n][k] = *(const PG8_LAS bf16x8*)(lds + PG8_SB(b, h) + boff + n * 2048 + k * 1024); } while (0)
; #define PG8_MMA(ai, bj, At, Bt) do { __builtin_amdgcn_s_setprio(1); _Pragma("unroll") for (int m = 0; m < 4; ++m) _Pragma("unroll") for (int n = 0; n < 2; ++n) _Pragma("unroll") for (int k = 0; k < 2; ++k) \
;         acc[ai][bj][m][n] = __builtin_amdgcn_mfma_f32_16x16x32_bf16(Bt[n][k], At[m][k], acc[ai][bj][m][n], 0, 0, 0); __builtin_amdgcn_s_setprio(0); } while (0)
; #define PG8_WAIT_V(n) asm volatile("s_waitcnt vmcnt(" #n ")" ::: "memory")
; #define PG8_WAIT_L(n) asm volatile("s_waitcnt lgkmcnt(" #n ")" ::: "memory")
; #define PG8_BAR __builtin_amdgcn_s_barrier()
; #define PG8_SCHED __builtin_amdgcn_sched_barrier(0)
; template <class Epi, class Sched, bool ALIGN_EPI = false, bool SP2 = false>
; __device__ __forceinline__ void gemm_phase(PG8_LAS unsigned char* lds, const Gemm g, const Sched& S, const Epi& E, const int wave_in) {
;     ...
;             PG8_LDB(B0, 0, 0); PG8_LDB(B1, 0, 1); PG8_SCHED; PG8_LDA(At, 0, 0); PG8_STAGE(PG8_SA(1, 1), a1 + hstepA, voffA);
;             PG8_WAIT_V(8); PG8_WAIT_L(0); PG8_BAR; PG8_MMA(0, 0, At, B0); PG8_MMA(0, 1, At, B1); PG8_BAR; PG8_SCHED;
;             PG8_LDA(At, 0, 1); PG8_STAGE(PG8_SB(0, 0), b2, voffB); PG8_STAGE(PG8_SB(0, 1), b2 + hstepB, voffB); PG8_STAGE(PG8_SA(0, 0), a2, voffA);
;             PG8_WAIT_V(8); PG8_WAIT_L(0); PG8_BAR; PG8_MMA(1, 0, At, B0); PG8_MMA(1, 1, At, B1); PG8_BAR; PG8_SCHED;
	v_mfma_f32_16x16x32_bf16 v[124:127], v[128:131], v[186:189], v[124:127]
	v_mfma_f32_16x16x32_bf16 v[120:123], v[136:139], v[186:189], v[120:123]
	v_mfma_f32_16x16x32_bf16 v[112:115], v[128:131], v[194:197], v[112:115]
	v_mfma_f32_16x16x32_bf16 v[104:107], v[136:139], v[194:197], v[104:107]
	v_mfma_f32_16x16x32_bf16 v[96:99], v[128:131], v[202:205], v[96:99]
	v_mfma_f32_16x16x32_bf16 v[88:91], v[136:139], v[202:205], v[88:91]
	v_mfma_f32_16x16x32_bf16 v[80:83], v[128:131], v[210:213], v[80:83]
	v_mfma_f32_16x16x32_bf16 v[72:75], v[136:139], v[210:213], v[72:75]
	v_mfma_f32_16x16x32_bf16 v[124:127], v[132:135], v[190:193], v[124:127]
	v_mfma_f32_16x16x32_bf16 v[120:123], v[140:143], v[190:193], v[120:123]
	v_mfma_f32_16x16x32_bf16 v[112:115], v[132:135], v[198:201], v[112:115]
	v_mfma_f32_16x16x32_bf16 v[104:107], v[140:143], v[198:201], v[104:107]
	v_mfma_f32_16x16x32_bf16 v[96:99], v[132:135], v[206:209], v[96:99]
	v_mfma_f32_16x16x32_bf16 v[88:91], v[140:143], v[206:209], v[88:91]
	v_mfma_f32_16x16x32_bf16 v[80:83], v[132:135], v[214:217], v[80:83]
	v_mfma_f32_16x16x32_bf16 v[72:75], v[140:143], v[214:217], v[72:75]
	v_mfma_f32_16x16x32_bf16 v[116:119], v[162:165], v[186:189], v[116:119]
	v_mfma_f32_16x16x32_bf16 v[108:111], v[178:181], v[186:189], v[108:111]
	v_mfma_f32_16x16x32_bf16 v[100:103], v[162:165], v[194:197], v[100:103]
	v_mfma_f32_16x16x32_bf16 v[92:95], v[178:181], v[194:197], v[92:95]
	v_mfma_f32_16x16x32_bf16 v[84:87], v[162:165], v[202:205], v[84:87]
	v_mfma_f32_16x16x32_bf16 v[76:79], v[178:181], v[202:205], v[76:79]
	v_mfma_f32_16x16x32_bf16 v[68:71], v[162:165], v[210:213], v[68:71]
	v_mfma_f32_16x16x32_bf16 v[64:67], v[178:181], v[210:213], v[64:67]
	v_mfma_f32_16x16x32_bf16 v[116:119], v[174:177], v[190:193], v[116:119]
	v_mfma_f32_16x16x32_bf16 v[108:111], v[182:185], v[190:193], v[108:111]
	v_mfma_f32_16x16x32_bf16 v[100:103], v[174:177], v[198:201], v[100:103]
	v_mfma_f32_16x16x32_bf16 v[92:95], v[182:185], v[198:201], v[92:95]
	v_mfma_f32_16x16x32_bf16 v[84:87], v[174:177], v[206:209], v[84:87]
	v_mfma_f32_16x16x32_bf16 v[76:79], v[182:185], v[206:209], v[76:79]
	v_mfma_f32_16x16x32_bf16 v[68:71], v[174:177], v[214:217], v[68:71]
	v_mfma_f32_16x16x32_bf16 v[64:67], v[182:185], v[214:217], v[64:67]
	s_setprio 0
	s_barrier
	s_add_i32 s26, s50, s39
	v_lshl_add_u64 v[166:167], s[28:29], 0, v[146:147]
	s_mov_b32 m0, s26
	ds_read_b128 v[186:189], v172 offset:16384
	ds_read_b128 v[190:193], v172 offset:17408
	ds_read_b128 v[194:197], v172 offset:18432
	ds_read_b128 v[198:201], v172 offset:19456
	ds_read_b128 v[202:205], v172 offset:20480
	ds_read_b128 v[206:209], v172 offset:21504
	ds_read_b128 v[210:213], v172 offset:22528
	ds_read_b128 v[214:217], v172 offset:23552
	global_load_lds_dwordx4 v[166:167], off
	s_add_i32 m0, s26, 0x2000
	s_add_u32 s26, s28, 0x80000
	v_lshl_add_u64 v[218:219], s[28:29], 0, v[150:151]
	s_addc_u32 s27, s29, 0
	s_add_i32 s61, s51, s39
	global_load_lds_dwordx4 v[218:219], off
	v_lshl_add_u64 v[220:221], s[26:27], 0, v[146:147]
	s_mov_b32 m0, s61
	v_lshl_add_u64 v[222:223], s[30:31], 0, v[148:149]
	global_load_lds_dwordx4 v[220:221], off
	v_lshl_add_u64 v[220:221], s[26:27], 0, v[150:151]
	s_add_i32 m0, s61, 0x2000
	s_nop 0
	global_load_lds_dwordx4 v[220:221], off
	v_lshl_add_u64 v[220:221], s[30:31], 0, v[144:145]
	s_mov_b32 m0, s40
	s_nop 0
	global_load_lds_dwordx4 v[220:221], off
	s_mov_b32 m0, s41
	s_nop 0
	global_load_lds_dwordx4 v[222:223], off
	s_waitcnt vmcnt(8)
	s_waitcnt lgkmcnt(0)
	s_setprio 1
	s_barrier
	v_mfma_f32_16x16x32_bf16 v[60:63], v[128:131], v[186:189], v[60:63]
	v_mfma_f32_16x16x32_bf16 v[56:59], v[136:139], v[186:189], v[56:59]
	v_mfma_f32_16x16x32_bf16 v[48:51], v[128:131], v[194:197], v[48:51]
	v_mfma_f32_16x16x32_bf16 v[40:43], v[136:139], v[194:197], v[40:43]
	v_mfma_f32_16x16x32_bf16 v[32:35], v[128:131], v[202:205], v[32:35]
	v_mfma_f32_16x16x32_bf16 v[24:27], v[136:139], v[202:205], v[24:27]
	v_mfma_f32_16x16x32_bf16 v[16:19], v[128:131], v[210:213], v[16:19]
	v_mfma_f32_16x16x32_bf16 v[8:11], v[136:139], v[210:213], v[8:11]
	v_mfma_f32_16x16x32_bf16 v[60:63], v[132:135], v[190:193], v[60:63]
	v_mfma_f32_16x16x32_bf16 v[56:59], v[140:143], v[190:193], v[56:59]
	v_mfma_f32_16x16x32_bf16 v[48:51], v[132:135], v[198:201], v[48:51]
	v_mfma_f32_16x16x32_bf16 v[40:43], v[140:143], v[198:201], v[40:43]
	v_mfma_f32_16x16x32_bf16 v[32:35], v[132:135], v[206:209], v[32:35]
	v_mfma_f32_16x16x32_bf16 v[24:27], v[140:143], v[206:209], v[24:27]
	v_mfma_f32_16x16x32_bf16 v[16:19], v[132:135], v[214:217], v[16:19]
	v_mfma_f32_16x16x32_bf16 v[8:11], v[140:143], v[214:217], v[8:11]
	v_mfma_f32_16x16x32_bf16 v[52:55], v[162:165], v[186:189], v[52:55]
	v_mfma_f32_16x16x32_bf16 v[44:47], v[178:181], v[186:189], v[44:47]
	v_mfma_f32_16x16x32_bf16 v[36:39], v[162:165], v[194:197], v[36:39]
	v_mfma_f32_16x16x32_bf16 v[28:31], v[178:181], v[194:197], v[28:31]
	v_mfma_f32_16x16x32_bf16 v[20:23], v[162:165], v[202:205], v[20:23]
	v_mfma_f32_16x16x32_bf16 v[12:15], v[178:181], v[202:205], v[12:15]
	v_mfma_f32_16x16x32_bf16 v[4:7], v[162:165], v[210:213], v[4:7]
	v_mfma_f32_16x16x32_bf16 v[0:3], v[178:181], v[210:213], v[0:3]
	v_mfma_f32_16x16x32_bf16 v[52:55], v[174:177], v[190:193], v[52:55]
	v_mfma_f32_16x16x32_bf16 v[44:47], v[182:185], v[190:193], v[44:47]
	v_mfma_f32_16x16x32_bf16 v[36:39], v[174:177], v[198:201], v[36:39]
	v_mfma_f32_16x16x32_bf16 v[28:31], v[182:185], v[198:201], v[28:31]
	v_mfma_f32_16x16x32_bf16 v[20:23], v[174:177], v[206:209], v[20:23]
	v_mfma_f32_16x16x32_bf16 v[12:15], v[182:185], v[206:209], v[12:15]
	v_mfma_f32_16x16x32_bf16 v[4:7], v[174:177], v[214:217], v[4:7]
	v_mfma_f32_16x16x32_bf16 v[0:3], v[182:185], v[214:217], v[0:3]
	s_setprio 0
	s_barrier
; #define PG8_STAGE(bufoff, gbase, voff) do { _Pragma("unroll") for (int _i = 0; _i < 2; ++_i) \
;         __builtin_amdgcn_global_load_lds((const unsigned*)((const char*)(gbase) + (voff)[_i]), (PG8_LAS unsigned*)(lds + (bufoff) + ldsw + _i * 8192), 16, 0, 0); } while (0)
; #define PG8_LDA(dst, b, h) do { _Pragma("unroll") for (int m = 0; m < 4; ++m) _Pragma("unroll") for (int k = 0; k < 2; ++k) dst[m][k] = *(const PG8_LAS bf16x8*)(lds + PG8_SA(b, h) + aoff + m * 2048 + k * 1024); } while (0)
; #define PG8_LDB(dst, b, h) do { _Pragma("unroll") for (int n = 0; n < 2; ++n) _Pragma("unroll") for (int k = 0; k < 2; ++k) dst[n][k] = *(const PG8_LAS bf16x8*)(lds + PG8_SB(b, h) + boff + n * 2048 + k * 1024); } while (0)
; #define PG8_MMA(ai, bj, At, Bt) do { __builtin_amdgcn_s_setprio(1); _Pragma("unroll") for (int m = 0; m < 4; ++m) _Pragma("unroll") for (int n = 0; n < 2; ++n) _Pragma("unroll") for (int k = 0; k < 2; ++k) \
;         acc[ai][bj][m][n] = __builtin_amdgcn_mfma_f32_16x16x32_bf16(Bt[n][k], At[m][k], acc[ai][bj][m][n], 0, 0, 0); __builtin_amdgcn_s_setprio(0); } while (0)
; #define PG8_WAIT_V(n) asm volatile("s_waitcnt vmcnt(" #n ")" ::: "memory")
; #define PG8_WAIT_L(n) asm volatile("s_waitcnt lgkmcnt(" #n ")" ::: "memory")
; #define PG8_BAR __builtin_amdgcn_s_barrier()
; #define PG8_SCHED __builtin_amdgcn_sched_barrier(0)
; template <class Epi, class Sched, bool ALIGN_EPI = false, bool SP2 = false>
; __device__ __forceinline__ void gemm_phase(PG8_LAS unsigned char* lds, const Gemm g, const Sched& S, const Epi& E, const int wave_in) {
;     ...
;         for (int t = 0; t < nt; t += 2) {
;     ...
;             PG8_LDB(B0, 1, 0); PG8_LDB(B1, 1, 1); PG8_SCHED; PG8_LDA(At, 1, 0); PG8_STAGE(PG8_SA(0, 1), a2 + hstepA, voffA);
;             PG8_WAIT_V(8); PG8_WAIT_L(0); PG8_BAR; PG8_MMA(0, 0, At, B0); PG8_MMA(0, 1, At, B1); PG8_BAR; PG8_SCHED;
;             PG8_LDA(At, 1, 1); PG8_STAGE(PG8_SB(1, 0), b3, voffB); PG8_STAGE(PG8_SB(1, 1), b3 + hstepB, voffB); PG8_STAGE(PG8_SA(1, 0), a3, voffA);
;             PG8_WAIT_V(8); PG8_WAIT_L(0); PG8_BAR; PG8_MMA(1, 0, At, B0); PG8_MMA(1, 1, At, B1); PG8_BAR; PG8_SCHED;
	s_add_i32 s61, 0, 0x18000
	s_add_i32 s62, 0, 0x1c000
	v_add_u32_e32 v140, s61, v168
	v_add_u32_e32 v173, s62, v168
	ds_read_b128 v[128:131], v140
	ds_read_b128 v[132:135], v140 offset:1024
	ds_read_b128 v[136:139], v140 offset:2048
	ds_read_b128 v[140:143], v140 offset:3072
	ds_read_b128 v[162:165], v173
	ds_read_b128 v[174:177], v173 offset:1024
	ds_read_b128 v[178:181], v173 offset:2048
	ds_read_b128 v[182:185], v173 offset:3072
	s_add_u32 s26, s30, 0x280000
	s_addc_u32 s27, s31, 0
	s_mov_b32 m0, s42
	v_lshl_add_u64 v[224:225], s[26:27], 0, v[144:145]
	ds_read_b128 v[186:189], v172 offset:32768
	ds_read_b128 v[190:193], v172 offset:33792
	ds_read_b128 v[194:197], v172 offset:34816
	ds_read_b128 v[198:201], v172 offset:35840
	ds_read_b128 v[202:205], v172 offset:36864
	ds_read_b128 v[206:209], v172 offset:37888
	ds_read_b128 v[210:213], v172 offset:38912
	ds_read_b128 v[214:217], v172 offset:39936
	global_load_lds_dwordx4 v[224:225], off
	v_lshl_add_u64 v[224:225], s[26:27], 0, v[148:149]
	s_mov_b32 m0, s43
	s_nop 0
	global_load_lds_dwordx4 v[224:225], off
	s_waitcnt vmcnt(8)
	s_waitcnt lgkmcnt(0)
	s_setprio 1
	s_barrier
	v_mfma_f32_16x16x32_bf16 v[124:127], v[128:131], v[186:189], v[124:127]
	v_mfma_f32_16x16x32_bf16 v[120:123], v[136:139], v[186:189], v[120:123]
	v_mfma_f32_16x16x32_bf16 v[112:115], v[128:131], v[194:197], v[112:115]
	v_mfma_f32_16x16x32_bf16 v[104:107], v[136:139], v[194:197], v[104:107]
	v_mfma_f32_16x16x32_bf16 v[96:99], v[128:131], v[202:205], v[96:99]
	v_mfma_f32_16x16x32_bf16 v[88:91], v[136:139], v[202:205], v[88:91]
	v_mfma_f32_16x16x32_bf16 v[80:83], v[128:131], v[210:213], v[80:83]
	v_mfma_f32_16x16x32_bf16 v[72:75], v[136:139], v[210:213], v[72:75]
	v_mfma_f32_16x16x32_bf16 v[124:127], v[132:135], v[190:193], v[124:127]
	v_mfma_f32_16x16x32_bf16 v[120:123], v[140:143], v[190:193], v[120:123]
	v_mfma_f32_16x16x32_bf16 v[112:115], v[132:135], v[198:201], v[112:115]
	v_mfma_f32_16x16x32_bf16 v[104:107], v[140:143], v[198:201], v[104:107]
	v_mfma_f32_16x16x32_bf16 v[96:99], v[132:135], v[206:209], v[96:99]
	v_mfma_f32_16x16x32_bf16 v[88:91], v[140:143], v[206:209], v[88:91]
	v_mfma_f32_16x16x32_bf16 v[80:83], v[132:135], v[214:217], v[80:83]
	v_mfma_f32_16x16x32_bf16 v[72:75], v[140:143], v[214:217], v[72:75]
	v_mfma_f32_16x16x32_bf16 v[116:119], v[162:165], v[186:189], v[116:119]
	v_mfma_f32_16x16x32_bf16 v[108:111], v[178:181], v[186:189], v[108:111]
	v_mfma_f32_16x16x32_bf16 v[100:103], v[162:165], v[194:197], v[100:103]
	v_mfma_f32_16x16x32_bf16 v[92:95], v[178:181], v[194:197], v[92:95]
	v_mfma_f32_16x16x32_bf16 v[84:87], v[162:165], v[202:205], v[84:87]
	v_mfma_f32_16x16x32_bf16 v[76:79], v[178:181], v[202:205], v[76:79]
	v_mfma_f32_16x16x32_bf16 v[68:71], v[162:165], v[210:213], v[68:71]
	v_mfma_f32_16x16x32_bf16 v[64:67], v[178:181], v[210:213], v[64:67]
	v_mfma_f32_16x16x32_bf16 v[116:119], v[174:177], v[190:193], v[116:119]
	v_mfma_f32_16x16x32_bf16 v[108:111], v[182:185], v[190:193], v[108:111]
	v_mfma_f32_16x16x32_bf16 v[100:103], v[174:177], v[198:201], v[100:103]
	v_mfma_f32_16x16x32_bf16 v[92:95], v[182:185], v[198:201], v[92:95]
	v_mfma_f32_16x16x32_bf16 v[84:87], v[174:177], v[206:209], v[84:87]
	v_mfma_f32_16x16x32_bf16 v[76:79], v[182:185], v[206:209], v[76:79]
	v_mfma_f32_16x16x32_bf16 v[68:71], v[174:177], v[214:217], v[68:71]
	v_mfma_f32_16x16x32_bf16 v[64:67], v[182:185], v[214:217], v[64:67]
	s_setprio 0
	s_barrier
	s_add_i32 s26, s61, s39
	v_lshl_add_u64 v[166:167], v[166:167], 0, s[8:9]
	s_mov_b32 m0, s26
	ds_read_b128 v[186:189], v172 offset:49152
	ds_read_b128 v[190:193], v172 offset:50176
	ds_read_b128 v[194:197], v172 offset:51200
	ds_read_b128 v[198:201], v172 offset:52224
	ds_read_b128 v[202:205], v172 offset:53248
	ds_read_b128 v[206:209], v172 offset:54272
	ds_read_b128 v[210:213], v172 offset:55296
	ds_read_b128 v[214:217], v172 offset:56320
	global_load_lds_dwordx4 v[166:167], off
	s_add_i32 m0, s26, 0x2000
	s_add_u32 s26, s28, 0x80080
	v_lshl_add_u64 v[166:167], v[218:219], 0, s[8:9]
	s_addc_u32 s27, s29, 0
	s_add_i32 s28, s62, s39
	global_load_lds_dwordx4 v[166:167], off
	v_lshl_add_u64 v[166:167], s[26:27], 0, v[146:147]
	s_mov_b32 m0, s28
	s_nop 0
	global_load_lds_dwordx4 v[166:167], off
	v_lshl_add_u64 v[166:167], s[26:27], 0, v[150:151]
	s_add_i32 m0, s28, 0x2000
	s_nop 0
	global_load_lds_dwordx4 v[166:167], off
	v_lshl_add_u64 v[166:167], v[220:221], 0, s[8:9]
	s_mov_b32 m0, s47
	s_nop 0
	global_load_lds_dwordx4 v[166:167], off
	v_lshl_add_u64 v[166:167], v[222:223], 0, s[8:9]
	s_mov_b32 m0, s48
	s_nop 0
	global_load_lds_dwordx4 v[166:167], off
	s_waitcnt vmcnt(8)
	s_waitcnt lgkmcnt(0)
	s_setprio 1
	s_barrier
	v_mfma_f32_16x16x32_bf16 v[60:63], v[128:131], v[186:189], v[60:63]
	v_mfma_f32_16x16x32_bf16 v[56:59], v[136:139], v[186:189], v[56:59]
	v_mfma_f32_16x16x32_bf16 v[48:51], v[128:131], v[194:197], v[48:51]
	v_mfma_f32_16x16x32_bf16 v[40:43], v[136:139], v[194:197], v[40:43]
	v_mfma_f32_16x16x32_bf16 v[32:35], v[128:131], v[202:205], v[32:35]
	v_mfma_f32_16x16x32_bf16 v[24:27], v[136:139], v[202:205], v[24:27]
	v_mfma_f32_16x16x32_bf16 v[16:19], v[128:131], v[210:213], v[16:19]
	v_mfma_f32_16x16x32_bf16 v[8:11], v[136:139], v[210:213], v[8:11]
	v_mfma_f32_16x16x32_bf16 v[60:63], v[132:135], v[190:193], v[60:63]
	v_mfma_f32_16x16x32_bf16 v[56:59], v[140:143], v[190:193], v[56:59]
	v_mfma_f32_16x16x32_bf16 v[48:51], v[132:135], v[198:201], v[48:51]
	v_mfma_f32_16x16x32_bf16 v[40:43], v[140:143], v[198:201], v[40:43]
	v_mfma_f32_16x16x32_bf16 v[32:35], v[132:135], v[206:209], v[32:35]
	v_mfma_f32_16x16x32_bf16 v[24:27], v[140:143], v[206:209], v[24:27]
	v_mfma_f32_16x16x32_bf16 v[16:19], v[132:135], v[214:217], v[16:19]
	v_mfma_f32_16x16x32_bf16 v[8:11], v[140:143], v[214:217], v[8:11]
	v_mfma_f32_16x16x32_bf16 v[52:55], v[162:165], v[186:189], v[52:55]
	v_mfma_f32_16x16x32_bf16 v[44:47], v[178:181], v[186:189], v[44:47]
	v_mfma_f32_16x16x32_bf16 v[36:39], v[162:165], v[194:197], v[36:39]
	v_mfma_f32_16x16x32_bf16 v[28:31], v[178:181], v[194:197], v[28:31]
	v_mfma_f32_16x16x32_bf16 v[20:23], v[162:165], v[202:205], v[20:23]
	v_mfma_f32_16x16x32_bf16 v[12:15], v[178:181], v[202:205], v[12:15]
	v_mfma_f32_16x16x32_bf16 v[4:7], v[162:165], v[210:213], v[4:7]
	v_mfma_f32_16x16x32_bf16 v[0:3], v[178:181], v[210:213], v[0:3]
	v_mfma_f32_16x16x32_bf16 v[52:55], v[174:177], v[190:193], v[52:55]
	v_mfma_f32_16x16x32_bf16 v[44:47], v[182:185], v[190:193], v[44:47]
	v_mfma_f32_16x16x32_bf16 v[36:39], v[174:177], v[198:201], v[36:39]
	v_mfma_f32_16x16x32_bf16 v[28:31], v[182:185], v[198:201], v[28:31]
	v_mfma_f32_16x16x32_bf16 v[20:23], v[174:177], v[206:209], v[20:23]
	v_mfma_f32_16x16x32_bf16 v[12:15], v[182:185], v[206:209], v[12:15]
	v_mfma_f32_16x16x32_bf16 v[4:7], v[174:177], v[214:217], v[4:7]
	v_mfma_f32_16x16x32_bf16 v[0:3], v[182:185], v[214:217], v[0:3]
	s_setprio 0
	s_barrier
	s_add_i32 s60, s60, 2
	s_add_u32 s58, s58, 0x100
	s_addc_u32 s59, s59, 0
	s_cmp_gt_u32 s60, 29
	s_mov_b64 s[26:27], s[4:5]
	s_cbranch_scc0 .LBB0_2451

;     __host__ __device__ bool next(int i, Unit& u) const { const bool ok = StaticOrder::next(i, u); u.pm = 0; u.pn = 0; return ok; }
; #define PG8_STAGE(bufoff, gbase, voff) do { _Pragma("unroll") for (int _i = 0; _i < 2; ++_i) \
;         __builtin_amdgcn_global_load_lds((const unsigned*)((const char*)(gbase) + (voff)[_i]), (PG8_LAS unsigned*)(lds + (bufoff) + ldsw + _i * 8192), 16, 0, 0); } while (0)
; #define PG8_LDA(dst, b, h) do { _Pragma("unroll") for (int m = 0; m < 4; ++m) _Pragma("unroll") for (int k = 0; k < 2; ++k) dst[m][k] = *(const PG8_LAS bf16x8*)(lds + PG8_SA(b, h) + aoff + m * 2048 + k * 1024); } while (0)
; #define PG8_LDB(dst, b, h) do { _Pragma("unroll") for (int n = 0; n < 2; ++n) _Pragma("unroll") for (int k = 0; k < 2; ++k) dst[n][k] = *(const PG8_LAS bf16x8*)(lds + PG8_SB(b, h) + boff + n * 2048 + k * 1024); } while (0)
; #define PG8_WAIT_V(n) asm volatile("s_waitcnt vmcnt(" #n ")" ::: "memory")
; #define PG8_WAIT_L(n) asm volatile("s_waitcnt lgkmcnt(" #n ")" ::: "memory")
; #define PG8_BAR __builtin_amdgcn_s_barrier()
; #define PG8_SCHED __builtin_amdgcn_sched_barrier(0)
; template <class Epi, class Sched, bool ALIGN_EPI = false, bool SP2 = false>
; __device__ __forceinline__ void gemm_phase(PG8_LAS unsigned char* lds, const Gemm g, const Sched& S, const Epi& E, const int wave_in) {
;     ...
;         const bool has_next = S.next(ui + 1, nxt);
;         const char* nA = has_next ? (const char*)g.A + (size_t)nxt.pm * tstepA : cA; const char* nB = has_next ? (const char*)g.Bt + (size_t)nxt.pn * tstepB : cB;
;         for (int t = 0; t < nt; t += 2) {
;             const bool last = (t == nt - 2);
;             const char* a1 = cA + (size_t)(t + 1) * kstep;
;             const char* a2 = last ? nA : cA + (size_t)(t + 2) * kstep; const char* b2 = last ? nB : cB + (size_t)(t + 2) * kstep;
;             const char* a3 = a2 + kstep; const char* b3 = b2 + kstep;
;             if (last && has_next) S.a_ready(nxt);
;             if constexpr (SP2) {
;             PG8_LDB(B0, 0, 0); PG8_LDB(B1, 0, 1); PG8_SCHED; PG8_LDA(At, 0, 0); PG8_STAGE(PG8_SA(1, 1), a1 + hstepA, voffA);
;             PG8_WAIT_V(8); PG8_WAIT_L(0); PG8_BAR; PG8_MMA(0, 0, At, B0); PG8_MMA(0, 1, At, B1); PG8_BAR; PG8_SCHED;
;             PG8_LDA(At, 0, 1); PG8_STAGE(PG8_SB(0, 0), b2, voffB); PG8_STAGE(PG8_SB(0, 1), b2 + hstepB, voffB); PG8_STAGE(PG8_SA(0, 0), a2, voffA);
.LBB0_2576:
	s_ashr_i32 s39, s38, 31
	s_lshl_b64 s[40:41], s[38:39], 20
	s_add_u32 s40, s52, s40
	s_addc_u32 s41, s53, s41
	s_and_b64 s[42:43], s[8:9], exec
	s_cselect_b32 s11, s41, s47
	s_cselect_b32 s39, s40, s46
	s_ashr_i32 s37, s36, 31
	s_lshl_b64 s[42:43], s[36:37], 20
	s_add_u32 s42, s54, s42
	s_addc_u32 s43, s55, s43
	s_and_b64 s[50:51], s[8:9], exec
	s_cselect_b32 s37, s43, s49
	s_cselect_b32 s45, s42, s48
	s_add_u32 s46, s46, 0x80080
	s_addc_u32 s47, s47, 0
	s_add_u32 s72, s48, 0x100
	v_mov_b32_e32 v0, 0
	s_addc_u32 s73, s49, 0
	s_mov_b32 s75, -2
	s_waitcnt vmcnt(0)
	ds_read_b128 v[64:67], v189
	ds_read_b128 v[68:71], v189 offset:1024
	ds_read_b128 v[72:75], v189 offset:2048
	ds_read_b128 v[76:79], v189 offset:3072
	ds_read_b128 v[80:83], v197
	ds_read_b128 v[84:87], v197 offset:1024
	ds_read_b128 v[88:91], v197 offset:2048
	ds_read_b128 v[92:95], v197 offset:3072
	s_add_u32 s48, s46, 0xfff80080
	s_addc_u32 s49, s47, -1
	s_cmp_eq_u32 s75, 28
	s_cselect_b32 s51, s11, s49
	s_cselect_b32 s50, s39, s48
	s_cselect_b32 s49, s37, s73
	s_cselect_b32 s48, s45, s72
	v_lshl_add_u64 v[224:225], s[46:47], 0, v[206:207]
	s_add_i32 m0, s57, 0xc000
	ds_read_b128 v[96:99], v199
	ds_read_b128 v[100:103], v199 offset:1024
	ds_read_b128 v[104:107], v199 offset:2048
	ds_read_b128 v[108:111], v199 offset:3072
	ds_read_b128 v[176:179], v199 offset:4096
	ds_read_b128 v[212:215], v199 offset:5120
	ds_read_b128 v[216:219], v199 offset:6144
	ds_read_b128 v[220:223], v199 offset:7168
	global_load_lds_dwordx4 v[224:225], off
	v_lshl_add_u64 v[224:225], s[46:47], 0, v[208:209]
	s_add_i32 m0, s57, 0xe000
	s_nop 0
	global_load_lds_dwordx4 v[224:225], off
	s_waitcnt vmcnt(8)
	s_waitcnt lgkmcnt(0)
	s_setprio 1
	s_barrier
	v_mfma_f32_16x16x32_bf16 v[172:175], v[64:67], v[96:99], 0
	v_mfma_f32_16x16x32_bf16 v[164:167], v[72:75], v[96:99], 0
	v_mfma_f32_16x16x32_bf16 v[156:159], v[64:67], v[104:107], 0
	v_mfma_f32_16x16x32_bf16 v[148:151], v[72:75], v[104:107], 0
	v_mfma_f32_16x16x32_bf16 v[140:143], v[64:67], v[176:179], 0
	v_mfma_f32_16x16x32_bf16 v[132:135], v[72:75], v[176:179], 0
	v_mfma_f32_16x16x32_bf16 v[124:127], v[64:67], v[216:219], 0
	v_mfma_f32_16x16x32_bf16 v[120:123], v[72:75], v[216:219], 0
	v_mfma_f32_16x16x32_bf16 v[172:175], v[68:71], v[100:103], v[172:175]
	v_mfma_f32_16x16x32_bf16 v[164:167], v[76:79], v[100:103], v[164:167]
	v_mfma_f32_16x16x32_bf16 v[156:159], v[68:71], v[108:111], v[156:159]
	v_mfma_f32_16x16x32_bf16 v[148:151], v[76:79], v[108:111], v[148:151]
	v_mfma_f32_16x16x32_bf16 v[140:143], v[68:71], v[212:215], v[140:143]
	v_mfma_f32_16x16x32_bf16 v[132:135], v[76:79], v[212:215], v[132:135]
	v_mfma_f32_16x16x32_bf16 v[124:127], v[68:71], v[220:223], v[124:127]
	v_mfma_f32_16x16x32_bf16 v[120:123], v[76:79], v[220:223], v[120:123]
	v_mfma_f32_16x16x32_bf16 v[168:171], v[80:83], v[96:99], 0
	v_mfma_f32_16x16x32_bf16 v[96:99], v[88:91], v[96:99], 0
	v_mfma_f32_16x16x32_bf16 v[168:171], v[84:87], v[100:103], v[168:171]
	v_mfma_f32_16x16x32_bf16 v[96:99], v[92:95], v[100:103], v[96:99]
	v_mfma_f32_16x16x32_bf16 v[100:103], v[80:83], v[104:107], 0
	v_mfma_f32_16x16x32_bf16 v[104:107], v[88:91], v[104:107], 0
	v_mfma_f32_16x16x32_bf16 v[128:131], v[88:91], v[176:179], 0
	v_mfma_f32_16x16x32_bf16 v[116:119], v[80:83], v[216:219], 0
	v_mfma_f32_16x16x32_bf16 v[112:115], v[88:91], v[216:219], 0
	v_mfma_f32_16x16x32_bf16 v[100:103], v[84:87], v[108:111], v[100:103]
	v_mfma_f32_16x16x32_bf16 v[104:107], v[92:95], v[108:111], v[104:107]
	v_mfma_f32_16x16x32_bf16 v[108:111], v[80:83], v[176:179], 0
	v_mfma_f32_16x16x32_bf16 v[128:131], v[92:95], v[212:215], v[128:131]
	v_mfma_f32_16x16x32_bf16 v[116:119], v[84:87], v[220:223], v[116:119]
	v_mfma_f32_16x16x32_bf16 v[112:115], v[92:95], v[220:223], v[112:115]
	v_mfma_f32_16x16x32_bf16 v[108:111], v[84:87], v[212:215], v[108:111]
	s_setprio 0
	s_barrier
	s_add_i32 s76, s69, s56
	v_lshl_add_u64 v[232:233], s[48:49], 0, v[182:183]
	s_mov_b32 m0, s76
	ds_read_b128 v[136:139], v199 offset:16384
	ds_read_b128 v[144:147], v199 offset:17408
	ds_read_b128 v[152:155], v199 offset:18432
	ds_read_b128 v[160:163], v199 offset:19456
	ds_read_b128 v[176:179], v199 offset:20480
	ds_read_b128 v[212:215], v199 offset:21504
	ds_read_b128 v[216:219], v199 offset:22528
	ds_read_b128 v[220:223], v199 offset:23552
	global_load_lds_dwordx4 v[232:233], off
	s_add_i32 m0, s76, 0x2000
	s_add_u32 s76, s48, 0x80000
	v_lshl_add_u64 v[234:235], s[48:49], 0, v[186:187]
	s_addc_u32 s77, s49, 0
	s_add_i32 s78, s70, s56
	global_load_lds_dwordx4 v[234:235], off
	v_lshl_add_u64 v[224:225], s[76:77], 0, v[182:183]
	s_mov_b32 m0, s78
	v_lshl_add_u64 v[236:237], s[50:51], 0, v[180:181]
	global_load_lds_dwordx4 v[224:225], off
	v_lshl_add_u64 v[224:225], s[76:77], 0, v[186:187]
	s_add_i32 m0, s78, 0x2000
	v_lshl_add_u64 v[238:239], s[50:51], 0, v[184:185]
	global_load_lds_dwordx4 v[224:225], off
	s_mov_b32 m0, s57
	s_nop 0
	global_load_lds_dwordx4 v[236:237], off
	s_mov_b32 m0, s58
	s_nop 0
	global_load_lds_dwordx4 v[238:239], off
	s_waitcnt vmcnt(8)
	s_waitcnt lgkmcnt(0)
	s_setprio 1
	s_barrier
; #define PG8_STAGE(bufoff, gbase, voff) do { _Pragma("unroll") for (int _i = 0; _i < 2; ++_i) \
;         __builtin_amdgcn_global_load_lds((const unsigned*)((const char*)(gbase) + (voff)[_i]), (PG8_LAS unsigned*)(lds + (bufoff) + ldsw + _i * 8192), 16, 0, 0); } while (0)
; #define PG8_LDA(dst, b, h) do { _Pragma("unroll") for (int m = 0; m < 4; ++m) _Pragma("unroll") for (int k = 0; k < 2; ++k) dst[m][k] = *(const PG8_LAS bf16x8*)(lds + PG8_SA(b, h) + aoff + m * 2048 + k * 1024); } while (0)
; #define PG8_LDB(dst, b, h) do { _Pragma("unroll") for (int n = 0; n < 2; ++n) _Pragma("unroll") for (int k = 0; k < 2; ++k) dst[n][k] = *(const PG8_LAS bf16x8*)(lds + PG8_SB(b, h) + boff + n * 2048 + k * 1024); } while (0)
; #define PG8_MMA(ai, bj, At, Bt) do { __builtin_amdgcn_s_setprio(1); _Pragma("unroll") for (int m = 0; m < 4; ++m) _Pragma("unroll") for (int n = 0; n < 2; ++n) _Pragma("unroll") for (int k = 0; k < 2; ++k) \
;         acc[ai][bj][m][n] = __builtin_amdgcn_mfma_f32_16x16x32_bf16(Bt[n][k], At[m][k], acc[ai][bj][m][n], 0, 0, 0); __builtin_amdgcn_s_setprio(0); } while (0)
; #define PG8_WAIT_V(n) asm volatile("s_waitcnt vmcnt(" #n ")" ::: "memory")
; #define PG8_WAIT_L(n) asm volatile("s_waitcnt lgkmcnt(" #n ")" ::: "memory")
; #define PG8_BAR __builtin_amdgcn_s_barrier()
; #define PG8_SCHED __builtin_amdgcn_sched_barrier(0)
; template <class Epi, class Sched, bool ALIGN_EPI = false, bool SP2 = false>
; __device__ __forceinline__ void gemm_phase(PG8_LAS unsigned char* lds, const Gemm g, const Sched& S, const Epi& E, const int wave_in) {
;     ...
;             PG8_WAIT_V(8); PG8_WAIT_L(0); PG8_BAR; PG8_MMA(1, 0, At, B0); PG8_MMA(1, 1, At, B1); PG8_BAR; PG8_SCHED;
;             PG8_LDB(B0, 1, 0); PG8_LDB(B1, 1, 1); PG8_SCHED; PG8_LDA(At, 1, 0); PG8_STAGE(PG8_SA(0, 1), a2 + hstepA, voffA);
;             PG8_WAIT_V(8); PG8_WAIT_L(0); PG8_BAR; PG8_MMA(0, 0, At, B0); PG8_MMA(0, 1, At, B1); PG8_BAR; PG8_SCHED;
	v_mfma_f32_16x16x32_bf16 v[60:63], v[64:67], v[136:139], 0
	v_mfma_f32_16x16x32_bf16 v[52:55], v[72:75], v[136:139], 0
	v_mfma_f32_16x16x32_bf16 v[44:47], v[64:67], v[152:155], 0
	v_mfma_f32_16x16x32_bf16 v[36:39], v[72:75], v[152:155], 0
	v_mfma_f32_16x16x32_bf16 v[28:31], v[64:67], v[176:179], 0
	v_mfma_f32_16x16x32_bf16 v[20:23], v[72:75], v[176:179], 0
	v_mfma_f32_16x16x32_bf16 v[12:15], v[64:67], v[216:219], 0
	v_mfma_f32_16x16x32_bf16 v[8:11], v[72:75], v[216:219], 0
	v_mfma_f32_16x16x32_bf16 v[60:63], v[68:71], v[144:147], v[60:63]
	v_mfma_f32_16x16x32_bf16 v[52:55], v[76:79], v[144:147], v[52:55]
	v_mfma_f32_16x16x32_bf16 v[44:47], v[68:71], v[160:163], v[44:47]
	v_mfma_f32_16x16x32_bf16 v[36:39], v[76:79], v[160:163], v[36:39]
	v_mfma_f32_16x16x32_bf16 v[28:31], v[68:71], v[212:215], v[28:31]
	v_mfma_f32_16x16x32_bf16 v[20:23], v[76:79], v[212:215], v[20:23]
	v_mfma_f32_16x16x32_bf16 v[12:15], v[68:71], v[220:223], v[12:15]
	v_mfma_f32_16x16x32_bf16 v[8:11], v[76:79], v[220:223], v[8:11]
	v_mfma_f32_16x16x32_bf16 v[56:59], v[80:83], v[136:139], 0
	v_mfma_f32_16x16x32_bf16 v[48:51], v[88:91], v[136:139], 0
	v_mfma_f32_16x16x32_bf16 v[40:43], v[80:83], v[152:155], 0
	v_mfma_f32_16x16x32_bf16 v[32:35], v[88:91], v[152:155], 0
	v_mfma_f32_16x16x32_bf16 v[24:27], v[80:83], v[176:179], 0
	v_mfma_f32_16x16x32_bf16 v[16:19], v[88:91], v[176:179], 0
	v_mfma_f32_16x16x32_bf16 v[4:7], v[80:83], v[216:219], 0
	v_mfma_f32_16x16x32_bf16 v[0:3], v[88:91], v[216:219], 0
	v_mfma_f32_16x16x32_bf16 v[56:59], v[84:87], v[144:147], v[56:59]
	v_mfma_f32_16x16x32_bf16 v[48:51], v[92:95], v[144:147], v[48:51]
	v_mfma_f32_16x16x32_bf16 v[40:43], v[84:87], v[160:163], v[40:43]
	v_mfma_f32_16x16x32_bf16 v[32:35], v[92:95], v[160:163], v[32:35]
	v_mfma_f32_16x16x32_bf16 v[24:27], v[84:87], v[212:215], v[24:27]
	v_mfma_f32_16x16x32_bf16 v[16:19], v[92:95], v[212:215], v[16:19]
	v_mfma_f32_16x16x32_bf16 v[4:7], v[84:87], v[220:223], v[4:7]
	v_mfma_f32_16x16x32_bf16 v[0:3], v[92:95], v[220:223], v[0:3]
	s_setprio 0
	s_barrier
	s_add_i32 s76, 0, 0x18000
	s_add_i32 s77, 0, 0x1c000
	v_add_u32_e32 v76, s76, v195
	v_add_u32_e32 v92, s77, v195
	ds_read_b128 v[64:67], v76
	ds_read_b128 v[68:71], v76 offset:1024
	ds_read_b128 v[72:75], v76 offset:2048
	ds_read_b128 v[76:79], v76 offset:3072
	ds_read_b128 v[80:83], v92
	ds_read_b128 v[84:87], v92 offset:1024
	ds_read_b128 v[88:91], v92 offset:2048
	ds_read_b128 v[92:95], v92 offset:3072
	s_add_u32 s50, s50, 0x80000
	s_addc_u32 s51, s51, 0
	s_mov_b32 m0, s59
	v_lshl_add_u64 v[152:153], s[50:51], 0, v[180:181]
	ds_read_b128 v[136:139], v199 offset:32768
	ds_read_b128 v[144:147], v199 offset:33792
	ds_read_b128 v[176:179], v199 offset:34816
	ds_read_b128 v[212:215], v199 offset:35840
	ds_read_b128 v[216:219], v199 offset:36864
	ds_read_b128 v[220:223], v199 offset:37888
	ds_read_b128 v[224:227], v199 offset:38912
	ds_read_b128 v[228:231], v199 offset:39936
	global_load_lds_dwordx4 v[152:153], off
	v_lshl_add_u64 v[152:153], s[50:51], 0, v[184:185]
	s_mov_b32 m0, s60
	s_nop 0
	global_load_lds_dwordx4 v[152:153], off
	s_waitcnt vmcnt(8)
	s_waitcnt lgkmcnt(0)
	s_setprio 1
	s_barrier
	v_mfma_f32_16x16x32_bf16 v[152:155], v[64:67], v[136:139], v[172:175]
	v_mfma_f32_16x16x32_bf16 v[172:175], v[68:71], v[144:147], v[152:155]
	v_mfma_f32_16x16x32_bf16 v[152:155], v[72:75], v[136:139], v[164:167]
	v_mfma_f32_16x16x32_bf16 v[164:167], v[76:79], v[144:147], v[152:155]
	v_mfma_f32_16x16x32_bf16 v[152:155], v[64:67], v[176:179], v[156:159]
	v_mfma_f32_16x16x32_bf16 v[148:151], v[72:75], v[176:179], v[148:151]
	v_mfma_f32_16x16x32_bf16 v[140:143], v[64:67], v[216:219], v[140:143]
	v_mfma_f32_16x16x32_bf16 v[132:135], v[72:75], v[216:219], v[132:135]
	v_mfma_f32_16x16x32_bf16 v[124:127], v[64:67], v[224:227], v[124:127]
	v_mfma_f32_16x16x32_bf16 v[120:123], v[72:75], v[224:227], v[120:123]
	v_mfma_f32_16x16x32_bf16 v[156:159], v[68:71], v[212:215], v[152:155]
	v_mfma_f32_16x16x32_bf16 v[148:151], v[76:79], v[212:215], v[148:151]
	v_mfma_f32_16x16x32_bf16 v[140:143], v[68:71], v[220:223], v[140:143]
	v_mfma_f32_16x16x32_bf16 v[132:135], v[76:79], v[220:223], v[132:135]
	v_mfma_f32_16x16x32_bf16 v[124:127], v[68:71], v[228:231], v[124:127]
	v_mfma_f32_16x16x32_bf16 v[120:123], v[76:79], v[228:231], v[120:123]
	v_mfma_f32_16x16x32_bf16 v[96:99], v[88:91], v[136:139], v[96:99]
	v_mfma_f32_16x16x32_bf16 v[152:155], v[80:83], v[136:139], v[168:171]
	v_mfma_f32_16x16x32_bf16 v[160:163], v[92:95], v[144:147], v[96:99]
	v_mfma_f32_16x16x32_bf16 v[96:99], v[80:83], v[176:179], v[100:103]
	v_mfma_f32_16x16x32_bf16 v[168:171], v[84:87], v[144:147], v[152:155]
	v_mfma_f32_16x16x32_bf16 v[152:155], v[84:87], v[212:215], v[96:99]
	v_mfma_f32_16x16x32_bf16 v[96:99], v[88:91], v[176:179], v[104:107]
	v_mfma_f32_16x16x32_bf16 v[144:147], v[92:95], v[212:215], v[96:99]
	v_mfma_f32_16x16x32_bf16 v[96:99], v[80:83], v[216:219], v[108:111]
	v_mfma_f32_16x16x32_bf16 v[136:139], v[84:87], v[220:223], v[96:99]
	v_mfma_f32_16x16x32_bf16 v[96:99], v[88:91], v[216:219], v[128:131]
	v_mfma_f32_16x16x32_bf16 v[128:131], v[92:95], v[220:223], v[96:99]
	v_mfma_f32_16x16x32_bf16 v[96:99], v[80:83], v[224:227], v[116:119]
	v_mfma_f32_16x16x32_bf16 v[116:119], v[84:87], v[228:231], v[96:99]
	v_mfma_f32_16x16x32_bf16 v[96:99], v[88:91], v[224:227], v[112:115]
	v_mfma_f32_16x16x32_bf16 v[112:115], v[92:95], v[228:231], v[96:99]
	s_setprio 0
	s_barrier
; #define PG8_STAGE(bufoff, gbase, voff) do { _Pragma("unroll") for (int _i = 0; _i < 2; ++_i) \
;         __builtin_amdgcn_global_load_lds((const unsigned*)((const char*)(gbase) + (voff)[_i]), (PG8_LAS unsigned*)(lds + (bufoff) + ldsw + _i * 8192), 16, 0, 0); } while (0)
; #define PG8_LDA(dst, b, h) do { _Pragma("unroll") for (int m = 0; m < 4; ++m) _Pragma("unroll") for (int k = 0; k < 2; ++k) dst[m][k] = *(const PG8_LAS bf16x8*)(lds + PG8_SA(b, h) + aoff + m * 2048 + k * 1024); } while (0)
; #define PG8_LDB(dst, b, h) do { _Pragma("unroll") for (int n = 0; n < 2; ++n) _Pragma("unroll") for (int k = 0; k < 2; ++k) dst[n][k] = *(const PG8_LAS bf16x8*)(lds + PG8_SB(b, h) + boff + n * 2048 + k * 1024); } while (0)
; #define PG8_MMA(ai, bj, At, Bt) do { __builtin_amdgcn_s_setprio(1); _Pragma("unroll") for (int m = 0; m < 4; ++m) _Pragma("unroll") for (int n = 0; n < 2; ++n) _Pragma("unroll") for (int k = 0; k < 2; ++k) \
;         acc[ai][bj][m][n] = __builtin_amdgcn_mfma_f32_16x16x32_bf16(Bt[n][k], At[m][k], acc[ai][bj][m][n], 0, 0, 0); __builtin_amdgcn_s_setprio(0); } while (0)
; #define PG8_WAIT_V(n) asm volatile("s_waitcnt vmcnt(" #n ")" ::: "memory")
; #define PG8_WAIT_L(n) asm volatile("s_waitcnt lgkmcnt(" #n ")" ::: "memory")
; #define PG8_BAR __builtin_amdgcn_s_barrier()
; #define PG8_SCHED __builtin_amdgcn_sched_barrier(0)
; template <class Epi, class Sched, bool ALIGN_EPI = false, bool SP2 = false>
; __device__ __forceinline__ void gemm_phase(PG8_LAS unsigned char* lds, const Gemm g, const Sched& S, const Epi& E, const int wave_in) {
;     ...
;             PG8_LDB(B0, 0, 0); PG8_LDB(B1, 0, 1); PG8_SCHED; PG8_LDA(At, 0, 0); PG8_STAGE(PG8_SA(1, 1), a1 + hstepA, voffA);
;     ...
;             PG8_LDA(At, 1, 1); PG8_STAGE(PG8_SB(1, 0), b3, voffB); PG8_STAGE(PG8_SB(1, 1), b3 + hstepB, voffB); PG8_STAGE(PG8_SA(1, 0), a3, voffA);
;             PG8_WAIT_V(8); PG8_WAIT_L(0); PG8_BAR; PG8_MMA(1, 0, At, B0); PG8_MMA(1, 1, At, B1); PG8_BAR; PG8_SCHED;
	s_add_i32 s50, s76, s56
	v_lshl_add_u64 v[224:225], v[232:233], 0, s[20:21]
	s_mov_b32 m0, s50
	s_nop 1
	ds_read_b128 v[96:99], v199 offset:49152
	ds_read_b128 v[100:103], v199 offset:50176
	ds_read_b128 v[104:107], v199 offset:51200
	ds_read_b128 v[108:111], v199 offset:52224
	ds_read_b128 v[176:179], v199 offset:53248
	ds_read_b128 v[212:215], v199 offset:54272
	ds_read_b128 v[216:219], v199 offset:55296
	ds_read_b128 v[220:223], v199 offset:56320
	global_load_lds_dwordx4 v[224:225], off
	s_add_i32 m0, s50, 0x2000
	s_add_u32 s48, s48, 0x80080
	v_lshl_add_u64 v[224:225], v[234:235], 0, s[20:21]
	s_addc_u32 s49, s49, 0
	s_add_i32 s50, s77, s56
	global_load_lds_dwordx4 v[224:225], off
	v_lshl_add_u64 v[224:225], s[48:49], 0, v[182:183]
	s_mov_b32 m0, s50
	s_nop 0
	global_load_lds_dwordx4 v[224:225], off
	v_lshl_add_u64 v[224:225], s[48:49], 0, v[186:187]
	s_add_i32 m0, s50, 0x2000
	s_nop 0
	global_load_lds_dwordx4 v[224:225], off
	v_lshl_add_u64 v[224:225], v[236:237], 0, s[20:21]
	s_mov_b32 m0, s63
	s_nop 0
	global_load_lds_dwordx4 v[224:225], off
	v_lshl_add_u64 v[224:225], v[238:239], 0, s[20:21]
	s_mov_b32 m0, s64
	s_nop 0
	global_load_lds_dwordx4 v[224:225], off
	s_waitcnt vmcnt(8)
	s_waitcnt lgkmcnt(0)
	s_setprio 1
	s_barrier
	v_mfma_f32_16x16x32_bf16 v[60:63], v[64:67], v[96:99], v[60:63]
	v_mfma_f32_16x16x32_bf16 v[52:55], v[72:75], v[96:99], v[52:55]
	v_mfma_f32_16x16x32_bf16 v[44:47], v[64:67], v[104:107], v[44:47]
	v_mfma_f32_16x16x32_bf16 v[36:39], v[72:75], v[104:107], v[36:39]
	v_mfma_f32_16x16x32_bf16 v[28:31], v[64:67], v[176:179], v[28:31]
	v_mfma_f32_16x16x32_bf16 v[20:23], v[72:75], v[176:179], v[20:23]
	v_mfma_f32_16x16x32_bf16 v[12:15], v[64:67], v[216:219], v[12:15]
	v_mfma_f32_16x16x32_bf16 v[8:11], v[72:75], v[216:219], v[8:11]
	v_mfma_f32_16x16x32_bf16 v[60:63], v[68:71], v[100:103], v[60:63]
	v_mfma_f32_16x16x32_bf16 v[52:55], v[76:79], v[100:103], v[52:55]
	v_mfma_f32_16x16x32_bf16 v[44:47], v[68:71], v[108:111], v[44:47]
	v_mfma_f32_16x16x32_bf16 v[36:39], v[76:79], v[108:111], v[36:39]
	v_mfma_f32_16x16x32_bf16 v[28:31], v[68:71], v[212:215], v[28:31]
	v_mfma_f32_16x16x32_bf16 v[20:23], v[76:79], v[212:215], v[20:23]
	v_mfma_f32_16x16x32_bf16 v[12:15], v[68:71], v[220:223], v[12:15]
	v_mfma_f32_16x16x32_bf16 v[8:11], v[76:79], v[220:223], v[8:11]
	v_mfma_f32_16x16x32_bf16 v[56:59], v[80:83], v[96:99], v[56:59]
	v_mfma_f32_16x16x32_bf16 v[48:51], v[88:91], v[96:99], v[48:51]
	v_mfma_f32_16x16x32_bf16 v[40:43], v[80:83], v[104:107], v[40:43]
	v_mfma_f32_16x16x32_bf16 v[32:35], v[88:91], v[104:107], v[32:35]
	v_mfma_f32_16x16x32_bf16 v[24:27], v[80:83], v[176:179], v[24:27]
	v_mfma_f32_16x16x32_bf16 v[16:19], v[88:91], v[176:179], v[16:19]
	v_mfma_f32_16x16x32_bf16 v[4:7], v[80:83], v[216:219], v[4:7]
	v_mfma_f32_16x16x32_bf16 v[0:3], v[88:91], v[216:219], v[0:3]
	v_mfma_f32_16x16x32_bf16 v[56:59], v[84:87], v[100:103], v[56:59]
	v_mfma_f32_16x16x32_bf16 v[48:51], v[92:95], v[100:103], v[48:51]
	v_mfma_f32_16x16x32_bf16 v[40:43], v[84:87], v[108:111], v[40:43]
	v_mfma_f32_16x16x32_bf16 v[32:35], v[92:95], v[108:111], v[32:35]
	v_mfma_f32_16x16x32_bf16 v[24:27], v[84:87], v[212:215], v[24:27]
	v_mfma_f32_16x16x32_bf16 v[16:19], v[92:95], v[212:215], v[16:19]
	v_mfma_f32_16x16x32_bf16 v[4:7], v[84:87], v[220:223], v[4:7]
	v_mfma_f32_16x16x32_bf16 v[0:3], v[92:95], v[220:223], v[0:3]
	s_setprio 0
	s_barrier
	s_add_i32 s75, s75, 2
	s_add_u32 s46, s46, 0x100
	s_addc_u32 s47, s47, 0
	s_add_u32 s72, s72, 0x100
	s_addc_u32 s73, s73, 0
	s_cmp_gt_u32 s75, 29
	s_cbranch_scc0 .LBB0_2577
	s_branch .Lkx_30
.LBB0_2577:
	ds_read_b128 v[64:67], v189
	ds_read_b128 v[68:71], v189 offset:1024
	ds_read_b128 v[72:75], v189 offset:2048
	ds_read_b128 v[76:79], v189 offset:3072
	ds_read_b128 v[80:83], v197
	ds_read_b128 v[84:87], v197 offset:1024
	ds_read_b128 v[88:91], v197 offset:2048
	ds_read_b128 v[92:95], v197 offset:3072
	s_add_u32 s48, s46, 0xfff80080
	s_addc_u32 s49, s47, -1
	s_cmp_eq_u32 s75, 28
	s_cselect_b32 s51, s11, s49
	s_cselect_b32 s50, s39, s48
	s_cselect_b32 s49, s37, s73
	s_cselect_b32 s48, s45, s72
	v_lshl_add_u64 v[224:225], s[46:47], 0, v[206:207]
	s_add_i32 m0, s57, 0xc000
	ds_read_b128 v[96:99], v199
	ds_read_b128 v[100:103], v199 offset:1024
	ds_read_b128 v[104:107], v199 offset:2048
	ds_read_b128 v[108:111], v199 offset:3072
	ds_read_b128 v[176:179], v199 offset:4096
	ds_read_b128 v[212:215], v199 offset:5120
	ds_read_b128 v[216:219], v199 offset:6144
	ds_read_b128 v[220:223], v199 offset:7168
	global_load_lds_dwordx4 v[224:225], off
	v_lshl_add_u64 v[224:225], s[46:47], 0, v[208:209]
	s_add_i32 m0, s57, 0xe000
	s_nop 0
	global_load_lds_dwordx4 v[224:225], off
	s_waitcnt vmcnt(8)
	s_waitcnt lgkmcnt(0)
	s_setprio 1
	s_barrier
; #define PG8_STAGE(bufoff, gbase, voff) do { _Pragma("unroll") for (int _i = 0; _i < 2; ++_i) \
;         __builtin_amdgcn_global_load_lds((const unsigned*)((const char*)(gbase) + (voff)[_i]), (PG8_LAS unsigned*)(lds + (bufoff) + ldsw + _i * 8192), 16, 0, 0); } while (0)
; #define PG8_LDA(dst, b, h) do { _Pragma("unroll") for (int m = 0; m < 4; ++m) _Pragma("unroll") for (int k = 0; k < 2; ++k) dst[m][k] = *(const PG8_LAS bf16x8*)(lds + PG8_SA(b, h) + aoff + m * 2048 + k * 1024); } while (0)
; #define PG8_LDB(dst, b, h) do { _Pragma("unroll") for (int n = 0; n < 2; ++n) _Pragma("unroll") for (int k = 0; k < 2; ++k) dst[n][k] = *(const PG8_LAS bf16x8*)(lds + PG8_SB(b, h) + boff + n * 2048 + k * 1024); } while (0)
; #define PG8_MMA(ai, bj, At, Bt) do { __builtin_amdgcn_s_setprio(1); _Pragma("unroll") for (int m = 0; m < 4; ++m) _Pragma("unroll") for (int n = 0; n < 2; ++n) _Pragma("unroll") for (int k = 0; k < 2; ++k) \
;         acc[ai][bj][m][n] = __builtin_amdgcn_mfma_f32_16x16x32_bf16(Bt[n][k], At[m][k], acc[ai][bj][m][n], 0, 0, 0); __builtin_amdgcn_s_setprio(0); } while (0)
; #define PG8_WAIT_V(n) asm volatile("s_waitcnt vmcnt(" #n ")" ::: "memory")
; #define PG8_WAIT_L(n) asm volatile("s_waitcnt lgkmcnt(" #n ")" ::: "memory")
; #define PG8_BAR __builtin_amdgcn_s_barrier()
; #define PG8_SCHED __builtin_amdgcn_sched_barrier(0)
; template <class Epi, class Sched, bool ALIGN_EPI = false, bool SP2 = false>
; __device__ __forceinline__ void gemm_phase(PG8_LAS unsigned char* lds, const Gemm g, const Sched& S, const Epi& E, const int wave_in) {
;     ...
;             PG8_LDB(B0, 0, 0); PG8_LDB(B1, 0, 1); PG8_SCHED; PG8_LDA(At, 0, 0); PG8_STAGE(PG8_SA(1, 1), a1 + hstepA, voffA);
;             PG8_WAIT_V(8); PG8_WAIT_L(0); PG8_BAR; PG8_MMA(0, 0, At, B0); PG8_MMA(0, 1, At, B1); PG8_BAR; PG8_SCHED;
;             PG8_LDA(At, 0, 1); PG8_STAGE(PG8_SB(0, 0), b2, voffB); PG8_STAGE(PG8_SB(0, 1), b2 + hstepB, voffB); PG8_STAGE(PG8_SA(0, 0), a2, voffA);
;             PG8_WAIT_V(8); PG8_WAIT_L(0); PG8_BAR; PG8_MMA(1, 0, At, B0); PG8_MMA(1, 1, At, B1); PG8_BAR; PG8_SCHED;
	v_mfma_f32_16x16x32_bf16 v[172:175], v[64:67], v[96:99], v[172:175]
	v_mfma_f32_16x16x32_bf16 v[164:167], v[72:75], v[96:99], v[164:167]
	v_mfma_f32_16x16x32_bf16 v[156:159], v[64:67], v[104:107], v[156:159]
	v_mfma_f32_16x16x32_bf16 v[148:151], v[72:75], v[104:107], v[148:151]
	v_mfma_f32_16x16x32_bf16 v[140:143], v[64:67], v[176:179], v[140:143]
	v_mfma_f32_16x16x32_bf16 v[132:135], v[72:75], v[176:179], v[132:135]
	v_mfma_f32_16x16x32_bf16 v[124:127], v[64:67], v[216:219], v[124:127]
	v_mfma_f32_16x16x32_bf16 v[120:123], v[72:75], v[216:219], v[120:123]
	v_mfma_f32_16x16x32_bf16 v[172:175], v[68:71], v[100:103], v[172:175]
	v_mfma_f32_16x16x32_bf16 v[164:167], v[76:79], v[100:103], v[164:167]
	v_mfma_f32_16x16x32_bf16 v[156:159], v[68:71], v[108:111], v[156:159]
	v_mfma_f32_16x16x32_bf16 v[148:151], v[76:79], v[108:111], v[148:151]
	v_mfma_f32_16x16x32_bf16 v[140:143], v[68:71], v[212:215], v[140:143]
	v_mfma_f32_16x16x32_bf16 v[132:135], v[76:79], v[212:215], v[132:135]
	v_mfma_f32_16x16x32_bf16 v[124:127], v[68:71], v[220:223], v[124:127]
	v_mfma_f32_16x16x32_bf16 v[120:123], v[76:79], v[220:223], v[120:123]
	v_mfma_f32_16x16x32_bf16 v[168:171], v[80:83], v[96:99], v[168:171]
	v_mfma_f32_16x16x32_bf16 v[96:99], v[88:91], v[96:99], v[160:163]
	v_mfma_f32_16x16x32_bf16 v[168:171], v[84:87], v[100:103], v[168:171]
	v_mfma_f32_16x16x32_bf16 v[96:99], v[92:95], v[100:103], v[96:99]
	v_mfma_f32_16x16x32_bf16 v[100:103], v[80:83], v[104:107], v[152:155]
	v_mfma_f32_16x16x32_bf16 v[104:107], v[88:91], v[104:107], v[144:147]
	v_mfma_f32_16x16x32_bf16 v[128:131], v[88:91], v[176:179], v[128:131]
	v_mfma_f32_16x16x32_bf16 v[116:119], v[80:83], v[216:219], v[116:119]
	v_mfma_f32_16x16x32_bf16 v[112:115], v[88:91], v[216:219], v[112:115]
	v_mfma_f32_16x16x32_bf16 v[100:103], v[84:87], v[108:111], v[100:103]
	v_mfma_f32_16x16x32_bf16 v[104:107], v[92:95], v[108:111], v[104:107]
	v_mfma_f32_16x16x32_bf16 v[108:111], v[80:83], v[176:179], v[136:139]
	v_mfma_f32_16x16x32_bf16 v[128:131], v[92:95], v[212:215], v[128:131]
	v_mfma_f32_16x16x32_bf16 v[116:119], v[84:87], v[220:223], v[116:119]
	v_mfma_f32_16x16x32_bf16 v[112:115], v[92:95], v[220:223], v[112:115]
	v_mfma_f32_16x16x32_bf16 v[108:111], v[84:87], v[212:215], v[108:111]
	s_setprio 0
	s_barrier
	s_add_i32 s76, s69, s56
	v_lshl_add_u64 v[232:233], s[48:49], 0, v[182:183]
	s_mov_b32 m0, s76
	ds_read_b128 v[136:139], v199 offset:16384
	ds_read_b128 v[144:147], v199 offset:17408
	ds_read_b128 v[152:155], v199 offset:18432
	ds_read_b128 v[160:163], v199 offset:19456
	ds_read_b128 v[176:179], v199 offset:20480
	ds_read_b128 v[212:215], v199 offset:21504
	ds_read_b128 v[216:219], v199 offset:22528
	ds_read_b128 v[220:223], v199 offset:23552
	global_load_lds_dwordx4 v[232:233], off
	s_add_i32 m0, s76, 0x2000
	s_add_u32 s76, s48, 0x80000
	v_lshl_add_u64 v[234:235], s[48:49], 0, v[186:187]
	s_addc_u32 s77, s49, 0
	s_add_i32 s78, s70, s56
	global_load_lds_dwordx4 v[234:235], off
	v_lshl_add_u64 v[224:225], s[76:77], 0, v[182:183]
	s_mov_b32 m0, s78
	v_lshl_add_u64 v[236:237], s[50:51], 0, v[180:181]
	global_load_lds_dwordx4 v[224:225], off
	v_lshl_add_u64 v[224:225], s[76:77], 0, v[186:187]
	s_add_i32 m0, s78, 0x2000
	v_lshl_add_u64 v[238:239], s[50:51], 0, v[184:185]
	global_load_lds_dwordx4 v[224:225], off
	s_mov_b32 m0, s57
	s_nop 0
	global_load_lds_dwordx4 v[236:237], off
	s_mov_b32 m0, s58
	s_nop 0
	global_load_lds_dwordx4 v[238:239], off
	s_waitcnt vmcnt(8)
	s_waitcnt lgkmcnt(0)
	s_setprio 1
	s_barrier
	v_mfma_f32_16x16x32_bf16 v[60:63], v[64:67], v[136:139], v[60:63]
	v_mfma_f32_16x16x32_bf16 v[52:55], v[72:75], v[136:139], v[52:55]
	v_mfma_f32_16x16x32_bf16 v[44:47], v[64:67], v[152:155], v[44:47]
	v_mfma_f32_16x16x32_bf16 v[36:39], v[72:75], v[152:155], v[36:39]
	v_mfma_f32_16x16x32_bf16 v[28:31], v[64:67], v[176:179], v[28:31]
	v_mfma_f32_16x16x32_bf16 v[20:23], v[72:75], v[176:179], v[20:23]
	v_mfma_f32_16x16x32_bf16 v[12:15], v[64:67], v[216:219], v[12:15]
	v_mfma_f32_16x16x32_bf16 v[8:11], v[72:75], v[216:219], v[8:11]
	v_mfma_f32_16x16x32_bf16 v[60:63], v[68:71], v[144:147], v[60:63]
	v_mfma_f32_16x16x32_bf16 v[52:55], v[76:79], v[144:147], v[52:55]
	v_mfma_f32_16x16x32_bf16 v[44:47], v[68:71], v[160:163], v[44:47]
	v_mfma_f32_16x16x32_bf16 v[36:39], v[76:79], v[160:163], v[36:39]
	v_mfma_f32_16x16x32_bf16 v[28:31], v[68:71], v[212:215], v[28:31]
	v_mfma_f32_16x16x32_bf16 v[20:23], v[76:79], v[212:215], v[20:23]
	v_mfma_f32_16x16x32_bf16 v[12:15], v[68:71], v[220:223], v[12:15]
	v_mfma_f32_16x16x32_bf16 v[8:11], v[76:79], v[220:223], v[8:11]
	v_mfma_f32_16x16x32_bf16 v[56:59], v[80:83], v[136:139], v[56:59]
	v_mfma_f32_16x16x32_bf16 v[48:51], v[88:91], v[136:139], v[48:51]
	v_mfma_f32_16x16x32_bf16 v[40:43], v[80:83], v[152:155], v[40:43]
	v_mfma_f32_16x16x32_bf16 v[32:35], v[88:91], v[152:155], v[32:35]
	v_mfma_f32_16x16x32_bf16 v[24:27], v[80:83], v[176:179], v[24:27]
	v_mfma_f32_16x16x32_bf16 v[16:19], v[88:91], v[176:179], v[16:19]
	v_mfma_f32_16x16x32_bf16 v[4:7], v[80:83], v[216:219], v[4:7]
	v_mfma_f32_16x16x32_bf16 v[0:3], v[88:91], v[216:219], v[0:3]
	v_mfma_f32_16x16x32_bf16 v[56:59], v[84:87], v[144:147], v[56:59]
	v_mfma_f32_16x16x32_bf16 v[48:51], v[92:95], v[144:147], v[48:51]
	v_mfma_f32_16x16x32_bf16 v[40:43], v[84:87], v[160:163], v[40:43]
	v_mfma_f32_16x16x32_bf16 v[32:35], v[92:95], v[160:163], v[32:35]
	v_mfma_f32_16x16x32_bf16 v[24:27], v[84:87], v[212:215], v[24:27]
	v_mfma_f32_16x16x32_bf16 v[16:19], v[92:95], v[212:215], v[16:19]
	v_mfma_f32_16x16x32_bf16 v[4:7], v[84:87], v[220:223], v[4:7]
	v_mfma_f32_16x16x32_bf16 v[0:3], v[92:95], v[220:223], v[0:3]
	s_setprio 0
	s_barrier
; #define PG8_STAGE(bufoff, gbase, voff) do { _Pragma("unroll") for (int _i = 0; _i < 2; ++_i) \
;         __builtin_amdgcn_global_load_lds((const unsigned*)((const char*)(gbase) + (voff)[_i]), (PG8_LAS unsigned*)(lds + (bufoff) + ldsw + _i * 8192), 16, 0, 0); } while (0)
; #define PG8_LDA(dst, b, h) do { _Pragma("unroll") for (int m = 0; m < 4; ++m) _Pragma("unroll") for (int k = 0; k < 2; ++k) dst[m][k] = *(const PG8_LAS bf16x8*)(lds + PG8_SA(b, h) + aoff + m * 2048 + k * 1024); } while (0)
; #define PG8_LDB(dst, b, h) do { _Pragma("unroll") for (int n = 0; n < 2; ++n) _Pragma("unroll") for (int k = 0; k < 2; ++k) dst[n][k] = *(const PG8_LAS bf16x8*)(lds + PG8_SB(b, h) + boff + n * 2048 + k * 1024); } while (0)
; #define PG8_MMA(ai, bj, At, Bt) do { __builtin_amdgcn_s_setprio(1); _Pragma("unroll") for (int m = 0; m < 4; ++m) _Pragma("unroll") for (int n = 0; n < 2; ++n) _Pragma("unroll") for (int k = 0; k < 2; ++k) \
;         acc[ai][bj][m][n] = __builtin_amdgcn_mfma_f32_16x16x32_bf16(Bt[n][k], At[m][k], acc[ai][bj][m][n], 0, 0, 0); __builtin_amdgcn_s_setprio(0); } while (0)
; #define PG8_WAIT_V(n) asm volatile("s_waitcnt vmcnt(" #n ")" ::: "memory")
; #define PG8_WAIT_L(n) asm volatile("s_waitcnt lgkmcnt(" #n ")" ::: "memory")
; #define PG8_BAR __builtin_amdgcn_s_barrier()
; #define PG8_SCHED __builtin_amdgcn_sched_barrier(0)
; template <class Epi, class Sched, bool ALIGN_EPI = false, bool SP2 = false>
; __device__ __forceinline__ void gemm_phase(PG8_LAS unsigned char* lds, const Gemm g, const Sched& S, const Epi& E, const int wave_in) {
;     ...
;         for (int t = 0; t < nt; t += 2) {
;     ...
;             PG8_LDB(B0, 1, 0); PG8_LDB(B1, 1, 1); PG8_SCHED; PG8_LDA(At, 1, 0); PG8_STAGE(PG8_SA(0, 1), a2 + hstepA, voffA);
;             PG8_WAIT_V(8); PG8_WAIT_L(0); PG8_BAR; PG8_MMA(0, 0, At, B0); PG8_MMA(0, 1, At, B1); PG8_BAR; PG8_SCHED;
;             PG8_LDA(At, 1, 1); PG8_STAGE(PG8_SB(1, 0), b3, voffB); PG8_STAGE(PG8_SB(1, 1), b3 + hstepB, voffB); PG8_STAGE(PG8_SA(1, 0), a3, voffA);
;             PG8_WAIT_V(8); PG8_WAIT_L(0); PG8_BAR; PG8_MMA(1, 0, At, B0); PG8_MMA(1, 1, At, B1); PG8_BAR; PG8_SCHED;
	s_add_i32 s76, 0, 0x18000
	s_add_i32 s77, 0, 0x1c000
	v_add_u32_e32 v76, s76, v195
	v_add_u32_e32 v92, s77, v195
	ds_read_b128 v[64:67], v76
	ds_read_b128 v[68:71], v76 offset:1024
	ds_read_b128 v[72:75], v76 offset:2048
	ds_read_b128 v[76:79], v76 offset:3072
	ds_read_b128 v[80:83], v92
	ds_read_b128 v[84:87], v92 offset:1024
	ds_read_b128 v[88:91], v92 offset:2048
	ds_read_b128 v[92:95], v92 offset:3072
	s_add_u32 s50, s50, 0x80000
	s_addc_u32 s51, s51, 0
	s_mov_b32 m0, s59
	v_lshl_add_u64 v[152:153], s[50:51], 0, v[180:181]
	ds_read_b128 v[136:139], v199 offset:32768
	ds_read_b128 v[144:147], v199 offset:33792
	ds_read_b128 v[176:179], v199 offset:34816
	ds_read_b128 v[212:215], v199 offset:35840
	ds_read_b128 v[216:219], v199 offset:36864
	ds_read_b128 v[220:223], v199 offset:37888
	ds_read_b128 v[224:227], v199 offset:38912
	ds_read_b128 v[228:231], v199 offset:39936
	global_load_lds_dwordx4 v[152:153], off
	v_lshl_add_u64 v[152:153], s[50:51], 0, v[184:185]
	s_mov_b32 m0, s60
	s_nop 0
	global_load_lds_dwordx4 v[152:153], off
	s_waitcnt vmcnt(8)
	s_waitcnt lgkmcnt(0)
	s_setprio 1
	s_barrier
	v_mfma_f32_16x16x32_bf16 v[152:155], v[64:67], v[136:139], v[172:175]
	v_mfma_f32_16x16x32_bf16 v[172:175], v[68:71], v[144:147], v[152:155]
	v_mfma_f32_16x16x32_bf16 v[152:155], v[72:75], v[136:139], v[164:167]
	v_mfma_f32_16x16x32_bf16 v[164:167], v[76:79], v[144:147], v[152:155]
	v_mfma_f32_16x16x32_bf16 v[152:155], v[64:67], v[176:179], v[156:159]
	v_mfma_f32_16x16x32_bf16 v[148:151], v[72:75], v[176:179], v[148:151]
	v_mfma_f32_16x16x32_bf16 v[140:143], v[64:67], v[216:219], v[140:143]
	v_mfma_f32_16x16x32_bf16 v[132:135], v[72:75], v[216:219], v[132:135]
	v_mfma_f32_16x16x32_bf16 v[124:127], v[64:67], v[224:227], v[124:127]
	v_mfma_f32_16x16x32_bf16 v[120:123], v[72:75], v[224:227], v[120:123]
	v_mfma_f32_16x16x32_bf16 v[156:159], v[68:71], v[212:215], v[152:155]
	v_mfma_f32_16x16x32_bf16 v[148:151], v[76:79], v[212:215], v[148:151]
	v_mfma_f32_16x16x32_bf16 v[140:143], v[68:71], v[220:223], v[140:143]
	v_mfma_f32_16x16x32_bf16 v[132:135], v[76:79], v[220:223], v[132:135]
	v_mfma_f32_16x16x32_bf16 v[124:127], v[68:71], v[228:231], v[124:127]
	v_mfma_f32_16x16x32_bf16 v[120:123], v[76:79], v[228:231], v[120:123]
	v_mfma_f32_16x16x32_bf16 v[96:99], v[88:91], v[136:139], v[96:99]
	v_mfma_f32_16x16x32_bf16 v[152:155], v[80:83], v[136:139], v[168:171]
	v_mfma_f32_16x16x32_bf16 v[160:163], v[92:95], v[144:147], v[96:99]
	v_mfma_f32_16x16x32_bf16 v[96:99], v[80:83], v[176:179], v[100:103]
	v_mfma_f32_16x16x32_bf16 v[168:171], v[84:87], v[144:147], v[152:155]
	v_mfma_f32_16x16x32_bf16 v[152:155], v[84:87], v[212:215], v[96:99]
	v_mfma_f32_16x16x32_bf16 v[96:99], v[88:91], v[176:179], v[104:107]
	v_mfma_f32_16x16x32_bf16 v[144:147], v[92:95], v[212:215], v[96:99]
	v_mfma_f32_16x16x32_bf16 v[96:99], v[80:83], v[216:219], v[108:111]
	v_mfma_f32_16x16x32_bf16 v[136:139], v[84:87], v[220:223], v[96:99]
	v_mfma_f32_16x16x32_bf16 v[96:99], v[88:91], v[216:219], v[128:131]
	v_mfma_f32_16x16x32_bf16 v[128:131], v[92:95], v[220:223], v[96:99]
	v_mfma_f32_16x16x32_bf16 v[96:99], v[80:83], v[224:227], v[116:119]
	v_mfma_f32_16x16x32_bf16 v[116:119], v[84:87], v[228:231], v[96:99]
	v_mfma_f32_16x16x32_bf16 v[96:99], v[88:91], v[224:227], v[112:115]
	v_mfma_f32_16x16x32_bf16 v[112:115], v[92:95], v[228:231], v[96:99]
	s_setprio 0
	s_barrier
	s_add_i32 s50, s76, s56
	v_lshl_add_u64 v[224:225], v[232:233], 0, s[20:21]
	s_mov_b32 m0, s50
	s_nop 1
	ds_read_b128 v[96:99], v199 offset:49152
	ds_read_b128 v[100:103], v199 offset:50176
	ds_read_b128 v[104:107], v199 offset:51200
	ds_read_b128 v[108:111], v199 offset:52224
	ds_read_b128 v[176:179], v199 offset:53248
	ds_read_b128 v[212:215], v199 offset:54272
	ds_read_b128 v[216:219], v199 offset:55296
	ds_read_b128 v[220:223], v199 offset:56320
	global_load_lds_dwordx4 v[224:225], off
	s_add_i32 m0, s50, 0x2000
	s_add_u32 s48, s48, 0x80080
	v_lshl_add_u64 v[224:225], v[234:235], 0, s[20:21]
	s_addc_u32 s49, s49, 0
	s_add_i32 s50, s77, s56
	global_load_lds_dwordx4 v[224:225], off
	v_lshl_add_u64 v[224:225], s[48:49], 0, v[182:183]
	s_mov_b32 m0, s50
	s_nop 0
	global_load_lds_dwordx4 v[224:225], off
	v_lshl_add_u64 v[224:225], s[48:49], 0, v[186:187]
	s_add_i32 m0, s50, 0x2000
	s_nop 0
	global_load_lds_dwordx4 v[224:225], off
	v_lshl_add_u64 v[224:225], v[236:237], 0, s[20:21]
	s_mov_b32 m0, s63
	s_nop 0
	global_load_lds_dwordx4 v[224:225], off
	v_lshl_add_u64 v[224:225], v[238:239], 0, s[20:21]
	s_mov_b32 m0, s64
	s_nop 0
	global_load_lds_dwordx4 v[224:225], off
	s_waitcnt vmcnt(8)
	s_waitcnt lgkmcnt(0)
	s_setprio 1
	s_barrier
	v_mfma_f32_16x16x32_bf16 v[60:63], v[64:67], v[96:99], v[60:63]
	v_mfma_f32_16x16x32_bf16 v[52:55], v[72:75], v[96:99], v[52:55]
	v_mfma_f32_16x16x32_bf16 v[44:47], v[64:67], v[104:107], v[44:47]
	v_mfma_f32_16x16x32_bf16 v[36:39], v[72:75], v[104:107], v[36:39]
	v_mfma_f32_16x16x32_bf16 v[28:31], v[64:67], v[176:179], v[28:31]
	v_mfma_f32_16x16x32_bf16 v[20:23], v[72:75], v[176:179], v[20:23]
	v_mfma_f32_16x16x32_bf16 v[12:15], v[64:67], v[216:219], v[12:15]
	v_mfma_f32_16x16x32_bf16 v[8:11], v[72:75], v[216:219], v[8:11]
	v_mfma_f32_16x16x32_bf16 v[60:63], v[68:71], v[100:103], v[60:63]
	v_mfma_f32_16x16x32_bf16 v[52:55], v[76:79], v[100:103], v[52:55]
	v_mfma_f32_16x16x32_bf16 v[44:47], v[68:71], v[108:111], v[44:47]
	v_mfma_f32_16x16x32_bf16 v[36:39], v[76:79], v[108:111], v[36:39]
	v_mfma_f32_16x16x32_bf16 v[28:31], v[68:71], v[212:215], v[28:31]
	v_mfma_f32_16x16x32_bf16 v[20:23], v[76:79], v[212:215], v[20:23]
	v_mfma_f32_16x16x32_bf16 v[12:15], v[68:71], v[220:223], v[12:15]
	v_mfma_f32_16x16x32_bf16 v[8:11], v[76:79], v[220:223], v[8:11]
	v_mfma_f32_16x16x32_bf16 v[56:59], v[80:83], v[96:99], v[56:59]
	v_mfma_f32_16x16x32_bf16 v[48:51], v[88:91], v[96:99], v[48:51]
	v_mfma_f32_16x16x32_bf16 v[40:43], v[80:83], v[104:107], v[40:43]
	v_mfma_f32_16x16x32_bf16 v[32:35], v[88:91], v[104:107], v[32:35]
	v_mfma_f32_16x16x32_bf16 v[24:27], v[80:83], v[176:179], v[24:27]
	v_mfma_f32_16x16x32_bf16 v[16:19], v[88:91], v[176:179], v[16:19]
	v_mfma_f32_16x16x32_bf16 v[4:7], v[80:83], v[216:219], v[4:7]
	v_mfma_f32_16x16x32_bf16 v[0:3], v[88:91], v[216:219], v[0:3]
	v_mfma_f32_16x16x32_bf16 v[56:59], v[84:87], v[100:103], v[56:59]
	v_mfma_f32_16x16x32_bf16 v[48:51], v[92:95], v[100:103], v[48:51]
	v_mfma_f32_16x16x32_bf16 v[40:43], v[84:87], v[108:111], v[40:43]
	v_mfma_f32_16x16x32_bf16 v[32:35], v[92:95], v[108:111], v[32:35]
	v_mfma_f32_16x16x32_bf16 v[24:27], v[84:87], v[212:215], v[24:27]
	v_mfma_f32_16x16x32_bf16 v[16:19], v[92:95], v[212:215], v[16:19]
	v_mfma_f32_16x16x32_bf16 v[4:7], v[84:87], v[220:223], v[4:7]
	v_mfma_f32_16x16x32_bf16 v[0:3], v[92:95], v[220:223], v[0:3]
	s_setprio 0
	s_barrier
	s_add_i32 s75, s75, 2
	s_add_u32 s46, s46, 0x100
	s_addc_u32 s47, s47, 0
	s_add_u32 s72, s72, 0x100
	s_addc_u32 s73, s73, 0
	s_cmp_gt_u32 s75, 29
	s_cbranch_scc0 .LBB0_2577

; #define PG8_STAGE(bufoff, gbase, voff) do { _Pragma("unroll") for (int _i = 0; _i < 2; ++_i) \
;         __builtin_amdgcn_global_load_lds((const unsigned*)((const char*)(gbase) + (voff)[_i]), (PG8_LAS unsigned*)(lds + (bufoff) + ldsw + _i * 8192), 16, 0, 0); } while (0)
; #define PG8_LDA(dst, b, h) do { _Pragma("unroll") for (int m = 0; m < 4; ++m) _Pragma("unroll") for (int k = 0; k < 2; ++k) dst[m][k] = *(const PG8_LAS bf16x8*)(lds + PG8_SA(b, h) + aoff + m * 2048 + k * 1024); } while (0)
; #define PG8_LDB(dst, b, h) do { _Pragma("unroll") for (int n = 0; n < 2; ++n) _Pragma("unroll") for (int k = 0; k < 2; ++k) dst[n][k] = *(const PG8_LAS bf16x8*)(lds + PG8_SB(b, h) + boff + n * 2048 + k * 1024); } while (0)
; #define PG8_BAR __builtin_amdgcn_s_barrier()
; template <class Epi, class Sched, bool ALIGN_EPI = false, bool SP2 = false>
; __device__ __forceinline__ void gemm_phase(PG8_LAS unsigned char* lds, const Gemm g, const Sched& S, const Epi& E, const int wave_in) {
;     ...
;         const char* nA = has_next ? (const char*)g.A + (size_t)nxt.pm * tstepA : cA; const char* nB = has_next ? (const char*)g.Bt + (size_t)nxt.pn * tstepB : cB;
;         for (int t = 0; t < nt; t += 2) {
;             const bool last = (t == nt - 2);
;             const char* a1 = cA + (size_t)(t + 1) * kstep;
;             const char* a2 = last ? nA : cA + (size_t)(t + 2) * kstep; const char* b2 = last ? nB : cB + (size_t)(t + 2) * kstep;
;             const char* a3 = a2 + kstep; const char* b3 = b2 + kstep;
;             if (last && has_next) S.a_ready(nxt);
;             if constexpr (SP2) {
;             PG8_LDB(B0, 0, 0); PG8_LDB(B1, 0, 1); PG8_SCHED; PG8_LDA(At, 0, 0); PG8_STAGE(PG8_SA(1, 1), a1 + hstepA, voffA);
;             PG8_WAIT_V(8); PG8_WAIT_L(0); PG8_BAR; PG8_MMA(0, 0, At, B0); PG8_MMA(0, 1, At, B1); PG8_BAR; PG8_SCHED;
;             PG8_LDA(At, 0, 1); PG8_STAGE(PG8_SB(0, 0), b2, voffB); PG8_STAGE(PG8_SB(0, 1), b2 + hstepB, voffB); PG8_STAGE(PG8_SA(0, 0), a2, voffA);
;             PG8_WAIT_V(8); PG8_WAIT_L(0); PG8_BAR; PG8_MMA(1, 0, At, B0); PG8_MMA(1, 1, At, B1); PG8_BAR; PG8_SCHED;
;     ...
;         for (int a = 0; a < 2; ++a)
; #pragma unroll
;             for (int b = 0; b < 2; ++b)
; #pragma unroll
;                 for (int m = 0; m < 4; ++m)
; #pragma unroll
;                     for (int n = 0; n < 2; ++n) acc[a][b][m][n] = (f32x4){0.f, 0.f, 0.f, 0.f};
.LBB0_2740:
	s_add_u32 s25, s28, 0x100
	v_mov_b32_e32 v0, 0
	s_addc_u32 s65, s29, 0
	s_mov_b32 s66, -2
	s_waitcnt vmcnt(0)
	ds_read_b128 v[128:131], v170
	ds_read_b128 v[132:135], v170 offset:1024
	ds_read_b128 v[136:139], v170 offset:2048
	ds_read_b128 v[140:143], v170 offset:3072
	ds_read_b128 v[162:165], v171
	ds_read_b128 v[174:177], v171 offset:1024
	ds_read_b128 v[178:181], v171 offset:2048
	ds_read_b128 v[182:185], v171 offset:3072
	s_add_u32 s2, s26, 0x100
	s_addc_u32 s3, s27, 0
	s_cmpk_eq_i32 s66, 0x52
	s_cselect_b32 s31, s21, s3
	s_cselect_b32 s30, s20, s2
	s_cselect_b32 s29, s23, s65
	s_cselect_b32 s28, s22, s25
	v_lshl_add_u64 v[166:167], s[26:27], 0, v[154:155]
	s_add_i32 m0, s40, 0xc000
	ds_read_b128 v[186:189], v172
	ds_read_b128 v[190:193], v172 offset:1024
	ds_read_b128 v[194:197], v172 offset:2048
	ds_read_b128 v[198:201], v172 offset:3072
	ds_read_b128 v[202:205], v172 offset:4096
	ds_read_b128 v[206:209], v172 offset:5120
	ds_read_b128 v[210:213], v172 offset:6144
	ds_read_b128 v[214:217], v172 offset:7168
	global_load_lds_dwordx4 v[166:167], off
	v_lshl_add_u64 v[166:167], s[26:27], 0, v[156:157]
	s_add_i32 m0, s40, 0xe000
	s_nop 0
	global_load_lds_dwordx4 v[166:167], off
	s_waitcnt vmcnt(8)
	s_waitcnt lgkmcnt(0)
	s_setprio 1
	s_barrier
	v_mfma_f32_16x16x32_bf16 v[124:127], v[128:131], v[186:189], 0
	v_mfma_f32_16x16x32_bf16 v[120:123], v[136:139], v[186:189], 0
	v_mfma_f32_16x16x32_bf16 v[104:107], v[128:131], v[194:197], 0
	v_mfma_f32_16x16x32_bf16 v[108:111], v[136:139], v[194:197], 0
	v_mfma_f32_16x16x32_bf16 v[88:91], v[128:131], v[202:205], 0
	v_mfma_f32_16x16x32_bf16 v[92:95], v[136:139], v[202:205], 0
	v_mfma_f32_16x16x32_bf16 v[72:75], v[128:131], v[210:213], 0
	v_mfma_f32_16x16x32_bf16 v[76:79], v[136:139], v[210:213], 0
	v_mfma_f32_16x16x32_bf16 v[124:127], v[132:135], v[190:193], v[124:127]
	v_mfma_f32_16x16x32_bf16 v[120:123], v[140:143], v[190:193], v[120:123]
	v_mfma_f32_16x16x32_bf16 v[104:107], v[132:135], v[198:201], v[104:107]
	v_mfma_f32_16x16x32_bf16 v[108:111], v[140:143], v[198:201], v[108:111]
	v_mfma_f32_16x16x32_bf16 v[88:91], v[132:135], v[206:209], v[88:91]
	v_mfma_f32_16x16x32_bf16 v[92:95], v[140:143], v[206:209], v[92:95]
	v_mfma_f32_16x16x32_bf16 v[72:75], v[132:135], v[214:217], v[72:75]
	v_mfma_f32_16x16x32_bf16 v[76:79], v[140:143], v[214:217], v[76:79]
	v_mfma_f32_16x16x32_bf16 v[112:115], v[162:165], v[186:189], 0
	v_mfma_f32_16x16x32_bf16 v[116:119], v[178:181], v[186:189], 0
	v_mfma_f32_16x16x32_bf16 v[96:99], v[162:165], v[194:197], 0
	v_mfma_f32_16x16x32_bf16 v[100:103], v[178:181], v[194:197], 0
	v_mfma_f32_16x16x32_bf16 v[80:83], v[162:165], v[202:205], 0
	v_mfma_f32_16x16x32_bf16 v[84:87], v[178:181], v[202:205], 0
	v_mfma_f32_16x16x32_bf16 v[64:67], v[162:165], v[210:213], 0
	v_mfma_f32_16x16x32_bf16 v[68:71], v[178:181], v[210:213], 0
	v_mfma_f32_16x16x32_bf16 v[112:115], v[174:177], v[190:193], v[112:115]
	v_mfma_f32_16x16x32_bf16 v[116:119], v[182:185], v[190:193], v[116:119]
	v_mfma_f32_16x16x32_bf16 v[96:99], v[174:177], v[198:201], v[96:99]
	v_mfma_f32_16x16x32_bf16 v[100:103], v[182:185], v[198:201], v[100:103]
	v_mfma_f32_16x16x32_bf16 v[80:83], v[174:177], v[206:209], v[80:83]
	v_mfma_f32_16x16x32_bf16 v[84:87], v[182:185], v[206:209], v[84:87]
	v_mfma_f32_16x16x32_bf16 v[64:67], v[174:177], v[214:217], v[64:67]
	v_mfma_f32_16x16x32_bf16 v[68:71], v[182:185], v[214:217], v[68:71]
	s_setprio 0
	s_barrier
	s_add_i32 s26, s50, s39
	v_lshl_add_u64 v[166:167], s[28:29], 0, v[146:147]
	s_mov_b32 m0, s26
	ds_read_b128 v[186:189], v172 offset:16384
	ds_read_b128 v[190:193], v172 offset:17408
	ds_read_b128 v[194:197], v172 offset:18432
	ds_read_b128 v[198:201], v172 offset:19456
	ds_read_b128 v[202:205], v172 offset:20480
	ds_read_b128 v[206:209], v172 offset:21504
	ds_read_b128 v[210:213], v172 offset:22528
	ds_read_b128 v[214:217], v172 offset:23552
	global_load_lds_dwordx4 v[166:167], off
	s_add_i32 m0, s26, 0x2000
	s_add_u32 s26, s28, 0x158000
	v_lshl_add_u64 v[218:219], s[28:29], 0, v[150:151]
	s_addc_u32 s27, s29, 0
	s_add_i32 s67, s51, s39
	global_load_lds_dwordx4 v[218:219], off
	v_lshl_add_u64 v[220:221], s[26:27], 0, v[146:147]
	s_mov_b32 m0, s67
	v_lshl_add_u64 v[222:223], s[30:31], 0, v[148:149]
	global_load_lds_dwordx4 v[220:221], off
	v_lshl_add_u64 v[220:221], s[26:27], 0, v[150:151]
	s_add_i32 m0, s67, 0x2000
	s_nop 0
	global_load_lds_dwordx4 v[220:221], off
	v_lshl_add_u64 v[220:221], s[30:31], 0, v[144:145]
	s_mov_b32 m0, s40
	s_nop 0
	global_load_lds_dwordx4 v[220:221], off
	s_mov_b32 m0, s41
	s_nop 0
	global_load_lds_dwordx4 v[222:223], off
	s_waitcnt vmcnt(8)
	s_waitcnt lgkmcnt(0)
	s_setprio 1
	s_barrier
; #define PG8_STAGE(bufoff, gbase, voff) do { _Pragma("unroll") for (int _i = 0; _i < 2; ++_i) \
;         __builtin_amdgcn_global_load_lds((const unsigned*)((const char*)(gbase) + (voff)[_i]), (PG8_LAS unsigned*)(lds + (bufoff) + ldsw + _i * 8192), 16, 0, 0); } while (0)
; #define PG8_LDA(dst, b, h) do { _Pragma("unroll") for (int m = 0; m < 4; ++m) _Pragma("unroll") for (int k = 0; k < 2; ++k) dst[m][k] = *(const PG8_LAS bf16x8*)(lds + PG8_SA(b, h) + aoff + m * 2048 + k * 1024); } while (0)
; #define PG8_LDB(dst, b, h) do { _Pragma("unroll") for (int n = 0; n < 2; ++n) _Pragma("unroll") for (int k = 0; k < 2; ++k) dst[n][k] = *(const PG8_LAS bf16x8*)(lds + PG8_SB(b, h) + boff + n * 2048 + k * 1024); } while (0)
; #define PG8_MMA(ai, bj, At, Bt) do { __builtin_amdgcn_s_setprio(1); _Pragma("unroll") for (int m = 0; m < 4; ++m) _Pragma("unroll") for (int n = 0; n < 2; ++n) _Pragma("unroll") for (int k = 0; k < 2; ++k) \
;         acc[ai][bj][m][n] = __builtin_amdgcn_mfma_f32_16x16x32_bf16(Bt[n][k], At[m][k], acc[ai][bj][m][n], 0, 0, 0); __builtin_amdgcn_s_setprio(0); } while (0)
; #define PG8_WAIT_V(n) asm volatile("s_waitcnt vmcnt(" #n ")" ::: "memory")
; #define PG8_WAIT_L(n) asm volatile("s_waitcnt lgkmcnt(" #n ")" ::: "memory")
; #define PG8_BAR __builtin_amdgcn_s_barrier()
; #define PG8_SCHED __builtin_amdgcn_sched_barrier(0)
; template <class Epi, class Sched, bool ALIGN_EPI = false, bool SP2 = false>
; __device__ __forceinline__ void gemm_phase(PG8_LAS unsigned char* lds, const Gemm g, const Sched& S, const Epi& E, const int wave_in) {
;     ...
;             PG8_WAIT_V(8); PG8_WAIT_L(0); PG8_BAR; PG8_MMA(1, 0, At, B0); PG8_MMA(1, 1, At, B1); PG8_BAR; PG8_SCHED;
;             PG8_LDB(B0, 1, 0); PG8_LDB(B1, 1, 1); PG8_SCHED; PG8_LDA(At, 1, 0); PG8_STAGE(PG8_SA(0, 1), a2 + hstepA, voffA);
;             PG8_WAIT_V(8); PG8_WAIT_L(0); PG8_BAR; PG8_MMA(0, 0, At, B0); PG8_MMA(0, 1, At, B1); PG8_BAR; PG8_SCHED;
	v_mfma_f32_16x16x32_bf16 v[60:63], v[128:131], v[186:189], 0
	v_mfma_f32_16x16x32_bf16 v[56:59], v[136:139], v[186:189], 0
	v_mfma_f32_16x16x32_bf16 v[40:43], v[128:131], v[194:197], 0
	v_mfma_f32_16x16x32_bf16 v[48:51], v[136:139], v[194:197], 0
	v_mfma_f32_16x16x32_bf16 v[24:27], v[128:131], v[202:205], 0
	v_mfma_f32_16x16x32_bf16 v[32:35], v[136:139], v[202:205], 0
	v_mfma_f32_16x16x32_bf16 v[8:11], v[128:131], v[210:213], 0
	v_mfma_f32_16x16x32_bf16 v[16:19], v[136:139], v[210:213], 0
	v_mfma_f32_16x16x32_bf16 v[60:63], v[132:135], v[190:193], v[60:63]
	v_mfma_f32_16x16x32_bf16 v[56:59], v[140:143], v[190:193], v[56:59]
	v_mfma_f32_16x16x32_bf16 v[40:43], v[132:135], v[198:201], v[40:43]
	v_mfma_f32_16x16x32_bf16 v[48:51], v[140:143], v[198:201], v[48:51]
	v_mfma_f32_16x16x32_bf16 v[24:27], v[132:135], v[206:209], v[24:27]
	v_mfma_f32_16x16x32_bf16 v[32:35], v[140:143], v[206:209], v[32:35]
	v_mfma_f32_16x16x32_bf16 v[8:11], v[132:135], v[214:217], v[8:11]
	v_mfma_f32_16x16x32_bf16 v[16:19], v[140:143], v[214:217], v[16:19]
	v_mfma_f32_16x16x32_bf16 v[44:47], v[162:165], v[186:189], 0
	v_mfma_f32_16x16x32_bf16 v[52:55], v[178:181], v[186:189], 0
	v_mfma_f32_16x16x32_bf16 v[28:31], v[162:165], v[194:197], 0
	v_mfma_f32_16x16x32_bf16 v[36:39], v[178:181], v[194:197], 0
	v_mfma_f32_16x16x32_bf16 v[12:15], v[162:165], v[202:205], 0
	v_mfma_f32_16x16x32_bf16 v[20:23], v[178:181], v[202:205], 0
	v_mfma_f32_16x16x32_bf16 v[4:7], v[162:165], v[210:213], 0
	v_mfma_f32_16x16x32_bf16 v[0:3], v[178:181], v[210:213], 0
	v_mfma_f32_16x16x32_bf16 v[44:47], v[174:177], v[190:193], v[44:47]
	v_mfma_f32_16x16x32_bf16 v[52:55], v[182:185], v[190:193], v[52:55]
	v_mfma_f32_16x16x32_bf16 v[28:31], v[174:177], v[198:201], v[28:31]
	v_mfma_f32_16x16x32_bf16 v[36:39], v[182:185], v[198:201], v[36:39]
	v_mfma_f32_16x16x32_bf16 v[12:15], v[174:177], v[206:209], v[12:15]
	v_mfma_f32_16x16x32_bf16 v[20:23], v[182:185], v[206:209], v[20:23]
	v_mfma_f32_16x16x32_bf16 v[4:7], v[174:177], v[214:217], v[4:7]
	v_mfma_f32_16x16x32_bf16 v[0:3], v[182:185], v[214:217], v[0:3]
	s_setprio 0
	s_barrier
	s_add_i32 s67, 0, 0x18000
	s_add_i32 s68, 0, 0x1c000
	v_add_u32_e32 v140, s67, v168
	v_add_u32_e32 v173, s68, v168
	ds_read_b128 v[128:131], v140
	ds_read_b128 v[132:135], v140 offset:1024
	ds_read_b128 v[136:139], v140 offset:2048
	ds_read_b128 v[140:143], v140 offset:3072
	ds_read_b128 v[162:165], v173
	ds_read_b128 v[174:177], v173 offset:1024
	ds_read_b128 v[178:181], v173 offset:2048
	ds_read_b128 v[182:185], v173 offset:3072
	s_add_u32 s26, s30, 0x158000
	s_addc_u32 s27, s31, 0
	s_mov_b32 m0, s42
	v_lshl_add_u64 v[224:225], s[26:27], 0, v[144:145]
	ds_read_b128 v[186:189], v172 offset:32768
	ds_read_b128 v[190:193], v172 offset:33792
	ds_read_b128 v[194:197], v172 offset:34816
	ds_read_b128 v[198:201], v172 offset:35840
	ds_read_b128 v[202:205], v172 offset:36864
	ds_read_b128 v[206:209], v172 offset:37888
	ds_read_b128 v[210:213], v172 offset:38912
	ds_read_b128 v[214:217], v172 offset:39936
	global_load_lds_dwordx4 v[224:225], off
	v_lshl_add_u64 v[224:225], s[26:27], 0, v[148:149]
	s_mov_b32 m0, s43
	s_nop 0
	global_load_lds_dwordx4 v[224:225], off
	s_waitcnt vmcnt(8)
	s_waitcnt lgkmcnt(0)
	s_setprio 1
	s_barrier
	v_mfma_f32_16x16x32_bf16 v[124:127], v[128:131], v[186:189], v[124:127]
	v_mfma_f32_16x16x32_bf16 v[120:123], v[136:139], v[186:189], v[120:123]
	v_mfma_f32_16x16x32_bf16 v[104:107], v[128:131], v[194:197], v[104:107]
	v_mfma_f32_16x16x32_bf16 v[108:111], v[136:139], v[194:197], v[108:111]
	v_mfma_f32_16x16x32_bf16 v[88:91], v[128:131], v[202:205], v[88:91]
	v_mfma_f32_16x16x32_bf16 v[92:95], v[136:139], v[202:205], v[92:95]
	v_mfma_f32_16x16x32_bf16 v[72:75], v[128:131], v[210:213], v[72:75]
	v_mfma_f32_16x16x32_bf16 v[76:79], v[136:139], v[210:213], v[76:79]
	v_mfma_f32_16x16x32_bf16 v[124:127], v[132:135], v[190:193], v[124:127]
	v_mfma_f32_16x16x32_bf16 v[120:123], v[140:143], v[190:193], v[120:123]
	v_mfma_f32_16x16x32_bf16 v[104:107], v[132:135], v[198:201], v[104:107]
	v_mfma_f32_16x16x32_bf16 v[108:111], v[140:143], v[198:201], v[108:111]
	v_mfma_f32_16x16x32_bf16 v[88:91], v[132:135], v[206:209], v[88:91]
	v_mfma_f32_16x16x32_bf16 v[92:95], v[140:143], v[206:209], v[92:95]
	v_mfma_f32_16x16x32_bf16 v[72:75], v[132:135], v[214:217], v[72:75]
	v_mfma_f32_16x16x32_bf16 v[76:79], v[140:143], v[214:217], v[76:79]
	v_mfma_f32_16x16x32_bf16 v[112:115], v[162:165], v[186:189], v[112:115]
	v_mfma_f32_16x16x32_bf16 v[116:119], v[178:181], v[186:189], v[116:119]
	v_mfma_f32_16x16x32_bf16 v[96:99], v[162:165], v[194:197], v[96:99]
	v_mfma_f32_16x16x32_bf16 v[100:103], v[178:181], v[194:197], v[100:103]
	v_mfma_f32_16x16x32_bf16 v[80:83], v[162:165], v[202:205], v[80:83]
	v_mfma_f32_16x16x32_bf16 v[84:87], v[178:181], v[202:205], v[84:87]
	v_mfma_f32_16x16x32_bf16 v[64:67], v[162:165], v[210:213], v[64:67]
	v_mfma_f32_16x16x32_bf16 v[68:71], v[178:181], v[210:213], v[68:71]
	v_mfma_f32_16x16x32_bf16 v[112:115], v[174:177], v[190:193], v[112:115]
	v_mfma_f32_16x16x32_bf16 v[116:119], v[182:185], v[190:193], v[116:119]
	v_mfma_f32_16x16x32_bf16 v[96:99], v[174:177], v[198:201], v[96:99]
	v_mfma_f32_16x16x32_bf16 v[100:103], v[182:185], v[198:201], v[100:103]
	v_mfma_f32_16x16x32_bf16 v[80:83], v[174:177], v[206:209], v[80:83]
	v_mfma_f32_16x16x32_bf16 v[84:87], v[182:185], v[206:209], v[84:87]
	v_mfma_f32_16x16x32_bf16 v[64:67], v[174:177], v[214:217], v[64:67]
	v_mfma_f32_16x16x32_bf16 v[68:71], v[182:185], v[214:217], v[68:71]
	s_setprio 0
	s_barrier
; #define PG8_STAGE(bufoff, gbase, voff) do { _Pragma("unroll") for (int _i = 0; _i < 2; ++_i) \
;         __builtin_amdgcn_global_load_lds((const unsigned*)((const char*)(gbase) + (voff)[_i]), (PG8_LAS unsigned*)(lds + (bufoff) + ldsw + _i * 8192), 16, 0, 0); } while (0)
; #define PG8_LDA(dst, b, h) do { _Pragma("unroll") for (int m = 0; m < 4; ++m) _Pragma("unroll") for (int k = 0; k < 2; ++k) dst[m][k] = *(const PG8_LAS bf16x8*)(lds + PG8_SA(b, h) + aoff + m * 2048 + k * 1024); } while (0)
; #define PG8_LDB(dst, b, h) do { _Pragma("unroll") for (int n = 0; n < 2; ++n) _Pragma("unroll") for (int k = 0; k < 2; ++k) dst[n][k] = *(const PG8_LAS bf16x8*)(lds + PG8_SB(b, h) + boff + n * 2048 + k * 1024); } while (0)
; #define PG8_MMA(ai, bj, At, Bt) do { __builtin_amdgcn_s_setprio(1); _Pragma("unroll") for (int m = 0; m < 4; ++m) _Pragma("unroll") for (int n = 0; n < 2; ++n) _Pragma("unroll") for (int k = 0; k < 2; ++k) \
;         acc[ai][bj][m][n] = __builtin_amdgcn_mfma_f32_16x16x32_bf16(Bt[n][k], At[m][k], acc[ai][bj][m][n], 0, 0, 0); __builtin_amdgcn_s_setprio(0); } while (0)
; #define PG8_WAIT_V(n) asm volatile("s_waitcnt vmcnt(" #n ")" ::: "memory")
; #define PG8_WAIT_L(n) asm volatile("s_waitcnt lgkmcnt(" #n ")" ::: "memory")
; #define PG8_BAR __builtin_amdgcn_s_barrier()
; #define PG8_SCHED __builtin_amdgcn_sched_barrier(0)
; template <class Epi, class Sched, bool ALIGN_EPI = false, bool SP2 = false>
; __device__ __forceinline__ void gemm_phase(PG8_LAS unsigned char* lds, const Gemm g, const Sched& S, const Epi& E, const int wave_in) {
;     ...
;             PG8_LDB(B0, 0, 0); PG8_LDB(B1, 0, 1); PG8_SCHED; PG8_LDA(At, 0, 0); PG8_STAGE(PG8_SA(1, 1), a1 + hstepA, voffA);
;             PG8_WAIT_V(8); PG8_WAIT_L(0); PG8_BAR; PG8_MMA(0, 0, At, B0); PG8_MMA(0, 1, At, B1); PG8_BAR; PG8_SCHED;
;     ...
;             PG8_LDA(At, 1, 1); PG8_STAGE(PG8_SB(1, 0), b3, voffB); PG8_STAGE(PG8_SB(1, 1), b3 + hstepB, voffB); PG8_STAGE(PG8_SA(1, 0), a3, voffA);
;             PG8_WAIT_V(8); PG8_WAIT_L(0); PG8_BAR; PG8_MMA(1, 0, At, B0); PG8_MMA(1, 1, At, B1); PG8_BAR; PG8_SCHED;
	s_add_i32 s26, s67, s39
	v_lshl_add_u64 v[166:167], v[166:167], 0, s[6:7]
	s_mov_b32 m0, s26
	ds_read_b128 v[186:189], v172 offset:49152
	ds_read_b128 v[190:193], v172 offset:50176
	ds_read_b128 v[194:197], v172 offset:51200
	ds_read_b128 v[198:201], v172 offset:52224
	ds_read_b128 v[202:205], v172 offset:53248
	ds_read_b128 v[206:209], v172 offset:54272
	ds_read_b128 v[210:213], v172 offset:55296
	ds_read_b128 v[214:217], v172 offset:56320
	global_load_lds_dwordx4 v[166:167], off
	s_add_i32 m0, s26, 0x2000
	s_add_u32 s26, s28, 0x158080
	v_lshl_add_u64 v[166:167], v[218:219], 0, s[6:7]
	s_addc_u32 s27, s29, 0
	s_add_i32 s28, s68, s39
	global_load_lds_dwordx4 v[166:167], off
	v_lshl_add_u64 v[166:167], s[26:27], 0, v[146:147]
	s_mov_b32 m0, s28
	s_nop 0
	global_load_lds_dwordx4 v[166:167], off
	v_lshl_add_u64 v[166:167], s[26:27], 0, v[150:151]
	s_add_i32 m0, s28, 0x2000
	s_nop 0
	global_load_lds_dwordx4 v[166:167], off
	v_lshl_add_u64 v[166:167], v[220:221], 0, s[6:7]
	s_mov_b32 m0, s48
	s_nop 0
	global_load_lds_dwordx4 v[166:167], off
	v_lshl_add_u64 v[166:167], v[222:223], 0, s[6:7]
	s_mov_b32 m0, s49
	s_nop 0
	global_load_lds_dwordx4 v[166:167], off
	s_waitcnt vmcnt(8)
	s_waitcnt lgkmcnt(0)
	s_setprio 1
	s_barrier
	v_mfma_f32_16x16x32_bf16 v[60:63], v[128:131], v[186:189], v[60:63]
	v_mfma_f32_16x16x32_bf16 v[56:59], v[136:139], v[186:189], v[56:59]
	v_mfma_f32_16x16x32_bf16 v[40:43], v[128:131], v[194:197], v[40:43]
	v_mfma_f32_16x16x32_bf16 v[48:51], v[136:139], v[194:197], v[48:51]
	v_mfma_f32_16x16x32_bf16 v[24:27], v[128:131], v[202:205], v[24:27]
	v_mfma_f32_16x16x32_bf16 v[32:35], v[136:139], v[202:205], v[32:35]
	v_mfma_f32_16x16x32_bf16 v[8:11], v[128:131], v[210:213], v[8:11]
	v_mfma_f32_16x16x32_bf16 v[16:19], v[136:139], v[210:213], v[16:19]
	v_mfma_f32_16x16x32_bf16 v[60:63], v[132:135], v[190:193], v[60:63]
	v_mfma_f32_16x16x32_bf16 v[56:59], v[140:143], v[190:193], v[56:59]
	v_mfma_f32_16x16x32_bf16 v[40:43], v[132:135], v[198:201], v[40:43]
	v_mfma_f32_16x16x32_bf16 v[48:51], v[140:143], v[198:201], v[48:51]
	v_mfma_f32_16x16x32_bf16 v[24:27], v[132:135], v[206:209], v[24:27]
	v_mfma_f32_16x16x32_bf16 v[32:35], v[140:143], v[206:209], v[32:35]
	v_mfma_f32_16x16x32_bf16 v[8:11], v[132:135], v[214:217], v[8:11]
	v_mfma_f32_16x16x32_bf16 v[16:19], v[140:143], v[214:217], v[16:19]
	v_mfma_f32_16x16x32_bf16 v[44:47], v[162:165], v[186:189], v[44:47]
	v_mfma_f32_16x16x32_bf16 v[52:55], v[178:181], v[186:189], v[52:55]
	v_mfma_f32_16x16x32_bf16 v[28:31], v[162:165], v[194:197], v[28:31]
	v_mfma_f32_16x16x32_bf16 v[36:39], v[178:181], v[194:197], v[36:39]
	v_mfma_f32_16x16x32_bf16 v[12:15], v[162:165], v[202:205], v[12:15]
	v_mfma_f32_16x16x32_bf16 v[20:23], v[178:181], v[202:205], v[20:23]
	v_mfma_f32_16x16x32_bf16 v[4:7], v[162:165], v[210:213], v[4:7]
	v_mfma_f32_16x16x32_bf16 v[0:3], v[178:181], v[210:213], v[0:3]
	v_mfma_f32_16x16x32_bf16 v[44:47], v[174:177], v[190:193], v[44:47]
	v_mfma_f32_16x16x32_bf16 v[52:55], v[182:185], v[190:193], v[52:55]
	v_mfma_f32_16x16x32_bf16 v[28:31], v[174:177], v[198:201], v[28:31]
	v_mfma_f32_16x16x32_bf16 v[36:39], v[182:185], v[198:201], v[36:39]
	v_mfma_f32_16x16x32_bf16 v[12:15], v[174:177], v[206:209], v[12:15]
	v_mfma_f32_16x16x32_bf16 v[20:23], v[182:185], v[206:209], v[20:23]
	v_mfma_f32_16x16x32_bf16 v[4:7], v[174:177], v[214:217], v[4:7]
	v_mfma_f32_16x16x32_bf16 v[0:3], v[182:185], v[214:217], v[0:3]
	s_setprio 0
	s_barrier
	s_add_i32 s66, s66, 2
	s_add_u32 s25, s25, 0x100
	s_addc_u32 s65, s65, 0
	s_cmpk_gt_u32 s66, 0x53
	s_mov_b64 s[26:27], s[2:3]
	s_cbranch_scc0 .LBB0_2741
	s_branch .Lkx_32
.LBB0_2741:
	ds_read_b128 v[128:131], v170
	ds_read_b128 v[132:135], v170 offset:1024
	ds_read_b128 v[136:139], v170 offset:2048
	ds_read_b128 v[140:143], v170 offset:3072
	ds_read_b128 v[162:165], v171
	ds_read_b128 v[174:177], v171 offset:1024
	ds_read_b128 v[178:181], v171 offset:2048
	ds_read_b128 v[182:185], v171 offset:3072
	s_add_u32 s2, s26, 0x100
	s_addc_u32 s3, s27, 0
	s_cmpk_eq_i32 s66, 0x52
	s_cselect_b32 s31, s21, s3
	s_cselect_b32 s30, s20, s2
	s_cselect_b32 s29, s23, s65
	s_cselect_b32 s28, s22, s25
	v_lshl_add_u64 v[166:167], s[26:27], 0, v[154:155]
	s_add_i32 m0, s40, 0xc000
	ds_read_b128 v[186:189], v172
	ds_read_b128 v[190:193], v172 offset:1024
	ds_read_b128 v[194:197], v172 offset:2048
	ds_read_b128 v[198:201], v172 offset:3072
	ds_read_b128 v[202:205], v172 offset:4096
	ds_read_b128 v[206:209], v172 offset:5120
	ds_read_b128 v[210:213], v172 offset:6144
	ds_read_b128 v[214:217], v172 offset:7168
	global_load_lds_dwordx4 v[166:167], off
	v_lshl_add_u64 v[166:167], s[26:27], 0, v[156:157]
	s_add_i32 m0, s40, 0xe000
	s_nop 0
	global_load_lds_dwordx4 v[166:167], off
	s_waitcnt vmcnt(8)
	s_waitcnt lgkmcnt(0)
	s_setprio 1
	s_barrier
; #define PG8_STAGE(bufoff, gbase, voff) do { _Pragma("unroll") for (int _i = 0; _i < 2; ++_i) \
;         __builtin_amdgcn_global_load_lds((const unsigned*)((const char*)(gbase) + (voff)[_i]), (PG8_LAS unsigned*)(lds + (bufoff) + ldsw + _i * 8192), 16, 0, 0); } while (0)
; #define PG8_LDA(dst, b, h) do { _Pragma("unroll") for (int m = 0; m < 4; ++m) _Pragma("unroll") for (int k = 0; k < 2; ++k) dst[m][k] = *(const PG8_LAS bf16x8*)(lds + PG8_SA(b, h) + aoff + m * 2048 + k * 1024); } while (0)
; #define PG8_MMA(ai, bj, At, Bt) do { __builtin_amdgcn_s_setprio(1); _Pragma("unroll") for (int m = 0; m < 4; ++m) _Pragma("unroll") for (int n = 0; n < 2; ++n) _Pragma("unroll") for (int k = 0; k < 2; ++k) \
;         acc[ai][bj][m][n] = __builtin_amdgcn_mfma_f32_16x16x32_bf16(Bt[n][k], At[m][k], acc[ai][bj][m][n], 0, 0, 0); __builtin_amdgcn_s_setprio(0); } while (0)
; #define PG8_WAIT_V(n) asm volatile("s_waitcnt vmcnt(" #n ")" ::: "memory")
; #define PG8_WAIT_L(n) asm volatile("s_waitcnt lgkmcnt(" #n ")" ::: "memory")
; #define PG8_BAR __builtin_amdgcn_s_barrier()
; #define PG8_SCHED __builtin_amdgcn_sched_barrier(0)
; template <class Epi, class Sched, bool ALIGN_EPI = false, bool SP2 = false>
; __device__ __forceinline__ void gemm_phase(PG8_LAS unsigned char* lds, const Gemm g, const Sched& S, const Epi& E, const int wave_in) {
;     ...
;             PG8_WAIT_V(8); PG8_WAIT_L(0); PG8_BAR; PG8_MMA(0, 0, At, B0); PG8_MMA(0, 1, At, B1); PG8_BAR; PG8_SCHED;
;             PG8_LDA(At, 0, 1); PG8_STAGE(PG8_SB(0, 0), b2, voffB); PG8_STAGE(PG8_SB(0, 1), b2 + hstepB, voffB); PG8_STAGE(PG8_SA(0, 0), a2, voffA);
;             PG8_WAIT_V(8); PG8_WAIT_L(0); PG8_BAR; PG8_MMA(1, 0, At, B0); PG8_MMA(1, 1, At, B1); PG8_BAR; PG8_SCHED;
	v_mfma_f32_16x16x32_bf16 v[124:127], v[128:131], v[186:189], v[124:127]
	v_mfma_f32_16x16x32_bf16 v[120:123], v[136:139], v[186:189], v[120:123]
	v_mfma_f32_16x16x32_bf16 v[104:107], v[128:131], v[194:197], v[104:107]
	v_mfma_f32_16x16x32_bf16 v[108:111], v[136:139], v[194:197], v[108:111]
	v_mfma_f32_16x16x32_bf16 v[88:91], v[128:131], v[202:205], v[88:91]
	v_mfma_f32_16x16x32_bf16 v[92:95], v[136:139], v[202:205], v[92:95]
	v_mfma_f32_16x16x32_bf16 v[72:75], v[128:131], v[210:213], v[72:75]
	v_mfma_f32_16x16x32_bf16 v[76:79], v[136:139], v[210:213], v[76:79]
	v_mfma_f32_16x16x32_bf16 v[124:127], v[132:135], v[190:193], v[124:127]
	v_mfma_f32_16x16x32_bf16 v[120:123], v[140:143], v[190:193], v[120:123]
	v_mfma_f32_16x16x32_bf16 v[104:107], v[132:135], v[198:201], v[104:107]
	v_mfma_f32_16x16x32_bf16 v[108:111], v[140:143], v[198:201], v[108:111]
	v_mfma_f32_16x16x32_bf16 v[88:91], v[132:135], v[206:209], v[88:91]
	v_mfma_f32_16x16x32_bf16 v[92:95], v[140:143], v[206:209], v[92:95]
	v_mfma_f32_16x16x32_bf16 v[72:75], v[132:135], v[214:217], v[72:75]
	v_mfma_f32_16x16x32_bf16 v[76:79], v[140:143], v[214:217], v[76:79]
	v_mfma_f32_16x16x32_bf16 v[112:115], v[162:165], v[186:189], v[112:115]
	v_mfma_f32_16x16x32_bf16 v[116:119], v[178:181], v[186:189], v[116:119]
	v_mfma_f32_16x16x32_bf16 v[96:99], v[162:165], v[194:197], v[96:99]
	v_mfma_f32_16x16x32_bf16 v[100:103], v[178:181], v[194:197], v[100:103]
	v_mfma_f32_16x16x32_bf16 v[80:83], v[162:165], v[202:205], v[80:83]
	v_mfma_f32_16x16x32_bf16 v[84:87], v[178:181], v[202:205], v[84:87]
	v_mfma_f32_16x16x32_bf16 v[64:67], v[162:165], v[210:213], v[64:67]
	v_mfma_f32_16x16x32_bf16 v[68:71], v[178:181], v[210:213], v[68:71]
	v_mfma_f32_16x16x32_bf16 v[112:115], v[174:177], v[190:193], v[112:115]
	v_mfma_f32_16x16x32_bf16 v[116:119], v[182:185], v[190:193], v[116:119]
	v_mfma_f32_16x16x32_bf16 v[96:99], v[174:177], v[198:201], v[96:99]
	v_mfma_f32_16x16x32_bf16 v[100:103], v[182:185], v[198:201], v[100:103]
	v_mfma_f32_16x16x32_bf16 v[80:83], v[174:177], v[206:209], v[80:83]
	v_mfma_f32_16x16x32_bf16 v[84:87], v[182:185], v[206:209], v[84:87]
	v_mfma_f32_16x16x32_bf16 v[64:67], v[174:177], v[214:217], v[64:67]
	v_mfma_f32_16x16x32_bf16 v[68:71], v[182:185], v[214:217], v[68:71]
	s_setprio 0
	s_barrier
	s_add_i32 s26, s50, s39
	v_lshl_add_u64 v[166:167], s[28:29], 0, v[146:147]
	s_mov_b32 m0, s26
	ds_read_b128 v[186:189], v172 offset:16384
	ds_read_b128 v[190:193], v172 offset:17408
	ds_read_b128 v[194:197], v172 offset:18432
	ds_read_b128 v[198:201], v172 offset:19456
	ds_read_b128 v[202:205], v172 offset:20480
	ds_read_b128 v[206:209], v172 offset:21504
	ds_read_b128 v[210:213], v172 offset:22528
	ds_read_b128 v[214:217], v172 offset:23552
	global_load_lds_dwordx4 v[166:167], off
	s_add_i32 m0, s26, 0x2000
	s_add_u32 s26, s28, 0x158000
	v_lshl_add_u64 v[218:219], s[28:29], 0, v[150:151]
	s_addc_u32 s27, s29, 0
	s_add_i32 s67, s51, s39
	global_load_lds_dwordx4 v[218:219], off
	v_lshl_add_u64 v[220:221], s[26:27], 0, v[146:147]
	s_mov_b32 m0, s67
	v_lshl_add_u64 v[222:223], s[30:31], 0, v[148:149]
	global_load_lds_dwordx4 v[220:221], off
	v_lshl_add_u64 v[220:221], s[26:27], 0, v[150:151]
	s_add_i32 m0, s67, 0x2000
	s_nop 0
	global_load_lds_dwordx4 v[220:221], off
	v_lshl_add_u64 v[220:221], s[30:31], 0, v[144:145]
	s_mov_b32 m0, s40
	s_nop 0
	global_load_lds_dwordx4 v[220:221], off
	s_mov_b32 m0, s41
	s_nop 0
	global_load_lds_dwordx4 v[222:223], off
	s_waitcnt vmcnt(8)
	s_waitcnt lgkmcnt(0)
	s_setprio 1
	s_barrier
	v_mfma_f32_16x16x32_bf16 v[60:63], v[128:131], v[186:189], v[60:63]
	v_mfma_f32_16x16x32_bf16 v[56:59], v[136:139], v[186:189], v[56:59]
	v_mfma_f32_16x16x32_bf16 v[40:43], v[128:131], v[194:197], v[40:43]
	v_mfma_f32_16x16x32_bf16 v[48:51], v[136:139], v[194:197], v[48:51]
	v_mfma_f32_16x16x32_bf16 v[24:27], v[128:131], v[202:205], v[24:27]
	v_mfma_f32_16x16x32_bf16 v[32:35], v[136:139], v[202:205], v[32:35]
	v_mfma_f32_16x16x32_bf16 v[8:11], v[128:131], v[210:213], v[8:11]
	v_mfma_f32_16x16x32_bf16 v[16:19], v[136:139], v[210:213], v[16:19]
	v_mfma_f32_16x16x32_bf16 v[60:63], v[132:135], v[190:193], v[60:63]
	v_mfma_f32_16x16x32_bf16 v[56:59], v[140:143], v[190:193], v[56:59]
	v_mfma_f32_16x16x32_bf16 v[40:43], v[132:135], v[198:201], v[40:43]
	v_mfma_f32_16x16x32_bf16 v[48:51], v[140:143], v[198:201], v[48:51]
	v_mfma_f32_16x16x32_bf16 v[24:27], v[132:135], v[206:209], v[24:27]
	v_mfma_f32_16x16x32_bf16 v[32:35], v[140:143], v[206:209], v[32:35]
	v_mfma_f32_16x16x32_bf16 v[8:11], v[132:135], v[214:217], v[8:11]
	v_mfma_f32_16x16x32_bf16 v[16:19], v[140:143], v[214:217], v[16:19]
	v_mfma_f32_16x16x32_bf16 v[44:47], v[162:165], v[186:189], v[44:47]
	v_mfma_f32_16x16x32_bf16 v[52:55], v[178:181], v[186:189], v[52:55]
	v_mfma_f32_16x16x32_bf16 v[28:31], v[162:165], v[194:197], v[28:31]
	v_mfma_f32_16x16x32_bf16 v[36:39], v[178:181], v[194:197], v[36:39]
	v_mfma_f32_16x16x32_bf16 v[12:15], v[162:165], v[202:205], v[12:15]
	v_mfma_f32_16x16x32_bf16 v[20:23], v[178:181], v[202:205], v[20:23]
	v_mfma_f32_16x16x32_bf16 v[4:7], v[162:165], v[210:213], v[4:7]
	v_mfma_f32_16x16x32_bf16 v[0:3], v[178:181], v[210:213], v[0:3]
	v_mfma_f32_16x16x32_bf16 v[44:47], v[174:177], v[190:193], v[44:47]
	v_mfma_f32_16x16x32_bf16 v[52:55], v[182:185], v[190:193], v[52:55]
	v_mfma_f32_16x16x32_bf16 v[28:31], v[174:177], v[198:201], v[28:31]
	v_mfma_f32_16x16x32_bf16 v[36:39], v[182:185], v[198:201], v[36:39]
	v_mfma_f32_16x16x32_bf16 v[12:15], v[174:177], v[206:209], v[12:15]
	v_mfma_f32_16x16x32_bf16 v[20:23], v[182:185], v[206:209], v[20:23]
	v_mfma_f32_16x16x32_bf16 v[4:7], v[174:177], v[214:217], v[4:7]
	v_mfma_f32_16x16x32_bf16 v[0:3], v[182:185], v[214:217], v[0:3]
	s_setprio 0
	s_barrier
; #define PG8_STAGE(bufoff, gbase, voff) do { _Pragma("unroll") for (int _i = 0; _i < 2; ++_i) \
;         __builtin_amdgcn_global_load_lds((const unsigned*)((const char*)(gbase) + (voff)[_i]), (PG8_LAS unsigned*)(lds + (bufoff) + ldsw + _i * 8192), 16, 0, 0); } while (0)
; #define PG8_LDA(dst, b, h) do { _Pragma("unroll") for (int m = 0; m < 4; ++m) _Pragma("unroll") for (int k = 0; k < 2; ++k) dst[m][k] = *(const PG8_LAS bf16x8*)(lds + PG8_SA(b, h) + aoff + m * 2048 + k * 1024); } while (0)
; #define PG8_LDB(dst, b, h) do { _Pragma("unroll") for (int n = 0; n < 2; ++n) _Pragma("unroll") for (int k = 0; k < 2; ++k) dst[n][k] = *(const PG8_LAS bf16x8*)(lds + PG8_SB(b, h) + boff + n * 2048 + k * 1024); } while (0)
; #define PG8_MMA(ai, bj, At, Bt) do { __builtin_amdgcn_s_setprio(1); _Pragma("unroll") for (int m = 0; m < 4; ++m) _Pragma("unroll") for (int n = 0; n < 2; ++n) _Pragma("unroll") for (int k = 0; k < 2; ++k) \
;         acc[ai][bj][m][n] = __builtin_amdgcn_mfma_f32_16x16x32_bf16(Bt[n][k], At[m][k], acc[ai][bj][m][n], 0, 0, 0); __builtin_amdgcn_s_setprio(0); } while (0)
; #define PG8_WAIT_V(n) asm volatile("s_waitcnt vmcnt(" #n ")" ::: "memory")
; #define PG8_WAIT_L(n) asm volatile("s_waitcnt lgkmcnt(" #n ")" ::: "memory")
; #define PG8_BAR __builtin_amdgcn_s_barrier()
; #define PG8_SCHED __builtin_amdgcn_sched_barrier(0)
; template <class Epi, class Sched, bool ALIGN_EPI = false, bool SP2 = false>
; __device__ __forceinline__ void gemm_phase(PG8_LAS unsigned char* lds, const Gemm g, const Sched& S, const Epi& E, const int wave_in) {
;     ...
;         for (int t = 0; t < nt; t += 2) {
;     ...
;             PG8_LDB(B0, 1, 0); PG8_LDB(B1, 1, 1); PG8_SCHED; PG8_LDA(At, 1, 0); PG8_STAGE(PG8_SA(0, 1), a2 + hstepA, voffA);
;             PG8_WAIT_V(8); PG8_WAIT_L(0); PG8_BAR; PG8_MMA(0, 0, At, B0); PG8_MMA(0, 1, At, B1); PG8_BAR; PG8_SCHED;
;             PG8_LDA(At, 1, 1); PG8_STAGE(PG8_SB(1, 0), b3, voffB); PG8_STAGE(PG8_SB(1, 1), b3 + hstepB, voffB); PG8_STAGE(PG8_SA(1, 0), a3, voffA);
;             PG8_WAIT_V(8); PG8_WAIT_L(0); PG8_BAR; PG8_MMA(1, 0, At, B0); PG8_MMA(1, 1, At, B1); PG8_BAR; PG8_SCHED;
	s_add_i32 s67, 0, 0x18000
	s_add_i32 s68, 0, 0x1c000
	v_add_u32_e32 v140, s67, v168
	v_add_u32_e32 v173, s68, v168
	ds_read_b128 v[128:131], v140
	ds_read_b128 v[132:135], v140 offset:1024
	ds_read_b128 v[136:139], v140 offset:2048
	ds_read_b128 v[140:143], v140 offset:3072
	ds_read_b128 v[162:165], v173
	ds_read_b128 v[174:177], v173 offset:1024
	ds_read_b128 v[178:181], v173 offset:2048
	ds_read_b128 v[182:185], v173 offset:3072
	s_add_u32 s26, s30, 0x158000
	s_addc_u32 s27, s31, 0
	s_mov_b32 m0, s42
	v_lshl_add_u64 v[224:225], s[26:27], 0, v[144:145]
	ds_read_b128 v[186:189], v172 offset:32768
	ds_read_b128 v[190:193], v172 offset:33792
	ds_read_b128 v[194:197], v172 offset:34816
	ds_read_b128 v[198:201], v172 offset:35840
	ds_read_b128 v[202:205], v172 offset:36864
	ds_read_b128 v[206:209], v172 offset:37888
	ds_read_b128 v[210:213], v172 offset:38912
	ds_read_b128 v[214:217], v172 offset:39936
	global_load_lds_dwordx4 v[224:225], off
	v_lshl_add_u64 v[224:225], s[26:27], 0, v[148:149]
	s_mov_b32 m0, s43
	s_nop 0
	global_load_lds_dwordx4 v[224:225], off
	s_waitcnt vmcnt(8)
	s_waitcnt lgkmcnt(0)
	s_setprio 1
	s_barrier
	v_mfma_f32_16x16x32_bf16 v[124:127], v[128:131], v[186:189], v[124:127]
	v_mfma_f32_16x16x32_bf16 v[120:123], v[136:139], v[186:189], v[120:123]
	v_mfma_f32_16x16x32_bf16 v[104:107], v[128:131], v[194:197], v[104:107]
	v_mfma_f32_16x16x32_bf16 v[108:111], v[136:139], v[194:197], v[108:111]
	v_mfma_f32_16x16x32_bf16 v[88:91], v[128:131], v[202:205], v[88:91]
	v_mfma_f32_16x16x32_bf16 v[92:95], v[136:139], v[202:205], v[92:95]
	v_mfma_f32_16x16x32_bf16 v[72:75], v[128:131], v[210:213], v[72:75]
	v_mfma_f32_16x16x32_bf16 v[76:79], v[136:139], v[210:213], v[76:79]
	v_mfma_f32_16x16x32_bf16 v[124:127], v[132:135], v[190:193], v[124:127]
	v_mfma_f32_16x16x32_bf16 v[120:123], v[140:143], v[190:193], v[120:123]
	v_mfma_f32_16x16x32_bf16 v[104:107], v[132:135], v[198:201], v[104:107]
	v_mfma_f32_16x16x32_bf16 v[108:111], v[140:143], v[198:201], v[108:111]
	v_mfma_f32_16x16x32_bf16 v[88:91], v[132:135], v[206:209], v[88:91]
	v_mfma_f32_16x16x32_bf16 v[92:95], v[140:143], v[206:209], v[92:95]
	v_mfma_f32_16x16x32_bf16 v[72:75], v[132:135], v[214:217], v[72:75]
	v_mfma_f32_16x16x32_bf16 v[76:79], v[140:143], v[214:217], v[76:79]
	v_mfma_f32_16x16x32_bf16 v[112:115], v[162:165], v[186:189], v[112:115]
	v_mfma_f32_16x16x32_bf16 v[116:119], v[178:181], v[186:189], v[116:119]
	v_mfma_f32_16x16x32_bf16 v[96:99], v[162:165], v[194:197], v[96:99]
	v_mfma_f32_16x16x32_bf16 v[100:103], v[178:181], v[194:197], v[100:103]
	v_mfma_f32_16x16x32_bf16 v[80:83], v[162:165], v[202:205], v[80:83]
	v_mfma_f32_16x16x32_bf16 v[84:87], v[178:181], v[202:205], v[84:87]
	v_mfma_f32_16x16x32_bf16 v[64:67], v[162:165], v[210:213], v[64:67]
	v_mfma_f32_16x16x32_bf16 v[68:71], v[178:181], v[210:213], v[68:71]
	v_mfma_f32_16x16x32_bf16 v[112:115], v[174:177], v[190:193], v[112:115]
	v_mfma_f32_16x16x32_bf16 v[116:119], v[182:185], v[190:193], v[116:119]
	v_mfma_f32_16x16x32_bf16 v[96:99], v[174:177], v[198:201], v[96:99]
	v_mfma_f32_16x16x32_bf16 v[100:103], v[182:185], v[198:201], v[100:103]
	v_mfma_f32_16x16x32_bf16 v[80:83], v[174:177], v[206:209], v[80:83]
	v_mfma_f32_16x16x32_bf16 v[84:87], v[182:185], v[206:209], v[84:87]
	v_mfma_f32_16x16x32_bf16 v[64:67], v[174:177], v[214:217], v[64:67]
	v_mfma_f32_16x16x32_bf16 v[68:71], v[182:185], v[214:217], v[68:71]
	s_setprio 0
	s_barrier
	s_add_i32 s26, s67, s39
	v_lshl_add_u64 v[166:167], v[166:167], 0, s[6:7]
	s_mov_b32 m0, s26
	ds_read_b128 v[186:189], v172 offset:49152
	ds_read_b128 v[190:193], v172 offset:50176
	ds_read_b128 v[194:197], v172 offset:51200
	ds_read_b128 v[198:201], v172 offset:52224
	ds_read_b128 v[202:205], v172 offset:53248
	ds_read_b128 v[206:209], v172 offset:54272
	ds_read_b128 v[210:213], v172 offset:55296
	ds_read_b128 v[214:217], v172 offset:56320
	global_load_lds_dwordx4 v[166:167], off
	s_add_i32 m0, s26, 0x2000
	s_add_u32 s26, s28, 0x158080
	v_lshl_add_u64 v[166:167], v[218:219], 0, s[6:7]
	s_addc_u32 s27, s29, 0
	s_add_i32 s28, s68, s39
	global_load_lds_dwordx4 v[166:167], off
	v_lshl_add_u64 v[166:167], s[26:27], 0, v[146:147]
	s_mov_b32 m0, s28
	s_nop 0
	global_load_lds_dwordx4 v[166:167], off
	v_lshl_add_u64 v[166:167], s[26:27], 0, v[150:151]
	s_add_i32 m0, s28, 0x2000
	s_nop 0
	global_load_lds_dwordx4 v[166:167], off
	v_lshl_add_u64 v[166:167], v[220:221], 0, s[6:7]
	s_mov_b32 m0, s48
	s_nop 0
	global_load_lds_dwordx4 v[166:167], off
	v_lshl_add_u64 v[166:167], v[222:223], 0, s[6:7]
	s_mov_b32 m0, s49
	s_nop 0
	global_load_lds_dwordx4 v[166:167], off
	s_waitcnt vmcnt(8)
	s_waitcnt lgkmcnt(0)
	s_setprio 1
	s_barrier
	v_mfma_f32_16x16x32_bf16 v[60:63], v[128:131], v[186:189], v[60:63]
	v_mfma_f32_16x16x32_bf16 v[56:59], v[136:139], v[186:189], v[56:59]
	v_mfma_f32_16x16x32_bf16 v[40:43], v[128:131], v[194:197], v[40:43]
	v_mfma_f32_16x16x32_bf16 v[48:51], v[136:139], v[194:197], v[48:51]
	v_mfma_f32_16x16x32_bf16 v[24:27], v[128:131], v[202:205], v[24:27]
	v_mfma_f32_16x16x32_bf16 v[32:35], v[136:139], v[202:205], v[32:35]
	v_mfma_f32_16x16x32_bf16 v[8:11], v[128:131], v[210:213], v[8:11]
	v_mfma_f32_16x16x32_bf16 v[16:19], v[136:139], v[210:213], v[16:19]
	v_mfma_f32_16x16x32_bf16 v[60:63], v[132:135], v[190:193], v[60:63]
	v_mfma_f32_16x16x32_bf16 v[56:59], v[140:143], v[190:193], v[56:59]
	v_mfma_f32_16x16x32_bf16 v[40:43], v[132:135], v[198:201], v[40:43]
	v_mfma_f32_16x16x32_bf16 v[48:51], v[140:143], v[198:201], v[48:51]
	v_mfma_f32_16x16x32_bf16 v[24:27], v[132:135], v[206:209], v[24:27]
	v_mfma_f32_16x16x32_bf16 v[32:35], v[140:143], v[206:209], v[32:35]
	v_mfma_f32_16x16x32_bf16 v[8:11], v[132:135], v[214:217], v[8:11]
	v_mfma_f32_16x16x32_bf16 v[16:19], v[140:143], v[214:217], v[16:19]
	v_mfma_f32_16x16x32_bf16 v[44:47], v[162:165], v[186:189], v[44:47]
	v_mfma_f32_16x16x32_bf16 v[52:55], v[178:181], v[186:189], v[52:55]
	v_mfma_f32_16x16x32_bf16 v[28:31], v[162:165], v[194:197], v[28:31]
	v_mfma_f32_16x16x32_bf16 v[36:39], v[178:181], v[194:197], v[36:39]
	v_mfma_f32_16x16x32_bf16 v[12:15], v[162:165], v[202:205], v[12:15]
	v_mfma_f32_16x16x32_bf16 v[20:23], v[178:181], v[202:205], v[20:23]
	v_mfma_f32_16x16x32_bf16 v[4:7], v[162:165], v[210:213], v[4:7]
	v_mfma_f32_16x16x32_bf16 v[0:3], v[178:181], v[210:213], v[0:3]
	v_mfma_f32_16x16x32_bf16 v[44:47], v[174:177], v[190:193], v[44:47]
	v_mfma_f32_16x16x32_bf16 v[52:55], v[182:185], v[190:193], v[52:55]
	v_mfma_f32_16x16x32_bf16 v[28:31], v[174:177], v[198:201], v[28:31]
	v_mfma_f32_16x16x32_bf16 v[36:39], v[182:185], v[198:201], v[36:39]
	v_mfma_f32_16x16x32_bf16 v[12:15], v[174:177], v[206:209], v[12:15]
	v_mfma_f32_16x16x32_bf16 v[20:23], v[182:185], v[206:209], v[20:23]
	v_mfma_f32_16x16x32_bf16 v[4:7], v[174:177], v[214:217], v[4:7]
	v_mfma_f32_16x16x32_bf16 v[0:3], v[182:185], v[214:217], v[0:3]
	s_setprio 0
	s_barrier
	s_add_i32 s66, s66, 2
	s_add_u32 s25, s25, 0x100
	s_addc_u32 s65, s65, 0
	s_cmpk_gt_u32 s66, 0x53
	s_mov_b64 s[26:27], s[2:3]
	s_cbranch_scc0 .LBB0_2741
